# strategy 9 (back-edge rotation): all 9 GEMM K-loops test their counter before the loop-back barrier, barrier is the loop head, exit path has its own barrier copy
# baseline (speedup 1.0000x reference)
; #define PG8_STAGE(bufoff, gbase, voff) do { _Pragma("unroll") for (int _i = 0; _i < 2; ++_i) \
;         __builtin_amdgcn_global_load_lds((const unsigned*)((const char*)(gbase) + (voff)[_i]), (PG8_LAS unsigned*)(lds + (bufoff) + ldsw + _i * 8192), 16, 0, 0); } while (0)
; #define PG8_LDA(dst, b, h) do { _Pragma("unroll") for (int m = 0; m < 4; ++m) _Pragma("unroll") for (int k = 0; k < 2; ++k) dst[m][k] = *(const PG8_LAS bf16x8*)(lds + PG8_SA(b, h) + aoff + m * 2048 + k * 1024); } while (0)
; #define PG8_LDB(dst, b, h) do { _Pragma("unroll") for (int n = 0; n < 2; ++n) _Pragma("unroll") for (int k = 0; k < 2; ++k) dst[n][k] = *(const PG8_LAS bf16x8*)(lds + PG8_SB(b, h) + boff + n * 2048 + k * 1024); } while (0)
; #define PG8_WAIT_V(n) asm volatile("s_waitcnt vmcnt(" #n ")" ::: "memory")
; #define PG8_WAIT_L(n) asm volatile("s_waitcnt lgkmcnt(" #n ")" ::: "memory")
; #define PG8_BAR __builtin_amdgcn_s_barrier()
; template <class Epi, class Sched, bool ALIGN_EPI = false, bool SP2 = false, bool F8 = false>
; __device__ __forceinline__ void gemm_phase(PG8_LAS unsigned char* lds, const Gemm g, const Sched& S, const Epi& E) {
;     ...
;         const bool has_next = S.next(ui + 1, nxt);
;         const char* nA = has_next ? (const char*)g.A + (size_t)nxt.pm * tA + (size_t)(nxt.pn >> g.gshift) * g.goff : cA; const char* nB = has_next ? (const char*)g.Bt + (size_t)nxt.pn * tB : cB;
;         for (int t = 0; t < nt; t += 2) {
;             const bool last = (t == nt - 2);
;             const char* a1 = cA + (size_t)(t + 1) * kstep;
;             const char* a2 = last ? nA : cA + (size_t)(t + 2) * kstep; const char* b2 = last ? nB : cB + (size_t)(t + 2) * kstep;
;             const char* a3 = a2 + kstep; const char* b3 = b2 + kstep;
;             if (last && has_next) S.a_ready(nxt);
;             if constexpr (SP2) {
;             PG8_LDB(B0, 0, 0); PG8_LDB(B1, 0, 1); PG8_SCHED; PG8_LDA(At, 0, 0); PG8_STAGE(PG8_SA(1, 1), a1 + hA, voffA);
;             PG8_WAIT_V(8); PG8_WAIT_L(0); PG8_BAR; PG8_MMA(0, 0, At, B0); PG8_MMA(0, 1, At, B1); PG8_BAR; PG8_SCHED;
;     ...
;         for (int a = 0; a < 2; ++a)
; #pragma unroll
;             for (int b = 0; b < 2; ++b)
; #pragma unroll
;                 for (int m = 0; m < 4; ++m)
; #pragma unroll
;                     for (int n = 0; n < 2; ++n) acc[a][b][m][n] = (f32x4){0.f, 0.f, 0.f, 0.f};
.LBB0_127:
	s_ashr_i32 s31, s30, 31
	s_lshl_b64 s[34:35], s[30:31], 21
	s_add_u32 s34, s18, s34
	s_addc_u32 s35, s19, s35
	s_and_b64 s[36:37], s[4:5], exec
	s_cselect_b32 s31, s35, s41
	s_cselect_b32 s62, s34, s40
	s_ashr_i32 s29, s28, 31
	s_lshl_b64 s[36:37], s[28:29], 21
	s_add_u32 s36, s33, s36
	s_addc_u32 s37, s44, s37
	s_and_b64 s[42:43], s[4:5], exec
	s_cselect_b32 s29, s37, s39
	s_cselect_b32 s63, s36, s38
	s_add_u32 s64, s38, 0x100
	s_addc_u32 s65, s39, 0
	s_add_u32 s38, s40, 0x100080
	v_mov_b32_e32 v2, 0
	s_addc_u32 s39, s41, 0
	s_mov_b32 s66, -2
	v_mov_b32_e32 v3, v2
	v_mov_b32_e32 v4, v2
	v_mov_b32_e32 v5, v2
	v_mov_b32_e32 v6, v2
	v_mov_b32_e32 v7, v2
	v_mov_b32_e32 v8, v2
	v_mov_b32_e32 v9, v2
	v_mov_b32_e32 v10, v2
	v_mov_b32_e32 v11, v2
	v_mov_b32_e32 v12, v2
	v_mov_b32_e32 v13, v2
	v_mov_b32_e32 v14, v2
	v_mov_b32_e32 v15, v2
	v_mov_b32_e32 v16, v2
	v_mov_b32_e32 v17, v2
	v_mov_b32_e32 v26, v2
	v_mov_b32_e32 v27, v2
	v_mov_b32_e32 v28, v2
	v_mov_b32_e32 v29, v2
	v_mov_b32_e32 v30, v2
	v_mov_b32_e32 v31, v2
	v_mov_b32_e32 v32, v2
	v_mov_b32_e32 v33, v2
	v_mov_b32_e32 v42, v2
	v_mov_b32_e32 v43, v2
	v_mov_b32_e32 v44, v2
	v_mov_b32_e32 v45, v2
	v_mov_b32_e32 v46, v2
	v_mov_b32_e32 v47, v2
	v_mov_b32_e32 v48, v2
	v_mov_b32_e32 v49, v2
	v_mov_b32_e32 v18, v2
	v_mov_b32_e32 v19, v2
	v_mov_b32_e32 v20, v2
	v_mov_b32_e32 v21, v2
	v_mov_b32_e32 v22, v2
	v_mov_b32_e32 v23, v2
	v_mov_b32_e32 v24, v2
	v_mov_b32_e32 v25, v2
	v_mov_b32_e32 v34, v2
	v_mov_b32_e32 v35, v2
	v_mov_b32_e32 v36, v2
	v_mov_b32_e32 v37, v2
	v_mov_b32_e32 v38, v2
	v_mov_b32_e32 v39, v2
	v_mov_b32_e32 v40, v2
	v_mov_b32_e32 v41, v2
	v_mov_b32_e32 v50, v2
	v_mov_b32_e32 v51, v2
	v_mov_b32_e32 v52, v2
	v_mov_b32_e32 v53, v2
	v_mov_b32_e32 v54, v2
	v_mov_b32_e32 v55, v2
	v_mov_b32_e32 v56, v2
	v_mov_b32_e32 v57, v2
	v_mov_b32_e32 v58, v2
	v_mov_b32_e32 v59, v2
	v_mov_b32_e32 v60, v2
	v_mov_b32_e32 v61, v2
	v_mov_b32_e32 v62, v2
	v_mov_b32_e32 v63, v2
	v_mov_b32_e32 v64, v2
	v_mov_b32_e32 v65, v2
	v_mov_b32_e32 v66, v2
	v_mov_b32_e32 v67, v2
	v_mov_b32_e32 v68, v2
	v_mov_b32_e32 v69, v2
	v_mov_b32_e32 v70, v2
	v_mov_b32_e32 v71, v2
	v_mov_b32_e32 v72, v2
	v_mov_b32_e32 v73, v2
	v_mov_b32_e32 v74, v2
	v_mov_b32_e32 v75, v2
	v_mov_b32_e32 v76, v2
	v_mov_b32_e32 v77, v2
	v_mov_b32_e32 v78, v2
	v_mov_b32_e32 v79, v2
	v_mov_b32_e32 v80, v2
	v_mov_b32_e32 v81, v2
	v_mov_b32_e32 v90, v2
	v_mov_b32_e32 v91, v2
	v_mov_b32_e32 v92, v2
	v_mov_b32_e32 v93, v2
	v_mov_b32_e32 v94, v2
	v_mov_b32_e32 v95, v2
	v_mov_b32_e32 v96, v2
	v_mov_b32_e32 v97, v2
	v_mov_b32_e32 v106, v2
	v_mov_b32_e32 v107, v2
	v_mov_b32_e32 v108, v2
	v_mov_b32_e32 v109, v2
	v_mov_b32_e32 v110, v2
	v_mov_b32_e32 v111, v2
	v_mov_b32_e32 v112, v2
	v_mov_b32_e32 v113, v2
	v_mov_b32_e32 v82, v2
	v_mov_b32_e32 v83, v2
	v_mov_b32_e32 v84, v2
	v_mov_b32_e32 v85, v2
	v_mov_b32_e32 v86, v2
	v_mov_b32_e32 v87, v2
	v_mov_b32_e32 v88, v2
	v_mov_b32_e32 v89, v2
	v_mov_b32_e32 v98, v2
	v_mov_b32_e32 v99, v2
	v_mov_b32_e32 v100, v2
	v_mov_b32_e32 v101, v2
	v_mov_b32_e32 v102, v2
	v_mov_b32_e32 v103, v2
	v_mov_b32_e32 v104, v2
	v_mov_b32_e32 v105, v2
	v_mov_b32_e32 v114, v2
	v_mov_b32_e32 v115, v2
	v_mov_b32_e32 v116, v2
	v_mov_b32_e32 v117, v2
	v_mov_b32_e32 v118, v2
	v_mov_b32_e32 v119, v2
	v_mov_b32_e32 v120, v2
	v_mov_b32_e32 v121, v2
	v_mov_b32_e32 v122, v2
	v_mov_b32_e32 v123, v2
	v_mov_b32_e32 v124, v2
	v_mov_b32_e32 v125, v2
	v_mov_b32_e32 v126, v2
	v_mov_b32_e32 v127, v2
	v_mov_b32_e32 v128, v2
	v_mov_b32_e32 v129, v2
	s_branch .LBB0_128
.Lber_128:
	s_barrier
	s_setprio 0
.LBB0_128:
	ds_read_b128 v[152:155], v149
	ds_read_b128 v[156:159], v149 offset:1024
	ds_read_b128 v[160:163], v149 offset:2048
	ds_read_b128 v[164:167], v149 offset:3072
	ds_read_b128 v[168:171], v150
	ds_read_b128 v[172:175], v150 offset:1024
	ds_read_b128 v[176:179], v150 offset:2048
	ds_read_b128 v[180:183], v150 offset:3072
	s_add_u32 s40, s38, 0xfff00080
	s_addc_u32 s41, s39, -1
	s_cmp_eq_u32 s66, 60
	s_cselect_b32 s43, s31, s41
	s_cselect_b32 s42, s62, s40
	s_cselect_b32 s41, s29, s65
	s_cselect_b32 s40, s63, s64
	v_lshl_add_u64 v[216:217], s[38:39], 0, v[140:141]
	s_add_i32 m0, s27, 0xc000
	ds_read_b128 v[184:187], v151
	ds_read_b128 v[188:191], v151 offset:1024
	ds_read_b128 v[192:195], v151 offset:2048
	ds_read_b128 v[196:199], v151 offset:3072
	ds_read_b128 v[200:203], v151 offset:4096
	ds_read_b128 v[204:207], v151 offset:5120
	ds_read_b128 v[208:211], v151 offset:6144
	ds_read_b128 v[212:215], v151 offset:7168
	global_load_lds_dwordx4 v[216:217], off
	v_lshl_add_u64 v[216:217], s[38:39], 0, v[138:139]
	s_add_i32 m0, s27, 0xe000
	s_nop 0
	global_load_lds_dwordx4 v[216:217], off
	s_waitcnt vmcnt(8)
	s_waitcnt lgkmcnt(0)
	s_setprio 1
	s_barrier
; #define PG8_STAGE(bufoff, gbase, voff) do { _Pragma("unroll") for (int _i = 0; _i < 2; ++_i) \
;         __builtin_amdgcn_global_load_lds((const unsigned*)((const char*)(gbase) + (voff)[_i]), (PG8_LAS unsigned*)(lds + (bufoff) + ldsw + _i * 8192), 16, 0, 0); } while (0)
; #define PG8_LDA(dst, b, h) do { _Pragma("unroll") for (int m = 0; m < 4; ++m) _Pragma("unroll") for (int k = 0; k < 2; ++k) dst[m][k] = *(const PG8_LAS bf16x8*)(lds + PG8_SA(b, h) + aoff + m * 2048 + k * 1024); } while (0)
; #define PG8_LDB(dst, b, h) do { _Pragma("unroll") for (int n = 0; n < 2; ++n) _Pragma("unroll") for (int k = 0; k < 2; ++k) dst[n][k] = *(const PG8_LAS bf16x8*)(lds + PG8_SB(b, h) + boff + n * 2048 + k * 1024); } while (0)
; #define PG8_WAIT_V(n) asm volatile("s_waitcnt vmcnt(" #n ")" ::: "memory")
; #define PG8_WAIT_L(n) asm volatile("s_waitcnt lgkmcnt(" #n ")" ::: "memory")
; #define PG8_BAR __builtin_amdgcn_s_barrier()
; #define PG8_SCHED __builtin_amdgcn_sched_barrier(0)
; template <class Epi, class Sched, bool ALIGN_EPI = false, bool SP2 = false, bool F8 = false>
; __device__ __forceinline__ void gemm_phase(PG8_LAS unsigned char* lds, const Gemm g, const Sched& S, const Epi& E) {
;     ...
;             PG8_WAIT_V(8); PG8_WAIT_L(0); PG8_BAR; PG8_MMA(0, 0, At, B0); PG8_MMA(0, 1, At, B1); PG8_BAR; PG8_SCHED;
;             PG8_LDA(At, 0, 1); PG8_STAGE(PG8_SB(0, 0), b2, voffB); PG8_STAGE(PG8_SB(0, 1), b2 + hB, voffB); PG8_STAGE(PG8_SA(0, 0), a2, voffA);
;             PG8_WAIT_V(8); PG8_WAIT_L(0); PG8_BAR; PG8_MMA(1, 0, At, B0); PG8_MMA(1, 1, At, B1); PG8_BAR; PG8_SCHED;
;             PG8_LDB(B0, 1, 0); PG8_LDB(B1, 1, 1); PG8_SCHED; PG8_LDA(At, 1, 0); PG8_STAGE(PG8_SA(0, 1), a2 + hA, voffA);
;             PG8_WAIT_V(8); PG8_WAIT_L(0); PG8_BAR; PG8_MMA(0, 0, At, B0); PG8_MMA(0, 1, At, B1); PG8_BAR; PG8_SCHED;
	v_mfma_f32_16x16x32_bf16 v[126:129], v[152:155], v[184:187], v[126:129]
	v_mfma_f32_16x16x32_bf16 v[122:125], v[160:163], v[184:187], v[122:125]
	v_mfma_f32_16x16x32_bf16 v[118:121], v[152:155], v[192:195], v[118:121]
	v_mfma_f32_16x16x32_bf16 v[114:117], v[160:163], v[192:195], v[114:117]
	v_mfma_f32_16x16x32_bf16 v[102:105], v[152:155], v[200:203], v[102:105]
	v_mfma_f32_16x16x32_bf16 v[98:101], v[160:163], v[200:203], v[98:101]
	v_mfma_f32_16x16x32_bf16 v[86:89], v[152:155], v[208:211], v[86:89]
	v_mfma_f32_16x16x32_bf16 v[82:85], v[160:163], v[208:211], v[82:85]
	v_mfma_f32_16x16x32_bf16 v[126:129], v[156:159], v[188:191], v[126:129]
	v_mfma_f32_16x16x32_bf16 v[122:125], v[164:167], v[188:191], v[122:125]
	v_mfma_f32_16x16x32_bf16 v[118:121], v[156:159], v[196:199], v[118:121]
	v_mfma_f32_16x16x32_bf16 v[114:117], v[164:167], v[196:199], v[114:117]
	v_mfma_f32_16x16x32_bf16 v[102:105], v[156:159], v[204:207], v[102:105]
	v_mfma_f32_16x16x32_bf16 v[98:101], v[164:167], v[204:207], v[98:101]
	v_mfma_f32_16x16x32_bf16 v[86:89], v[156:159], v[212:215], v[86:89]
	v_mfma_f32_16x16x32_bf16 v[82:85], v[164:167], v[212:215], v[82:85]
	v_mfma_f32_16x16x32_bf16 v[110:113], v[168:171], v[184:187], v[110:113]
	v_mfma_f32_16x16x32_bf16 v[106:109], v[176:179], v[184:187], v[106:109]
	v_mfma_f32_16x16x32_bf16 v[94:97], v[168:171], v[192:195], v[94:97]
	v_mfma_f32_16x16x32_bf16 v[90:93], v[176:179], v[192:195], v[90:93]
	v_mfma_f32_16x16x32_bf16 v[78:81], v[168:171], v[200:203], v[78:81]
	v_mfma_f32_16x16x32_bf16 v[74:77], v[176:179], v[200:203], v[74:77]
	v_mfma_f32_16x16x32_bf16 v[70:73], v[168:171], v[208:211], v[70:73]
	v_mfma_f32_16x16x32_bf16 v[66:69], v[176:179], v[208:211], v[66:69]
	v_mfma_f32_16x16x32_bf16 v[110:113], v[172:175], v[188:191], v[110:113]
	v_mfma_f32_16x16x32_bf16 v[106:109], v[180:183], v[188:191], v[106:109]
	v_mfma_f32_16x16x32_bf16 v[94:97], v[172:175], v[196:199], v[94:97]
	v_mfma_f32_16x16x32_bf16 v[90:93], v[180:183], v[196:199], v[90:93]
	v_mfma_f32_16x16x32_bf16 v[78:81], v[172:175], v[204:207], v[78:81]
	v_mfma_f32_16x16x32_bf16 v[74:77], v[180:183], v[204:207], v[74:77]
	v_mfma_f32_16x16x32_bf16 v[70:73], v[172:175], v[212:215], v[70:73]
	v_mfma_f32_16x16x32_bf16 v[66:69], v[180:183], v[212:215], v[66:69]
	s_barrier
	s_setprio 0
	s_add_i32 s67, s55, s45
	v_lshl_add_u64 v[216:217], s[40:41], 0, v[134:135]
	s_mov_b32 m0, s67
	ds_read_b128 v[184:187], v151 offset:16384
	ds_read_b128 v[188:191], v151 offset:17408
	ds_read_b128 v[192:195], v151 offset:18432
	ds_read_b128 v[196:199], v151 offset:19456
	ds_read_b128 v[200:203], v151 offset:20480
	ds_read_b128 v[204:207], v151 offset:21504
	ds_read_b128 v[208:211], v151 offset:22528
	ds_read_b128 v[212:215], v151 offset:23552
	global_load_lds_dwordx4 v[216:217], off
	s_add_i32 m0, s67, 0x2000
	s_add_u32 s70, s40, 0x100000
	v_lshl_add_u64 v[218:219], s[40:41], 0, v[130:131]
	s_addc_u32 s71, s41, 0
	s_add_i32 s67, s56, s45
	global_load_lds_dwordx4 v[218:219], off
	v_lshl_add_u64 v[220:221], s[70:71], 0, v[134:135]
	s_mov_b32 m0, s67
	v_lshl_add_u64 v[222:223], s[42:43], 0, v[132:133]
	global_load_lds_dwordx4 v[220:221], off
	v_lshl_add_u64 v[220:221], s[70:71], 0, v[130:131]
	s_add_i32 m0, s67, 0x2000
	s_nop 0
	global_load_lds_dwordx4 v[220:221], off
	v_lshl_add_u64 v[220:221], s[42:43], 0, v[136:137]
	s_mov_b32 m0, s27
	s_nop 0
	global_load_lds_dwordx4 v[220:221], off
	s_mov_b32 m0, s48
	s_nop 0
	global_load_lds_dwordx4 v[222:223], off
	s_waitcnt vmcnt(8)
	s_waitcnt lgkmcnt(0)
	s_setprio 1
	s_barrier
	v_mfma_f32_16x16x32_bf16 v[62:65], v[152:155], v[184:187], v[62:65]
	v_mfma_f32_16x16x32_bf16 v[58:61], v[160:163], v[184:187], v[58:61]
	v_mfma_f32_16x16x32_bf16 v[54:57], v[152:155], v[192:195], v[54:57]
	v_mfma_f32_16x16x32_bf16 v[50:53], v[160:163], v[192:195], v[50:53]
	v_mfma_f32_16x16x32_bf16 v[38:41], v[152:155], v[200:203], v[38:41]
	v_mfma_f32_16x16x32_bf16 v[34:37], v[160:163], v[200:203], v[34:37]
	v_mfma_f32_16x16x32_bf16 v[22:25], v[152:155], v[208:211], v[22:25]
	v_mfma_f32_16x16x32_bf16 v[18:21], v[160:163], v[208:211], v[18:21]
	v_mfma_f32_16x16x32_bf16 v[62:65], v[156:159], v[188:191], v[62:65]
	v_mfma_f32_16x16x32_bf16 v[58:61], v[164:167], v[188:191], v[58:61]
	v_mfma_f32_16x16x32_bf16 v[54:57], v[156:159], v[196:199], v[54:57]
	v_mfma_f32_16x16x32_bf16 v[50:53], v[164:167], v[196:199], v[50:53]
	v_mfma_f32_16x16x32_bf16 v[38:41], v[156:159], v[204:207], v[38:41]
	v_mfma_f32_16x16x32_bf16 v[34:37], v[164:167], v[204:207], v[34:37]
	v_mfma_f32_16x16x32_bf16 v[22:25], v[156:159], v[212:215], v[22:25]
	v_mfma_f32_16x16x32_bf16 v[18:21], v[164:167], v[212:215], v[18:21]
	v_mfma_f32_16x16x32_bf16 v[46:49], v[168:171], v[184:187], v[46:49]
	v_mfma_f32_16x16x32_bf16 v[42:45], v[176:179], v[184:187], v[42:45]
	v_mfma_f32_16x16x32_bf16 v[30:33], v[168:171], v[192:195], v[30:33]
	v_mfma_f32_16x16x32_bf16 v[26:29], v[176:179], v[192:195], v[26:29]
	v_mfma_f32_16x16x32_bf16 v[14:17], v[168:171], v[200:203], v[14:17]
	v_mfma_f32_16x16x32_bf16 v[10:13], v[176:179], v[200:203], v[10:13]
	v_mfma_f32_16x16x32_bf16 v[6:9], v[168:171], v[208:211], v[6:9]
	v_mfma_f32_16x16x32_bf16 v[2:5], v[176:179], v[208:211], v[2:5]
	v_mfma_f32_16x16x32_bf16 v[46:49], v[172:175], v[188:191], v[46:49]
	v_mfma_f32_16x16x32_bf16 v[42:45], v[180:183], v[188:191], v[42:45]
	v_mfma_f32_16x16x32_bf16 v[30:33], v[172:175], v[196:199], v[30:33]
	v_mfma_f32_16x16x32_bf16 v[26:29], v[180:183], v[196:199], v[26:29]
	v_mfma_f32_16x16x32_bf16 v[14:17], v[172:175], v[204:207], v[14:17]
	v_mfma_f32_16x16x32_bf16 v[10:13], v[180:183], v[204:207], v[10:13]
	v_mfma_f32_16x16x32_bf16 v[6:9], v[172:175], v[212:215], v[6:9]
	v_mfma_f32_16x16x32_bf16 v[2:5], v[180:183], v[212:215], v[2:5]
	s_barrier
; #define PG8_STAGE(bufoff, gbase, voff) do { _Pragma("unroll") for (int _i = 0; _i < 2; ++_i) \
;         __builtin_amdgcn_global_load_lds((const unsigned*)((const char*)(gbase) + (voff)[_i]), (PG8_LAS unsigned*)(lds + (bufoff) + ldsw + _i * 8192), 16, 0, 0); } while (0)
; #define PG8_LDA(dst, b, h) do { _Pragma("unroll") for (int m = 0; m < 4; ++m) _Pragma("unroll") for (int k = 0; k < 2; ++k) dst[m][k] = *(const PG8_LAS bf16x8*)(lds + PG8_SA(b, h) + aoff + m * 2048 + k * 1024); } while (0)
; #define PG8_LDB(dst, b, h) do { _Pragma("unroll") for (int n = 0; n < 2; ++n) _Pragma("unroll") for (int k = 0; k < 2; ++k) dst[n][k] = *(const PG8_LAS bf16x8*)(lds + PG8_SB(b, h) + boff + n * 2048 + k * 1024); } while (0)
; #define PG8_WAIT_V(n) asm volatile("s_waitcnt vmcnt(" #n ")" ::: "memory")
; #define PG8_WAIT_L(n) asm volatile("s_waitcnt lgkmcnt(" #n ")" ::: "memory")
; #define PG8_BAR __builtin_amdgcn_s_barrier()
; #define PG8_SCHED __builtin_amdgcn_sched_barrier(0)
; template <class Epi, class Sched, bool ALIGN_EPI = false, bool SP2 = false, bool F8 = false>
; __device__ __forceinline__ void gemm_phase(PG8_LAS unsigned char* lds, const Gemm g, const Sched& S, const Epi& E) {
;     ...
;             PG8_LDB(B0, 1, 0); PG8_LDB(B1, 1, 1); PG8_SCHED; PG8_LDA(At, 1, 0); PG8_STAGE(PG8_SA(0, 1), a2 + hA, voffA);
;             PG8_WAIT_V(8); PG8_WAIT_L(0); PG8_BAR; PG8_MMA(0, 0, At, B0); PG8_MMA(0, 1, At, B1); PG8_BAR; PG8_SCHED;
	s_setprio 0
	s_add_i32 s67, 0, 0x18000
	s_add_i32 s69, 0, 0x1c000
	v_add_u32_e32 v164, s67, v147
	v_add_u32_e32 v180, s69, v147
	ds_read_b128 v[152:155], v164
	ds_read_b128 v[156:159], v164 offset:1024
	ds_read_b128 v[160:163], v164 offset:2048
	ds_read_b128 v[164:167], v164 offset:3072
	ds_read_b128 v[168:171], v180
	ds_read_b128 v[172:175], v180 offset:1024
	ds_read_b128 v[176:179], v180 offset:2048
	ds_read_b128 v[180:183], v180 offset:3072
	s_add_u32 s42, s42, 0x100000
	s_addc_u32 s43, s43, 0
	s_mov_b32 m0, s49
	v_lshl_add_u64 v[224:225], s[42:43], 0, v[136:137]
	ds_read_b128 v[184:187], v151 offset:32768
	ds_read_b128 v[188:191], v151 offset:33792
	ds_read_b128 v[192:195], v151 offset:34816
	ds_read_b128 v[196:199], v151 offset:35840
	ds_read_b128 v[200:203], v151 offset:36864
	ds_read_b128 v[204:207], v151 offset:37888
	ds_read_b128 v[208:211], v151 offset:38912
	ds_read_b128 v[212:215], v151 offset:39936
	global_load_lds_dwordx4 v[224:225], off
	v_lshl_add_u64 v[224:225], s[42:43], 0, v[132:133]
	s_mov_b32 m0, s50
	s_nop 0
	global_load_lds_dwordx4 v[224:225], off
	s_waitcnt vmcnt(8)
	s_waitcnt lgkmcnt(0)
	s_setprio 1
	s_barrier
	v_mfma_f32_16x16x32_bf16 v[126:129], v[152:155], v[184:187], v[126:129]
	v_mfma_f32_16x16x32_bf16 v[122:125], v[160:163], v[184:187], v[122:125]
	v_mfma_f32_16x16x32_bf16 v[118:121], v[152:155], v[192:195], v[118:121]
	v_mfma_f32_16x16x32_bf16 v[114:117], v[160:163], v[192:195], v[114:117]
	v_mfma_f32_16x16x32_bf16 v[102:105], v[152:155], v[200:203], v[102:105]
	v_mfma_f32_16x16x32_bf16 v[98:101], v[160:163], v[200:203], v[98:101]
	v_mfma_f32_16x16x32_bf16 v[86:89], v[152:155], v[208:211], v[86:89]
	v_mfma_f32_16x16x32_bf16 v[82:85], v[160:163], v[208:211], v[82:85]
	v_mfma_f32_16x16x32_bf16 v[126:129], v[156:159], v[188:191], v[126:129]
	v_mfma_f32_16x16x32_bf16 v[122:125], v[164:167], v[188:191], v[122:125]
	v_mfma_f32_16x16x32_bf16 v[118:121], v[156:159], v[196:199], v[118:121]
	v_mfma_f32_16x16x32_bf16 v[114:117], v[164:167], v[196:199], v[114:117]
	v_mfma_f32_16x16x32_bf16 v[102:105], v[156:159], v[204:207], v[102:105]
	v_mfma_f32_16x16x32_bf16 v[98:101], v[164:167], v[204:207], v[98:101]
	v_mfma_f32_16x16x32_bf16 v[86:89], v[156:159], v[212:215], v[86:89]
	v_mfma_f32_16x16x32_bf16 v[82:85], v[164:167], v[212:215], v[82:85]
	v_mfma_f32_16x16x32_bf16 v[110:113], v[168:171], v[184:187], v[110:113]
	v_mfma_f32_16x16x32_bf16 v[106:109], v[176:179], v[184:187], v[106:109]
	v_mfma_f32_16x16x32_bf16 v[94:97], v[168:171], v[192:195], v[94:97]
	v_mfma_f32_16x16x32_bf16 v[90:93], v[176:179], v[192:195], v[90:93]
	v_mfma_f32_16x16x32_bf16 v[78:81], v[168:171], v[200:203], v[78:81]
	v_mfma_f32_16x16x32_bf16 v[74:77], v[176:179], v[200:203], v[74:77]
	v_mfma_f32_16x16x32_bf16 v[70:73], v[168:171], v[208:211], v[70:73]
	v_mfma_f32_16x16x32_bf16 v[66:69], v[176:179], v[208:211], v[66:69]
	v_mfma_f32_16x16x32_bf16 v[110:113], v[172:175], v[188:191], v[110:113]
	v_mfma_f32_16x16x32_bf16 v[106:109], v[180:183], v[188:191], v[106:109]
	v_mfma_f32_16x16x32_bf16 v[94:97], v[172:175], v[196:199], v[94:97]
	v_mfma_f32_16x16x32_bf16 v[90:93], v[180:183], v[196:199], v[90:93]
	v_mfma_f32_16x16x32_bf16 v[78:81], v[172:175], v[204:207], v[78:81]
	v_mfma_f32_16x16x32_bf16 v[74:77], v[180:183], v[204:207], v[74:77]
	v_mfma_f32_16x16x32_bf16 v[70:73], v[172:175], v[212:215], v[70:73]
	v_mfma_f32_16x16x32_bf16 v[66:69], v[180:183], v[212:215], v[66:69]
	s_barrier
; #define PG8_STAGE(bufoff, gbase, voff) do { _Pragma("unroll") for (int _i = 0; _i < 2; ++_i) \
;         __builtin_amdgcn_global_load_lds((const unsigned*)((const char*)(gbase) + (voff)[_i]), (PG8_LAS unsigned*)(lds + (bufoff) + ldsw + _i * 8192), 16, 0, 0); } while (0)
; #define PG8_LDA(dst, b, h) do { _Pragma("unroll") for (int m = 0; m < 4; ++m) _Pragma("unroll") for (int k = 0; k < 2; ++k) dst[m][k] = *(const PG8_LAS bf16x8*)(lds + PG8_SA(b, h) + aoff + m * 2048 + k * 1024); } while (0)
; #define PG8_WAIT_V(n) asm volatile("s_waitcnt vmcnt(" #n ")" ::: "memory")
; #define PG8_WAIT_L(n) asm volatile("s_waitcnt lgkmcnt(" #n ")" ::: "memory")
; #define PG8_BAR __builtin_amdgcn_s_barrier()
; #define PG8_SCHED __builtin_amdgcn_sched_barrier(0)
; template <class Epi, class Sched, bool ALIGN_EPI = false, bool SP2 = false, bool F8 = false>
; __device__ __forceinline__ void gemm_phase(PG8_LAS unsigned char* lds, const Gemm g, const Sched& S, const Epi& E) {
;     ...
;             PG8_LDA(At, 1, 1); PG8_STAGE(PG8_SB(1, 0), b3, voffB); PG8_STAGE(PG8_SB(1, 1), b3 + hB, voffB); PG8_STAGE(PG8_SA(1, 0), a3, voffA);
;             PG8_WAIT_V(8); PG8_WAIT_L(0); PG8_BAR; PG8_MMA(1, 0, At, B0); PG8_MMA(1, 1, At, B1); PG8_BAR; PG8_SCHED;
;     ...
;         if constexpr (ALIGN_EPI) { if (wr == 0) PG8_BAR; }
	s_setprio 0
	s_add_i32 s42, s67, s45
	v_lshl_add_u64 v[216:217], v[216:217], 0, s[12:13]
	s_mov_b32 m0, s42
	ds_read_b128 v[184:187], v151 offset:49152
	ds_read_b128 v[188:191], v151 offset:50176
	ds_read_b128 v[192:195], v151 offset:51200
	ds_read_b128 v[196:199], v151 offset:52224
	ds_read_b128 v[200:203], v151 offset:53248
	ds_read_b128 v[204:207], v151 offset:54272
	ds_read_b128 v[208:211], v151 offset:55296
	ds_read_b128 v[212:215], v151 offset:56320
	global_load_lds_dwordx4 v[216:217], off
	s_add_i32 m0, s42, 0x2000
	s_add_u32 s40, s40, 0x100080
	v_lshl_add_u64 v[216:217], v[218:219], 0, s[12:13]
	s_addc_u32 s41, s41, 0
	s_add_i32 s42, s69, s45
	global_load_lds_dwordx4 v[216:217], off
	v_lshl_add_u64 v[216:217], s[40:41], 0, v[134:135]
	s_mov_b32 m0, s42
	s_nop 0
	global_load_lds_dwordx4 v[216:217], off
	v_lshl_add_u64 v[216:217], s[40:41], 0, v[130:131]
	s_add_i32 m0, s42, 0x2000
	s_nop 0
	global_load_lds_dwordx4 v[216:217], off
	v_lshl_add_u64 v[216:217], v[220:221], 0, s[12:13]
	s_mov_b32 m0, s52
	s_nop 0
	global_load_lds_dwordx4 v[216:217], off
	v_lshl_add_u64 v[216:217], v[222:223], 0, s[12:13]
	s_mov_b32 m0, s53
	s_nop 0
	global_load_lds_dwordx4 v[216:217], off
	s_waitcnt vmcnt(8)
	s_waitcnt lgkmcnt(0)
	s_setprio 1
	s_barrier
	v_mfma_f32_16x16x32_bf16 v[62:65], v[152:155], v[184:187], v[62:65]
	v_mfma_f32_16x16x32_bf16 v[58:61], v[160:163], v[184:187], v[58:61]
	v_mfma_f32_16x16x32_bf16 v[54:57], v[152:155], v[192:195], v[54:57]
	v_mfma_f32_16x16x32_bf16 v[50:53], v[160:163], v[192:195], v[50:53]
	v_mfma_f32_16x16x32_bf16 v[38:41], v[152:155], v[200:203], v[38:41]
	v_mfma_f32_16x16x32_bf16 v[34:37], v[160:163], v[200:203], v[34:37]
	v_mfma_f32_16x16x32_bf16 v[22:25], v[152:155], v[208:211], v[22:25]
	v_mfma_f32_16x16x32_bf16 v[18:21], v[160:163], v[208:211], v[18:21]
	v_mfma_f32_16x16x32_bf16 v[62:65], v[156:159], v[188:191], v[62:65]
	v_mfma_f32_16x16x32_bf16 v[58:61], v[164:167], v[188:191], v[58:61]
	v_mfma_f32_16x16x32_bf16 v[54:57], v[156:159], v[196:199], v[54:57]
	v_mfma_f32_16x16x32_bf16 v[50:53], v[164:167], v[196:199], v[50:53]
	v_mfma_f32_16x16x32_bf16 v[38:41], v[156:159], v[204:207], v[38:41]
	v_mfma_f32_16x16x32_bf16 v[34:37], v[164:167], v[204:207], v[34:37]
	v_mfma_f32_16x16x32_bf16 v[22:25], v[156:159], v[212:215], v[22:25]
	v_mfma_f32_16x16x32_bf16 v[18:21], v[164:167], v[212:215], v[18:21]
	v_mfma_f32_16x16x32_bf16 v[46:49], v[168:171], v[184:187], v[46:49]
	v_mfma_f32_16x16x32_bf16 v[42:45], v[176:179], v[184:187], v[42:45]
	v_mfma_f32_16x16x32_bf16 v[30:33], v[168:171], v[192:195], v[30:33]
	v_mfma_f32_16x16x32_bf16 v[26:29], v[176:179], v[192:195], v[26:29]
	v_mfma_f32_16x16x32_bf16 v[14:17], v[168:171], v[200:203], v[14:17]
	v_mfma_f32_16x16x32_bf16 v[10:13], v[176:179], v[200:203], v[10:13]
	v_mfma_f32_16x16x32_bf16 v[6:9], v[168:171], v[208:211], v[6:9]
	v_mfma_f32_16x16x32_bf16 v[2:5], v[176:179], v[208:211], v[2:5]
	v_mfma_f32_16x16x32_bf16 v[46:49], v[172:175], v[188:191], v[46:49]
	v_mfma_f32_16x16x32_bf16 v[42:45], v[180:183], v[188:191], v[42:45]
	v_mfma_f32_16x16x32_bf16 v[30:33], v[172:175], v[196:199], v[30:33]
	v_mfma_f32_16x16x32_bf16 v[26:29], v[180:183], v[196:199], v[26:29]
	v_mfma_f32_16x16x32_bf16 v[14:17], v[172:175], v[204:207], v[14:17]
	v_mfma_f32_16x16x32_bf16 v[10:13], v[180:183], v[204:207], v[10:13]
	v_mfma_f32_16x16x32_bf16 v[6:9], v[172:175], v[212:215], v[6:9]
	v_mfma_f32_16x16x32_bf16 v[2:5], v[180:183], v[212:215], v[2:5]
	s_add_i32 s66, s66, 2
	s_add_u32 s64, s64, 0x100
	s_addc_u32 s65, s65, 0
	s_add_u32 s38, s38, 0x100
	s_addc_u32 s39, s39, 0
	s_cmp_gt_u32 s66, 61
	s_cbranch_scc0 .Lber_128
	s_barrier
	s_setprio 0
	s_and_b64 vcc, exec, s[14:15]
	s_cbranch_vccz .LBB0_131
	s_barrier

; template <class Epi, class Sched, bool ALIGN_EPI = false, bool SP2 = false, bool F8 = false>
; __device__ __forceinline__ void gemm_phase(PG8_LAS unsigned char* lds, const Gemm g, const Sched& S, const Epi& E) {
;     ...
;         for (int a = 0; a < 2; ++a)
; #pragma unroll
;             for (int b = 0; b < 2; ++b)
; #pragma unroll
;                 for (int m = 0; m < 4; ++m)
; #pragma unroll
;                     for (int n = 0; n < 2; ++n) acc[a][b][m][n] = (f32x4){0.f, 0.f, 0.f, 0.f};
.LBB0_145:
	s_ashr_i32 s29, s28, 31
	s_lshl_b64 s[6:7], s[28:29], 20
	s_add_u32 s30, s18, s6
	s_addc_u32 s31, s19, s7
	s_and_b64 s[6:7], s[4:5], exec
	s_cselect_b32 s29, s31, s43
	s_cselect_b32 s37, s30, s42
	s_ashr_i32 s27, s26, 31
	s_lshl_b64 s[6:7], s[26:27], 20
	s_add_u32 s34, s33, s6
	s_addc_u32 s35, s46, s7
	s_and_b64 s[6:7], s[4:5], exec
	s_cselect_b32 s27, s35, s41
	s_cselect_b32 s44, s34, s40
	s_add_u32 s45, s40, 0x100
	s_addc_u32 s59, s41, 0
	s_add_u32 s6, s42, 0x80080
	v_mov_b32_e32 v34, 0
	s_addc_u32 s7, s43, 0
	s_mov_b32 s60, -2
	v_mov_b32_e32 v35, v34
	v_mov_b32_e32 v36, v34
	v_mov_b32_e32 v37, v34
	v_mov_b32_e32 v38, v34
	v_mov_b32_e32 v39, v34
	v_mov_b32_e32 v40, v34
	v_mov_b32_e32 v41, v34
	v_mov_b32_e32 v50, v34
	v_mov_b32_e32 v51, v34
	v_mov_b32_e32 v52, v34
	v_mov_b32_e32 v53, v34
	v_mov_b32_e32 v54, v34
	v_mov_b32_e32 v55, v34
	v_mov_b32_e32 v56, v34
	v_mov_b32_e32 v57, v34
	v_mov_b32_e32 v66, v34
	v_mov_b32_e32 v67, v34
	v_mov_b32_e32 v68, v34
	v_mov_b32_e32 v69, v34
	v_mov_b32_e32 v70, v34
	v_mov_b32_e32 v71, v34
	v_mov_b32_e32 v72, v34
	v_mov_b32_e32 v73, v34
	v_mov_b32_e32 v82, v34
	v_mov_b32_e32 v83, v34
	v_mov_b32_e32 v84, v34
	v_mov_b32_e32 v85, v34
	v_mov_b32_e32 v86, v34
	v_mov_b32_e32 v87, v34
	v_mov_b32_e32 v88, v34
	v_mov_b32_e32 v89, v34
	v_mov_b32_e32 v42, v34
	v_mov_b32_e32 v43, v34
	v_mov_b32_e32 v44, v34
	v_mov_b32_e32 v45, v34
	v_mov_b32_e32 v46, v34
	v_mov_b32_e32 v47, v34
	v_mov_b32_e32 v48, v34
	v_mov_b32_e32 v49, v34
	v_mov_b32_e32 v58, v34
	v_mov_b32_e32 v59, v34
	v_mov_b32_e32 v60, v34
	v_mov_b32_e32 v61, v34
	v_mov_b32_e32 v62, v34
	v_mov_b32_e32 v63, v34
	v_mov_b32_e32 v64, v34
	v_mov_b32_e32 v65, v34
	v_mov_b32_e32 v74, v34
	v_mov_b32_e32 v75, v34
	v_mov_b32_e32 v76, v34
	v_mov_b32_e32 v77, v34
	v_mov_b32_e32 v78, v34
	v_mov_b32_e32 v79, v34
	v_mov_b32_e32 v80, v34
	v_mov_b32_e32 v81, v34
	v_mov_b32_e32 v90, v34
	v_mov_b32_e32 v91, v34
	v_mov_b32_e32 v92, v34
	v_mov_b32_e32 v93, v34
	v_mov_b32_e32 v94, v34
	v_mov_b32_e32 v95, v34
	v_mov_b32_e32 v96, v34
	v_mov_b32_e32 v97, v34
	v_mov_b32_e32 v98, v34
	v_mov_b32_e32 v99, v34
	v_mov_b32_e32 v100, v34
	v_mov_b32_e32 v101, v34
	v_mov_b32_e32 v102, v34
	v_mov_b32_e32 v103, v34
	v_mov_b32_e32 v104, v34
	v_mov_b32_e32 v105, v34
	v_mov_b32_e32 v114, v34
	v_mov_b32_e32 v115, v34
	v_mov_b32_e32 v116, v34
	v_mov_b32_e32 v117, v34
	v_mov_b32_e32 v118, v34
	v_mov_b32_e32 v119, v34
	v_mov_b32_e32 v120, v34
	v_mov_b32_e32 v121, v34
	v_mov_b32_e32 v130, v34
	v_mov_b32_e32 v131, v34
	v_mov_b32_e32 v132, v34
	v_mov_b32_e32 v133, v34
	v_mov_b32_e32 v134, v34
	v_mov_b32_e32 v135, v34
	v_mov_b32_e32 v136, v34
	v_mov_b32_e32 v137, v34
	v_mov_b32_e32 v146, v34
	v_mov_b32_e32 v147, v34
	v_mov_b32_e32 v148, v34
	v_mov_b32_e32 v149, v34
	v_mov_b32_e32 v150, v34
	v_mov_b32_e32 v151, v34
	v_mov_b32_e32 v152, v34
	v_mov_b32_e32 v153, v34
	v_mov_b32_e32 v106, v34
	v_mov_b32_e32 v107, v34
	v_mov_b32_e32 v108, v34
	v_mov_b32_e32 v109, v34
	v_mov_b32_e32 v110, v34
	v_mov_b32_e32 v111, v34
	v_mov_b32_e32 v112, v34
	v_mov_b32_e32 v113, v34
	v_mov_b32_e32 v122, v34
	v_mov_b32_e32 v123, v34
	v_mov_b32_e32 v124, v34
	v_mov_b32_e32 v125, v34
	v_mov_b32_e32 v126, v34
	v_mov_b32_e32 v127, v34
	v_mov_b32_e32 v128, v34
	v_mov_b32_e32 v129, v34
	v_mov_b32_e32 v138, v34
	v_mov_b32_e32 v139, v34
	v_mov_b32_e32 v140, v34
	v_mov_b32_e32 v141, v34
	v_mov_b32_e32 v142, v34
	v_mov_b32_e32 v143, v34
	v_mov_b32_e32 v144, v34
	v_mov_b32_e32 v145, v34
	v_mov_b32_e32 v154, v34
	v_mov_b32_e32 v155, v34
	v_mov_b32_e32 v156, v34
	v_mov_b32_e32 v157, v34
	v_mov_b32_e32 v158, v34
	v_mov_b32_e32 v159, v34
	v_mov_b32_e32 v160, v34
	v_mov_b32_e32 v161, v34
	s_branch .LBB0_146

; #define PG8_STAGE(bufoff, gbase, voff) do { _Pragma("unroll") for (int _i = 0; _i < 2; ++_i) \
;         __builtin_amdgcn_global_load_lds((const unsigned*)((const char*)(gbase) + (voff)[_i]), (PG8_LAS unsigned*)(lds + (bufoff) + ldsw + _i * 8192), 16, 0, 0); } while (0)
; #define PG8_LDA(dst, b, h) do { _Pragma("unroll") for (int m = 0; m < 4; ++m) _Pragma("unroll") for (int k = 0; k < 2; ++k) dst[m][k] = *(const PG8_LAS bf16x8*)(lds + PG8_SA(b, h) + aoff + m * 2048 + k * 1024); } while (0)
; #define PG8_LDB(dst, b, h) do { _Pragma("unroll") for (int n = 0; n < 2; ++n) _Pragma("unroll") for (int k = 0; k < 2; ++k) dst[n][k] = *(const PG8_LAS bf16x8*)(lds + PG8_SB(b, h) + boff + n * 2048 + k * 1024); } while (0)
; #define PG8_WAIT_V(n) asm volatile("s_waitcnt vmcnt(" #n ")" ::: "memory")
; #define PG8_WAIT_L(n) asm volatile("s_waitcnt lgkmcnt(" #n ")" ::: "memory")
; #define PG8_BAR __builtin_amdgcn_s_barrier()
; #define PG8_SCHED __builtin_amdgcn_sched_barrier(0)
; template <class Epi, class Sched, bool ALIGN_EPI = false, bool SP2 = false, bool F8 = false>
; __device__ __forceinline__ void gemm_phase(PG8_LAS unsigned char* lds, const Gemm g, const Sched& S, const Epi& E) {
;     ...
;             PG8_LDB(B0, 0, 0); PG8_LDB(B1, 0, 1); PG8_SCHED; PG8_LDA(At, 0, 0); PG8_STAGE(PG8_SA(1, 1), a1 + hA, voffA);
;             PG8_WAIT_V(8); PG8_WAIT_L(0); PG8_BAR; PG8_MMA(0, 0, At, B0); PG8_MMA(0, 1, At, B1); PG8_BAR; PG8_SCHED;
;             PG8_LDA(At, 0, 1); PG8_STAGE(PG8_SB(0, 0), b2, voffB); PG8_STAGE(PG8_SB(0, 1), b2 + hB, voffB); PG8_STAGE(PG8_SA(0, 0), a2, voffA);
;             PG8_WAIT_V(8); PG8_WAIT_L(0); PG8_BAR; PG8_MMA(1, 0, At, B0); PG8_MMA(1, 1, At, B1); PG8_BAR; PG8_SCHED;
.LBB0_146:
	ds_read_b128 v[26:29], v190
	ds_read_b128 v[30:33], v190 offset:1024
	ds_read_b128 v[18:21], v190 offset:2048
	ds_read_b128 v[22:25], v190 offset:3072
	ds_read_b128 v[10:13], v191
	ds_read_b128 v[14:17], v191 offset:1024
	ds_read_b128 v[2:5], v191 offset:2048
	ds_read_b128 v[6:9], v191 offset:3072
	s_add_u32 s40, s6, 0xfff80080
	s_addc_u32 s41, s7, -1
	s_cmp_eq_u32 s60, 28
	s_cselect_b32 s43, s29, s41
	s_cselect_b32 s42, s37, s40
	s_cselect_b32 s41, s27, s59
	s_cselect_b32 s40, s44, s45
	v_lshl_add_u64 v[218:219], s[6:7], 0, v[172:173]
	s_add_i32 m0, s39, 0xc000
	ds_read_b128 v[178:181], v192
	ds_read_b128 v[182:185], v192 offset:1024
	ds_read_b128 v[194:197], v192 offset:2048
	ds_read_b128 v[198:201], v192 offset:3072
	ds_read_b128 v[202:205], v192 offset:4096
	ds_read_b128 v[206:209], v192 offset:5120
	ds_read_b128 v[210:213], v192 offset:6144
	ds_read_b128 v[214:217], v192 offset:7168
	global_load_lds_dwordx4 v[218:219], off
	v_lshl_add_u64 v[218:219], s[6:7], 0, v[170:171]
	s_add_i32 m0, s39, 0xe000
	s_nop 0
	global_load_lds_dwordx4 v[218:219], off
	s_waitcnt vmcnt(8)
	s_waitcnt lgkmcnt(0)
	s_setprio 1
	s_barrier
	v_mfma_scale_f32_16x16x128_f8f6f4 v[158:161], v[26:33], v[178:185], v[158:161], v186, v186 op_sel_hi:[0,0,0]
	v_mfma_scale_f32_16x16x128_f8f6f4 v[154:157], v[18:25], v[178:185], v[154:157], v186, v186 op_sel_hi:[0,0,0]
	v_mfma_scale_f32_16x16x128_f8f6f4 v[142:145], v[26:33], v[194:201], v[142:145], v186, v186 op_sel_hi:[0,0,0]
	v_mfma_scale_f32_16x16x128_f8f6f4 v[138:141], v[18:25], v[194:201], v[138:141], v186, v186 op_sel_hi:[0,0,0]
	v_mfma_scale_f32_16x16x128_f8f6f4 v[126:129], v[26:33], v[202:209], v[126:129], v186, v186 op_sel_hi:[0,0,0]
	v_mfma_scale_f32_16x16x128_f8f6f4 v[122:125], v[18:25], v[202:209], v[122:125], v186, v186 op_sel_hi:[0,0,0]
	v_mfma_scale_f32_16x16x128_f8f6f4 v[110:113], v[26:33], v[210:217], v[110:113], v186, v186 op_sel_hi:[0,0,0]
	v_mfma_scale_f32_16x16x128_f8f6f4 v[106:109], v[18:25], v[210:217], v[106:109], v186, v186 op_sel_hi:[0,0,0]
	v_mfma_scale_f32_16x16x128_f8f6f4 v[150:153], v[10:17], v[178:185], v[150:153], v186, v186 op_sel_hi:[0,0,0]
	v_mfma_scale_f32_16x16x128_f8f6f4 v[146:149], v[2:9], v[178:185], v[146:149], v186, v186 op_sel_hi:[0,0,0]
	v_mfma_scale_f32_16x16x128_f8f6f4 v[134:137], v[10:17], v[194:201], v[134:137], v186, v186 op_sel_hi:[0,0,0]
	v_mfma_scale_f32_16x16x128_f8f6f4 v[130:133], v[2:9], v[194:201], v[130:133], v186, v186 op_sel_hi:[0,0,0]
	v_mfma_scale_f32_16x16x128_f8f6f4 v[118:121], v[10:17], v[202:209], v[118:121], v186, v186 op_sel_hi:[0,0,0]
	v_mfma_scale_f32_16x16x128_f8f6f4 v[114:117], v[2:9], v[202:209], v[114:117], v186, v186 op_sel_hi:[0,0,0]
	v_mfma_scale_f32_16x16x128_f8f6f4 v[102:105], v[10:17], v[210:217], v[102:105], v186, v186 op_sel_hi:[0,0,0]
	v_mfma_scale_f32_16x16x128_f8f6f4 v[98:101], v[2:9], v[210:217], v[98:101], v186, v186 op_sel_hi:[0,0,0]
	s_barrier
	s_setprio 0
	s_add_i32 s61, s57, s47
	v_lshl_add_u64 v[178:179], s[40:41], 0, v[164:165]
	s_mov_b32 m0, s61
	ds_read_b128 v[194:197], v192 offset:16384
	ds_read_b128 v[198:201], v192 offset:17408
	ds_read_b128 v[202:205], v192 offset:18432
	ds_read_b128 v[206:209], v192 offset:19456
	ds_read_b128 v[210:213], v192 offset:20480
	ds_read_b128 v[214:217], v192 offset:21504
	ds_read_b128 v[218:221], v192 offset:22528
	ds_read_b128 v[222:225], v192 offset:23552
	global_load_lds_dwordx4 v[178:179], off
	s_add_i32 m0, s61, 0x2000
	s_add_u32 s62, s40, 0x80000
	v_lshl_add_u64 v[180:181], s[40:41], 0, v[168:169]
	s_addc_u32 s63, s41, 0
	s_add_i32 s61, s58, s47
	global_load_lds_dwordx4 v[180:181], off
	v_lshl_add_u64 v[182:183], s[62:63], 0, v[164:165]
	s_mov_b32 m0, s61
	v_lshl_add_u64 v[184:185], s[42:43], 0, v[166:167]
	global_load_lds_dwordx4 v[182:183], off
	v_lshl_add_u64 v[182:183], s[62:63], 0, v[168:169]
	s_add_i32 m0, s61, 0x2000
	s_nop 0
	global_load_lds_dwordx4 v[182:183], off
	v_lshl_add_u64 v[182:183], s[42:43], 0, v[162:163]
	s_mov_b32 m0, s39
	s_nop 0
	global_load_lds_dwordx4 v[182:183], off
	s_mov_b32 m0, s48
	s_nop 0
	global_load_lds_dwordx4 v[184:185], off
	s_waitcnt vmcnt(8)
	s_waitcnt lgkmcnt(0)
	s_setprio 1
	s_barrier
	v_mfma_scale_f32_16x16x128_f8f6f4 v[94:97], v[26:33], v[194:201], v[94:97], v186, v186 op_sel_hi:[0,0,0]
	v_mfma_scale_f32_16x16x128_f8f6f4 v[90:93], v[18:25], v[194:201], v[90:93], v186, v186 op_sel_hi:[0,0,0]
	v_mfma_scale_f32_16x16x128_f8f6f4 v[78:81], v[26:33], v[202:209], v[78:81], v186, v186 op_sel_hi:[0,0,0]
	v_mfma_scale_f32_16x16x128_f8f6f4 v[74:77], v[18:25], v[202:209], v[74:77], v186, v186 op_sel_hi:[0,0,0]
	v_mfma_scale_f32_16x16x128_f8f6f4 v[62:65], v[26:33], v[210:217], v[62:65], v186, v186 op_sel_hi:[0,0,0]
	v_mfma_scale_f32_16x16x128_f8f6f4 v[58:61], v[18:25], v[210:217], v[58:61], v186, v186 op_sel_hi:[0,0,0]
	v_mfma_scale_f32_16x16x128_f8f6f4 v[46:49], v[26:33], v[218:225], v[46:49], v186, v186 op_sel_hi:[0,0,0]
	v_mfma_scale_f32_16x16x128_f8f6f4 v[42:45], v[18:25], v[218:225], v[42:45], v186, v186 op_sel_hi:[0,0,0]
	v_mfma_scale_f32_16x16x128_f8f6f4 v[86:89], v[10:17], v[194:201], v[86:89], v186, v186 op_sel_hi:[0,0,0]
	v_mfma_scale_f32_16x16x128_f8f6f4 v[82:85], v[2:9], v[194:201], v[82:85], v186, v186 op_sel_hi:[0,0,0]
	v_mfma_scale_f32_16x16x128_f8f6f4 v[70:73], v[10:17], v[202:209], v[70:73], v186, v186 op_sel_hi:[0,0,0]
	v_mfma_scale_f32_16x16x128_f8f6f4 v[66:69], v[2:9], v[202:209], v[66:69], v186, v186 op_sel_hi:[0,0,0]
	v_mfma_scale_f32_16x16x128_f8f6f4 v[54:57], v[10:17], v[210:217], v[54:57], v186, v186 op_sel_hi:[0,0,0]
	v_mfma_scale_f32_16x16x128_f8f6f4 v[50:53], v[2:9], v[210:217], v[50:53], v186, v186 op_sel_hi:[0,0,0]
	v_mfma_scale_f32_16x16x128_f8f6f4 v[38:41], v[10:17], v[218:225], v[38:41], v186, v186 op_sel_hi:[0,0,0]
	v_mfma_scale_f32_16x16x128_f8f6f4 v[34:37], v[2:9], v[218:225], v[34:37], v186, v186 op_sel_hi:[0,0,0]
	s_barrier
; #define PG8_STAGE(bufoff, gbase, voff) do { _Pragma("unroll") for (int _i = 0; _i < 2; ++_i) \
;         __builtin_amdgcn_global_load_lds((const unsigned*)((const char*)(gbase) + (voff)[_i]), (PG8_LAS unsigned*)(lds + (bufoff) + ldsw + _i * 8192), 16, 0, 0); } while (0)
; #define PG8_LDA(dst, b, h) do { _Pragma("unroll") for (int m = 0; m < 4; ++m) _Pragma("unroll") for (int k = 0; k < 2; ++k) dst[m][k] = *(const PG8_LAS bf16x8*)(lds + PG8_SA(b, h) + aoff + m * 2048 + k * 1024); } while (0)
; #define PG8_LDB(dst, b, h) do { _Pragma("unroll") for (int n = 0; n < 2; ++n) _Pragma("unroll") for (int k = 0; k < 2; ++k) dst[n][k] = *(const PG8_LAS bf16x8*)(lds + PG8_SB(b, h) + boff + n * 2048 + k * 1024); } while (0)
; #define PG8_WAIT_V(n) asm volatile("s_waitcnt vmcnt(" #n ")" ::: "memory")
; #define PG8_WAIT_L(n) asm volatile("s_waitcnt lgkmcnt(" #n ")" ::: "memory")
; #define PG8_BAR __builtin_amdgcn_s_barrier()
; #define PG8_SCHED __builtin_amdgcn_sched_barrier(0)
; template <class Epi, class Sched, bool ALIGN_EPI = false, bool SP2 = false, bool F8 = false>
; __device__ __forceinline__ void gemm_phase(PG8_LAS unsigned char* lds, const Gemm g, const Sched& S, const Epi& E) {
;     ...
;             PG8_LDB(B0, 1, 0); PG8_LDB(B1, 1, 1); PG8_SCHED; PG8_LDA(At, 1, 0); PG8_STAGE(PG8_SA(0, 1), a2 + hA, voffA);
;             PG8_WAIT_V(8); PG8_WAIT_L(0); PG8_BAR; PG8_MMA(0, 0, At, B0); PG8_MMA(0, 1, At, B1); PG8_BAR; PG8_SCHED;
;             PG8_LDA(At, 1, 1); PG8_STAGE(PG8_SB(1, 0), b3, voffB); PG8_STAGE(PG8_SB(1, 1), b3 + hB, voffB); PG8_STAGE(PG8_SA(1, 0), a3, voffA);
;             PG8_WAIT_V(8); PG8_WAIT_L(0); PG8_BAR; PG8_MMA(1, 0, At, B0); PG8_MMA(1, 1, At, B1); PG8_BAR; PG8_SCHED;
;     ...
;         if constexpr (ALIGN_EPI) { if (wr == 0) PG8_BAR; }
	s_setprio 0
	s_add_i32 s61, 0, 0x18000
	s_add_i32 s62, 0, 0x1c000
	v_add_u32_e32 v14, s61, v188
	v_add_u32_e32 v30, s62, v188
	ds_read_b128 v[2:5], v14
	ds_read_b128 v[6:9], v14 offset:1024
	ds_read_b128 v[10:13], v14 offset:2048
	ds_read_b128 v[14:17], v14 offset:3072
	ds_read_b128 v[18:21], v30
	ds_read_b128 v[22:25], v30 offset:1024
	ds_read_b128 v[26:29], v30 offset:2048
	ds_read_b128 v[30:33], v30 offset:3072
	s_add_u32 s42, s42, 0x80000
	s_addc_u32 s43, s43, 0
	s_mov_b32 m0, s49
	v_lshl_add_u64 v[226:227], s[42:43], 0, v[162:163]
	ds_read_b128 v[194:197], v192 offset:32768
	ds_read_b128 v[198:201], v192 offset:33792
	ds_read_b128 v[202:205], v192 offset:34816
	ds_read_b128 v[206:209], v192 offset:35840
	ds_read_b128 v[210:213], v192 offset:36864
	ds_read_b128 v[214:217], v192 offset:37888
	ds_read_b128 v[218:221], v192 offset:38912
	ds_read_b128 v[222:225], v192 offset:39936
	global_load_lds_dwordx4 v[226:227], off
	v_lshl_add_u64 v[226:227], s[42:43], 0, v[166:167]
	s_mov_b32 m0, s50
	s_nop 0
	global_load_lds_dwordx4 v[226:227], off
	s_waitcnt vmcnt(8)
	s_waitcnt lgkmcnt(0)
	s_setprio 1
	s_barrier
	v_mfma_scale_f32_16x16x128_f8f6f4 v[158:161], v[2:9], v[194:201], v[158:161], v186, v186 op_sel_hi:[0,0,0]
	v_mfma_scale_f32_16x16x128_f8f6f4 v[154:157], v[10:17], v[194:201], v[154:157], v186, v186 op_sel_hi:[0,0,0]
	v_mfma_scale_f32_16x16x128_f8f6f4 v[142:145], v[2:9], v[202:209], v[142:145], v186, v186 op_sel_hi:[0,0,0]
	v_mfma_scale_f32_16x16x128_f8f6f4 v[138:141], v[10:17], v[202:209], v[138:141], v186, v186 op_sel_hi:[0,0,0]
	v_mfma_scale_f32_16x16x128_f8f6f4 v[126:129], v[2:9], v[210:217], v[126:129], v186, v186 op_sel_hi:[0,0,0]
	v_mfma_scale_f32_16x16x128_f8f6f4 v[122:125], v[10:17], v[210:217], v[122:125], v186, v186 op_sel_hi:[0,0,0]
	v_mfma_scale_f32_16x16x128_f8f6f4 v[110:113], v[2:9], v[218:225], v[110:113], v186, v186 op_sel_hi:[0,0,0]
	v_mfma_scale_f32_16x16x128_f8f6f4 v[106:109], v[10:17], v[218:225], v[106:109], v186, v186 op_sel_hi:[0,0,0]
	v_mfma_scale_f32_16x16x128_f8f6f4 v[150:153], v[18:25], v[194:201], v[150:153], v186, v186 op_sel_hi:[0,0,0]
	v_mfma_scale_f32_16x16x128_f8f6f4 v[146:149], v[26:33], v[194:201], v[146:149], v186, v186 op_sel_hi:[0,0,0]
	v_mfma_scale_f32_16x16x128_f8f6f4 v[134:137], v[18:25], v[202:209], v[134:137], v186, v186 op_sel_hi:[0,0,0]
	v_mfma_scale_f32_16x16x128_f8f6f4 v[130:133], v[26:33], v[202:209], v[130:133], v186, v186 op_sel_hi:[0,0,0]
	v_mfma_scale_f32_16x16x128_f8f6f4 v[118:121], v[18:25], v[210:217], v[118:121], v186, v186 op_sel_hi:[0,0,0]
	v_mfma_scale_f32_16x16x128_f8f6f4 v[114:117], v[26:33], v[210:217], v[114:117], v186, v186 op_sel_hi:[0,0,0]
	v_mfma_scale_f32_16x16x128_f8f6f4 v[102:105], v[18:25], v[218:225], v[102:105], v186, v186 op_sel_hi:[0,0,0]
	v_mfma_scale_f32_16x16x128_f8f6f4 v[98:101], v[26:33], v[218:225], v[98:101], v186, v186 op_sel_hi:[0,0,0]
	s_barrier
	s_setprio 0
	s_add_i32 s42, s61, s47
	v_lshl_add_u64 v[178:179], v[178:179], 0, s[22:23]
	s_mov_b32 m0, s42
	ds_read_b128 v[194:197], v192 offset:49152
	ds_read_b128 v[198:201], v192 offset:50176
	ds_read_b128 v[202:205], v192 offset:51200
	ds_read_b128 v[206:209], v192 offset:52224
	ds_read_b128 v[210:213], v192 offset:53248
	ds_read_b128 v[214:217], v192 offset:54272
	ds_read_b128 v[218:221], v192 offset:55296
	ds_read_b128 v[222:225], v192 offset:56320
	global_load_lds_dwordx4 v[178:179], off
	s_add_i32 m0, s42, 0x2000
	s_add_u32 s40, s40, 0x80080
	v_lshl_add_u64 v[178:179], v[180:181], 0, s[22:23]
	s_addc_u32 s41, s41, 0
	s_add_i32 s42, s62, s47
	global_load_lds_dwordx4 v[178:179], off
	v_lshl_add_u64 v[178:179], s[40:41], 0, v[164:165]
	s_mov_b32 m0, s42
	s_nop 0
	global_load_lds_dwordx4 v[178:179], off
	v_lshl_add_u64 v[178:179], s[40:41], 0, v[168:169]
	s_add_i32 m0, s42, 0x2000
	s_nop 0
	global_load_lds_dwordx4 v[178:179], off
	v_lshl_add_u64 v[178:179], v[182:183], 0, s[22:23]
	s_mov_b32 m0, s52
	s_nop 0
	global_load_lds_dwordx4 v[178:179], off
	v_lshl_add_u64 v[178:179], v[184:185], 0, s[22:23]
	s_mov_b32 m0, s53
	s_nop 0
	global_load_lds_dwordx4 v[178:179], off
	s_waitcnt vmcnt(8)
	s_waitcnt lgkmcnt(0)
	s_setprio 1
	s_barrier
	v_mfma_scale_f32_16x16x128_f8f6f4 v[94:97], v[2:9], v[194:201], v[94:97], v186, v186 op_sel_hi:[0,0,0]
	v_mfma_scale_f32_16x16x128_f8f6f4 v[90:93], v[10:17], v[194:201], v[90:93], v186, v186 op_sel_hi:[0,0,0]
	v_mfma_scale_f32_16x16x128_f8f6f4 v[78:81], v[2:9], v[202:209], v[78:81], v186, v186 op_sel_hi:[0,0,0]
	v_mfma_scale_f32_16x16x128_f8f6f4 v[74:77], v[10:17], v[202:209], v[74:77], v186, v186 op_sel_hi:[0,0,0]
	v_mfma_scale_f32_16x16x128_f8f6f4 v[62:65], v[2:9], v[210:217], v[62:65], v186, v186 op_sel_hi:[0,0,0]
	v_mfma_scale_f32_16x16x128_f8f6f4 v[58:61], v[10:17], v[210:217], v[58:61], v186, v186 op_sel_hi:[0,0,0]
	v_mfma_scale_f32_16x16x128_f8f6f4 v[46:49], v[2:9], v[218:225], v[46:49], v186, v186 op_sel_hi:[0,0,0]
	v_mfma_scale_f32_16x16x128_f8f6f4 v[42:45], v[10:17], v[218:225], v[42:45], v186, v186 op_sel_hi:[0,0,0]
	v_mfma_scale_f32_16x16x128_f8f6f4 v[86:89], v[18:25], v[194:201], v[86:89], v186, v186 op_sel_hi:[0,0,0]
	v_mfma_scale_f32_16x16x128_f8f6f4 v[82:85], v[26:33], v[194:201], v[82:85], v186, v186 op_sel_hi:[0,0,0]
	v_mfma_scale_f32_16x16x128_f8f6f4 v[70:73], v[18:25], v[202:209], v[70:73], v186, v186 op_sel_hi:[0,0,0]
	v_mfma_scale_f32_16x16x128_f8f6f4 v[66:69], v[26:33], v[202:209], v[66:69], v186, v186 op_sel_hi:[0,0,0]
	v_mfma_scale_f32_16x16x128_f8f6f4 v[54:57], v[18:25], v[210:217], v[54:57], v186, v186 op_sel_hi:[0,0,0]
	v_mfma_scale_f32_16x16x128_f8f6f4 v[50:53], v[26:33], v[210:217], v[50:53], v186, v186 op_sel_hi:[0,0,0]
	v_mfma_scale_f32_16x16x128_f8f6f4 v[38:41], v[18:25], v[218:225], v[38:41], v186, v186 op_sel_hi:[0,0,0]
	v_mfma_scale_f32_16x16x128_f8f6f4 v[34:37], v[26:33], v[218:225], v[34:37], v186, v186 op_sel_hi:[0,0,0]
	s_add_i32 s60, s60, 2
	s_add_u32 s45, s45, 0x100
	s_addc_u32 s59, s59, 0
	s_add_u32 s6, s6, 0x100
	s_addc_u32 s7, s7, 0
	s_cmp_gt_u32 s60, 29
	s_cbranch_scc0 .Lber_146
	s_barrier
	s_setprio 0
	s_and_b64 vcc, exec, s[24:25]
	s_cbranch_vccz .LBB0_149
	s_barrier

; template <class Epi, class Sched, bool ALIGN_EPI = false, bool SP2 = false, bool F8 = false>
; __device__ __forceinline__ void gemm_phase(PG8_LAS unsigned char* lds, const Gemm g, const Sched& S, const Epi& E) {
;     ...
;         const bool has_next = S.next(ui + 1, nxt);
;         const char* nA = has_next ? (const char*)g.A + (size_t)nxt.pm * tA + (size_t)(nxt.pn >> g.gshift) * g.goff : cA; const char* nB = has_next ? (const char*)g.Bt + (size_t)nxt.pn * tB : cB;
;     ...
;         for (int a = 0; a < 2; ++a)
; #pragma unroll
;             for (int b = 0; b < 2; ++b)
; #pragma unroll
;                 for (int m = 0; m < 4; ++m)
; #pragma unroll
;                     for (int n = 0; n < 2; ++n) acc[a][b][m][n] = (f32x4){0.f, 0.f, 0.f, 0.f};
.LBB0_617:
	s_ashr_i32 s29, s28, 31
	v_cmp_lt_i64_e32 vcc, s[30:31], v[170:171]
	s_lshl_b64 s[30:31], s[28:29], 20
	s_add_u32 s27, s5, s30
	s_addc_u32 s29, s6, s31
	s_ashr_i32 s30, s26, 2
	s_ashr_i32 s31, s30, 31
	s_lshl_b64 s[30:31], s[30:31], 10
	s_add_u32 s30, s27, s30
	s_addc_u32 s31, s29, s31
	s_and_b64 s[34:35], vcc, exec
	s_cselect_b32 s29, s31, s41
	s_cselect_b32 s55, s30, s40
	s_ashr_i32 s27, s26, 31
	s_lshl_b64 s[34:35], s[26:27], 18
	s_add_u32 s34, s7, s34
	s_addc_u32 s35, s18, s35
	s_and_b64 s[42:43], vcc, exec
	s_cselect_b32 s27, s35, s39
	s_cselect_b32 s56, s34, s38
	s_add_u32 s57, s38, 0x100
	s_addc_u32 s58, s39, 0
	s_add_u32 s38, s40, 0x80080
	v_mov_b32_e32 v2, 0
	s_addc_u32 s39, s41, 0
	s_mov_b32 s59, -2
	v_mov_b32_e32 v3, v2
	v_mov_b32_e32 v4, v2
	v_mov_b32_e32 v5, v2
	v_mov_b32_e32 v6, v2
	v_mov_b32_e32 v7, v2
	v_mov_b32_e32 v8, v2
	v_mov_b32_e32 v9, v2
	v_mov_b32_e32 v18, v2
	v_mov_b32_e32 v19, v2
	v_mov_b32_e32 v20, v2
	v_mov_b32_e32 v21, v2
	v_mov_b32_e32 v22, v2
	v_mov_b32_e32 v23, v2
	v_mov_b32_e32 v24, v2
	v_mov_b32_e32 v25, v2
	v_mov_b32_e32 v34, v2
	v_mov_b32_e32 v35, v2
	v_mov_b32_e32 v36, v2
	v_mov_b32_e32 v37, v2
	v_mov_b32_e32 v38, v2
	v_mov_b32_e32 v39, v2
	v_mov_b32_e32 v40, v2
	v_mov_b32_e32 v41, v2
	v_mov_b32_e32 v50, v2
	v_mov_b32_e32 v51, v2
	v_mov_b32_e32 v52, v2
	v_mov_b32_e32 v53, v2
	v_mov_b32_e32 v54, v2
	v_mov_b32_e32 v55, v2
	v_mov_b32_e32 v56, v2
	v_mov_b32_e32 v57, v2
	v_mov_b32_e32 v10, v2
	v_mov_b32_e32 v11, v2
	v_mov_b32_e32 v12, v2
	v_mov_b32_e32 v13, v2
	v_mov_b32_e32 v14, v2
	v_mov_b32_e32 v15, v2
	v_mov_b32_e32 v16, v2
	v_mov_b32_e32 v17, v2
	v_mov_b32_e32 v26, v2
	v_mov_b32_e32 v27, v2
	v_mov_b32_e32 v28, v2
	v_mov_b32_e32 v29, v2
	v_mov_b32_e32 v30, v2
	v_mov_b32_e32 v31, v2
	v_mov_b32_e32 v32, v2
	v_mov_b32_e32 v33, v2
	v_mov_b32_e32 v42, v2
	v_mov_b32_e32 v43, v2
	v_mov_b32_e32 v44, v2
	v_mov_b32_e32 v45, v2
	v_mov_b32_e32 v46, v2
	v_mov_b32_e32 v47, v2
	v_mov_b32_e32 v48, v2
	v_mov_b32_e32 v49, v2
	v_mov_b32_e32 v58, v2
	v_mov_b32_e32 v59, v2
	v_mov_b32_e32 v60, v2
	v_mov_b32_e32 v61, v2
	v_mov_b32_e32 v62, v2
	v_mov_b32_e32 v63, v2
	v_mov_b32_e32 v64, v2
	v_mov_b32_e32 v65, v2
	v_mov_b32_e32 v66, v2
	v_mov_b32_e32 v67, v2
	v_mov_b32_e32 v68, v2
	v_mov_b32_e32 v69, v2
	v_mov_b32_e32 v70, v2
	v_mov_b32_e32 v71, v2
	v_mov_b32_e32 v72, v2
	v_mov_b32_e32 v73, v2
	v_mov_b32_e32 v82, v2
	v_mov_b32_e32 v83, v2
	v_mov_b32_e32 v84, v2
	v_mov_b32_e32 v85, v2
	v_mov_b32_e32 v86, v2
	v_mov_b32_e32 v87, v2
	v_mov_b32_e32 v88, v2
	v_mov_b32_e32 v89, v2
	v_mov_b32_e32 v98, v2
	v_mov_b32_e32 v99, v2
	v_mov_b32_e32 v100, v2
	v_mov_b32_e32 v101, v2
	v_mov_b32_e32 v102, v2
	v_mov_b32_e32 v103, v2
	v_mov_b32_e32 v104, v2
	v_mov_b32_e32 v105, v2
	v_mov_b32_e32 v114, v2
	v_mov_b32_e32 v115, v2
	v_mov_b32_e32 v116, v2
	v_mov_b32_e32 v117, v2
	v_mov_b32_e32 v118, v2
	v_mov_b32_e32 v119, v2
	v_mov_b32_e32 v120, v2
	v_mov_b32_e32 v121, v2
	v_mov_b32_e32 v74, v2
	v_mov_b32_e32 v75, v2
	v_mov_b32_e32 v76, v2
	v_mov_b32_e32 v77, v2
	v_mov_b32_e32 v78, v2
	v_mov_b32_e32 v79, v2
	v_mov_b32_e32 v80, v2
	v_mov_b32_e32 v81, v2
	v_mov_b32_e32 v90, v2
	v_mov_b32_e32 v91, v2
	v_mov_b32_e32 v92, v2
	v_mov_b32_e32 v93, v2
	v_mov_b32_e32 v94, v2
	v_mov_b32_e32 v95, v2
	v_mov_b32_e32 v96, v2
	v_mov_b32_e32 v97, v2
	v_mov_b32_e32 v106, v2
	v_mov_b32_e32 v107, v2
	v_mov_b32_e32 v108, v2
	v_mov_b32_e32 v109, v2
	v_mov_b32_e32 v110, v2
	v_mov_b32_e32 v111, v2
	v_mov_b32_e32 v112, v2
	v_mov_b32_e32 v113, v2
	v_mov_b32_e32 v122, v2
	v_mov_b32_e32 v123, v2
	v_mov_b32_e32 v124, v2
	v_mov_b32_e32 v125, v2
	v_mov_b32_e32 v126, v2
	v_mov_b32_e32 v127, v2
	v_mov_b32_e32 v128, v2
	v_mov_b32_e32 v129, v2
	s_branch .LBB0_618

; #define PG8_STAGE(bufoff, gbase, voff) do { _Pragma("unroll") for (int _i = 0; _i < 2; ++_i) \
;         __builtin_amdgcn_global_load_lds((const unsigned*)((const char*)(gbase) + (voff)[_i]), (PG8_LAS unsigned*)(lds + (bufoff) + ldsw + _i * 8192), 16, 0, 0); } while (0)
; #define PG8_LDA(dst, b, h) do { _Pragma("unroll") for (int m = 0; m < 4; ++m) _Pragma("unroll") for (int k = 0; k < 2; ++k) dst[m][k] = *(const PG8_LAS bf16x8*)(lds + PG8_SA(b, h) + aoff + m * 2048 + k * 1024); } while (0)
; #define PG8_LDB(dst, b, h) do { _Pragma("unroll") for (int n = 0; n < 2; ++n) _Pragma("unroll") for (int k = 0; k < 2; ++k) dst[n][k] = *(const PG8_LAS bf16x8*)(lds + PG8_SB(b, h) + boff + n * 2048 + k * 1024); } while (0)
; #define PG8_WAIT_V(n) asm volatile("s_waitcnt vmcnt(" #n ")" ::: "memory")
; #define PG8_WAIT_L(n) asm volatile("s_waitcnt lgkmcnt(" #n ")" ::: "memory")
; #define PG8_BAR __builtin_amdgcn_s_barrier()
; #define PG8_SCHED __builtin_amdgcn_sched_barrier(0)
; template <class Epi, class Sched, bool ALIGN_EPI = false, bool SP2 = false, bool F8 = false>
; __device__ __forceinline__ void gemm_phase(PG8_LAS unsigned char* lds, const Gemm g, const Sched& S, const Epi& E) {
;     ...
;             PG8_LDB(B0, 0, 0); PG8_LDB(B1, 0, 1); PG8_SCHED; PG8_LDA(At, 0, 0); PG8_STAGE(PG8_SA(1, 1), a1 + hA, voffA);
;             PG8_WAIT_V(8); PG8_WAIT_L(0); PG8_BAR; PG8_MMA(0, 0, At, B0); PG8_MMA(0, 1, At, B1); PG8_BAR; PG8_SCHED;
;             PG8_LDA(At, 0, 1); PG8_STAGE(PG8_SB(0, 0), b2, voffB); PG8_STAGE(PG8_SB(0, 1), b2 + hB, voffB); PG8_STAGE(PG8_SA(0, 0), a2, voffA);
;             PG8_WAIT_V(8); PG8_WAIT_L(0); PG8_BAR; PG8_MMA(1, 0, At, B0); PG8_MMA(1, 1, At, B1); PG8_BAR; PG8_SCHED;
.LBB0_618:
	ds_read_b128 v[130:133], v185
	ds_read_b128 v[134:137], v185 offset:1024
	ds_read_b128 v[138:141], v185 offset:2048
	ds_read_b128 v[142:145], v185 offset:3072
	ds_read_b128 v[146:149], v186
	ds_read_b128 v[150:153], v186 offset:1024
	ds_read_b128 v[154:157], v186 offset:2048
	ds_read_b128 v[174:177], v186 offset:3072
	s_add_u32 s40, s38, 0xfff80080
	s_addc_u32 s41, s39, -1
	s_cmp_eq_u32 s59, 4
	s_cselect_b32 s43, s29, s41
	s_cselect_b32 s42, s55, s40
	s_cselect_b32 s41, s27, s58
	s_cselect_b32 s40, s56, s57
	v_lshl_add_u64 v[216:217], s[38:39], 0, v[168:169]
	s_add_i32 m0, s37, 0xc000
	ds_read_b128 v[178:181], v187
	ds_read_b128 v[188:191], v187 offset:1024
	ds_read_b128 v[192:195], v187 offset:2048
	ds_read_b128 v[196:199], v187 offset:3072
	ds_read_b128 v[200:203], v187 offset:4096
	ds_read_b128 v[204:207], v187 offset:5120
	ds_read_b128 v[208:211], v187 offset:6144
	ds_read_b128 v[212:215], v187 offset:7168
	global_load_lds_dwordx4 v[216:217], off
	v_lshl_add_u64 v[216:217], s[38:39], 0, v[166:167]
	s_add_i32 m0, s37, 0xe000
	s_nop 0
	global_load_lds_dwordx4 v[216:217], off
	s_waitcnt vmcnt(8)
	s_waitcnt lgkmcnt(0)
	s_setprio 1
	s_barrier
	v_mfma_f32_16x16x32_bf16 v[126:129], v[130:133], v[178:181], v[126:129]
	v_mfma_f32_16x16x32_bf16 v[122:125], v[138:141], v[178:181], v[122:125]
	v_mfma_f32_16x16x32_bf16 v[110:113], v[130:133], v[192:195], v[110:113]
	v_mfma_f32_16x16x32_bf16 v[106:109], v[138:141], v[192:195], v[106:109]
	v_mfma_f32_16x16x32_bf16 v[94:97], v[130:133], v[200:203], v[94:97]
	v_mfma_f32_16x16x32_bf16 v[90:93], v[138:141], v[200:203], v[90:93]
	v_mfma_f32_16x16x32_bf16 v[78:81], v[130:133], v[208:211], v[78:81]
	v_mfma_f32_16x16x32_bf16 v[74:77], v[138:141], v[208:211], v[74:77]
	v_mfma_f32_16x16x32_bf16 v[126:129], v[134:137], v[188:191], v[126:129]
	v_mfma_f32_16x16x32_bf16 v[122:125], v[142:145], v[188:191], v[122:125]
	v_mfma_f32_16x16x32_bf16 v[110:113], v[134:137], v[196:199], v[110:113]
	v_mfma_f32_16x16x32_bf16 v[106:109], v[142:145], v[196:199], v[106:109]
	v_mfma_f32_16x16x32_bf16 v[94:97], v[134:137], v[204:207], v[94:97]
	v_mfma_f32_16x16x32_bf16 v[90:93], v[142:145], v[204:207], v[90:93]
	v_mfma_f32_16x16x32_bf16 v[78:81], v[134:137], v[212:215], v[78:81]
	v_mfma_f32_16x16x32_bf16 v[74:77], v[142:145], v[212:215], v[74:77]
	v_mfma_f32_16x16x32_bf16 v[118:121], v[146:149], v[178:181], v[118:121]
	v_mfma_f32_16x16x32_bf16 v[114:117], v[154:157], v[178:181], v[114:117]
	v_mfma_f32_16x16x32_bf16 v[102:105], v[146:149], v[192:195], v[102:105]
	v_mfma_f32_16x16x32_bf16 v[98:101], v[154:157], v[192:195], v[98:101]
	v_mfma_f32_16x16x32_bf16 v[86:89], v[146:149], v[200:203], v[86:89]
	v_mfma_f32_16x16x32_bf16 v[82:85], v[154:157], v[200:203], v[82:85]
	v_mfma_f32_16x16x32_bf16 v[70:73], v[146:149], v[208:211], v[70:73]
	v_mfma_f32_16x16x32_bf16 v[66:69], v[154:157], v[208:211], v[66:69]
	v_mfma_f32_16x16x32_bf16 v[118:121], v[150:153], v[188:191], v[118:121]
	v_mfma_f32_16x16x32_bf16 v[114:117], v[174:177], v[188:191], v[114:117]
	v_mfma_f32_16x16x32_bf16 v[102:105], v[150:153], v[196:199], v[102:105]
	v_mfma_f32_16x16x32_bf16 v[98:101], v[174:177], v[196:199], v[98:101]
	v_mfma_f32_16x16x32_bf16 v[86:89], v[150:153], v[204:207], v[86:89]
	v_mfma_f32_16x16x32_bf16 v[82:85], v[174:177], v[204:207], v[82:85]
	v_mfma_f32_16x16x32_bf16 v[70:73], v[150:153], v[212:215], v[70:73]
	v_mfma_f32_16x16x32_bf16 v[66:69], v[174:177], v[212:215], v[66:69]
	s_barrier
	s_setprio 0
	s_add_i32 s60, s52, s19
	v_lshl_add_u64 v[216:217], s[40:41], 0, v[162:163]
	s_mov_b32 m0, s60
	ds_read_b128 v[178:181], v187 offset:16384
	ds_read_b128 v[188:191], v187 offset:17408
	ds_read_b128 v[192:195], v187 offset:18432
	ds_read_b128 v[196:199], v187 offset:19456
	ds_read_b128 v[200:203], v187 offset:20480
	ds_read_b128 v[204:207], v187 offset:21504
	ds_read_b128 v[208:211], v187 offset:22528
	ds_read_b128 v[212:215], v187 offset:23552
	global_load_lds_dwordx4 v[216:217], off
	s_add_i32 m0, s60, 0x2000
	s_add_u32 s60, s40, 0x20000
	v_lshl_add_u64 v[218:219], s[40:41], 0, v[158:159]
	s_addc_u32 s61, s41, 0
	s_add_i32 s62, s53, s19
	global_load_lds_dwordx4 v[218:219], off
	v_lshl_add_u64 v[220:221], s[60:61], 0, v[162:163]
	s_mov_b32 m0, s62
	v_lshl_add_u64 v[222:223], s[42:43], 0, v[160:161]
	global_load_lds_dwordx4 v[220:221], off
	v_lshl_add_u64 v[220:221], s[60:61], 0, v[158:159]
	s_add_i32 m0, s62, 0x2000
	s_nop 0
	global_load_lds_dwordx4 v[220:221], off
	v_lshl_add_u64 v[220:221], s[42:43], 0, v[164:165]
	s_mov_b32 m0, s37
	s_nop 0
	global_load_lds_dwordx4 v[220:221], off
	s_mov_b32 m0, s45
	s_nop 0
	global_load_lds_dwordx4 v[222:223], off
	s_waitcnt vmcnt(8)
	s_waitcnt lgkmcnt(0)
	s_setprio 1
	s_barrier
; #define PG8_STAGE(bufoff, gbase, voff) do { _Pragma("unroll") for (int _i = 0; _i < 2; ++_i) \
;         __builtin_amdgcn_global_load_lds((const unsigned*)((const char*)(gbase) + (voff)[_i]), (PG8_LAS unsigned*)(lds + (bufoff) + ldsw + _i * 8192), 16, 0, 0); } while (0)
; #define PG8_LDA(dst, b, h) do { _Pragma("unroll") for (int m = 0; m < 4; ++m) _Pragma("unroll") for (int k = 0; k < 2; ++k) dst[m][k] = *(const PG8_LAS bf16x8*)(lds + PG8_SA(b, h) + aoff + m * 2048 + k * 1024); } while (0)
; #define PG8_LDB(dst, b, h) do { _Pragma("unroll") for (int n = 0; n < 2; ++n) _Pragma("unroll") for (int k = 0; k < 2; ++k) dst[n][k] = *(const PG8_LAS bf16x8*)(lds + PG8_SB(b, h) + boff + n * 2048 + k * 1024); } while (0)
; #define PG8_WAIT_V(n) asm volatile("s_waitcnt vmcnt(" #n ")" ::: "memory")
; #define PG8_WAIT_L(n) asm volatile("s_waitcnt lgkmcnt(" #n ")" ::: "memory")
; #define PG8_BAR __builtin_amdgcn_s_barrier()
; #define PG8_SCHED __builtin_amdgcn_sched_barrier(0)
; template <class Epi, class Sched, bool ALIGN_EPI = false, bool SP2 = false, bool F8 = false>
; __device__ __forceinline__ void gemm_phase(PG8_LAS unsigned char* lds, const Gemm g, const Sched& S, const Epi& E) {
;     ...
;             PG8_WAIT_V(8); PG8_WAIT_L(0); PG8_BAR; PG8_MMA(1, 0, At, B0); PG8_MMA(1, 1, At, B1); PG8_BAR; PG8_SCHED;
;             PG8_LDB(B0, 1, 0); PG8_LDB(B1, 1, 1); PG8_SCHED; PG8_LDA(At, 1, 0); PG8_STAGE(PG8_SA(0, 1), a2 + hA, voffA);
;             PG8_WAIT_V(8); PG8_WAIT_L(0); PG8_BAR; PG8_MMA(0, 0, At, B0); PG8_MMA(0, 1, At, B1); PG8_BAR; PG8_SCHED;
	v_mfma_f32_16x16x32_bf16 v[62:65], v[130:133], v[178:181], v[62:65]
	v_mfma_f32_16x16x32_bf16 v[58:61], v[138:141], v[178:181], v[58:61]
	v_mfma_f32_16x16x32_bf16 v[46:49], v[130:133], v[192:195], v[46:49]
	v_mfma_f32_16x16x32_bf16 v[42:45], v[138:141], v[192:195], v[42:45]
	v_mfma_f32_16x16x32_bf16 v[30:33], v[130:133], v[200:203], v[30:33]
	v_mfma_f32_16x16x32_bf16 v[26:29], v[138:141], v[200:203], v[26:29]
	v_mfma_f32_16x16x32_bf16 v[14:17], v[130:133], v[208:211], v[14:17]
	v_mfma_f32_16x16x32_bf16 v[10:13], v[138:141], v[208:211], v[10:13]
	v_mfma_f32_16x16x32_bf16 v[62:65], v[134:137], v[188:191], v[62:65]
	v_mfma_f32_16x16x32_bf16 v[58:61], v[142:145], v[188:191], v[58:61]
	v_mfma_f32_16x16x32_bf16 v[46:49], v[134:137], v[196:199], v[46:49]
	v_mfma_f32_16x16x32_bf16 v[42:45], v[142:145], v[196:199], v[42:45]
	v_mfma_f32_16x16x32_bf16 v[30:33], v[134:137], v[204:207], v[30:33]
	v_mfma_f32_16x16x32_bf16 v[26:29], v[142:145], v[204:207], v[26:29]
	v_mfma_f32_16x16x32_bf16 v[14:17], v[134:137], v[212:215], v[14:17]
	v_mfma_f32_16x16x32_bf16 v[10:13], v[142:145], v[212:215], v[10:13]
	v_mfma_f32_16x16x32_bf16 v[54:57], v[146:149], v[178:181], v[54:57]
	v_mfma_f32_16x16x32_bf16 v[50:53], v[154:157], v[178:181], v[50:53]
	v_mfma_f32_16x16x32_bf16 v[38:41], v[146:149], v[192:195], v[38:41]
	v_mfma_f32_16x16x32_bf16 v[34:37], v[154:157], v[192:195], v[34:37]
	v_mfma_f32_16x16x32_bf16 v[22:25], v[146:149], v[200:203], v[22:25]
	v_mfma_f32_16x16x32_bf16 v[18:21], v[154:157], v[200:203], v[18:21]
	v_mfma_f32_16x16x32_bf16 v[6:9], v[146:149], v[208:211], v[6:9]
	v_mfma_f32_16x16x32_bf16 v[2:5], v[154:157], v[208:211], v[2:5]
	v_mfma_f32_16x16x32_bf16 v[54:57], v[150:153], v[188:191], v[54:57]
	v_mfma_f32_16x16x32_bf16 v[50:53], v[174:177], v[188:191], v[50:53]
	v_mfma_f32_16x16x32_bf16 v[38:41], v[150:153], v[196:199], v[38:41]
	v_mfma_f32_16x16x32_bf16 v[34:37], v[174:177], v[196:199], v[34:37]
	v_mfma_f32_16x16x32_bf16 v[22:25], v[150:153], v[204:207], v[22:25]
	v_mfma_f32_16x16x32_bf16 v[18:21], v[174:177], v[204:207], v[18:21]
	v_mfma_f32_16x16x32_bf16 v[6:9], v[150:153], v[212:215], v[6:9]
	v_mfma_f32_16x16x32_bf16 v[2:5], v[174:177], v[212:215], v[2:5]
	s_barrier
	s_setprio 0
	s_add_i32 s60, 0, 0x18000
	s_add_i32 s61, 0, 0x1c000
	v_add_u32_e32 v142, s60, v183
	v_add_u32_e32 v174, s61, v183
	ds_read_b128 v[130:133], v142
	ds_read_b128 v[134:137], v142 offset:1024
	ds_read_b128 v[138:141], v142 offset:2048
	ds_read_b128 v[142:145], v142 offset:3072
	ds_read_b128 v[146:149], v174
	ds_read_b128 v[150:153], v174 offset:1024
	ds_read_b128 v[154:157], v174 offset:2048
	ds_read_b128 v[174:177], v174 offset:3072
	s_add_u32 s42, s42, 0x80000
	s_addc_u32 s43, s43, 0
	s_mov_b32 m0, s46
	v_lshl_add_u64 v[224:225], s[42:43], 0, v[164:165]
	ds_read_b128 v[178:181], v187 offset:32768
	ds_read_b128 v[188:191], v187 offset:33792
	ds_read_b128 v[192:195], v187 offset:34816
	ds_read_b128 v[196:199], v187 offset:35840
	ds_read_b128 v[200:203], v187 offset:36864
	ds_read_b128 v[204:207], v187 offset:37888
	ds_read_b128 v[208:211], v187 offset:38912
	ds_read_b128 v[212:215], v187 offset:39936
	global_load_lds_dwordx4 v[224:225], off
	v_lshl_add_u64 v[224:225], s[42:43], 0, v[160:161]
	s_mov_b32 m0, s47
	s_nop 0
	global_load_lds_dwordx4 v[224:225], off
	s_waitcnt vmcnt(8)
	s_waitcnt lgkmcnt(0)
	s_setprio 1
	s_barrier
	v_mfma_f32_16x16x32_bf16 v[126:129], v[130:133], v[178:181], v[126:129]
	v_mfma_f32_16x16x32_bf16 v[122:125], v[138:141], v[178:181], v[122:125]
	v_mfma_f32_16x16x32_bf16 v[110:113], v[130:133], v[192:195], v[110:113]
	v_mfma_f32_16x16x32_bf16 v[106:109], v[138:141], v[192:195], v[106:109]
	v_mfma_f32_16x16x32_bf16 v[94:97], v[130:133], v[200:203], v[94:97]
	v_mfma_f32_16x16x32_bf16 v[90:93], v[138:141], v[200:203], v[90:93]
	v_mfma_f32_16x16x32_bf16 v[78:81], v[130:133], v[208:211], v[78:81]
	v_mfma_f32_16x16x32_bf16 v[74:77], v[138:141], v[208:211], v[74:77]
	v_mfma_f32_16x16x32_bf16 v[126:129], v[134:137], v[188:191], v[126:129]
	v_mfma_f32_16x16x32_bf16 v[122:125], v[142:145], v[188:191], v[122:125]
	v_mfma_f32_16x16x32_bf16 v[110:113], v[134:137], v[196:199], v[110:113]
	v_mfma_f32_16x16x32_bf16 v[106:109], v[142:145], v[196:199], v[106:109]
	v_mfma_f32_16x16x32_bf16 v[94:97], v[134:137], v[204:207], v[94:97]
	v_mfma_f32_16x16x32_bf16 v[90:93], v[142:145], v[204:207], v[90:93]
	v_mfma_f32_16x16x32_bf16 v[78:81], v[134:137], v[212:215], v[78:81]
	v_mfma_f32_16x16x32_bf16 v[74:77], v[142:145], v[212:215], v[74:77]
	v_mfma_f32_16x16x32_bf16 v[118:121], v[146:149], v[178:181], v[118:121]
	v_mfma_f32_16x16x32_bf16 v[114:117], v[154:157], v[178:181], v[114:117]
	v_mfma_f32_16x16x32_bf16 v[102:105], v[146:149], v[192:195], v[102:105]
	v_mfma_f32_16x16x32_bf16 v[98:101], v[154:157], v[192:195], v[98:101]
	v_mfma_f32_16x16x32_bf16 v[86:89], v[146:149], v[200:203], v[86:89]
	v_mfma_f32_16x16x32_bf16 v[82:85], v[154:157], v[200:203], v[82:85]
	v_mfma_f32_16x16x32_bf16 v[70:73], v[146:149], v[208:211], v[70:73]
	v_mfma_f32_16x16x32_bf16 v[66:69], v[154:157], v[208:211], v[66:69]
	v_mfma_f32_16x16x32_bf16 v[118:121], v[150:153], v[188:191], v[118:121]
	v_mfma_f32_16x16x32_bf16 v[114:117], v[174:177], v[188:191], v[114:117]
	v_mfma_f32_16x16x32_bf16 v[102:105], v[150:153], v[196:199], v[102:105]
	v_mfma_f32_16x16x32_bf16 v[98:101], v[174:177], v[196:199], v[98:101]
	v_mfma_f32_16x16x32_bf16 v[86:89], v[150:153], v[204:207], v[86:89]
	v_mfma_f32_16x16x32_bf16 v[82:85], v[174:177], v[204:207], v[82:85]
	v_mfma_f32_16x16x32_bf16 v[70:73], v[150:153], v[212:215], v[70:73]
	v_mfma_f32_16x16x32_bf16 v[66:69], v[174:177], v[212:215], v[66:69]
	s_barrier
; #define PG8_GAS __attribute__((address_space(1)))
; #define PG8_STAGE(bufoff, gbase, voff) do { _Pragma("unroll") for (int _i = 0; _i < 2; ++_i) \
;         __builtin_amdgcn_global_load_lds((const unsigned*)((const char*)(gbase) + (voff)[_i]), (PG8_LAS unsigned*)(lds + (bufoff) + ldsw + _i * 8192), 16, 0, 0); } while (0)
; #define PG8_LDA(dst, b, h) do { _Pragma("unroll") for (int m = 0; m < 4; ++m) _Pragma("unroll") for (int k = 0; k < 2; ++k) dst[m][k] = *(const PG8_LAS bf16x8*)(lds + PG8_SA(b, h) + aoff + m * 2048 + k * 1024); } while (0)
; #define PG8_WAIT_V(n) asm volatile("s_waitcnt vmcnt(" #n ")" ::: "memory")
; #define PG8_WAIT_L(n) asm volatile("s_waitcnt lgkmcnt(" #n ")" ::: "memory")
; #define PG8_BAR __builtin_amdgcn_s_barrier()
; #define PG8_SCHED __builtin_amdgcn_sched_barrier(0)
;     __device__ __forceinline__ void operator()(const f32x4 (&acc)[2][2][4][2], const Unit& un, int wr, int wc, int fr, int fq) const {
;         const int row0 = un.pm * BM + wr * 64 + fr, col0 = un.pn * BM + wc * 32 + 8 * fq;
;         f32x4 sc[2][2];
; #pragma unroll
;         for (int bj = 0; bj < 2; ++bj)
; #pragma unroll
;             for (int n = 0; n < 2; ++n) sc[bj][n] = *(const PG8_GAS f32x4*)(ps + col0 + bj * HALF + 4 * n);
; #pragma unroll
;         for (int ai = 0; ai < 2; ++ai) {
;             u32x4 gg[4][2];
; #pragma unroll
;             for (int m = 0; m < 4; ++m)
; #pragma unroll
;                 for (int bj = 0; bj < 2; ++bj) gg[m][bj] = *(const PG8_GAS u32x4*)(sp + (size_t)(row0 + ai * HALF + m * 16) * 4096 + col0 + bj * HALF);
; template <class Epi, class Sched, bool ALIGN_EPI = false, bool SP2 = false, bool F8 = false>
; __device__ __forceinline__ void gemm_phase(PG8_LAS unsigned char* lds, const Gemm g, const Sched& S, const Epi& E) {
;     ...
;             PG8_LDA(At, 1, 1); PG8_STAGE(PG8_SB(1, 0), b3, voffB); PG8_STAGE(PG8_SB(1, 1), b3 + hB, voffB); PG8_STAGE(PG8_SA(1, 0), a3, voffA);
;             PG8_WAIT_V(8); PG8_WAIT_L(0); PG8_BAR; PG8_MMA(1, 0, At, B0); PG8_MMA(1, 1, At, B1); PG8_BAR; PG8_SCHED;
	s_setprio 0
	s_add_i32 s42, s60, s19
	v_lshl_add_u64 v[216:217], v[216:217], 0, s[14:15]
	s_mov_b32 m0, s42
	ds_read_b128 v[178:181], v187 offset:49152
	ds_read_b128 v[188:191], v187 offset:50176
	ds_read_b128 v[192:195], v187 offset:51200
	ds_read_b128 v[196:199], v187 offset:52224
	ds_read_b128 v[200:203], v187 offset:53248
	ds_read_b128 v[204:207], v187 offset:54272
	ds_read_b128 v[208:211], v187 offset:55296
	ds_read_b128 v[212:215], v187 offset:56320
	global_load_lds_dwordx4 v[216:217], off
	s_add_i32 m0, s42, 0x2000
	s_add_u32 s40, s40, 0x20080
	v_lshl_add_u64 v[216:217], v[218:219], 0, s[14:15]
	s_addc_u32 s41, s41, 0
	s_add_i32 s42, s61, s19
	global_load_lds_dwordx4 v[216:217], off
	v_lshl_add_u64 v[216:217], s[40:41], 0, v[162:163]
	s_mov_b32 m0, s42
	s_nop 0
	global_load_lds_dwordx4 v[216:217], off
	v_lshl_add_u64 v[216:217], s[40:41], 0, v[158:159]
	s_add_i32 m0, s42, 0x2000
	s_nop 0
	global_load_lds_dwordx4 v[216:217], off
	v_lshl_add_u64 v[216:217], v[220:221], 0, s[14:15]
	s_mov_b32 m0, s49
	s_nop 0
	global_load_lds_dwordx4 v[216:217], off
	v_lshl_add_u64 v[216:217], v[222:223], 0, s[14:15]
	s_mov_b32 m0, s50
	s_nop 0
	global_load_lds_dwordx4 v[216:217], off
	s_waitcnt vmcnt(8)
	s_waitcnt lgkmcnt(0)
	s_setprio 1
	s_barrier
	v_mfma_f32_16x16x32_bf16 v[62:65], v[130:133], v[178:181], v[62:65]
	v_mfma_f32_16x16x32_bf16 v[58:61], v[138:141], v[178:181], v[58:61]
	v_mfma_f32_16x16x32_bf16 v[46:49], v[130:133], v[192:195], v[46:49]
	v_mfma_f32_16x16x32_bf16 v[42:45], v[138:141], v[192:195], v[42:45]
	v_mfma_f32_16x16x32_bf16 v[30:33], v[130:133], v[200:203], v[30:33]
	v_mfma_f32_16x16x32_bf16 v[26:29], v[138:141], v[200:203], v[26:29]
	v_mfma_f32_16x16x32_bf16 v[14:17], v[130:133], v[208:211], v[14:17]
	v_mfma_f32_16x16x32_bf16 v[10:13], v[138:141], v[208:211], v[10:13]
	v_mfma_f32_16x16x32_bf16 v[62:65], v[134:137], v[188:191], v[62:65]
	v_mfma_f32_16x16x32_bf16 v[58:61], v[142:145], v[188:191], v[58:61]
	v_mfma_f32_16x16x32_bf16 v[46:49], v[134:137], v[196:199], v[46:49]
	v_mfma_f32_16x16x32_bf16 v[42:45], v[142:145], v[196:199], v[42:45]
	v_mfma_f32_16x16x32_bf16 v[30:33], v[134:137], v[204:207], v[30:33]
	v_mfma_f32_16x16x32_bf16 v[26:29], v[142:145], v[204:207], v[26:29]
	v_mfma_f32_16x16x32_bf16 v[14:17], v[134:137], v[212:215], v[14:17]
	v_mfma_f32_16x16x32_bf16 v[10:13], v[142:145], v[212:215], v[10:13]
	v_mfma_f32_16x16x32_bf16 v[54:57], v[146:149], v[178:181], v[54:57]
	v_mfma_f32_16x16x32_bf16 v[50:53], v[154:157], v[178:181], v[50:53]
	v_mfma_f32_16x16x32_bf16 v[38:41], v[146:149], v[192:195], v[38:41]
	v_mfma_f32_16x16x32_bf16 v[34:37], v[154:157], v[192:195], v[34:37]
	v_mfma_f32_16x16x32_bf16 v[22:25], v[146:149], v[200:203], v[22:25]
	v_mfma_f32_16x16x32_bf16 v[18:21], v[154:157], v[200:203], v[18:21]
	v_mfma_f32_16x16x32_bf16 v[6:9], v[146:149], v[208:211], v[6:9]
	v_mfma_f32_16x16x32_bf16 v[2:5], v[154:157], v[208:211], v[2:5]
	v_mfma_f32_16x16x32_bf16 v[54:57], v[150:153], v[188:191], v[54:57]
	v_mfma_f32_16x16x32_bf16 v[50:53], v[174:177], v[188:191], v[50:53]
	v_mfma_f32_16x16x32_bf16 v[38:41], v[150:153], v[196:199], v[38:41]
	v_mfma_f32_16x16x32_bf16 v[34:37], v[174:177], v[196:199], v[34:37]
	v_mfma_f32_16x16x32_bf16 v[22:25], v[150:153], v[204:207], v[22:25]
	v_mfma_f32_16x16x32_bf16 v[18:21], v[174:177], v[204:207], v[18:21]
	v_mfma_f32_16x16x32_bf16 v[6:9], v[150:153], v[212:215], v[6:9]
	v_mfma_f32_16x16x32_bf16 v[2:5], v[174:177], v[212:215], v[2:5]
	s_add_i32 s59, s59, 2
	s_add_u32 s57, s57, 0x100
	s_addc_u32 s58, s58, 0
	s_add_u32 s38, s38, 0x100
	s_addc_u32 s39, s39, 0
	s_cmp_gt_u32 s59, 5
	s_cbranch_scc0 .Lber_618
	s_barrier
	s_setprio 0
	v_lshl_or_b32 v146, s54, 8, v184
	v_ashrrev_i32_e32 v147, 31, v146
	v_lshl_add_u32 v148, s36, 8, v182
	v_ashrrev_i32_e32 v149, 31, v148
	v_lshlrev_b64 v[174:175], 1, v[146:147]
	v_lshlrev_b64 v[178:179], 13, v[148:149]
	v_lshl_add_u64 v[176:177], s[12:13], 0, v[174:175]
	v_lshl_add_u64 v[130:131], v[146:147], 2, s[10:11]
	v_lshl_add_u64 v[146:147], v[176:177], 0, v[178:179]
	global_load_dwordx4 v[142:145], v[130:131], off
	global_load_dwordx4 v[138:141], v[130:131], off offset:16
	global_load_dwordx4 v[134:137], v[130:131], off offset:512
	s_nop 0
	global_load_dwordx4 v[130:133], v[130:131], off offset:528
	s_nop 0
	global_load_dwordx4 v[188:191], v[146:147], off
	global_load_dwordx4 v[192:195], v[146:147], off offset:256
	v_or_b32_e32 v146, 16, v148
	v_ashrrev_i32_e32 v147, 31, v146
	v_lshlrev_b64 v[208:209], 13, v[146:147]
	v_lshl_add_u64 v[146:147], v[176:177], 0, v[208:209]
	global_load_dwordx4 v[196:199], v[146:147], off
	global_load_dwordx4 v[200:203], v[146:147], off offset:256
	v_or_b32_e32 v150, 32, v148
	v_or_b32_e32 v148, 48, v148
	v_ashrrev_i32_e32 v151, 31, v150
	v_ashrrev_i32_e32 v149, 31, v148
	v_lshlrev_b64 v[210:211], 13, v[150:151]
	v_lshlrev_b64 v[180:181], 13, v[148:149]
	v_lshl_add_u64 v[146:147], s[12:13], 0, v[178:179]
	v_lshl_add_u64 v[148:149], v[176:177], 0, v[210:211]
	v_lshl_add_u64 v[212:213], v[176:177], 0, v[180:181]
	v_lshl_add_u64 v[214:215], v[146:147], 0, v[174:175]
	global_load_dwordx4 v[204:207], v[148:149], off
	global_load_dwordx4 v[154:157], v[148:149], off offset:256
	global_load_dwordx4 v[150:153], v[212:213], off
	s_nop 0
	global_load_dwordx4 v[146:149], v[212:213], off offset:256
	s_and_b64 vcc, exec, s[8:9]
	s_mov_b32 s54, s26
	s_mov_b32 s36, s28
	s_mov_b64 s[38:39], s[34:35]
	s_mov_b64 s[40:41], s[30:31]
	s_waitcnt vmcnt(0)
; #define PG8_GAS __attribute__((address_space(1)))
; __device__ __forceinline__ unsigned cvt_pk_bf16(float lo, float hi) { const f32x2c v = {lo, hi}; return __builtin_bit_cast(unsigned, __builtin_convertvector(v, bf16x2c)); }
; __device__ __forceinline__ float bf_lo(unsigned w) { return __uint_as_float(w << 16); }
; __device__ __forceinline__ float bf_hi(unsigned w) { return __uint_as_float(w & 0xffff0000u); }
;     __device__ __forceinline__ void operator()(const f32x4 (&acc)[2][2][4][2], const Unit& un, int wr, int wc, int fr, int fq) const {
;     ...
; #pragma unroll
;             for (int m = 0; m < 4; ++m)
; #pragma unroll
;                 for (int bj = 0; bj < 2; ++bj) { const u32x4 g = gg[m][bj];
;                     const f32x4 v0 = acc[ai][bj][m][0] * sc[bj][0], v1 = acc[ai][bj][m][1] * sc[bj][1];
;                     u32x4 w; w.x = cvt_pk_bf16(v0[0] * bf_lo(g.x), v0[1] * bf_hi(g.x)); w.y = cvt_pk_bf16(v0[2] * bf_lo(g.y), v0[3] * bf_hi(g.y));
;                     w.z = cvt_pk_bf16(v1[0] * bf_lo(g.z), v1[1] * bf_hi(g.z)); w.w = cvt_pk_bf16(v1[2] * bf_lo(g.w), v1[3] * bf_hi(g.w));
;                     *(PG8_GAS u32x4*)(sp + (size_t)(row0 + ai * HALF + m * 16) * 4096 + col0 + bj * HALF) = w; }
	v_pk_mul_f32 v[128:129], v[128:129], v[144:145]
	v_pk_mul_f32 v[126:127], v[126:127], v[142:143]
	v_pk_mul_f32 v[124:125], v[124:125], v[140:141]
	v_pk_mul_f32 v[122:123], v[122:123], v[138:139]
	v_pk_mul_f32 v[212:213], v[108:109], v[140:141]
	v_pk_mul_f32 v[216:217], v[106:107], v[138:139]
	v_lshlrev_b32_e32 v106, 16, v188
	v_and_b32_e32 v107, 0xffff0000, v188
	v_lshlrev_b32_e32 v108, 16, v189
	v_and_b32_e32 v109, 0xffff0000, v189
	v_lshlrev_b32_e32 v188, 16, v190
	v_and_b32_e32 v189, 0xffff0000, v190
	v_lshlrev_b32_e32 v190, 16, v191
	v_and_b32_e32 v191, 0xffff0000, v191
	v_pk_mul_f32 v[120:121], v[120:121], v[136:137]
	v_pk_mul_f32 v[118:119], v[118:119], v[134:135]
	v_pk_mul_f32 v[116:117], v[116:117], v[132:133]
	v_pk_mul_f32 v[114:115], v[114:115], v[130:131]
	v_lshlrev_b32_e32 v218, 16, v192
	v_and_b32_e32 v219, 0xffff0000, v192
	v_lshlrev_b32_e32 v192, 16, v193
	v_and_b32_e32 v193, 0xffff0000, v193
	v_lshlrev_b32_e32 v220, 16, v194
	v_and_b32_e32 v221, 0xffff0000, v194
	v_lshlrev_b32_e32 v194, 16, v195
	v_and_b32_e32 v195, 0xffff0000, v195
	v_pk_mul_f32 v[106:107], v[126:127], v[106:107]
	v_pk_mul_f32 v[108:109], v[128:129], v[108:109]
	v_pk_mul_f32 v[122:123], v[122:123], v[188:189]
	v_pk_mul_f32 v[124:125], v[124:125], v[190:191]
	v_pk_mul_f32 v[112:113], v[112:113], v[144:145]
	v_pk_mul_f32 v[110:111], v[110:111], v[142:143]
	v_lshlrev_b32_e32 v222, 16, v196
	v_and_b32_e32 v223, 0xffff0000, v196
	v_lshlrev_b32_e32 v196, 16, v197
	v_and_b32_e32 v197, 0xffff0000, v197
	v_pk_mul_f32 v[118:119], v[118:119], v[218:219]
	v_pk_mul_f32 v[120:121], v[120:121], v[192:193]
	v_pk_mul_f32 v[114:115], v[114:115], v[220:221]
	v_pk_mul_f32 v[116:117], v[116:117], v[194:195]
	v_cvt_pk_bf16_f32 v106, v106, v107
	v_cvt_pk_bf16_f32 v107, v108, v109
	v_cvt_pk_bf16_f32 v108, v122, v123
	v_cvt_pk_bf16_f32 v109, v124, v125
	v_pk_mul_f32 v[126:127], v[110:111], v[222:223]
	v_pk_mul_f32 v[128:129], v[112:113], v[196:197]
	v_cvt_pk_bf16_f32 v110, v118, v119
	v_cvt_pk_bf16_f32 v111, v120, v121
	v_cvt_pk_bf16_f32 v112, v114, v115
	v_cvt_pk_bf16_f32 v113, v116, v117
	global_store_dwordx4 v[214:215], v[106:109], off
	global_store_dwordx4 v[214:215], v[110:113], off offset:256
	v_pk_mul_f32 v[102:103], v[102:103], v[134:135]
	v_pk_mul_f32 v[108:109], v[100:101], v[132:133]
	v_pk_mul_f32 v[100:101], v[98:99], v[130:131]
	v_lshlrev_b32_e32 v98, 16, v200
	v_and_b32_e32 v99, 0xffff0000, v200
	v_lshlrev_b32_e32 v106, 16, v198
	v_and_b32_e32 v107, 0xffff0000, v198
	v_pk_mul_f32 v[104:105], v[104:105], v[136:137]
	v_pk_mul_f32 v[98:99], v[102:103], v[98:99]
	v_lshlrev_b32_e32 v102, 16, v201
	v_and_b32_e32 v103, 0xffff0000, v201
	v_pk_mul_f32 v[106:107], v[216:217], v[106:107]
	v_pk_mul_f32 v[102:103], v[104:105], v[102:103]
	v_cvt_pk_bf16_f32 v116, v106, v107
	v_lshlrev_b32_e32 v106, 16, v199
	v_and_b32_e32 v107, 0xffff0000, v199
	v_cvt_pk_bf16_f32 v98, v98, v99
	v_cvt_pk_bf16_f32 v99, v102, v103
	v_lshlrev_b32_e32 v102, 16, v202
	v_and_b32_e32 v103, 0xffff0000, v202
	v_pk_mul_f32 v[106:107], v[212:213], v[106:107]
	v_pk_mul_f32 v[100:101], v[100:101], v[102:103]
	v_lshlrev_b32_e32 v102, 16, v203
	v_and_b32_e32 v103, 0xffff0000, v203
	v_cvt_pk_bf16_f32 v117, v106, v107
	v_lshl_add_u64 v[106:107], s[12:13], 0, v[208:209]
	v_pk_mul_f32 v[102:103], v[108:109], v[102:103]
	v_lshl_add_u64 v[106:107], v[106:107], 0, v[174:175]
	v_cvt_pk_bf16_f32 v100, v100, v101
	v_cvt_pk_bf16_f32 v101, v102, v103
	global_store_dwordx4 v[106:107], v[98:101], off offset:256
	v_pk_mul_f32 v[94:95], v[94:95], v[142:143]
	v_pk_mul_f32 v[96:97], v[96:97], v[144:145]
	v_pk_mul_f32 v[98:99], v[92:93], v[140:141]
	v_pk_mul_f32 v[92:93], v[90:91], v[138:139]
	v_lshlrev_b32_e32 v90, 16, v204
	v_and_b32_e32 v91, 0xffff0000, v204
	v_pk_mul_f32 v[90:91], v[94:95], v[90:91]
	v_lshlrev_b32_e32 v94, 16, v205
	v_and_b32_e32 v95, 0xffff0000, v205
	v_pk_mul_f32 v[94:95], v[96:97], v[94:95]
	v_cvt_pk_bf16_f32 v90, v90, v91
	v_cvt_pk_bf16_f32 v91, v94, v95
	v_lshlrev_b32_e32 v94, 16, v206
	v_and_b32_e32 v95, 0xffff0000, v206
	v_pk_mul_f32 v[92:93], v[92:93], v[94:95]
	v_lshlrev_b32_e32 v94, 16, v207
	v_and_b32_e32 v95, 0xffff0000, v207
	v_pk_mul_f32 v[94:95], v[98:99], v[94:95]
	v_cvt_pk_bf16_f32 v92, v92, v93
	v_cvt_pk_bf16_f32 v93, v94, v95
	v_lshl_add_u64 v[94:95], s[12:13], 0, v[210:211]
	v_lshl_add_u64 v[102:103], v[178:179], 0, s[16:17]
	v_lshl_add_u64 v[94:95], v[94:95], 0, v[174:175]
	v_pk_mul_f32 v[86:87], v[86:87], v[134:135]
	v_lshl_add_u64 v[96:97], v[176:177], 0, v[102:103]
	v_lshlrev_b32_e32 v98, 16, v154
	v_and_b32_e32 v99, 0xffff0000, v154
	global_store_dwordx4 v[94:95], v[90:93], off
	v_pk_mul_f32 v[88:89], v[88:89], v[136:137]
	v_pk_mul_f32 v[86:87], v[86:87], v[98:99]
	v_pk_mul_f32 v[90:91], v[84:85], v[132:133]
	v_pk_mul_f32 v[92:93], v[82:83], v[130:131]
	global_load_dwordx4 v[82:85], v[96:97], off
	v_lshlrev_b32_e32 v98, 16, v155
	v_and_b32_e32 v99, 0xffff0000, v155
	v_pk_mul_f32 v[88:89], v[88:89], v[98:99]
	v_cvt_pk_bf16_f32 v86, v86, v87
	v_cvt_pk_bf16_f32 v87, v88, v89
	v_lshlrev_b32_e32 v88, 16, v156
	v_and_b32_e32 v89, 0xffff0000, v156
	v_pk_mul_f32 v[88:89], v[92:93], v[88:89]
	v_lshlrev_b32_e32 v92, 16, v157
	v_and_b32_e32 v93, 0xffff0000, v157
	v_pk_mul_f32 v[90:91], v[90:91], v[92:93]
	v_cvt_pk_bf16_f32 v88, v88, v89
	v_cvt_pk_bf16_f32 v89, v90, v91
	global_store_dwordx4 v[94:95], v[86:89], off offset:256
	v_pk_mul_f32 v[80:81], v[80:81], v[144:145]
	v_pk_mul_f32 v[90:91], v[76:77], v[140:141]
	v_pk_mul_f32 v[86:87], v[78:79], v[142:143]
	v_lshlrev_b32_e32 v88, 16, v150
	v_and_b32_e32 v89, 0xffff0000, v150
	v_pk_mul_f32 v[86:87], v[86:87], v[88:89]
	v_lshlrev_b32_e32 v88, 16, v151
; #define PG8_GAS __attribute__((address_space(1)))
; __device__ __forceinline__ unsigned cvt_pk_bf16(float lo, float hi) { const f32x2c v = {lo, hi}; return __builtin_bit_cast(unsigned, __builtin_convertvector(v, bf16x2c)); }
; __device__ __forceinline__ float bf_lo(unsigned w) { return __uint_as_float(w << 16); }
; __device__ __forceinline__ float bf_hi(unsigned w) { return __uint_as_float(w & 0xffff0000u); }
;     __device__ __forceinline__ void operator()(const f32x4 (&acc)[2][2][4][2], const Unit& un, int wr, int wc, int fr, int fq) const {
;     ...
;         for (int ai = 0; ai < 2; ++ai) {
;             u32x4 gg[4][2];
; #pragma unroll
;             for (int m = 0; m < 4; ++m)
; #pragma unroll
;                 for (int bj = 0; bj < 2; ++bj) gg[m][bj] = *(const PG8_GAS u32x4*)(sp + (size_t)(row0 + ai * HALF + m * 16) * 4096 + col0 + bj * HALF);
;             asm volatile("" ::: "memory");
; #pragma unroll
;             for (int m = 0; m < 4; ++m)
; #pragma unroll
;                 for (int bj = 0; bj < 2; ++bj) { const u32x4 g = gg[m][bj];
;                     const f32x4 v0 = acc[ai][bj][m][0] * sc[bj][0], v1 = acc[ai][bj][m][1] * sc[bj][1];
;                     u32x4 w; w.x = cvt_pk_bf16(v0[0] * bf_lo(g.x), v0[1] * bf_hi(g.x)); w.y = cvt_pk_bf16(v0[2] * bf_lo(g.y), v0[3] * bf_hi(g.y));
;                     w.z = cvt_pk_bf16(v1[0] * bf_lo(g.z), v1[1] * bf_hi(g.z)); w.w = cvt_pk_bf16(v1[2] * bf_lo(g.w), v1[3] * bf_hi(g.w));
;                     *(PG8_GAS u32x4*)(sp + (size_t)(row0 + ai * HALF + m * 16) * 4096 + col0 + bj * HALF) = w; }
	v_and_b32_e32 v89, 0xffff0000, v151
	global_load_dwordx4 v[76:79], v[96:97], off offset:256
	v_pk_mul_f32 v[80:81], v[80:81], v[88:89]
	v_pk_mul_f32 v[74:75], v[74:75], v[138:139]
	v_cvt_pk_bf16_f32 v86, v86, v87
	v_cvt_pk_bf16_f32 v87, v80, v81
	v_lshlrev_b32_e32 v80, 16, v152
	v_and_b32_e32 v81, 0xffff0000, v152
	v_pk_mul_f32 v[74:75], v[74:75], v[80:81]
	v_lshl_add_u64 v[80:81], v[178:179], 0, s[20:21]
	v_cvt_pk_bf16_f32 v88, v74, v75
	v_lshlrev_b32_e32 v74, 16, v153
	v_and_b32_e32 v75, 0xffff0000, v153
	v_pk_mul_f32 v[74:75], v[90:91], v[74:75]
	v_lshl_add_u64 v[90:91], v[176:177], 0, v[80:81]
	v_cvt_pk_bf16_f32 v89, v74, v75
	v_lshl_add_u64 v[74:75], s[12:13], 0, v[180:181]
	v_lshl_add_u64 v[74:75], v[74:75], 0, v[174:175]
	global_store_dwordx4 v[74:75], v[86:89], off
	global_load_dwordx4 v[86:89], v[90:91], off
	v_pk_mul_f32 v[70:71], v[70:71], v[134:135]
	v_pk_mul_f32 v[92:93], v[68:69], v[132:133]
	v_pk_mul_f32 v[68:69], v[66:67], v[130:131]
	v_lshlrev_b32_e32 v66, 16, v146
	v_and_b32_e32 v67, 0xffff0000, v146
	v_pk_mul_f32 v[72:73], v[72:73], v[136:137]
	v_pk_mul_f32 v[66:67], v[70:71], v[66:67]
	v_lshlrev_b32_e32 v70, 16, v147
	v_and_b32_e32 v71, 0xffff0000, v147
	v_pk_mul_f32 v[70:71], v[72:73], v[70:71]
	v_cvt_pk_bf16_f32 v66, v66, v67
	v_cvt_pk_bf16_f32 v67, v70, v71
	v_lshlrev_b32_e32 v70, 16, v148
	v_and_b32_e32 v71, 0xffff0000, v148
	v_pk_mul_f32 v[68:69], v[68:69], v[70:71]
	v_lshlrev_b32_e32 v70, 16, v149
	v_and_b32_e32 v71, 0xffff0000, v149
	v_pk_mul_f32 v[70:71], v[92:93], v[70:71]
	global_load_dwordx4 v[90:93], v[90:91], off offset:256
	v_cvt_pk_bf16_f32 v114, v126, v127
	v_cvt_pk_bf16_f32 v115, v128, v129
	v_cvt_pk_bf16_f32 v68, v68, v69
	v_cvt_pk_bf16_f32 v69, v70, v71
	v_lshl_add_u64 v[104:105], v[178:179], 0, s[22:23]
	global_store_dwordx4 v[106:107], v[114:117], off
	global_store_dwordx4 v[74:75], v[66:69], off offset:256
	v_lshl_add_u64 v[74:75], v[178:179], 0, s[24:25]
	v_pk_mul_f32 v[62:63], v[62:63], v[142:143]
	v_lshl_add_u64 v[66:67], v[176:177], 0, v[104:105]
	global_load_dwordx4 v[94:97], v[66:67], off
	global_load_dwordx4 v[98:101], v[66:67], off offset:256
	v_lshl_add_u64 v[66:67], v[176:177], 0, v[74:75]
	global_load_dwordx4 v[70:73], v[66:67], off
	s_nop 0
	global_load_dwordx4 v[66:69], v[66:67], off offset:256
	v_pk_mul_f32 v[106:107], v[60:61], v[140:141]
	v_pk_mul_f32 v[60:61], v[58:59], v[138:139]
	v_pk_mul_f32 v[64:65], v[64:65], v[144:145]
	v_pk_mul_f32 v[54:55], v[54:55], v[134:135]
	v_pk_mul_f32 v[56:57], v[56:57], v[136:137]
	s_waitcnt vmcnt(11)
	v_lshlrev_b32_e32 v58, 16, v82
	v_and_b32_e32 v59, 0xffff0000, v82
	v_pk_mul_f32 v[58:59], v[62:63], v[58:59]
	v_lshlrev_b32_e32 v62, 16, v83
	v_and_b32_e32 v63, 0xffff0000, v83
	v_pk_mul_f32 v[62:63], v[64:65], v[62:63]
	v_cvt_pk_bf16_f32 v58, v58, v59
	v_cvt_pk_bf16_f32 v59, v62, v63
	v_lshlrev_b32_e32 v62, 16, v84
	v_and_b32_e32 v63, 0xffff0000, v84
	v_pk_mul_f32 v[60:61], v[60:61], v[62:63]
	v_lshlrev_b32_e32 v62, 16, v85
	v_and_b32_e32 v63, 0xffff0000, v85
	v_pk_mul_f32 v[62:63], v[106:107], v[62:63]
	v_cvt_pk_bf16_f32 v60, v60, v61
	v_cvt_pk_bf16_f32 v61, v62, v63
	v_lshl_add_u64 v[62:63], s[12:13], 0, v[102:103]
	v_lshl_add_u64 v[62:63], v[62:63], 0, v[174:175]
	global_store_dwordx4 v[62:63], v[58:61], off
	v_pk_mul_f32 v[46:47], v[46:47], v[142:143]
	v_pk_mul_f32 v[48:49], v[48:49], v[144:145]
	v_pk_mul_f32 v[58:59], v[52:53], v[132:133]
	v_pk_mul_f32 v[52:53], v[50:51], v[130:131]
	s_waitcnt vmcnt(10)
	v_lshlrev_b32_e32 v50, 16, v76
	v_and_b32_e32 v51, 0xffff0000, v76
	v_pk_mul_f32 v[50:51], v[54:55], v[50:51]
	v_lshlrev_b32_e32 v54, 16, v77
	v_and_b32_e32 v55, 0xffff0000, v77
	v_pk_mul_f32 v[54:55], v[56:57], v[54:55]
	v_cvt_pk_bf16_f32 v50, v50, v51
	v_cvt_pk_bf16_f32 v51, v54, v55
	v_lshlrev_b32_e32 v54, 16, v78
	v_and_b32_e32 v55, 0xffff0000, v78
	v_pk_mul_f32 v[52:53], v[52:53], v[54:55]
	v_lshlrev_b32_e32 v54, 16, v79
	v_and_b32_e32 v55, 0xffff0000, v79
	v_pk_mul_f32 v[54:55], v[58:59], v[54:55]
	v_cvt_pk_bf16_f32 v52, v52, v53
	v_cvt_pk_bf16_f32 v53, v54, v55
	global_store_dwordx4 v[62:63], v[50:53], off offset:256
	v_pk_mul_f32 v[38:39], v[38:39], v[134:135]
	v_pk_mul_f32 v[40:41], v[40:41], v[136:137]
	v_pk_mul_f32 v[50:51], v[44:45], v[140:141]
	v_pk_mul_f32 v[44:45], v[42:43], v[138:139]
	s_waitcnt vmcnt(9)
; #define PG8_GAS __attribute__((address_space(1)))
; __device__ __forceinline__ unsigned cvt_pk_bf16(float lo, float hi) { const f32x2c v = {lo, hi}; return __builtin_bit_cast(unsigned, __builtin_convertvector(v, bf16x2c)); }
; __device__ __forceinline__ float bf_lo(unsigned w) { return __uint_as_float(w << 16); }
; __device__ __forceinline__ float bf_hi(unsigned w) { return __uint_as_float(w & 0xffff0000u); }
; #define PG8_WAIT_V(n) asm volatile("s_waitcnt vmcnt(" #n ")" ::: "memory")
; #define PG8_BAR __builtin_amdgcn_s_barrier()
;     __device__ __forceinline__ void operator()(const f32x4 (&acc)[2][2][4][2], const Unit& un, int wr, int wc, int fr, int fq) const {
;     ...
; #pragma unroll
;             for (int m = 0; m < 4; ++m)
; #pragma unroll
;                 for (int bj = 0; bj < 2; ++bj) { const u32x4 g = gg[m][bj];
;                     const f32x4 v0 = acc[ai][bj][m][0] * sc[bj][0], v1 = acc[ai][bj][m][1] * sc[bj][1];
;                     u32x4 w; w.x = cvt_pk_bf16(v0[0] * bf_lo(g.x), v0[1] * bf_hi(g.x)); w.y = cvt_pk_bf16(v0[2] * bf_lo(g.y), v0[3] * bf_hi(g.y));
;                     w.z = cvt_pk_bf16(v1[0] * bf_lo(g.z), v1[1] * bf_hi(g.z)); w.w = cvt_pk_bf16(v1[2] * bf_lo(g.w), v1[3] * bf_hi(g.w));
;                     *(PG8_GAS u32x4*)(sp + (size_t)(row0 + ai * HALF + m * 16) * 4096 + col0 + bj * HALF) = w; }
; template <class Epi, class Sched, bool ALIGN_EPI = false, bool SP2 = false, bool F8 = false>
; __device__ __forceinline__ void gemm_phase(PG8_LAS unsigned char* lds, const Gemm g, const Sched& S, const Epi& E) {
;     ...
;     PG8_WAIT_V(0);
;     if constexpr (!ALIGN_EPI) { if (wr == 0) PG8_BAR; }
;     PG8_BAR;
	v_lshlrev_b32_e32 v42, 16, v86
	v_and_b32_e32 v43, 0xffff0000, v86
	v_pk_mul_f32 v[42:43], v[46:47], v[42:43]
	v_lshlrev_b32_e32 v46, 16, v87
	v_and_b32_e32 v47, 0xffff0000, v87
	v_pk_mul_f32 v[46:47], v[48:49], v[46:47]
	v_cvt_pk_bf16_f32 v42, v42, v43
	v_cvt_pk_bf16_f32 v43, v46, v47
	v_lshlrev_b32_e32 v46, 16, v88
	v_and_b32_e32 v47, 0xffff0000, v88
	v_pk_mul_f32 v[44:45], v[44:45], v[46:47]
	v_lshlrev_b32_e32 v46, 16, v89
	v_and_b32_e32 v47, 0xffff0000, v89
	v_pk_mul_f32 v[46:47], v[50:51], v[46:47]
	v_cvt_pk_bf16_f32 v44, v44, v45
	v_cvt_pk_bf16_f32 v45, v46, v47
	v_lshl_add_u64 v[46:47], s[12:13], 0, v[80:81]
	v_lshl_add_u64 v[46:47], v[46:47], 0, v[174:175]
	global_store_dwordx4 v[46:47], v[42:45], off
	v_pk_mul_f32 v[30:31], v[30:31], v[142:143]
	v_pk_mul_f32 v[32:33], v[32:33], v[144:145]
	v_pk_mul_f32 v[42:43], v[36:37], v[132:133]
	v_pk_mul_f32 v[36:37], v[34:35], v[130:131]
	s_waitcnt vmcnt(9)
	v_lshlrev_b32_e32 v34, 16, v90
	v_and_b32_e32 v35, 0xffff0000, v90
	v_pk_mul_f32 v[34:35], v[38:39], v[34:35]
	v_lshlrev_b32_e32 v38, 16, v91
	v_and_b32_e32 v39, 0xffff0000, v91
	v_pk_mul_f32 v[38:39], v[40:41], v[38:39]
	v_cvt_pk_bf16_f32 v34, v34, v35
	v_cvt_pk_bf16_f32 v35, v38, v39
	v_lshlrev_b32_e32 v38, 16, v92
	v_and_b32_e32 v39, 0xffff0000, v92
	v_pk_mul_f32 v[36:37], v[36:37], v[38:39]
	v_lshlrev_b32_e32 v38, 16, v93
	v_and_b32_e32 v39, 0xffff0000, v93
	v_pk_mul_f32 v[38:39], v[42:43], v[38:39]
	v_cvt_pk_bf16_f32 v36, v36, v37
	v_cvt_pk_bf16_f32 v37, v38, v39
	global_store_dwordx4 v[46:47], v[34:37], off offset:256
	v_pk_mul_f32 v[22:23], v[22:23], v[134:135]
	v_pk_mul_f32 v[24:25], v[24:25], v[136:137]
	v_pk_mul_f32 v[34:35], v[28:29], v[140:141]
	v_pk_mul_f32 v[28:29], v[26:27], v[138:139]
	s_waitcnt vmcnt(7)
	v_lshlrev_b32_e32 v26, 16, v94
	v_and_b32_e32 v27, 0xffff0000, v94
	v_pk_mul_f32 v[26:27], v[30:31], v[26:27]
	v_lshlrev_b32_e32 v30, 16, v95
	v_and_b32_e32 v31, 0xffff0000, v95
	v_pk_mul_f32 v[30:31], v[32:33], v[30:31]
	v_cvt_pk_bf16_f32 v26, v26, v27
	v_cvt_pk_bf16_f32 v27, v30, v31
	v_lshlrev_b32_e32 v30, 16, v96
	v_and_b32_e32 v31, 0xffff0000, v96
	v_pk_mul_f32 v[28:29], v[28:29], v[30:31]
	v_lshlrev_b32_e32 v30, 16, v97
	v_and_b32_e32 v31, 0xffff0000, v97
	v_pk_mul_f32 v[30:31], v[34:35], v[30:31]
	v_cvt_pk_bf16_f32 v28, v28, v29
	v_cvt_pk_bf16_f32 v29, v30, v31
	v_lshl_add_u64 v[30:31], s[12:13], 0, v[104:105]
	v_lshl_add_u64 v[30:31], v[30:31], 0, v[174:175]
	global_store_dwordx4 v[30:31], v[26:29], off
	v_pk_mul_f32 v[14:15], v[14:15], v[142:143]
	v_pk_mul_f32 v[16:17], v[16:17], v[144:145]
	v_pk_mul_f32 v[26:27], v[20:21], v[132:133]
	v_pk_mul_f32 v[20:21], v[18:19], v[130:131]
	s_waitcnt vmcnt(7)
	v_lshlrev_b32_e32 v18, 16, v98
	v_and_b32_e32 v19, 0xffff0000, v98
	v_pk_mul_f32 v[18:19], v[22:23], v[18:19]
	v_lshlrev_b32_e32 v22, 16, v99
	v_and_b32_e32 v23, 0xffff0000, v99
	v_pk_mul_f32 v[22:23], v[24:25], v[22:23]
	v_cvt_pk_bf16_f32 v18, v18, v19
	v_cvt_pk_bf16_f32 v19, v22, v23
	v_lshlrev_b32_e32 v22, 16, v100
	v_and_b32_e32 v23, 0xffff0000, v100
	v_pk_mul_f32 v[20:21], v[20:21], v[22:23]
	v_lshlrev_b32_e32 v22, 16, v101
	v_and_b32_e32 v23, 0xffff0000, v101
	v_pk_mul_f32 v[22:23], v[26:27], v[22:23]
	v_cvt_pk_bf16_f32 v20, v20, v21
	v_cvt_pk_bf16_f32 v21, v22, v23
	global_store_dwordx4 v[30:31], v[18:21], off offset:256
	v_pk_mul_f32 v[6:7], v[6:7], v[134:135]
	v_pk_mul_f32 v[8:9], v[8:9], v[136:137]
	v_pk_mul_f32 v[18:19], v[12:13], v[140:141]
	v_pk_mul_f32 v[12:13], v[10:11], v[138:139]
	s_waitcnt vmcnt(7)
	v_lshlrev_b32_e32 v10, 16, v70
	v_and_b32_e32 v11, 0xffff0000, v70
	v_pk_mul_f32 v[10:11], v[14:15], v[10:11]
	v_lshlrev_b32_e32 v14, 16, v71
	v_and_b32_e32 v15, 0xffff0000, v71
	v_pk_mul_f32 v[14:15], v[16:17], v[14:15]
	v_cvt_pk_bf16_f32 v10, v10, v11
	v_cvt_pk_bf16_f32 v11, v14, v15
	v_lshlrev_b32_e32 v14, 16, v72
	v_and_b32_e32 v15, 0xffff0000, v72
	v_pk_mul_f32 v[12:13], v[12:13], v[14:15]
	v_lshlrev_b32_e32 v14, 16, v73
	v_and_b32_e32 v15, 0xffff0000, v73
	v_pk_mul_f32 v[14:15], v[18:19], v[14:15]
	v_cvt_pk_bf16_f32 v12, v12, v13
	v_cvt_pk_bf16_f32 v13, v14, v15
	v_lshl_add_u64 v[14:15], s[12:13], 0, v[74:75]
	v_lshl_add_u64 v[14:15], v[14:15], 0, v[174:175]
	global_store_dwordx4 v[14:15], v[10:13], off
	s_nop 1
	v_pk_mul_f32 v[10:11], v[4:5], v[132:133]
	v_pk_mul_f32 v[4:5], v[2:3], v[130:131]
	s_waitcnt vmcnt(7)
	v_lshlrev_b32_e32 v2, 16, v66
	v_and_b32_e32 v3, 0xffff0000, v66
	v_pk_mul_f32 v[2:3], v[6:7], v[2:3]
	v_lshlrev_b32_e32 v6, 16, v67
	v_and_b32_e32 v7, 0xffff0000, v67
	v_pk_mul_f32 v[6:7], v[8:9], v[6:7]
	v_cvt_pk_bf16_f32 v2, v2, v3
	v_cvt_pk_bf16_f32 v3, v6, v7
	v_lshlrev_b32_e32 v6, 16, v68
	v_and_b32_e32 v7, 0xffff0000, v68
	v_pk_mul_f32 v[4:5], v[4:5], v[6:7]
	v_lshlrev_b32_e32 v6, 16, v69
	v_and_b32_e32 v7, 0xffff0000, v69
	v_pk_mul_f32 v[6:7], v[10:11], v[6:7]
	v_cvt_pk_bf16_f32 v4, v4, v5
	v_cvt_pk_bf16_f32 v5, v6, v7
	global_store_dwordx4 v[14:15], v[2:5], off offset:256
	s_cbranch_vccz .LBB0_615
	s_waitcnt vmcnt(0)
	s_cmpk_gt_u32 s4, 0xff
	s_cbranch_scc1 .LBB0_622
	s_barrier

; template <class Epi, class Sched, bool ALIGN_EPI = false, bool SP2 = false, bool F8 = false>
; __device__ __forceinline__ void gemm_phase(PG8_LAS unsigned char* lds, const Gemm g, const Sched& S, const Epi& E) {
;     ...
;         for (int a = 0; a < 2; ++a)
; #pragma unroll
;             for (int b = 0; b < 2; ++b)
; #pragma unroll
;                 for (int m = 0; m < 4; ++m)
; #pragma unroll
;                     for (int n = 0; n < 2; ++n) acc[a][b][m][n] = (f32x4){0.f, 0.f, 0.f, 0.f};
.LBB0_629:
	s_ashr_i32 s21, s20, 31
	v_cmp_lt_i64_e32 vcc, s[22:23], v[174:175]
	s_lshl_b64 s[22:23], s[20:21], 19
	s_add_u32 s22, s5, s22
	s_addc_u32 s23, s6, s23
	s_and_b64 s[24:25], vcc, exec
	s_cselect_b32 s21, s23, s31
	s_cselect_b32 s47, s22, s30
	s_ashr_i32 s17, s16, 31
	s_lshl_b64 s[24:25], s[16:17], 19
	s_add_u32 s24, s7, s24
	s_addc_u32 s25, s18, s25
	s_and_b64 s[34:35], vcc, exec
	s_cselect_b32 s17, s25, s29
	s_cselect_b32 s48, s24, s28
	s_add_u32 s49, s28, 0x100
	s_addc_u32 s50, s29, 0
	s_add_u32 s28, s30, 0x40080
	v_mov_b32_e32 v34, 0
	s_addc_u32 s29, s31, 0
	s_mov_b32 s51, -2
	v_mov_b32_e32 v35, v34
	v_mov_b32_e32 v36, v34
	v_mov_b32_e32 v37, v34
	v_mov_b32_e32 v38, v34
	v_mov_b32_e32 v39, v34
	v_mov_b32_e32 v40, v34
	v_mov_b32_e32 v41, v34
	v_mov_b32_e32 v46, v34
	v_mov_b32_e32 v47, v34
	v_mov_b32_e32 v48, v34
	v_mov_b32_e32 v49, v34
	v_mov_b32_e32 v54, v34
	v_mov_b32_e32 v55, v34
	v_mov_b32_e32 v56, v34
	v_mov_b32_e32 v57, v34
	v_mov_b32_e32 v62, v34
	v_mov_b32_e32 v63, v34
	v_mov_b32_e32 v64, v34
	v_mov_b32_e32 v65, v34
	v_mov_b32_e32 v70, v34
	v_mov_b32_e32 v71, v34
	v_mov_b32_e32 v72, v34
	v_mov_b32_e32 v73, v34
	v_mov_b32_e32 v78, v34
	v_mov_b32_e32 v79, v34
	v_mov_b32_e32 v80, v34
	v_mov_b32_e32 v81, v34
	v_mov_b32_e32 v86, v34
	v_mov_b32_e32 v87, v34
	v_mov_b32_e32 v88, v34
	v_mov_b32_e32 v89, v34
	v_mov_b32_e32 v42, v34
	v_mov_b32_e32 v43, v34
	v_mov_b32_e32 v44, v34
	v_mov_b32_e32 v45, v34
	v_mov_b32_e32 v50, v34
	v_mov_b32_e32 v51, v34
	v_mov_b32_e32 v52, v34
	v_mov_b32_e32 v53, v34
	v_mov_b32_e32 v58, v34
	v_mov_b32_e32 v59, v34
	v_mov_b32_e32 v60, v34
	v_mov_b32_e32 v61, v34
	v_mov_b32_e32 v66, v34
	v_mov_b32_e32 v67, v34
	v_mov_b32_e32 v68, v34
	v_mov_b32_e32 v69, v34
	v_mov_b32_e32 v74, v34
	v_mov_b32_e32 v75, v34
	v_mov_b32_e32 v76, v34
	v_mov_b32_e32 v77, v34
	v_mov_b32_e32 v82, v34
	v_mov_b32_e32 v83, v34
	v_mov_b32_e32 v84, v34
	v_mov_b32_e32 v85, v34
	v_mov_b32_e32 v90, v34
	v_mov_b32_e32 v91, v34
	v_mov_b32_e32 v92, v34
	v_mov_b32_e32 v93, v34
	v_mov_b32_e32 v94, v34
	v_mov_b32_e32 v95, v34
	v_mov_b32_e32 v96, v34
	v_mov_b32_e32 v97, v34
	v_mov_b32_e32 v98, v34
	v_mov_b32_e32 v99, v34
	v_mov_b32_e32 v100, v34
	v_mov_b32_e32 v101, v34
	v_mov_b32_e32 v102, v34
	v_mov_b32_e32 v103, v34
	v_mov_b32_e32 v104, v34
	v_mov_b32_e32 v105, v34
	v_mov_b32_e32 v110, v34
	v_mov_b32_e32 v111, v34
	v_mov_b32_e32 v112, v34
	v_mov_b32_e32 v113, v34
	v_mov_b32_e32 v118, v34
	v_mov_b32_e32 v119, v34
	v_mov_b32_e32 v120, v34
	v_mov_b32_e32 v121, v34
	v_mov_b32_e32 v126, v34
	v_mov_b32_e32 v127, v34
	v_mov_b32_e32 v128, v34
	v_mov_b32_e32 v129, v34
	v_mov_b32_e32 v134, v34
	v_mov_b32_e32 v135, v34
	v_mov_b32_e32 v136, v34
	v_mov_b32_e32 v137, v34
	v_mov_b32_e32 v142, v34
	v_mov_b32_e32 v143, v34
	v_mov_b32_e32 v144, v34
	v_mov_b32_e32 v145, v34
	v_mov_b32_e32 v150, v34
	v_mov_b32_e32 v151, v34
	v_mov_b32_e32 v152, v34
	v_mov_b32_e32 v153, v34
	v_mov_b32_e32 v106, v34
	v_mov_b32_e32 v107, v34
	v_mov_b32_e32 v108, v34
	v_mov_b32_e32 v109, v34
	v_mov_b32_e32 v114, v34
	v_mov_b32_e32 v115, v34
	v_mov_b32_e32 v116, v34
	v_mov_b32_e32 v117, v34
	v_mov_b32_e32 v122, v34
	v_mov_b32_e32 v123, v34
	v_mov_b32_e32 v124, v34
	v_mov_b32_e32 v125, v34
	v_mov_b32_e32 v130, v34
	v_mov_b32_e32 v131, v34
	v_mov_b32_e32 v132, v34
	v_mov_b32_e32 v133, v34
	v_mov_b32_e32 v138, v34
	v_mov_b32_e32 v139, v34
	v_mov_b32_e32 v140, v34
	v_mov_b32_e32 v141, v34
	v_mov_b32_e32 v146, v34
	v_mov_b32_e32 v147, v34
	v_mov_b32_e32 v148, v34
	v_mov_b32_e32 v149, v34
	v_mov_b32_e32 v154, v34
	v_mov_b32_e32 v155, v34
	v_mov_b32_e32 v156, v34
	v_mov_b32_e32 v157, v34
	v_mov_b32_e32 v158, v34
	v_mov_b32_e32 v159, v34
	v_mov_b32_e32 v160, v34
	v_mov_b32_e32 v161, v34
	s_branch .LBB0_630

; #define PG8_STAGE(bufoff, gbase, voff) do { _Pragma("unroll") for (int _i = 0; _i < 2; ++_i) \
;         __builtin_amdgcn_global_load_lds((const unsigned*)((const char*)(gbase) + (voff)[_i]), (PG8_LAS unsigned*)(lds + (bufoff) + ldsw + _i * 8192), 16, 0, 0); } while (0)
; #define PG8_LDA(dst, b, h) do { _Pragma("unroll") for (int m = 0; m < 4; ++m) _Pragma("unroll") for (int k = 0; k < 2; ++k) dst[m][k] = *(const PG8_LAS bf16x8*)(lds + PG8_SA(b, h) + aoff + m * 2048 + k * 1024); } while (0)
; #define PG8_LDB(dst, b, h) do { _Pragma("unroll") for (int n = 0; n < 2; ++n) _Pragma("unroll") for (int k = 0; k < 2; ++k) dst[n][k] = *(const PG8_LAS bf16x8*)(lds + PG8_SB(b, h) + boff + n * 2048 + k * 1024); } while (0)
; #define PG8_WAIT_V(n) asm volatile("s_waitcnt vmcnt(" #n ")" ::: "memory")
; #define PG8_WAIT_L(n) asm volatile("s_waitcnt lgkmcnt(" #n ")" ::: "memory")
; #define PG8_BAR __builtin_amdgcn_s_barrier()
; #define PG8_SCHED __builtin_amdgcn_sched_barrier(0)
; template <class Epi, class Sched, bool ALIGN_EPI = false, bool SP2 = false, bool F8 = false>
; __device__ __forceinline__ void gemm_phase(PG8_LAS unsigned char* lds, const Gemm g, const Sched& S, const Epi& E) {
;     ...
;             PG8_LDB(B0, 0, 0); PG8_LDB(B1, 0, 1); PG8_SCHED; PG8_LDA(At, 0, 0); PG8_STAGE(PG8_SA(1, 1), a1 + hA, voffA);
;             PG8_WAIT_V(8); PG8_WAIT_L(0); PG8_BAR; PG8_MMA(0, 0, At, B0); PG8_MMA(0, 1, At, B1); PG8_BAR; PG8_SCHED;
;             PG8_LDA(At, 0, 1); PG8_STAGE(PG8_SB(0, 0), b2, voffB); PG8_STAGE(PG8_SB(0, 1), b2 + hB, voffB); PG8_STAGE(PG8_SA(0, 0), a2, voffA);
;             PG8_WAIT_V(8); PG8_WAIT_L(0); PG8_BAR; PG8_MMA(1, 0, At, B0); PG8_MMA(1, 1, At, B1); PG8_BAR; PG8_SCHED;
.LBB0_630:
	ds_read_b128 v[26:29], v190
	ds_read_b128 v[30:33], v190 offset:1024
	ds_read_b128 v[18:21], v190 offset:2048
	ds_read_b128 v[22:25], v190 offset:3072
	ds_read_b128 v[10:13], v191
	ds_read_b128 v[14:17], v191 offset:1024
	ds_read_b128 v[2:5], v191 offset:2048
	ds_read_b128 v[6:9], v191 offset:3072
	s_add_u32 s30, s28, 0xfffc0080
	s_addc_u32 s31, s29, -1
	s_cmp_eq_u32 s51, 12
	s_cselect_b32 s35, s21, s31
	s_cselect_b32 s34, s47, s30
	s_cselect_b32 s31, s17, s50
	s_cselect_b32 s30, s48, s49
	v_lshl_add_u64 v[218:219], s[28:29], 0, v[172:173]
	s_add_i32 m0, s27, 0xc000
	ds_read_b128 v[178:181], v192
	ds_read_b128 v[182:185], v192 offset:1024
	ds_read_b128 v[194:197], v192 offset:2048
	ds_read_b128 v[198:201], v192 offset:3072
	ds_read_b128 v[202:205], v192 offset:4096
	ds_read_b128 v[206:209], v192 offset:5120
	ds_read_b128 v[210:213], v192 offset:6144
	ds_read_b128 v[214:217], v192 offset:7168
	global_load_lds_dwordx4 v[218:219], off
	v_lshl_add_u64 v[218:219], s[28:29], 0, v[170:171]
	s_add_i32 m0, s27, 0xe000
	s_nop 0
	global_load_lds_dwordx4 v[218:219], off
	s_waitcnt vmcnt(8)
	s_waitcnt lgkmcnt(0)
	s_setprio 1
	s_barrier
	v_mfma_scale_f32_16x16x128_f8f6f4 v[158:161], v[26:33], v[178:185], v[158:161], v186, v186 op_sel_hi:[0,0,0]
	v_mfma_scale_f32_16x16x128_f8f6f4 v[154:157], v[18:25], v[178:185], v[154:157], v186, v186 op_sel_hi:[0,0,0]
	v_mfma_scale_f32_16x16x128_f8f6f4 v[146:149], v[26:33], v[194:201], v[146:149], v186, v186 op_sel_hi:[0,0,0]
	v_mfma_scale_f32_16x16x128_f8f6f4 v[138:141], v[18:25], v[194:201], v[138:141], v186, v186 op_sel_hi:[0,0,0]
	v_mfma_scale_f32_16x16x128_f8f6f4 v[130:133], v[26:33], v[202:209], v[130:133], v186, v186 op_sel_hi:[0,0,0]
	v_mfma_scale_f32_16x16x128_f8f6f4 v[122:125], v[18:25], v[202:209], v[122:125], v186, v186 op_sel_hi:[0,0,0]
	v_mfma_scale_f32_16x16x128_f8f6f4 v[114:117], v[26:33], v[210:217], v[114:117], v186, v186 op_sel_hi:[0,0,0]
	v_mfma_scale_f32_16x16x128_f8f6f4 v[106:109], v[18:25], v[210:217], v[106:109], v186, v186 op_sel_hi:[0,0,0]
	v_mfma_scale_f32_16x16x128_f8f6f4 v[150:153], v[10:17], v[178:185], v[150:153], v186, v186 op_sel_hi:[0,0,0]
	v_mfma_scale_f32_16x16x128_f8f6f4 v[142:145], v[2:9], v[178:185], v[142:145], v186, v186 op_sel_hi:[0,0,0]
	v_mfma_scale_f32_16x16x128_f8f6f4 v[134:137], v[10:17], v[194:201], v[134:137], v186, v186 op_sel_hi:[0,0,0]
	v_mfma_scale_f32_16x16x128_f8f6f4 v[126:129], v[2:9], v[194:201], v[126:129], v186, v186 op_sel_hi:[0,0,0]
	v_mfma_scale_f32_16x16x128_f8f6f4 v[118:121], v[10:17], v[202:209], v[118:121], v186, v186 op_sel_hi:[0,0,0]
	v_mfma_scale_f32_16x16x128_f8f6f4 v[110:113], v[2:9], v[202:209], v[110:113], v186, v186 op_sel_hi:[0,0,0]
	v_mfma_scale_f32_16x16x128_f8f6f4 v[102:105], v[10:17], v[210:217], v[102:105], v186, v186 op_sel_hi:[0,0,0]
	v_mfma_scale_f32_16x16x128_f8f6f4 v[98:101], v[2:9], v[210:217], v[98:101], v186, v186 op_sel_hi:[0,0,0]
	s_barrier
	s_setprio 0
	s_add_i32 s52, s44, s19
	v_lshl_add_u64 v[178:179], s[30:31], 0, v[166:167]
	s_mov_b32 m0, s52
	ds_read_b128 v[194:197], v192 offset:16384
	ds_read_b128 v[198:201], v192 offset:17408
	ds_read_b128 v[202:205], v192 offset:18432
	ds_read_b128 v[206:209], v192 offset:19456
	ds_read_b128 v[210:213], v192 offset:20480
	ds_read_b128 v[214:217], v192 offset:21504
	ds_read_b128 v[218:221], v192 offset:22528
	ds_read_b128 v[222:225], v192 offset:23552
	global_load_lds_dwordx4 v[178:179], off
	s_add_i32 m0, s52, 0x2000
	s_add_u32 s52, s30, 0x40000
	v_lshl_add_u64 v[180:181], s[30:31], 0, v[162:163]
	s_addc_u32 s53, s31, 0
	s_add_i32 s54, s45, s19
	global_load_lds_dwordx4 v[180:181], off
	v_lshl_add_u64 v[182:183], s[52:53], 0, v[166:167]
	s_mov_b32 m0, s54
	v_lshl_add_u64 v[184:185], s[34:35], 0, v[164:165]
	global_load_lds_dwordx4 v[182:183], off
	v_lshl_add_u64 v[182:183], s[52:53], 0, v[162:163]
	s_add_i32 m0, s54, 0x2000
	s_nop 0
	global_load_lds_dwordx4 v[182:183], off
	v_lshl_add_u64 v[182:183], s[34:35], 0, v[168:169]
	s_mov_b32 m0, s27
	s_nop 0
	global_load_lds_dwordx4 v[182:183], off
	s_mov_b32 m0, s37
	s_nop 0
	global_load_lds_dwordx4 v[184:185], off
	s_waitcnt vmcnt(8)
	s_waitcnt lgkmcnt(0)
	s_setprio 1
	s_barrier
	v_mfma_scale_f32_16x16x128_f8f6f4 v[94:97], v[26:33], v[194:201], v[94:97], v186, v186 op_sel_hi:[0,0,0]
	v_mfma_scale_f32_16x16x128_f8f6f4 v[90:93], v[18:25], v[194:201], v[90:93], v186, v186 op_sel_hi:[0,0,0]
	v_mfma_scale_f32_16x16x128_f8f6f4 v[82:85], v[26:33], v[202:209], v[82:85], v186, v186 op_sel_hi:[0,0,0]
	v_mfma_scale_f32_16x16x128_f8f6f4 v[74:77], v[18:25], v[202:209], v[74:77], v186, v186 op_sel_hi:[0,0,0]
	v_mfma_scale_f32_16x16x128_f8f6f4 v[66:69], v[26:33], v[210:217], v[66:69], v186, v186 op_sel_hi:[0,0,0]
	v_mfma_scale_f32_16x16x128_f8f6f4 v[58:61], v[18:25], v[210:217], v[58:61], v186, v186 op_sel_hi:[0,0,0]
	v_mfma_scale_f32_16x16x128_f8f6f4 v[50:53], v[26:33], v[218:225], v[50:53], v186, v186 op_sel_hi:[0,0,0]
	v_mfma_scale_f32_16x16x128_f8f6f4 v[42:45], v[18:25], v[218:225], v[42:45], v186, v186 op_sel_hi:[0,0,0]
	v_mfma_scale_f32_16x16x128_f8f6f4 v[86:89], v[10:17], v[194:201], v[86:89], v186, v186 op_sel_hi:[0,0,0]
	v_mfma_scale_f32_16x16x128_f8f6f4 v[78:81], v[2:9], v[194:201], v[78:81], v186, v186 op_sel_hi:[0,0,0]
	v_mfma_scale_f32_16x16x128_f8f6f4 v[70:73], v[10:17], v[202:209], v[70:73], v186, v186 op_sel_hi:[0,0,0]
	v_mfma_scale_f32_16x16x128_f8f6f4 v[62:65], v[2:9], v[202:209], v[62:65], v186, v186 op_sel_hi:[0,0,0]
	v_mfma_scale_f32_16x16x128_f8f6f4 v[54:57], v[10:17], v[210:217], v[54:57], v186, v186 op_sel_hi:[0,0,0]
	v_mfma_scale_f32_16x16x128_f8f6f4 v[46:49], v[2:9], v[210:217], v[46:49], v186, v186 op_sel_hi:[0,0,0]
	v_mfma_scale_f32_16x16x128_f8f6f4 v[38:41], v[10:17], v[218:225], v[38:41], v186, v186 op_sel_hi:[0,0,0]
	v_mfma_scale_f32_16x16x128_f8f6f4 v[34:37], v[2:9], v[218:225], v[34:37], v186, v186 op_sel_hi:[0,0,0]
	s_barrier
; #define PG8_STAGE(bufoff, gbase, voff) do { _Pragma("unroll") for (int _i = 0; _i < 2; ++_i) \
;         __builtin_amdgcn_global_load_lds((const unsigned*)((const char*)(gbase) + (voff)[_i]), (PG8_LAS unsigned*)(lds + (bufoff) + ldsw + _i * 8192), 16, 0, 0); } while (0)
; #define PG8_LDA(dst, b, h) do { _Pragma("unroll") for (int m = 0; m < 4; ++m) _Pragma("unroll") for (int k = 0; k < 2; ++k) dst[m][k] = *(const PG8_LAS bf16x8*)(lds + PG8_SA(b, h) + aoff + m * 2048 + k * 1024); } while (0)
; #define PG8_LDB(dst, b, h) do { _Pragma("unroll") for (int n = 0; n < 2; ++n) _Pragma("unroll") for (int k = 0; k < 2; ++k) dst[n][k] = *(const PG8_LAS bf16x8*)(lds + PG8_SB(b, h) + boff + n * 2048 + k * 1024); } while (0)
; #define PG8_WAIT_V(n) asm volatile("s_waitcnt vmcnt(" #n ")" ::: "memory")
; #define PG8_WAIT_L(n) asm volatile("s_waitcnt lgkmcnt(" #n ")" ::: "memory")
; #define PG8_BAR __builtin_amdgcn_s_barrier()
; #define PG8_SCHED __builtin_amdgcn_sched_barrier(0)
; template <class Epi, class Sched, bool ALIGN_EPI = false, bool SP2 = false, bool F8 = false>
; __device__ __forceinline__ void gemm_phase(PG8_LAS unsigned char* lds, const Gemm g, const Sched& S, const Epi& E) {
;     ...
;             PG8_LDB(B0, 1, 0); PG8_LDB(B1, 1, 1); PG8_SCHED; PG8_LDA(At, 1, 0); PG8_STAGE(PG8_SA(0, 1), a2 + hA, voffA);
;             PG8_WAIT_V(8); PG8_WAIT_L(0); PG8_BAR; PG8_MMA(0, 0, At, B0); PG8_MMA(0, 1, At, B1); PG8_BAR; PG8_SCHED;
;             PG8_LDA(At, 1, 1); PG8_STAGE(PG8_SB(1, 0), b3, voffB); PG8_STAGE(PG8_SB(1, 1), b3 + hB, voffB); PG8_STAGE(PG8_SA(1, 0), a3, voffA);
;             PG8_WAIT_V(8); PG8_WAIT_L(0); PG8_BAR; PG8_MMA(1, 0, At, B0); PG8_MMA(1, 1, At, B1); PG8_BAR; PG8_SCHED;
	s_setprio 0
	s_add_i32 s52, 0, 0x18000
	s_add_i32 s53, 0, 0x1c000
	v_add_u32_e32 v14, s52, v188
	v_add_u32_e32 v30, s53, v188
	ds_read_b128 v[2:5], v14
	ds_read_b128 v[6:9], v14 offset:1024
	ds_read_b128 v[10:13], v14 offset:2048
	ds_read_b128 v[14:17], v14 offset:3072
	ds_read_b128 v[18:21], v30
	ds_read_b128 v[22:25], v30 offset:1024
	ds_read_b128 v[26:29], v30 offset:2048
	ds_read_b128 v[30:33], v30 offset:3072
	s_add_u32 s34, s34, 0x40000
	s_addc_u32 s35, s35, 0
	s_mov_b32 m0, s38
	v_lshl_add_u64 v[226:227], s[34:35], 0, v[168:169]
	ds_read_b128 v[194:197], v192 offset:32768
	ds_read_b128 v[198:201], v192 offset:33792
	ds_read_b128 v[202:205], v192 offset:34816
	ds_read_b128 v[206:209], v192 offset:35840
	ds_read_b128 v[210:213], v192 offset:36864
	ds_read_b128 v[214:217], v192 offset:37888
	ds_read_b128 v[218:221], v192 offset:38912
	ds_read_b128 v[222:225], v192 offset:39936
	global_load_lds_dwordx4 v[226:227], off
	v_lshl_add_u64 v[226:227], s[34:35], 0, v[164:165]
	s_mov_b32 m0, s39
	s_nop 0
	global_load_lds_dwordx4 v[226:227], off
	s_waitcnt vmcnt(8)
	s_waitcnt lgkmcnt(0)
	s_setprio 1
	s_barrier
	v_mfma_scale_f32_16x16x128_f8f6f4 v[158:161], v[2:9], v[194:201], v[158:161], v186, v186 op_sel_hi:[0,0,0]
	v_mfma_scale_f32_16x16x128_f8f6f4 v[154:157], v[10:17], v[194:201], v[154:157], v186, v186 op_sel_hi:[0,0,0]
	v_mfma_scale_f32_16x16x128_f8f6f4 v[146:149], v[2:9], v[202:209], v[146:149], v186, v186 op_sel_hi:[0,0,0]
	v_mfma_scale_f32_16x16x128_f8f6f4 v[138:141], v[10:17], v[202:209], v[138:141], v186, v186 op_sel_hi:[0,0,0]
	v_mfma_scale_f32_16x16x128_f8f6f4 v[130:133], v[2:9], v[210:217], v[130:133], v186, v186 op_sel_hi:[0,0,0]
	v_mfma_scale_f32_16x16x128_f8f6f4 v[122:125], v[10:17], v[210:217], v[122:125], v186, v186 op_sel_hi:[0,0,0]
	v_mfma_scale_f32_16x16x128_f8f6f4 v[114:117], v[2:9], v[218:225], v[114:117], v186, v186 op_sel_hi:[0,0,0]
	v_mfma_scale_f32_16x16x128_f8f6f4 v[106:109], v[10:17], v[218:225], v[106:109], v186, v186 op_sel_hi:[0,0,0]
	v_mfma_scale_f32_16x16x128_f8f6f4 v[150:153], v[18:25], v[194:201], v[150:153], v186, v186 op_sel_hi:[0,0,0]
	v_mfma_scale_f32_16x16x128_f8f6f4 v[142:145], v[26:33], v[194:201], v[142:145], v186, v186 op_sel_hi:[0,0,0]
	v_mfma_scale_f32_16x16x128_f8f6f4 v[134:137], v[18:25], v[202:209], v[134:137], v186, v186 op_sel_hi:[0,0,0]
	v_mfma_scale_f32_16x16x128_f8f6f4 v[126:129], v[26:33], v[202:209], v[126:129], v186, v186 op_sel_hi:[0,0,0]
	v_mfma_scale_f32_16x16x128_f8f6f4 v[118:121], v[18:25], v[210:217], v[118:121], v186, v186 op_sel_hi:[0,0,0]
	v_mfma_scale_f32_16x16x128_f8f6f4 v[110:113], v[26:33], v[210:217], v[110:113], v186, v186 op_sel_hi:[0,0,0]
	v_mfma_scale_f32_16x16x128_f8f6f4 v[102:105], v[18:25], v[218:225], v[102:105], v186, v186 op_sel_hi:[0,0,0]
	v_mfma_scale_f32_16x16x128_f8f6f4 v[98:101], v[26:33], v[218:225], v[98:101], v186, v186 op_sel_hi:[0,0,0]
	s_barrier
	s_setprio 0
	s_add_i32 s34, s52, s19
	v_lshl_add_u64 v[178:179], v[178:179], 0, s[14:15]
	s_mov_b32 m0, s34
	ds_read_b128 v[194:197], v192 offset:49152
	ds_read_b128 v[198:201], v192 offset:50176
	ds_read_b128 v[202:205], v192 offset:51200
	ds_read_b128 v[206:209], v192 offset:52224
	ds_read_b128 v[210:213], v192 offset:53248
	ds_read_b128 v[214:217], v192 offset:54272
	ds_read_b128 v[218:221], v192 offset:55296
	ds_read_b128 v[222:225], v192 offset:56320
	global_load_lds_dwordx4 v[178:179], off
	s_add_i32 m0, s34, 0x2000
	s_add_u32 s30, s30, 0x40080
	v_lshl_add_u64 v[178:179], v[180:181], 0, s[14:15]
	s_addc_u32 s31, s31, 0
	s_add_i32 s34, s53, s19
	global_load_lds_dwordx4 v[178:179], off
	v_lshl_add_u64 v[178:179], s[30:31], 0, v[166:167]
	s_mov_b32 m0, s34
	s_nop 0
	global_load_lds_dwordx4 v[178:179], off
	v_lshl_add_u64 v[178:179], s[30:31], 0, v[162:163]
	s_add_i32 m0, s34, 0x2000
	s_nop 0
	global_load_lds_dwordx4 v[178:179], off
	v_lshl_add_u64 v[178:179], v[182:183], 0, s[14:15]
	s_mov_b32 m0, s41
	s_nop 0
	global_load_lds_dwordx4 v[178:179], off
	v_lshl_add_u64 v[178:179], v[184:185], 0, s[14:15]
	s_mov_b32 m0, s42
	s_nop 0
	global_load_lds_dwordx4 v[178:179], off
	s_waitcnt vmcnt(8)
	s_waitcnt lgkmcnt(0)
	s_setprio 1
	s_barrier
	v_mfma_scale_f32_16x16x128_f8f6f4 v[94:97], v[2:9], v[194:201], v[94:97], v186, v186 op_sel_hi:[0,0,0]
	v_mfma_scale_f32_16x16x128_f8f6f4 v[90:93], v[10:17], v[194:201], v[90:93], v186, v186 op_sel_hi:[0,0,0]
	v_mfma_scale_f32_16x16x128_f8f6f4 v[82:85], v[2:9], v[202:209], v[82:85], v186, v186 op_sel_hi:[0,0,0]
	v_mfma_scale_f32_16x16x128_f8f6f4 v[74:77], v[10:17], v[202:209], v[74:77], v186, v186 op_sel_hi:[0,0,0]
	v_mfma_scale_f32_16x16x128_f8f6f4 v[66:69], v[2:9], v[210:217], v[66:69], v186, v186 op_sel_hi:[0,0,0]
	v_mfma_scale_f32_16x16x128_f8f6f4 v[58:61], v[10:17], v[210:217], v[58:61], v186, v186 op_sel_hi:[0,0,0]
	v_mfma_scale_f32_16x16x128_f8f6f4 v[50:53], v[2:9], v[218:225], v[50:53], v186, v186 op_sel_hi:[0,0,0]
	v_mfma_scale_f32_16x16x128_f8f6f4 v[42:45], v[10:17], v[218:225], v[42:45], v186, v186 op_sel_hi:[0,0,0]
	v_mfma_scale_f32_16x16x128_f8f6f4 v[86:89], v[18:25], v[194:201], v[86:89], v186, v186 op_sel_hi:[0,0,0]
	v_mfma_scale_f32_16x16x128_f8f6f4 v[78:81], v[26:33], v[194:201], v[78:81], v186, v186 op_sel_hi:[0,0,0]
	v_mfma_scale_f32_16x16x128_f8f6f4 v[70:73], v[18:25], v[202:209], v[70:73], v186, v186 op_sel_hi:[0,0,0]
	v_mfma_scale_f32_16x16x128_f8f6f4 v[62:65], v[26:33], v[202:209], v[62:65], v186, v186 op_sel_hi:[0,0,0]
	v_mfma_scale_f32_16x16x128_f8f6f4 v[54:57], v[18:25], v[210:217], v[54:57], v186, v186 op_sel_hi:[0,0,0]
	v_mfma_scale_f32_16x16x128_f8f6f4 v[46:49], v[26:33], v[210:217], v[46:49], v186, v186 op_sel_hi:[0,0,0]
	v_mfma_scale_f32_16x16x128_f8f6f4 v[38:41], v[18:25], v[218:225], v[38:41], v186, v186 op_sel_hi:[0,0,0]
	v_mfma_scale_f32_16x16x128_f8f6f4 v[34:37], v[26:33], v[218:225], v[34:37], v186, v186 op_sel_hi:[0,0,0]
	s_add_i32 s51, s51, 2
	s_add_u32 s49, s49, 0x100
	s_addc_u32 s50, s50, 0
	s_add_u32 s28, s28, 0x100
	s_addc_u32 s29, s29, 0
	s_cmp_gt_u32 s51, 13
	s_cbranch_scc0 .Lber_630
; #define PG8_GAS __attribute__((address_space(1)))
; __device__ __forceinline__ unsigned cvt_pk_bf16(float lo, float hi) { const f32x2c v = {lo, hi}; return __builtin_bit_cast(unsigned, __builtin_convertvector(v, bf16x2c)); }
; __device__ __forceinline__ float bf_lo(unsigned w) { return __uint_as_float(w << 16); }
; __device__ __forceinline__ float bf_hi(unsigned w) { return __uint_as_float(w & 0xffff0000u); }
; #define PG8_BAR __builtin_amdgcn_s_barrier()
;     __device__ __forceinline__ void operator()(const f32x4 (&acc)[2][2][4][2], const Unit& un, int wr, int wc, int fr, int fq) const {
;         const int row0 = un.pm * BM + wr * 64 + fr, col0 = un.pn * BM + wc * 32 + 8 * fq;
; #pragma unroll
;         for (int ai = 0; ai < 2; ++ai) {
;             u32x4 gg[4][2], pp[4][2];
; #pragma unroll
;             for (int m = 0; m < 4; ++m)
; #pragma unroll
;                 for (int bj = 0; bj < 2; ++bj) { const size_t off = (size_t)(row0 + ai * HALF + m * 16) * 4096 + col0 + bj * HALF; gg[m][bj] = *(const PG8_GAS u32x4*)(sa + off); pp[m][bj] = *(const PG8_GAS u32x4*)(P + off); }
;             asm volatile("" ::: "memory");
; #pragma unroll
;             for (int m = 0; m < 4; ++m)
; #pragma unroll
;                 for (int bj = 0; bj < 2; ++bj) { const u32x4 g = gg[m][bj], p = pp[m][bj]; const f32x4 v0 = acc[ai][bj][m][0], v1 = acc[ai][bj][m][1];
;                     u32x4 w; w.x = cvt_pk_bf16(v0[0] * bf_lo(g.x) + bf_lo(p.x), v0[1] * bf_hi(g.x) + bf_hi(p.x)); w.y = cvt_pk_bf16(v0[2] * bf_lo(g.y) + bf_lo(p.y), v0[3] * bf_hi(g.y) + bf_hi(p.y));
;                     w.z = cvt_pk_bf16(v1[0] * bf_lo(g.z) + bf_lo(p.z), v1[1] * bf_hi(g.z) + bf_hi(p.z)); w.w = cvt_pk_bf16(v1[2] * bf_lo(g.w) + bf_lo(p.w), v1[3] * bf_hi(g.w) + bf_hi(p.w));
;                     *(PG8_GAS u32x4*)(sa + (size_t)(row0 + ai * HALF + m * 16) * 4096 + col0 + bj * HALF) = w; }
; template <class Epi, class Sched, bool ALIGN_EPI = false, bool SP2 = false, bool F8 = false>
; __device__ __forceinline__ void gemm_phase(PG8_LAS unsigned char* lds, const Gemm g, const Sched& S, const Epi& E) {
;     ...
;         if constexpr (ALIGN_EPI) { if (wr == 0) PG8_BAR; }
;         if constexpr (F8) asm volatile("s_nop 15\n\ts_nop 15\n\ts_nop 7" ::: "memory");
	s_barrier
	s_setprio 0
	v_lshl_add_u32 v182, s26, 8, v187
	v_lshl_or_b32 v180, s46, 8, v189
	v_ashrrev_i32_e32 v183, 31, v182
	v_ashrrev_i32_e32 v181, 31, v180
	v_lshlrev_b64 v[2:3], 12, v[182:183]
	v_lshl_add_u64 v[2:3], v[2:3], 0, v[180:181]
	v_lshlrev_b64 v[2:3], 1, v[2:3]
	s_nop 15
	s_nop 15
	s_nop 7
	v_lshl_add_u64 v[4:5], s[10:11], 0, v[2:3]
	global_load_dwordx4 v[30:33], v[4:5], off
	v_lshl_add_u64 v[4:5], s[12:13], 0, v[2:3]
	global_load_dwordx4 v[194:197], v[4:5], off
	v_or_b32_e32 v2, 0x100, v2
	v_lshl_add_u64 v[4:5], s[10:11], 0, v[2:3]
	v_lshl_add_u64 v[2:3], s[12:13], 0, v[2:3]
	global_load_dwordx4 v[198:201], v[4:5], off
	global_load_dwordx4 v[202:205], v[2:3], off
	v_or_b32_e32 v184, 16, v182
	v_ashrrev_i32_e32 v185, 31, v184
	v_lshlrev_b64 v[2:3], 13, v[182:183]
	v_lshlrev_b64 v[4:5], 12, v[184:185]
	v_lshlrev_b64 v[178:179], 1, v[180:181]
	v_lshl_add_u64 v[2:3], s[10:11], 0, v[2:3]
	v_lshl_add_u64 v[4:5], v[4:5], 0, v[180:181]
	v_lshl_add_u64 v[230:231], v[2:3], 0, v[178:179]
	v_lshlrev_b64 v[2:3], 1, v[4:5]
	v_lshl_add_u64 v[4:5], s[10:11], 0, v[2:3]
	global_load_dwordx4 v[206:209], v[4:5], off
	v_lshl_add_u64 v[4:5], s[12:13], 0, v[2:3]
	global_load_dwordx4 v[210:213], v[4:5], off
	v_or_b32_e32 v28, 32, v182
	v_or_b32_e32 v26, 48, v182
	v_ashrrev_i32_e32 v29, 31, v28
	v_ashrrev_i32_e32 v27, 31, v26
	v_lshlrev_b64 v[6:7], 12, v[28:29]
	v_lshlrev_b64 v[8:9], 12, v[26:27]
	v_lshl_add_u64 v[6:7], v[6:7], 0, v[180:181]
	v_lshl_add_u64 v[8:9], v[8:9], 0, v[180:181]
	v_lshlrev_b64 v[4:5], 1, v[6:7]
	v_lshlrev_b64 v[6:7], 1, v[8:9]
	v_or_b32_e32 v2, 0x100, v2
	v_lshl_add_u64 v[8:9], s[10:11], 0, v[4:5]
	v_lshl_add_u64 v[10:11], s[12:13], 0, v[4:5]
	v_or_b32_e32 v4, 0x100, v4
	v_lshl_add_u64 v[12:13], s[10:11], 0, v[6:7]
	v_lshl_add_u64 v[18:19], s[12:13], 0, v[6:7]
	v_or_b32_e32 v6, 0x100, v6
	v_lshl_add_u64 v[20:21], s[10:11], 0, v[2:3]
	v_lshl_add_u64 v[2:3], s[12:13], 0, v[2:3]
	global_load_dwordx4 v[214:217], v[8:9], off
	global_load_dwordx4 v[218:221], v[10:11], off
	v_lshl_add_u64 v[8:9], s[10:11], 0, v[4:5]
	v_lshl_add_u64 v[4:5], s[12:13], 0, v[4:5]
	global_load_dwordx4 v[14:17], v[12:13], off
	s_nop 0
	global_load_dwordx4 v[10:13], v[18:19], off
	v_lshl_add_u64 v[232:233], s[10:11], 0, v[6:7]
	v_lshl_add_u64 v[234:235], s[12:13], 0, v[6:7]
	global_load_dwordx4 v[222:225], v[20:21], off
	global_load_dwordx4 v[226:229], v[2:3], off
	global_load_dwordx4 v[22:25], v[8:9], off
	s_nop 0
	global_load_dwordx4 v[18:21], v[4:5], off
	global_load_dwordx4 v[6:9], v[232:233], off
	s_nop 0
	global_load_dwordx4 v[2:5], v[234:235], off
	s_and_b64 vcc, exec, s[8:9]
	s_mov_b32 s46, s16
	s_mov_b32 s26, s20
	s_mov_b64 s[28:29], s[24:25]
	s_mov_b64 s[30:31], s[22:23]
	s_waitcnt vmcnt(0)
	v_lshlrev_b32_e32 v232, 16, v30
	v_and_b32_e32 v233, 0xffff0000, v30
	v_lshlrev_b32_e32 v234, 16, v194
	v_and_b32_e32 v235, 0xffff0000, v194
	v_lshlrev_b32_e32 v30, 16, v31
	v_and_b32_e32 v31, 0xffff0000, v31
	v_lshlrev_b32_e32 v194, 16, v195
	v_and_b32_e32 v195, 0xffff0000, v195
	v_lshlrev_b32_e32 v236, 16, v32
	v_and_b32_e32 v237, 0xffff0000, v32
	v_lshlrev_b32_e32 v238, 16, v196
	v_and_b32_e32 v239, 0xffff0000, v196
	v_lshlrev_b32_e32 v32, 16, v33
	v_and_b32_e32 v33, 0xffff0000, v33
	v_lshlrev_b32_e32 v196, 16, v197
	v_and_b32_e32 v197, 0xffff0000, v197
	v_pk_fma_f32 v[158:159], v[158:159], v[232:233], v[234:235]
	v_pk_fma_f32 v[160:161], v[160:161], v[30:31], v[194:195]
	v_pk_fma_f32 v[154:155], v[154:155], v[236:237], v[238:239]
	v_pk_fma_f32 v[156:157], v[156:157], v[32:33], v[196:197]
	v_cvt_pk_bf16_f32 v30, v158, v159
	v_cvt_pk_bf16_f32 v31, v160, v161
	v_cvt_pk_bf16_f32 v32, v154, v155
	v_cvt_pk_bf16_f32 v33, v156, v157
	v_lshlrev_b32_e32 v194, 16, v198
	global_store_dwordx4 v[230:231], v[30:33], off
	v_and_b32_e32 v195, 0xffff0000, v198
	s_nop 0
	v_lshlrev_b32_e32 v30, 16, v202
	v_and_b32_e32 v31, 0xffff0000, v202
	v_pk_fma_f32 v[30:31], v[150:151], v[194:195], v[30:31]
	v_lshlrev_b32_e32 v32, 16, v199
	v_and_b32_e32 v33, 0xffff0000, v199
	v_lshlrev_b32_e32 v150, 16, v203
	v_and_b32_e32 v151, 0xffff0000, v203
	v_pk_fma_f32 v[32:33], v[152:153], v[32:33], v[150:151]
	v_cvt_pk_bf16_f32 v30, v30, v31
	v_cvt_pk_bf16_f32 v31, v32, v33
	v_lshlrev_b32_e32 v32, 16, v200
	v_and_b32_e32 v33, 0xffff0000, v200
	v_lshlrev_b32_e32 v150, 16, v204
	v_and_b32_e32 v151, 0xffff0000, v204
	v_pk_fma_f32 v[32:33], v[142:143], v[32:33], v[150:151]
	v_lshlrev_b32_e32 v142, 16, v201
	v_and_b32_e32 v143, 0xffff0000, v201
	v_lshlrev_b32_e32 v150, 16, v205
	v_and_b32_e32 v151, 0xffff0000, v205
	v_pk_fma_f32 v[142:143], v[144:145], v[142:143], v[150:151]
	v_cvt_pk_bf16_f32 v32, v32, v33
	v_cvt_pk_bf16_f32 v33, v142, v143
	global_store_dwordx4 v[230:231], v[30:33], off offset:256
	v_lshlrev_b32_e32 v144, 16, v211
	v_and_b32_e32 v145, 0xffff0000, v211
	v_lshlrev_b32_e32 v30, 16, v206
	v_and_b32_e32 v31, 0xffff0000, v206
	v_lshlrev_b32_e32 v32, 16, v210
	v_and_b32_e32 v33, 0xffff0000, v210
	v_pk_fma_f32 v[30:31], v[146:147], v[30:31], v[32:33]
	v_lshlrev_b32_e32 v32, 16, v207
	v_and_b32_e32 v33, 0xffff0000, v207
	v_pk_fma_f32 v[32:33], v[148:149], v[32:33], v[144:145]
	v_cvt_pk_bf16_f32 v30, v30, v31
	v_cvt_pk_bf16_f32 v31, v32, v33
	v_lshlrev_b32_e32 v32, 16, v208
	v_and_b32_e32 v33, 0xffff0000, v208
	v_lshlrev_b32_e32 v144, 16, v212
	v_and_b32_e32 v145, 0xffff0000, v212
	v_pk_fma_f32 v[32:33], v[138:139], v[32:33], v[144:145]
	v_lshlrev_b32_e32 v138, 16, v209
	v_and_b32_e32 v139, 0xffff0000, v209
	v_lshlrev_b32_e32 v144, 16, v213
	v_and_b32_e32 v145, 0xffff0000, v213
	v_lshlrev_b64 v[142:143], 13, v[184:185]
	v_pk_fma_f32 v[138:139], v[140:141], v[138:139], v[144:145]
; #define PG8_GAS __attribute__((address_space(1)))
; __device__ __forceinline__ unsigned cvt_pk_bf16(float lo, float hi) { const f32x2c v = {lo, hi}; return __builtin_bit_cast(unsigned, __builtin_convertvector(v, bf16x2c)); }
; __device__ __forceinline__ float bf_lo(unsigned w) { return __uint_as_float(w << 16); }
; __device__ __forceinline__ float bf_hi(unsigned w) { return __uint_as_float(w & 0xffff0000u); }
;     __device__ __forceinline__ void operator()(const f32x4 (&acc)[2][2][4][2], const Unit& un, int wr, int wc, int fr, int fq) const {
;     ...
;             for (int m = 0; m < 4; ++m)
; #pragma unroll
;                 for (int bj = 0; bj < 2; ++bj) { const u32x4 g = gg[m][bj], p = pp[m][bj]; const f32x4 v0 = acc[ai][bj][m][0], v1 = acc[ai][bj][m][1];
;                     u32x4 w; w.x = cvt_pk_bf16(v0[0] * bf_lo(g.x) + bf_lo(p.x), v0[1] * bf_hi(g.x) + bf_hi(p.x)); w.y = cvt_pk_bf16(v0[2] * bf_lo(g.y) + bf_lo(p.y), v0[3] * bf_hi(g.y) + bf_hi(p.y));
;                     w.z = cvt_pk_bf16(v1[0] * bf_lo(g.z) + bf_lo(p.z), v1[1] * bf_hi(g.z) + bf_hi(p.z)); w.w = cvt_pk_bf16(v1[2] * bf_lo(g.w) + bf_lo(p.w), v1[3] * bf_hi(g.w) + bf_hi(p.w));
;                     *(PG8_GAS u32x4*)(sa + (size_t)(row0 + ai * HALF + m * 16) * 4096 + col0 + bj * HALF) = w; }
	v_cvt_pk_bf16_f32 v32, v32, v33
	v_cvt_pk_bf16_f32 v33, v138, v139
	v_lshl_add_u64 v[138:139], s[10:11], 0, v[142:143]
	v_lshl_add_u64 v[138:139], v[138:139], 0, v[178:179]
	global_store_dwordx4 v[138:139], v[30:33], off
	s_nop 1
	v_lshlrev_b32_e32 v30, 16, v222
	v_and_b32_e32 v31, 0xffff0000, v222
	v_lshlrev_b32_e32 v32, 16, v226
	v_and_b32_e32 v33, 0xffff0000, v226
	v_pk_fma_f32 v[30:31], v[134:135], v[30:31], v[32:33]
	v_lshlrev_b32_e32 v32, 16, v223
	v_and_b32_e32 v33, 0xffff0000, v223
	v_lshlrev_b32_e32 v134, 16, v227
	v_and_b32_e32 v135, 0xffff0000, v227
	v_pk_fma_f32 v[32:33], v[136:137], v[32:33], v[134:135]
	v_cvt_pk_bf16_f32 v30, v30, v31
	v_cvt_pk_bf16_f32 v31, v32, v33
	v_lshlrev_b32_e32 v32, 16, v224
	v_and_b32_e32 v33, 0xffff0000, v224
	v_lshlrev_b32_e32 v134, 16, v228
	v_and_b32_e32 v135, 0xffff0000, v228
	v_pk_fma_f32 v[32:33], v[126:127], v[32:33], v[134:135]
	v_lshlrev_b32_e32 v126, 16, v225
	v_and_b32_e32 v127, 0xffff0000, v225
	v_lshlrev_b32_e32 v134, 16, v229
	v_and_b32_e32 v135, 0xffff0000, v229
	v_pk_fma_f32 v[126:127], v[128:129], v[126:127], v[134:135]
	v_cvt_pk_bf16_f32 v32, v32, v33
	v_cvt_pk_bf16_f32 v33, v126, v127
	global_store_dwordx4 v[138:139], v[30:33], off offset:256
	v_lshlrev_b32_e32 v126, 16, v219
	v_and_b32_e32 v127, 0xffff0000, v219
	v_lshlrev_b64 v[32:33], 13, v[28:29]
	v_lshlrev_b32_e32 v28, 16, v214
	v_and_b32_e32 v29, 0xffff0000, v214
	v_lshlrev_b32_e32 v30, 16, v218
	v_and_b32_e32 v31, 0xffff0000, v218
	v_pk_fma_f32 v[28:29], v[130:131], v[28:29], v[30:31]
	v_lshlrev_b32_e32 v30, 16, v215
	v_and_b32_e32 v31, 0xffff0000, v215
	v_pk_fma_f32 v[30:31], v[132:133], v[30:31], v[126:127]
	v_cvt_pk_bf16_f32 v28, v28, v29
	v_cvt_pk_bf16_f32 v29, v30, v31
	v_lshlrev_b32_e32 v30, 16, v216
	v_and_b32_e32 v31, 0xffff0000, v216
	v_lshlrev_b32_e32 v126, 16, v220
	v_and_b32_e32 v127, 0xffff0000, v220
	v_pk_fma_f32 v[30:31], v[122:123], v[30:31], v[126:127]
	v_lshlrev_b32_e32 v122, 16, v217
	v_and_b32_e32 v123, 0xffff0000, v217
	v_lshlrev_b32_e32 v126, 16, v221
	v_and_b32_e32 v127, 0xffff0000, v221
	v_pk_fma_f32 v[122:123], v[124:125], v[122:123], v[126:127]
	v_lshl_add_u64 v[32:33], s[10:11], 0, v[32:33]
	v_cvt_pk_bf16_f32 v30, v30, v31
	v_cvt_pk_bf16_f32 v31, v122, v123
	v_lshl_add_u64 v[32:33], v[32:33], 0, v[178:179]
	global_store_dwordx4 v[32:33], v[28:31], off
	v_add_u32_e32 v132, 0x80, v182
	v_ashrrev_i32_e32 v133, 31, v132
	v_lshlrev_b32_e32 v28, 16, v22
	v_and_b32_e32 v29, 0xffff0000, v22
	v_lshlrev_b32_e32 v30, 16, v18
	v_and_b32_e32 v31, 0xffff0000, v18
	v_pk_fma_f32 v[28:29], v[118:119], v[28:29], v[30:31]
	v_lshlrev_b32_e32 v22, 16, v23
	v_cvt_pk_bf16_f32 v18, v28, v29
	v_and_b32_e32 v23, 0xffff0000, v23
	v_lshlrev_b32_e32 v28, 16, v19
	v_and_b32_e32 v29, 0xffff0000, v19
	v_pk_fma_f32 v[22:23], v[120:121], v[22:23], v[28:29]
	v_lshlrev_b32_e32 v28, 16, v20
	v_cvt_pk_bf16_f32 v19, v22, v23
	v_lshlrev_b32_e32 v22, 16, v24
	v_and_b32_e32 v23, 0xffff0000, v24
	v_and_b32_e32 v29, 0xffff0000, v20
	v_pk_fma_f32 v[22:23], v[110:111], v[22:23], v[28:29]
	v_lshlrev_b32_e32 v24, 16, v21
	v_cvt_pk_bf16_f32 v20, v22, v23
	v_lshlrev_b32_e32 v22, 16, v25
	v_and_b32_e32 v23, 0xffff0000, v25
	v_and_b32_e32 v25, 0xffff0000, v21
	v_pk_fma_f32 v[22:23], v[112:113], v[22:23], v[24:25]
	v_add_u32_e32 v134, 0x90, v182
	v_cvt_pk_bf16_f32 v21, v22, v23
	global_store_dwordx4 v[32:33], v[18:21], off offset:256
	v_lshlrev_b32_e32 v22, 16, v10
	v_and_b32_e32 v23, 0xffff0000, v10
	v_lshlrev_b32_e32 v20, 16, v14
	v_and_b32_e32 v21, 0xffff0000, v14
	v_pk_fma_f32 v[20:21], v[114:115], v[20:21], v[22:23]
	v_lshlrev_b32_e32 v14, 16, v15
	v_cvt_pk_bf16_f32 v10, v20, v21
	v_and_b32_e32 v15, 0xffff0000, v15
	v_lshlrev_b32_e32 v20, 16, v11
	v_and_b32_e32 v21, 0xffff0000, v11
	v_pk_fma_f32 v[14:15], v[116:117], v[14:15], v[20:21]
	v_lshlrev_b32_e32 v20, 16, v12
	v_cvt_pk_bf16_f32 v11, v14, v15
	v_lshlrev_b32_e32 v14, 16, v16
	v_and_b32_e32 v15, 0xffff0000, v16
	v_and_b32_e32 v21, 0xffff0000, v12
	v_pk_fma_f32 v[14:15], v[106:107], v[14:15], v[20:21]
	v_lshlrev_b32_e32 v16, 16, v13
	v_cvt_pk_bf16_f32 v12, v14, v15
	v_lshlrev_b32_e32 v14, 16, v17
	v_and_b32_e32 v15, 0xffff0000, v17
	v_and_b32_e32 v17, 0xffff0000, v13
	v_lshlrev_b64 v[18:19], 13, v[26:27]
	v_pk_fma_f32 v[14:15], v[108:109], v[14:15], v[16:17]
	v_ashrrev_i32_e32 v135, 31, v134
	v_cvt_pk_bf16_f32 v13, v14, v15
	v_lshl_add_u64 v[14:15], s[10:11], 0, v[18:19]
	v_lshl_add_u64 v[14:15], v[14:15], 0, v[178:179]
	global_store_dwordx4 v[14:15], v[10:13], off
	v_add_u32_e32 v136, 0xa0, v182
	v_ashrrev_i32_e32 v137, 31, v136
	v_lshlrev_b32_e32 v10, 16, v6
	v_and_b32_e32 v11, 0xffff0000, v6
	v_lshlrev_b32_e32 v12, 16, v2
	v_and_b32_e32 v13, 0xffff0000, v2
	v_pk_fma_f32 v[10:11], v[102:103], v[10:11], v[12:13]
	v_lshlrev_b32_e32 v6, 16, v7
	v_cvt_pk_bf16_f32 v2, v10, v11
	v_and_b32_e32 v7, 0xffff0000, v7
	v_lshlrev_b32_e32 v10, 16, v3
	v_and_b32_e32 v11, 0xffff0000, v3
	v_pk_fma_f32 v[6:7], v[104:105], v[6:7], v[10:11]
	v_lshlrev_b32_e32 v10, 16, v4
	v_cvt_pk_bf16_f32 v3, v6, v7
	v_lshlrev_b32_e32 v6, 16, v8
	v_and_b32_e32 v7, 0xffff0000, v8
	v_and_b32_e32 v11, 0xffff0000, v4
	v_pk_fma_f32 v[6:7], v[98:99], v[6:7], v[10:11]
	v_lshlrev_b32_e32 v8, 16, v5
	v_cvt_pk_bf16_f32 v4, v6, v7
	v_lshlrev_b32_e32 v6, 16, v9
	v_and_b32_e32 v7, 0xffff0000, v9
	v_and_b32_e32 v9, 0xffff0000, v5
	v_pk_fma_f32 v[6:7], v[100:101], v[6:7], v[8:9]
	v_add_u32_e32 v98, 0xb0, v182
	v_cvt_pk_bf16_f32 v5, v6, v7
	global_store_dwordx4 v[14:15], v[2:5], off offset:256
	v_ashrrev_i32_e32 v99, 31, v98
	s_nop 0
	v_lshlrev_b64 v[2:3], 12, v[132:133]
	v_lshl_add_u64 v[2:3], v[2:3], 0, v[180:181]
	v_lshlrev_b64 v[2:3], 1, v[2:3]
; #define PG8_GAS __attribute__((address_space(1)))
; __device__ __forceinline__ unsigned cvt_pk_bf16(float lo, float hi) { const f32x2c v = {lo, hi}; return __builtin_bit_cast(unsigned, __builtin_convertvector(v, bf16x2c)); }
; __device__ __forceinline__ float bf_lo(unsigned w) { return __uint_as_float(w << 16); }
; __device__ __forceinline__ float bf_hi(unsigned w) { return __uint_as_float(w & 0xffff0000u); }
;     __device__ __forceinline__ void operator()(const f32x4 (&acc)[2][2][4][2], const Unit& un, int wr, int wc, int fr, int fq) const {
;     ...
;             for (int m = 0; m < 4; ++m)
; #pragma unroll
;                 for (int bj = 0; bj < 2; ++bj) { const size_t off = (size_t)(row0 + ai * HALF + m * 16) * 4096 + col0 + bj * HALF; gg[m][bj] = *(const PG8_GAS u32x4*)(sa + off); pp[m][bj] = *(const PG8_GAS u32x4*)(P + off); }
;             asm volatile("" ::: "memory");
; #pragma unroll
;             for (int m = 0; m < 4; ++m)
; #pragma unroll
;                 for (int bj = 0; bj < 2; ++bj) { const u32x4 g = gg[m][bj], p = pp[m][bj]; const f32x4 v0 = acc[ai][bj][m][0], v1 = acc[ai][bj][m][1];
;                     u32x4 w; w.x = cvt_pk_bf16(v0[0] * bf_lo(g.x) + bf_lo(p.x), v0[1] * bf_hi(g.x) + bf_hi(p.x)); w.y = cvt_pk_bf16(v0[2] * bf_lo(g.y) + bf_lo(p.y), v0[3] * bf_hi(g.y) + bf_hi(p.y));
;                     w.z = cvt_pk_bf16(v1[0] * bf_lo(g.z) + bf_lo(p.z), v1[1] * bf_hi(g.z) + bf_hi(p.z)); w.w = cvt_pk_bf16(v1[2] * bf_lo(g.w) + bf_lo(p.w), v1[3] * bf_hi(g.w) + bf_hi(p.w));
;                     *(PG8_GAS u32x4*)(sa + (size_t)(row0 + ai * HALF + m * 16) * 4096 + col0 + bj * HALF) = w; }
	v_lshl_add_u64 v[4:5], s[10:11], 0, v[2:3]
	global_load_dwordx4 v[100:103], v[4:5], off
	v_lshl_add_u64 v[4:5], s[12:13], 0, v[2:3]
	global_load_dwordx4 v[104:107], v[4:5], off
	v_or_b32_e32 v2, 0x100, v2
	v_lshl_add_u64 v[4:5], s[10:11], 0, v[2:3]
	v_lshl_add_u64 v[2:3], s[12:13], 0, v[2:3]
	global_load_dwordx4 v[108:111], v[4:5], off
	global_load_dwordx4 v[112:115], v[2:3], off
	v_lshlrev_b64 v[2:3], 12, v[134:135]
	v_lshl_add_u64 v[2:3], v[2:3], 0, v[180:181]
	v_lshlrev_b64 v[2:3], 1, v[2:3]
	v_lshl_add_u64 v[4:5], s[10:11], 0, v[2:3]
	v_lshl_add_u64 v[6:7], s[12:13], 0, v[2:3]
	global_load_dwordx4 v[116:119], v[4:5], off
	global_load_dwordx4 v[120:123], v[6:7], off
	v_or_b32_e32 v2, 0x100, v2
	v_lshl_add_u64 v[4:5], s[10:11], 0, v[2:3]
	v_lshl_add_u64 v[2:3], s[12:13], 0, v[2:3]
	global_load_dwordx4 v[124:127], v[4:5], off
	global_load_dwordx4 v[128:131], v[2:3], off
	v_lshlrev_b64 v[2:3], 12, v[136:137]
	v_lshl_add_u64 v[2:3], v[2:3], 0, v[180:181]
	v_lshlrev_b64 v[2:3], 1, v[2:3]
	v_lshl_add_u64 v[4:5], s[10:11], 0, v[2:3]
	v_lshl_add_u64 v[6:7], s[12:13], 0, v[2:3]
	global_load_dwordx4 v[30:33], v[4:5], off
	global_load_dwordx4 v[26:29], v[6:7], off
	v_or_b32_e32 v2, 0x100, v2
	v_lshl_add_u64 v[4:5], s[10:11], 0, v[2:3]
	v_lshl_add_u64 v[2:3], s[12:13], 0, v[2:3]
	global_load_dwordx4 v[22:25], v[4:5], off
	global_load_dwordx4 v[18:21], v[2:3], off
	v_lshlrev_b64 v[2:3], 12, v[98:99]
	v_lshl_add_u64 v[2:3], v[2:3], 0, v[180:181]
	v_lshlrev_b64 v[2:3], 1, v[2:3]
	v_lshl_add_u64 v[4:5], s[10:11], 0, v[2:3]
	v_lshl_add_u64 v[6:7], s[12:13], 0, v[2:3]
	global_load_dwordx4 v[14:17], v[4:5], off
	global_load_dwordx4 v[10:13], v[6:7], off
	v_or_b32_e32 v2, 0x100, v2
	v_lshl_add_u64 v[4:5], s[10:11], 0, v[2:3]
	v_lshl_add_u64 v[2:3], s[12:13], 0, v[2:3]
	global_load_dwordx4 v[6:9], v[4:5], off
	s_nop 0
	global_load_dwordx4 v[2:5], v[2:3], off
	v_lshlrev_b64 v[132:133], 13, v[132:133]
	s_waitcnt vmcnt(15)
	v_lshlrev_b32_e32 v138, 16, v100
	v_and_b32_e32 v139, 0xffff0000, v100
	s_waitcnt vmcnt(14)
	v_lshlrev_b32_e32 v140, 16, v104
	v_and_b32_e32 v141, 0xffff0000, v104
	v_lshlrev_b32_e32 v100, 16, v101
	v_and_b32_e32 v101, 0xffff0000, v101
	v_lshlrev_b32_e32 v104, 16, v105
	v_and_b32_e32 v105, 0xffff0000, v105
	v_pk_fma_f32 v[94:95], v[94:95], v[138:139], v[140:141]
	v_pk_fma_f32 v[96:97], v[96:97], v[100:101], v[104:105]
	v_cvt_pk_bf16_f32 v94, v94, v95
	v_cvt_pk_bf16_f32 v95, v96, v97
	v_lshlrev_b32_e32 v96, 16, v102
	v_and_b32_e32 v97, 0xffff0000, v102
	v_lshlrev_b32_e32 v100, 16, v106
	v_and_b32_e32 v101, 0xffff0000, v106
	v_pk_fma_f32 v[90:91], v[90:91], v[96:97], v[100:101]
	v_lshlrev_b32_e32 v100, 16, v107
	v_cvt_pk_bf16_f32 v96, v90, v91
	v_lshlrev_b32_e32 v90, 16, v103
	v_and_b32_e32 v91, 0xffff0000, v103
	v_and_b32_e32 v101, 0xffff0000, v107
	v_pk_fma_f32 v[90:91], v[92:93], v[90:91], v[100:101]
	s_waitcnt vmcnt(13)
	v_lshlrev_b32_e32 v92, 16, v108
	v_cvt_pk_bf16_f32 v97, v90, v91
	v_lshl_add_u64 v[90:91], s[10:11], 0, v[132:133]
	v_lshl_add_u64 v[90:91], v[90:91], 0, v[178:179]
	global_store_dwordx4 v[90:91], v[94:97], off
	v_and_b32_e32 v93, 0xffff0000, v108
	s_waitcnt vmcnt(13)
	v_lshlrev_b32_e32 v94, 16, v112
	v_and_b32_e32 v95, 0xffff0000, v112
	v_pk_fma_f32 v[86:87], v[86:87], v[92:93], v[94:95]
	v_lshlrev_b32_e32 v92, 16, v109
	v_and_b32_e32 v93, 0xffff0000, v109
	v_lshlrev_b32_e32 v94, 16, v113
	v_and_b32_e32 v95, 0xffff0000, v113
	v_pk_fma_f32 v[88:89], v[88:89], v[92:93], v[94:95]
	v_cvt_pk_bf16_f32 v86, v86, v87
	v_cvt_pk_bf16_f32 v87, v88, v89
	v_lshlrev_b32_e32 v88, 16, v110
	v_and_b32_e32 v89, 0xffff0000, v110
	v_lshlrev_b32_e32 v92, 16, v114
	v_and_b32_e32 v93, 0xffff0000, v114
	v_pk_fma_f32 v[78:79], v[78:79], v[88:89], v[92:93]
	v_lshlrev_b32_e32 v92, 16, v115
	v_cvt_pk_bf16_f32 v88, v78, v79
	v_lshlrev_b32_e32 v78, 16, v111
	v_and_b32_e32 v79, 0xffff0000, v111
	v_and_b32_e32 v93, 0xffff0000, v115
	v_pk_fma_f32 v[78:79], v[80:81], v[78:79], v[92:93]
	s_waitcnt vmcnt(11)
	v_lshlrev_b32_e32 v80, 16, v120
	v_cvt_pk_bf16_f32 v89, v78, v79
	v_lshlrev_b32_e32 v78, 16, v116
	v_and_b32_e32 v79, 0xffff0000, v116
	v_and_b32_e32 v81, 0xffff0000, v120
	v_pk_fma_f32 v[78:79], v[82:83], v[78:79], v[80:81]
	v_lshlrev_b32_e32 v80, 16, v117
	v_and_b32_e32 v81, 0xffff0000, v117
	v_lshlrev_b32_e32 v82, 16, v121
	v_and_b32_e32 v83, 0xffff0000, v121
	v_pk_fma_f32 v[80:81], v[84:85], v[80:81], v[82:83]
	v_cvt_pk_bf16_f32 v78, v78, v79
	v_cvt_pk_bf16_f32 v79, v80, v81
	v_lshlrev_b32_e32 v80, 16, v118
	v_and_b32_e32 v81, 0xffff0000, v118
	v_lshlrev_b32_e32 v82, 16, v122
	v_and_b32_e32 v83, 0xffff0000, v122
	v_pk_fma_f32 v[74:75], v[74:75], v[80:81], v[82:83]
	v_lshlrev_b32_e32 v82, 16, v123
	v_cvt_pk_bf16_f32 v80, v74, v75
	v_lshlrev_b32_e32 v74, 16, v119
	v_and_b32_e32 v75, 0xffff0000, v119
	v_and_b32_e32 v83, 0xffff0000, v123
	global_store_dwordx4 v[90:91], v[86:89], off offset:256
	v_pk_fma_f32 v[74:75], v[76:77], v[74:75], v[82:83]
	s_waitcnt vmcnt(11)
	v_lshlrev_b32_e32 v76, 16, v124
	v_lshlrev_b64 v[86:87], 13, v[134:135]
	v_cvt_pk_bf16_f32 v81, v74, v75
	v_lshl_add_u64 v[74:75], s[10:11], 0, v[86:87]
	v_lshl_add_u64 v[74:75], v[74:75], 0, v[178:179]
	global_store_dwordx4 v[74:75], v[78:81], off
	v_and_b32_e32 v77, 0xffff0000, v124
	s_waitcnt vmcnt(11)
; #define PG8_GAS __attribute__((address_space(1)))
; __device__ __forceinline__ unsigned cvt_pk_bf16(float lo, float hi) { const f32x2c v = {lo, hi}; return __builtin_bit_cast(unsigned, __builtin_convertvector(v, bf16x2c)); }
; __device__ __forceinline__ float bf_lo(unsigned w) { return __uint_as_float(w << 16); }
; __device__ __forceinline__ float bf_hi(unsigned w) { return __uint_as_float(w & 0xffff0000u); }
; #define PG8_WAIT_V(n) asm volatile("s_waitcnt vmcnt(" #n ")" ::: "memory")
; #define PG8_BAR __builtin_amdgcn_s_barrier()
;     __device__ __forceinline__ void operator()(const f32x4 (&acc)[2][2][4][2], const Unit& un, int wr, int wc, int fr, int fq) const {
;     ...
;             for (int m = 0; m < 4; ++m)
; #pragma unroll
;                 for (int bj = 0; bj < 2; ++bj) { const u32x4 g = gg[m][bj], p = pp[m][bj]; const f32x4 v0 = acc[ai][bj][m][0], v1 = acc[ai][bj][m][1];
;                     u32x4 w; w.x = cvt_pk_bf16(v0[0] * bf_lo(g.x) + bf_lo(p.x), v0[1] * bf_hi(g.x) + bf_hi(p.x)); w.y = cvt_pk_bf16(v0[2] * bf_lo(g.y) + bf_lo(p.y), v0[3] * bf_hi(g.y) + bf_hi(p.y));
;                     w.z = cvt_pk_bf16(v1[0] * bf_lo(g.z) + bf_lo(p.z), v1[1] * bf_hi(g.z) + bf_hi(p.z)); w.w = cvt_pk_bf16(v1[2] * bf_lo(g.w) + bf_lo(p.w), v1[3] * bf_hi(g.w) + bf_hi(p.w));
;                     *(PG8_GAS u32x4*)(sa + (size_t)(row0 + ai * HALF + m * 16) * 4096 + col0 + bj * HALF) = w; }
; template <class Epi, class Sched, bool ALIGN_EPI = false, bool SP2 = false, bool F8 = false>
; __device__ __forceinline__ void gemm_phase(PG8_LAS unsigned char* lds, const Gemm g, const Sched& S, const Epi& E) {
;     ...
;         if (!has_next) break;
; #pragma unroll
;         for (int a = 0; a < 2; ++a)
; #pragma unroll
;             for (int b = 0; b < 2; ++b)
; #pragma unroll
;                 for (int m = 0; m < 4; ++m)
; #pragma unroll
;                     for (int n = 0; n < 2; ++n) acc[a][b][m][n] = (f32x4){0.f, 0.f, 0.f, 0.f};
;         cur = nxt; cA = nA; cB = nB; ++ui;
;         if constexpr (ALIGN_EPI) { if (wr == 1) PG8_BAR; }
;     }
;     PG8_WAIT_V(0);
;     if constexpr (!ALIGN_EPI) { if (wr == 0) PG8_BAR; }
	v_lshlrev_b32_e32 v78, 16, v128
	v_and_b32_e32 v79, 0xffff0000, v128
	v_pk_fma_f32 v[70:71], v[70:71], v[76:77], v[78:79]
	v_lshlrev_b32_e32 v76, 16, v125
	v_and_b32_e32 v77, 0xffff0000, v125
	v_lshlrev_b32_e32 v78, 16, v129
	v_and_b32_e32 v79, 0xffff0000, v129
	v_pk_fma_f32 v[72:73], v[72:73], v[76:77], v[78:79]
	v_cvt_pk_bf16_f32 v70, v70, v71
	v_cvt_pk_bf16_f32 v71, v72, v73
	v_lshlrev_b32_e32 v72, 16, v126
	v_and_b32_e32 v73, 0xffff0000, v126
	v_lshlrev_b32_e32 v76, 16, v130
	v_and_b32_e32 v77, 0xffff0000, v130
	v_pk_fma_f32 v[62:63], v[62:63], v[72:73], v[76:77]
	v_lshlrev_b32_e32 v76, 16, v131
	v_cvt_pk_bf16_f32 v72, v62, v63
	v_lshlrev_b32_e32 v62, 16, v127
	v_and_b32_e32 v63, 0xffff0000, v127
	v_and_b32_e32 v77, 0xffff0000, v131
	v_pk_fma_f32 v[62:63], v[64:65], v[62:63], v[76:77]
	s_waitcnt vmcnt(10)
	v_lshlrev_b32_e32 v64, 16, v30
	v_cvt_pk_bf16_f32 v73, v62, v63
	global_store_dwordx4 v[74:75], v[70:73], off offset:256
	v_and_b32_e32 v65, 0xffff0000, v30
	v_lshlrev_b32_e32 v30, 16, v31
	s_waitcnt vmcnt(10)
	v_lshlrev_b32_e32 v70, 16, v26
	v_and_b32_e32 v71, 0xffff0000, v26
	v_pk_fma_f32 v[64:65], v[66:67], v[64:65], v[70:71]
	v_and_b32_e32 v31, 0xffff0000, v31
	v_cvt_pk_bf16_f32 v26, v64, v65
	v_lshlrev_b32_e32 v64, 16, v27
	v_and_b32_e32 v65, 0xffff0000, v27
	v_pk_fma_f32 v[30:31], v[68:69], v[30:31], v[64:65]
	v_lshlrev_b32_e32 v64, 16, v28
	v_cvt_pk_bf16_f32 v27, v30, v31
	v_lshlrev_b32_e32 v30, 16, v32
	v_and_b32_e32 v31, 0xffff0000, v32
	v_and_b32_e32 v65, 0xffff0000, v28
	v_pk_fma_f32 v[30:31], v[58:59], v[30:31], v[64:65]
	v_lshlrev_b32_e32 v32, 16, v29
	v_cvt_pk_bf16_f32 v28, v30, v31
	v_lshlrev_b32_e32 v30, 16, v33
	v_and_b32_e32 v31, 0xffff0000, v33
	v_and_b32_e32 v33, 0xffff0000, v29
	v_lshlrev_b64 v[62:63], 13, v[136:137]
	v_pk_fma_f32 v[30:31], v[60:61], v[30:31], v[32:33]
	s_nop 0
	v_cvt_pk_bf16_f32 v29, v30, v31
	v_lshl_add_u64 v[30:31], s[10:11], 0, v[62:63]
	v_lshl_add_u64 v[30:31], v[30:31], 0, v[178:179]
	global_store_dwordx4 v[30:31], v[26:29], off
	s_waitcnt vmcnt(10)
	s_nop 0
	v_lshlrev_b32_e32 v26, 16, v22
	v_and_b32_e32 v27, 0xffff0000, v22
	s_waitcnt vmcnt(9)
	v_lshlrev_b32_e32 v28, 16, v18
	v_and_b32_e32 v29, 0xffff0000, v18
	v_pk_fma_f32 v[26:27], v[54:55], v[26:27], v[28:29]
	v_lshlrev_b32_e32 v22, 16, v23
	v_cvt_pk_bf16_f32 v18, v26, v27
	v_and_b32_e32 v23, 0xffff0000, v23
	v_lshlrev_b32_e32 v26, 16, v19
	v_and_b32_e32 v27, 0xffff0000, v19
	v_pk_fma_f32 v[22:23], v[56:57], v[22:23], v[26:27]
	v_lshlrev_b32_e32 v26, 16, v20
	v_cvt_pk_bf16_f32 v19, v22, v23
	v_lshlrev_b32_e32 v22, 16, v24
	v_and_b32_e32 v23, 0xffff0000, v24
	v_and_b32_e32 v27, 0xffff0000, v20
	v_pk_fma_f32 v[22:23], v[46:47], v[22:23], v[26:27]
	v_lshlrev_b32_e32 v24, 16, v21
	v_cvt_pk_bf16_f32 v20, v22, v23
	v_lshlrev_b32_e32 v22, 16, v25
	v_and_b32_e32 v23, 0xffff0000, v25
	v_and_b32_e32 v25, 0xffff0000, v21
	v_pk_fma_f32 v[22:23], v[48:49], v[22:23], v[24:25]
	s_nop 0
	v_cvt_pk_bf16_f32 v21, v22, v23
	global_store_dwordx4 v[30:31], v[18:21], off offset:256
	s_waitcnt vmcnt(8)
	v_lshlrev_b32_e32 v22, 16, v10
	v_and_b32_e32 v23, 0xffff0000, v10
	v_lshlrev_b32_e32 v20, 16, v14
	v_and_b32_e32 v21, 0xffff0000, v14
	v_pk_fma_f32 v[20:21], v[50:51], v[20:21], v[22:23]
	v_lshlrev_b32_e32 v14, 16, v15
	v_cvt_pk_bf16_f32 v10, v20, v21
	v_and_b32_e32 v15, 0xffff0000, v15
	v_lshlrev_b32_e32 v20, 16, v11
	v_and_b32_e32 v21, 0xffff0000, v11
	v_pk_fma_f32 v[14:15], v[52:53], v[14:15], v[20:21]
	v_lshlrev_b32_e32 v20, 16, v12
	v_cvt_pk_bf16_f32 v11, v14, v15
	v_lshlrev_b32_e32 v14, 16, v16
	v_and_b32_e32 v15, 0xffff0000, v16
	v_and_b32_e32 v21, 0xffff0000, v12
	v_pk_fma_f32 v[14:15], v[42:43], v[14:15], v[20:21]
	v_lshlrev_b32_e32 v16, 16, v13
	v_cvt_pk_bf16_f32 v12, v14, v15
	v_lshlrev_b32_e32 v14, 16, v17
	v_and_b32_e32 v15, 0xffff0000, v17
	v_and_b32_e32 v17, 0xffff0000, v13
	v_lshlrev_b64 v[18:19], 13, v[98:99]
	v_pk_fma_f32 v[14:15], v[44:45], v[14:15], v[16:17]
	s_nop 0
	v_cvt_pk_bf16_f32 v13, v14, v15
	v_lshl_add_u64 v[14:15], s[10:11], 0, v[18:19]
	v_lshl_add_u64 v[14:15], v[14:15], 0, v[178:179]
	global_store_dwordx4 v[14:15], v[10:13], off
	s_waitcnt vmcnt(8)
	s_nop 0
	v_lshlrev_b32_e32 v10, 16, v6
	v_and_b32_e32 v11, 0xffff0000, v6
	s_waitcnt vmcnt(7)
	v_lshlrev_b32_e32 v12, 16, v2
	v_and_b32_e32 v13, 0xffff0000, v2
	v_pk_fma_f32 v[10:11], v[38:39], v[10:11], v[12:13]
	v_lshlrev_b32_e32 v6, 16, v7
	v_cvt_pk_bf16_f32 v2, v10, v11
	v_and_b32_e32 v7, 0xffff0000, v7
	v_lshlrev_b32_e32 v10, 16, v3
	v_and_b32_e32 v11, 0xffff0000, v3
	v_pk_fma_f32 v[6:7], v[40:41], v[6:7], v[10:11]
	v_lshlrev_b32_e32 v10, 16, v4
	v_cvt_pk_bf16_f32 v3, v6, v7
	v_lshlrev_b32_e32 v6, 16, v8
	v_and_b32_e32 v7, 0xffff0000, v8
	v_and_b32_e32 v11, 0xffff0000, v4
	v_pk_fma_f32 v[6:7], v[34:35], v[6:7], v[10:11]
	v_lshlrev_b32_e32 v8, 16, v5
	v_cvt_pk_bf16_f32 v4, v6, v7
	v_lshlrev_b32_e32 v6, 16, v9
	v_and_b32_e32 v7, 0xffff0000, v9
	v_and_b32_e32 v9, 0xffff0000, v5
	v_pk_fma_f32 v[6:7], v[36:37], v[6:7], v[8:9]
	s_nop 0
	v_cvt_pk_bf16_f32 v5, v6, v7
	global_store_dwordx4 v[14:15], v[2:5], off offset:256
	s_cbranch_vccz .LBB0_627
	s_waitcnt vmcnt(0)
	s_cmpk_gt_u32 s4, 0xff
	s_cbranch_scc1 .LBB0_634
	s_barrier

; template <class Epi, class Sched, bool ALIGN_EPI = false, bool SP2 = false, bool F8 = false>
; __device__ __forceinline__ void gemm_phase(PG8_LAS unsigned char* lds, const Gemm g, const Sched& S, const Epi& E) {
;     ...
;         const bool has_next = S.next(ui + 1, nxt);
;         const char* nA = has_next ? (const char*)g.A + (size_t)nxt.pm * tA + (size_t)(nxt.pn >> g.gshift) * g.goff : cA; const char* nB = has_next ? (const char*)g.Bt + (size_t)nxt.pn * tB : cB;
;     ...
; #pragma unroll
;         for (int a = 0; a < 2; ++a)
; #pragma unroll
;             for (int b = 0; b < 2; ++b)
; #pragma unroll
;                 for (int m = 0; m < 4; ++m)
; #pragma unroll
;                     for (int n = 0; n < 2; ++n) acc[a][b][m][n] = (f32x4){0.f, 0.f, 0.f, 0.f};
.LBB0_688:
	s_ashr_i32 s27, s26, 31
	v_cmp_lt_i64_e32 vcc, s[28:29], v[190:191]
	s_lshl_b64 s[28:29], s[26:27], 21
	s_add_u32 s28, s5, s28
	s_addc_u32 s29, s6, s29
	s_and_b64 s[30:31], vcc, exec
	s_cselect_b32 s17, s29, s39
	s_cselect_b32 s20, s28, s38
	s_ashr_i32 s25, s24, 31
	s_lshl_b64 s[30:31], s[24:25], 21
	s_add_u32 s30, s7, s30
	s_addc_u32 s31, s18, s31
	s_and_b64 s[40:41], vcc, exec
	s_cselect_b32 s25, s31, s37
	s_cselect_b32 s27, s30, s36
	s_add_u32 s35, s36, 0x100
	s_addc_u32 s60, s37, 0
	s_add_u32 s36, s38, 0x100080
	v_mov_b32_e32 v2, 0
	s_addc_u32 s37, s39, 0
	s_mov_b32 s61, -2
	s_waitcnt lgkmcnt(0)
	v_mov_b32_e32 v3, v2
	v_mov_b32_e32 v4, v2
	v_mov_b32_e32 v5, v2
	v_mov_b32_e32 v6, v2
	v_mov_b32_e32 v7, v2
	v_mov_b32_e32 v8, v2
	v_mov_b32_e32 v9, v2
	v_mov_b32_e32 v18, v2
	v_mov_b32_e32 v19, v2
	v_mov_b32_e32 v20, v2
	v_mov_b32_e32 v21, v2
	v_mov_b32_e32 v22, v2
	v_mov_b32_e32 v23, v2
	v_mov_b32_e32 v24, v2
	v_mov_b32_e32 v25, v2
	v_mov_b32_e32 v34, v2
	v_mov_b32_e32 v35, v2
	v_mov_b32_e32 v36, v2
	v_mov_b32_e32 v37, v2
	v_mov_b32_e32 v38, v2
	v_mov_b32_e32 v39, v2
	v_mov_b32_e32 v40, v2
	v_mov_b32_e32 v41, v2
	v_mov_b32_e32 v50, v2
	v_mov_b32_e32 v51, v2
	v_mov_b32_e32 v52, v2
	v_mov_b32_e32 v53, v2
	v_mov_b32_e32 v54, v2
	v_mov_b32_e32 v55, v2
	v_mov_b32_e32 v56, v2
	v_mov_b32_e32 v57, v2
	v_mov_b32_e32 v10, v2
	v_mov_b32_e32 v11, v2
	v_mov_b32_e32 v12, v2
	v_mov_b32_e32 v13, v2
	v_mov_b32_e32 v14, v2
	v_mov_b32_e32 v15, v2
	v_mov_b32_e32 v16, v2
	v_mov_b32_e32 v17, v2
	v_mov_b32_e32 v26, v2
	v_mov_b32_e32 v27, v2
	v_mov_b32_e32 v28, v2
	v_mov_b32_e32 v29, v2
	v_mov_b32_e32 v30, v2
	v_mov_b32_e32 v31, v2
	v_mov_b32_e32 v32, v2
	v_mov_b32_e32 v33, v2
	v_mov_b32_e32 v42, v2
	v_mov_b32_e32 v43, v2
	v_mov_b32_e32 v44, v2
	v_mov_b32_e32 v45, v2
	v_mov_b32_e32 v46, v2
	v_mov_b32_e32 v47, v2
	v_mov_b32_e32 v48, v2
	v_mov_b32_e32 v49, v2
	v_mov_b32_e32 v58, v2
	v_mov_b32_e32 v59, v2
	v_mov_b32_e32 v60, v2
	v_mov_b32_e32 v61, v2
	v_mov_b32_e32 v62, v2
	v_mov_b32_e32 v63, v2
	v_mov_b32_e32 v64, v2
	v_mov_b32_e32 v65, v2
	v_mov_b32_e32 v66, v2
	v_mov_b32_e32 v67, v2
	v_mov_b32_e32 v68, v2
	v_mov_b32_e32 v69, v2
	v_mov_b32_e32 v70, v2
	v_mov_b32_e32 v71, v2
	v_mov_b32_e32 v72, v2
	v_mov_b32_e32 v73, v2
	v_mov_b32_e32 v82, v2
	v_mov_b32_e32 v83, v2
	v_mov_b32_e32 v84, v2
	v_mov_b32_e32 v85, v2
	v_mov_b32_e32 v86, v2
	v_mov_b32_e32 v87, v2
	v_mov_b32_e32 v88, v2
	v_mov_b32_e32 v89, v2
	v_mov_b32_e32 v98, v2
	v_mov_b32_e32 v99, v2
	v_mov_b32_e32 v100, v2
	v_mov_b32_e32 v101, v2
	v_mov_b32_e32 v102, v2
	v_mov_b32_e32 v103, v2
	v_mov_b32_e32 v104, v2
	v_mov_b32_e32 v105, v2
	v_mov_b32_e32 v114, v2
	v_mov_b32_e32 v115, v2
	v_mov_b32_e32 v116, v2
	v_mov_b32_e32 v117, v2
	v_mov_b32_e32 v118, v2
	v_mov_b32_e32 v119, v2
	v_mov_b32_e32 v120, v2
	v_mov_b32_e32 v121, v2
	v_mov_b32_e32 v74, v2
	v_mov_b32_e32 v75, v2
	v_mov_b32_e32 v76, v2
	v_mov_b32_e32 v77, v2
	v_mov_b32_e32 v78, v2
	v_mov_b32_e32 v79, v2
	v_mov_b32_e32 v80, v2
	v_mov_b32_e32 v81, v2
	v_mov_b32_e32 v90, v2
	v_mov_b32_e32 v91, v2
	v_mov_b32_e32 v92, v2
	v_mov_b32_e32 v93, v2
	v_mov_b32_e32 v94, v2
	v_mov_b32_e32 v95, v2
	v_mov_b32_e32 v96, v2
	v_mov_b32_e32 v97, v2
	v_mov_b32_e32 v106, v2
	v_mov_b32_e32 v107, v2
	v_mov_b32_e32 v108, v2
	v_mov_b32_e32 v109, v2
	v_mov_b32_e32 v110, v2
	v_mov_b32_e32 v111, v2
	v_mov_b32_e32 v112, v2
	v_mov_b32_e32 v113, v2
	v_mov_b32_e32 v122, v2
	v_mov_b32_e32 v123, v2
	v_mov_b32_e32 v124, v2
	v_mov_b32_e32 v125, v2
	v_mov_b32_e32 v126, v2
	v_mov_b32_e32 v127, v2
	v_mov_b32_e32 v128, v2
	v_mov_b32_e32 v129, v2
	s_branch .LBB0_689

; #define PG8_STAGE(bufoff, gbase, voff) do { _Pragma("unroll") for (int _i = 0; _i < 2; ++_i) \
;         __builtin_amdgcn_global_load_lds((const unsigned*)((const char*)(gbase) + (voff)[_i]), (PG8_LAS unsigned*)(lds + (bufoff) + ldsw + _i * 8192), 16, 0, 0); } while (0)
; #define PG8_LDA(dst, b, h) do { _Pragma("unroll") for (int m = 0; m < 4; ++m) _Pragma("unroll") for (int k = 0; k < 2; ++k) dst[m][k] = *(const PG8_LAS bf16x8*)(lds + PG8_SA(b, h) + aoff + m * 2048 + k * 1024); } while (0)
; #define PG8_LDB(dst, b, h) do { _Pragma("unroll") for (int n = 0; n < 2; ++n) _Pragma("unroll") for (int k = 0; k < 2; ++k) dst[n][k] = *(const PG8_LAS bf16x8*)(lds + PG8_SB(b, h) + boff + n * 2048 + k * 1024); } while (0)
; #define PG8_WAIT_V(n) asm volatile("s_waitcnt vmcnt(" #n ")" ::: "memory")
; #define PG8_WAIT_L(n) asm volatile("s_waitcnt lgkmcnt(" #n ")" ::: "memory")
; #define PG8_BAR __builtin_amdgcn_s_barrier()
; #define PG8_SCHED __builtin_amdgcn_sched_barrier(0)
; template <class Epi, class Sched, bool ALIGN_EPI = false, bool SP2 = false, bool F8 = false>
; __device__ __forceinline__ void gemm_phase(PG8_LAS unsigned char* lds, const Gemm g, const Sched& S, const Epi& E) {
;     ...
;             PG8_LDB(B0, 0, 0); PG8_LDB(B1, 0, 1); PG8_SCHED; PG8_LDA(At, 0, 0); PG8_STAGE(PG8_SA(1, 1), a1 + hA, voffA);
;             PG8_WAIT_V(8); PG8_WAIT_L(0); PG8_BAR; PG8_MMA(0, 0, At, B0); PG8_MMA(0, 1, At, B1); PG8_BAR; PG8_SCHED;
;             PG8_LDA(At, 0, 1); PG8_STAGE(PG8_SB(0, 0), b2, voffB); PG8_STAGE(PG8_SB(0, 1), b2 + hB, voffB); PG8_STAGE(PG8_SA(0, 0), a2, voffA);
.LBB0_689:
	ds_read_b128 v[130:133], v210
	ds_read_b128 v[134:137], v210 offset:1024
	ds_read_b128 v[138:141], v210 offset:2048
	ds_read_b128 v[142:145], v210 offset:3072
	ds_read_b128 v[146:149], v211
	ds_read_b128 v[150:153], v211 offset:1024
	ds_read_b128 v[154:157], v211 offset:2048
	ds_read_b128 v[158:161], v211 offset:3072
	s_add_u32 s38, s36, 0xfff00080
	s_addc_u32 s39, s37, -1
	s_cmp_eq_u32 s61, 60
	s_cselect_b32 s41, s17, s39
	s_cselect_b32 s40, s20, s38
	s_cselect_b32 s39, s25, s60
	s_cselect_b32 s38, s27, s35
	v_lshl_add_u64 v[218:219], s[36:37], 0, v[188:189]
	s_add_i32 m0, s33, 0xc000
	ds_read_b128 v[162:165], v212
	ds_read_b128 v[166:169], v212 offset:1024
	ds_read_b128 v[170:173], v212 offset:2048
	ds_read_b128 v[174:177], v212 offset:3072
	ds_read_b128 v[194:197], v212 offset:4096
	ds_read_b128 v[198:201], v212 offset:5120
	ds_read_b128 v[202:205], v212 offset:6144
	ds_read_b128 v[214:217], v212 offset:7168
	global_load_lds_dwordx4 v[218:219], off
	v_lshl_add_u64 v[218:219], s[36:37], 0, v[186:187]
	s_add_i32 m0, s33, 0xe000
	s_nop 0
	global_load_lds_dwordx4 v[218:219], off
	s_waitcnt vmcnt(8)
	s_waitcnt lgkmcnt(0)
	s_setprio 1
	s_barrier
	v_mfma_f32_16x16x32_bf16 v[126:129], v[130:133], v[162:165], v[126:129]
	v_mfma_f32_16x16x32_bf16 v[122:125], v[138:141], v[162:165], v[122:125]
	v_mfma_f32_16x16x32_bf16 v[110:113], v[130:133], v[170:173], v[110:113]
	v_mfma_f32_16x16x32_bf16 v[106:109], v[138:141], v[170:173], v[106:109]
	v_mfma_f32_16x16x32_bf16 v[94:97], v[130:133], v[194:197], v[94:97]
	v_mfma_f32_16x16x32_bf16 v[90:93], v[138:141], v[194:197], v[90:93]
	v_mfma_f32_16x16x32_bf16 v[78:81], v[130:133], v[202:205], v[78:81]
	v_mfma_f32_16x16x32_bf16 v[74:77], v[138:141], v[202:205], v[74:77]
	v_mfma_f32_16x16x32_bf16 v[126:129], v[134:137], v[166:169], v[126:129]
	v_mfma_f32_16x16x32_bf16 v[122:125], v[142:145], v[166:169], v[122:125]
	v_mfma_f32_16x16x32_bf16 v[110:113], v[134:137], v[174:177], v[110:113]
	v_mfma_f32_16x16x32_bf16 v[106:109], v[142:145], v[174:177], v[106:109]
	v_mfma_f32_16x16x32_bf16 v[94:97], v[134:137], v[198:201], v[94:97]
	v_mfma_f32_16x16x32_bf16 v[90:93], v[142:145], v[198:201], v[90:93]
	v_mfma_f32_16x16x32_bf16 v[78:81], v[134:137], v[214:217], v[78:81]
	v_mfma_f32_16x16x32_bf16 v[74:77], v[142:145], v[214:217], v[74:77]
	v_mfma_f32_16x16x32_bf16 v[118:121], v[146:149], v[162:165], v[118:121]
	v_mfma_f32_16x16x32_bf16 v[114:117], v[154:157], v[162:165], v[114:117]
	v_mfma_f32_16x16x32_bf16 v[102:105], v[146:149], v[170:173], v[102:105]
	v_mfma_f32_16x16x32_bf16 v[98:101], v[154:157], v[170:173], v[98:101]
	v_mfma_f32_16x16x32_bf16 v[86:89], v[146:149], v[194:197], v[86:89]
	v_mfma_f32_16x16x32_bf16 v[82:85], v[154:157], v[194:197], v[82:85]
	v_mfma_f32_16x16x32_bf16 v[70:73], v[146:149], v[202:205], v[70:73]
	v_mfma_f32_16x16x32_bf16 v[66:69], v[154:157], v[202:205], v[66:69]
	v_mfma_f32_16x16x32_bf16 v[118:121], v[150:153], v[166:169], v[118:121]
	v_mfma_f32_16x16x32_bf16 v[114:117], v[158:161], v[166:169], v[114:117]
	v_mfma_f32_16x16x32_bf16 v[102:105], v[150:153], v[174:177], v[102:105]
	v_mfma_f32_16x16x32_bf16 v[98:101], v[158:161], v[174:177], v[98:101]
	v_mfma_f32_16x16x32_bf16 v[86:89], v[150:153], v[198:201], v[86:89]
	v_mfma_f32_16x16x32_bf16 v[82:85], v[158:161], v[198:201], v[82:85]
	v_mfma_f32_16x16x32_bf16 v[70:73], v[150:153], v[214:217], v[70:73]
	v_mfma_f32_16x16x32_bf16 v[66:69], v[158:161], v[214:217], v[66:69]
	s_barrier
	s_setprio 0
	s_add_i32 s62, s56, s19
	v_lshl_add_u64 v[218:219], s[38:39], 0, v[180:181]
	s_mov_b32 m0, s62
	ds_read_b128 v[162:165], v212 offset:16384
	ds_read_b128 v[166:169], v212 offset:17408
	ds_read_b128 v[170:173], v212 offset:18432
	ds_read_b128 v[174:177], v212 offset:19456
	ds_read_b128 v[194:197], v212 offset:20480
	ds_read_b128 v[198:201], v212 offset:21504
	ds_read_b128 v[202:205], v212 offset:22528
	ds_read_b128 v[214:217], v212 offset:23552
	global_load_lds_dwordx4 v[218:219], off
	s_add_i32 m0, s62, 0x2000
	s_add_u32 s62, s38, 0x100000
	v_lshl_add_u64 v[220:221], s[38:39], 0, v[184:185]
	s_addc_u32 s63, s39, 0
	s_add_i32 s64, s57, s19
	global_load_lds_dwordx4 v[220:221], off
	v_lshl_add_u64 v[222:223], s[62:63], 0, v[180:181]
	s_mov_b32 m0, s64
	v_lshl_add_u64 v[224:225], s[40:41], 0, v[182:183]
	global_load_lds_dwordx4 v[222:223], off
	v_lshl_add_u64 v[222:223], s[62:63], 0, v[184:185]
	s_add_i32 m0, s64, 0x2000
	s_nop 0
	global_load_lds_dwordx4 v[222:223], off
	v_lshl_add_u64 v[222:223], s[40:41], 0, v[178:179]
	s_mov_b32 m0, s33
	s_nop 0
	global_load_lds_dwordx4 v[222:223], off
	s_mov_b32 m0, s42
	s_nop 0
	global_load_lds_dwordx4 v[224:225], off
	s_waitcnt vmcnt(8)
	s_waitcnt lgkmcnt(0)
	s_setprio 1
	s_barrier
; #define PG8_STAGE(bufoff, gbase, voff) do { _Pragma("unroll") for (int _i = 0; _i < 2; ++_i) \
;         __builtin_amdgcn_global_load_lds((const unsigned*)((const char*)(gbase) + (voff)[_i]), (PG8_LAS unsigned*)(lds + (bufoff) + ldsw + _i * 8192), 16, 0, 0); } while (0)
; #define PG8_LDA(dst, b, h) do { _Pragma("unroll") for (int m = 0; m < 4; ++m) _Pragma("unroll") for (int k = 0; k < 2; ++k) dst[m][k] = *(const PG8_LAS bf16x8*)(lds + PG8_SA(b, h) + aoff + m * 2048 + k * 1024); } while (0)
; #define PG8_LDB(dst, b, h) do { _Pragma("unroll") for (int n = 0; n < 2; ++n) _Pragma("unroll") for (int k = 0; k < 2; ++k) dst[n][k] = *(const PG8_LAS bf16x8*)(lds + PG8_SB(b, h) + boff + n * 2048 + k * 1024); } while (0)
; #define PG8_WAIT_V(n) asm volatile("s_waitcnt vmcnt(" #n ")" ::: "memory")
; #define PG8_WAIT_L(n) asm volatile("s_waitcnt lgkmcnt(" #n ")" ::: "memory")
; #define PG8_BAR __builtin_amdgcn_s_barrier()
; #define PG8_SCHED __builtin_amdgcn_sched_barrier(0)
; template <class Epi, class Sched, bool ALIGN_EPI = false, bool SP2 = false, bool F8 = false>
; __device__ __forceinline__ void gemm_phase(PG8_LAS unsigned char* lds, const Gemm g, const Sched& S, const Epi& E) {
;     ...
;             PG8_WAIT_V(8); PG8_WAIT_L(0); PG8_BAR; PG8_MMA(1, 0, At, B0); PG8_MMA(1, 1, At, B1); PG8_BAR; PG8_SCHED;
;             PG8_LDB(B0, 1, 0); PG8_LDB(B1, 1, 1); PG8_SCHED; PG8_LDA(At, 1, 0); PG8_STAGE(PG8_SA(0, 1), a2 + hA, voffA);
;             PG8_WAIT_V(8); PG8_WAIT_L(0); PG8_BAR; PG8_MMA(0, 0, At, B0); PG8_MMA(0, 1, At, B1); PG8_BAR; PG8_SCHED;
	v_mfma_f32_16x16x32_bf16 v[62:65], v[130:133], v[162:165], v[62:65]
	v_mfma_f32_16x16x32_bf16 v[58:61], v[138:141], v[162:165], v[58:61]
	v_mfma_f32_16x16x32_bf16 v[46:49], v[130:133], v[170:173], v[46:49]
	v_mfma_f32_16x16x32_bf16 v[42:45], v[138:141], v[170:173], v[42:45]
	v_mfma_f32_16x16x32_bf16 v[30:33], v[130:133], v[194:197], v[30:33]
	v_mfma_f32_16x16x32_bf16 v[26:29], v[138:141], v[194:197], v[26:29]
	v_mfma_f32_16x16x32_bf16 v[14:17], v[130:133], v[202:205], v[14:17]
	v_mfma_f32_16x16x32_bf16 v[10:13], v[138:141], v[202:205], v[10:13]
	v_mfma_f32_16x16x32_bf16 v[62:65], v[134:137], v[166:169], v[62:65]
	v_mfma_f32_16x16x32_bf16 v[58:61], v[142:145], v[166:169], v[58:61]
	v_mfma_f32_16x16x32_bf16 v[46:49], v[134:137], v[174:177], v[46:49]
	v_mfma_f32_16x16x32_bf16 v[42:45], v[142:145], v[174:177], v[42:45]
	v_mfma_f32_16x16x32_bf16 v[30:33], v[134:137], v[198:201], v[30:33]
	v_mfma_f32_16x16x32_bf16 v[26:29], v[142:145], v[198:201], v[26:29]
	v_mfma_f32_16x16x32_bf16 v[14:17], v[134:137], v[214:217], v[14:17]
	v_mfma_f32_16x16x32_bf16 v[10:13], v[142:145], v[214:217], v[10:13]
	v_mfma_f32_16x16x32_bf16 v[54:57], v[146:149], v[162:165], v[54:57]
	v_mfma_f32_16x16x32_bf16 v[50:53], v[154:157], v[162:165], v[50:53]
	v_mfma_f32_16x16x32_bf16 v[38:41], v[146:149], v[170:173], v[38:41]
	v_mfma_f32_16x16x32_bf16 v[34:37], v[154:157], v[170:173], v[34:37]
	v_mfma_f32_16x16x32_bf16 v[22:25], v[146:149], v[194:197], v[22:25]
	v_mfma_f32_16x16x32_bf16 v[18:21], v[154:157], v[194:197], v[18:21]
	v_mfma_f32_16x16x32_bf16 v[6:9], v[146:149], v[202:205], v[6:9]
	v_mfma_f32_16x16x32_bf16 v[2:5], v[154:157], v[202:205], v[2:5]
	v_mfma_f32_16x16x32_bf16 v[54:57], v[150:153], v[166:169], v[54:57]
	v_mfma_f32_16x16x32_bf16 v[50:53], v[158:161], v[166:169], v[50:53]
	v_mfma_f32_16x16x32_bf16 v[38:41], v[150:153], v[174:177], v[38:41]
	v_mfma_f32_16x16x32_bf16 v[34:37], v[158:161], v[174:177], v[34:37]
	v_mfma_f32_16x16x32_bf16 v[22:25], v[150:153], v[198:201], v[22:25]
	v_mfma_f32_16x16x32_bf16 v[18:21], v[158:161], v[198:201], v[18:21]
	v_mfma_f32_16x16x32_bf16 v[6:9], v[150:153], v[214:217], v[6:9]
	v_mfma_f32_16x16x32_bf16 v[2:5], v[158:161], v[214:217], v[2:5]
	s_barrier
	s_setprio 0
	s_add_i32 s62, 0, 0x18000
	s_add_i32 s63, 0, 0x1c000
	v_add_u32_e32 v142, s62, v207
	v_add_u32_e32 v158, s63, v207
	ds_read_b128 v[130:133], v142
	ds_read_b128 v[134:137], v142 offset:1024
	ds_read_b128 v[138:141], v142 offset:2048
	ds_read_b128 v[142:145], v142 offset:3072
	ds_read_b128 v[146:149], v158
	ds_read_b128 v[150:153], v158 offset:1024
	ds_read_b128 v[154:157], v158 offset:2048
	ds_read_b128 v[158:161], v158 offset:3072
	s_add_u32 s40, s40, 0x100000
	s_addc_u32 s41, s41, 0
	s_mov_b32 m0, s43
	v_lshl_add_u64 v[226:227], s[40:41], 0, v[178:179]
	ds_read_b128 v[162:165], v212 offset:32768
	ds_read_b128 v[166:169], v212 offset:33792
	ds_read_b128 v[170:173], v212 offset:34816
	ds_read_b128 v[174:177], v212 offset:35840
	ds_read_b128 v[194:197], v212 offset:36864
	ds_read_b128 v[198:201], v212 offset:37888
	ds_read_b128 v[202:205], v212 offset:38912
	ds_read_b128 v[214:217], v212 offset:39936
	global_load_lds_dwordx4 v[226:227], off
	v_lshl_add_u64 v[226:227], s[40:41], 0, v[182:183]
	s_mov_b32 m0, s44
	s_nop 0
	global_load_lds_dwordx4 v[226:227], off
	s_waitcnt vmcnt(8)
	s_waitcnt lgkmcnt(0)
	s_setprio 1
	s_barrier
	v_mfma_f32_16x16x32_bf16 v[126:129], v[130:133], v[162:165], v[126:129]
	v_mfma_f32_16x16x32_bf16 v[122:125], v[138:141], v[162:165], v[122:125]
	v_mfma_f32_16x16x32_bf16 v[110:113], v[130:133], v[170:173], v[110:113]
	v_mfma_f32_16x16x32_bf16 v[106:109], v[138:141], v[170:173], v[106:109]
	v_mfma_f32_16x16x32_bf16 v[94:97], v[130:133], v[194:197], v[94:97]
	v_mfma_f32_16x16x32_bf16 v[90:93], v[138:141], v[194:197], v[90:93]
	v_mfma_f32_16x16x32_bf16 v[78:81], v[130:133], v[202:205], v[78:81]
	v_mfma_f32_16x16x32_bf16 v[74:77], v[138:141], v[202:205], v[74:77]
	v_mfma_f32_16x16x32_bf16 v[126:129], v[134:137], v[166:169], v[126:129]
	v_mfma_f32_16x16x32_bf16 v[122:125], v[142:145], v[166:169], v[122:125]
	v_mfma_f32_16x16x32_bf16 v[110:113], v[134:137], v[174:177], v[110:113]
	v_mfma_f32_16x16x32_bf16 v[106:109], v[142:145], v[174:177], v[106:109]
	v_mfma_f32_16x16x32_bf16 v[94:97], v[134:137], v[198:201], v[94:97]
	v_mfma_f32_16x16x32_bf16 v[90:93], v[142:145], v[198:201], v[90:93]
	v_mfma_f32_16x16x32_bf16 v[78:81], v[134:137], v[214:217], v[78:81]
	v_mfma_f32_16x16x32_bf16 v[74:77], v[142:145], v[214:217], v[74:77]
	v_mfma_f32_16x16x32_bf16 v[118:121], v[146:149], v[162:165], v[118:121]
	v_mfma_f32_16x16x32_bf16 v[114:117], v[154:157], v[162:165], v[114:117]
	v_mfma_f32_16x16x32_bf16 v[102:105], v[146:149], v[170:173], v[102:105]
	v_mfma_f32_16x16x32_bf16 v[98:101], v[154:157], v[170:173], v[98:101]
	v_mfma_f32_16x16x32_bf16 v[86:89], v[146:149], v[194:197], v[86:89]
	v_mfma_f32_16x16x32_bf16 v[82:85], v[154:157], v[194:197], v[82:85]
	v_mfma_f32_16x16x32_bf16 v[70:73], v[146:149], v[202:205], v[70:73]
	v_mfma_f32_16x16x32_bf16 v[66:69], v[154:157], v[202:205], v[66:69]
	v_mfma_f32_16x16x32_bf16 v[118:121], v[150:153], v[166:169], v[118:121]
	v_mfma_f32_16x16x32_bf16 v[114:117], v[158:161], v[166:169], v[114:117]
	v_mfma_f32_16x16x32_bf16 v[102:105], v[150:153], v[174:177], v[102:105]
	v_mfma_f32_16x16x32_bf16 v[98:101], v[158:161], v[174:177], v[98:101]
	v_mfma_f32_16x16x32_bf16 v[86:89], v[150:153], v[198:201], v[86:89]
	v_mfma_f32_16x16x32_bf16 v[82:85], v[158:161], v[198:201], v[82:85]
	v_mfma_f32_16x16x32_bf16 v[70:73], v[150:153], v[214:217], v[70:73]
	v_mfma_f32_16x16x32_bf16 v[66:69], v[158:161], v[214:217], v[66:69]
	s_barrier
; #define PG8_STAGE(bufoff, gbase, voff) do { _Pragma("unroll") for (int _i = 0; _i < 2; ++_i) \
;         __builtin_amdgcn_global_load_lds((const unsigned*)((const char*)(gbase) + (voff)[_i]), (PG8_LAS unsigned*)(lds + (bufoff) + ldsw + _i * 8192), 16, 0, 0); } while (0)
; #define PG8_LDA(dst, b, h) do { _Pragma("unroll") for (int m = 0; m < 4; ++m) _Pragma("unroll") for (int k = 0; k < 2; ++k) dst[m][k] = *(const PG8_LAS bf16x8*)(lds + PG8_SA(b, h) + aoff + m * 2048 + k * 1024); } while (0)
; #define PG8_WAIT_V(n) asm volatile("s_waitcnt vmcnt(" #n ")" ::: "memory")
; #define PG8_WAIT_L(n) asm volatile("s_waitcnt lgkmcnt(" #n ")" ::: "memory")
; #define PG8_BAR __builtin_amdgcn_s_barrier()
; #define PG8_SCHED __builtin_amdgcn_sched_barrier(0)
;     __device__ __forceinline__ void run(const f32x4 (&acc)[2][2][4][2], const Unit& un, int wr, int wc, int fr, int fq, PG8_LAS unsigned char* xl) const {
;     ...
;         const float* bs = un.pm < split_pm ? base + (size_t)un.pm * BM * 4096 : base2 + (size_t)(un.pm - split_pm) * BM * 4096;
; template <class Epi, class Sched, bool ALIGN_EPI = false, bool SP2 = false, bool F8 = false>
; __device__ __forceinline__ void gemm_phase(PG8_LAS unsigned char* lds, const Gemm g, const Sched& S, const Epi& E) {
;     ...
;         for (int t = 0; t < nt; t += 2) {
;             const bool last = (t == nt - 2);
;             const char* a1 = cA + (size_t)(t + 1) * kstep;
;             const char* a2 = last ? nA : cA + (size_t)(t + 2) * kstep; const char* b2 = last ? nB : cB + (size_t)(t + 2) * kstep;
;     ...
;             PG8_LDA(At, 1, 1); PG8_STAGE(PG8_SB(1, 0), b3, voffB); PG8_STAGE(PG8_SB(1, 1), b3 + hB, voffB); PG8_STAGE(PG8_SA(1, 0), a3, voffA);
;             PG8_WAIT_V(8); PG8_WAIT_L(0); PG8_BAR; PG8_MMA(1, 0, At, B0); PG8_MMA(1, 1, At, B1); PG8_BAR; PG8_SCHED;
	s_setprio 0
	s_add_i32 s40, s62, s19
	v_lshl_add_u64 v[218:219], v[218:219], 0, s[22:23]
	s_mov_b32 m0, s40
	ds_read_b128 v[162:165], v212 offset:49152
	ds_read_b128 v[166:169], v212 offset:50176
	ds_read_b128 v[170:173], v212 offset:51200
	ds_read_b128 v[174:177], v212 offset:52224
	ds_read_b128 v[194:197], v212 offset:53248
	ds_read_b128 v[198:201], v212 offset:54272
	ds_read_b128 v[202:205], v212 offset:55296
	ds_read_b128 v[214:217], v212 offset:56320
	global_load_lds_dwordx4 v[218:219], off
	s_add_i32 m0, s40, 0x2000
	s_add_u32 s38, s38, 0x100080
	v_lshl_add_u64 v[218:219], v[220:221], 0, s[22:23]
	s_addc_u32 s39, s39, 0
	s_add_i32 s40, s63, s19
	global_load_lds_dwordx4 v[218:219], off
	v_lshl_add_u64 v[218:219], s[38:39], 0, v[180:181]
	s_mov_b32 m0, s40
	s_nop 0
	global_load_lds_dwordx4 v[218:219], off
	v_lshl_add_u64 v[218:219], s[38:39], 0, v[184:185]
	s_add_i32 m0, s40, 0x2000
	s_nop 0
	global_load_lds_dwordx4 v[218:219], off
	v_lshl_add_u64 v[218:219], v[222:223], 0, s[22:23]
	s_mov_b32 m0, s50
	s_nop 0
	global_load_lds_dwordx4 v[218:219], off
	v_lshl_add_u64 v[218:219], v[224:225], 0, s[22:23]
	s_mov_b32 m0, s51
	s_nop 0
	global_load_lds_dwordx4 v[218:219], off
	s_waitcnt vmcnt(8)
	s_waitcnt lgkmcnt(0)
	s_setprio 1
	s_barrier
	v_mfma_f32_16x16x32_bf16 v[62:65], v[130:133], v[162:165], v[62:65]
	v_mfma_f32_16x16x32_bf16 v[58:61], v[138:141], v[162:165], v[58:61]
	v_mfma_f32_16x16x32_bf16 v[46:49], v[130:133], v[170:173], v[46:49]
	v_mfma_f32_16x16x32_bf16 v[42:45], v[138:141], v[170:173], v[42:45]
	v_mfma_f32_16x16x32_bf16 v[30:33], v[130:133], v[194:197], v[30:33]
	v_mfma_f32_16x16x32_bf16 v[26:29], v[138:141], v[194:197], v[26:29]
	v_mfma_f32_16x16x32_bf16 v[14:17], v[130:133], v[202:205], v[14:17]
	v_mfma_f32_16x16x32_bf16 v[10:13], v[138:141], v[202:205], v[10:13]
	v_mfma_f32_16x16x32_bf16 v[62:65], v[134:137], v[166:169], v[62:65]
	v_mfma_f32_16x16x32_bf16 v[58:61], v[142:145], v[166:169], v[58:61]
	v_mfma_f32_16x16x32_bf16 v[46:49], v[134:137], v[174:177], v[46:49]
	v_mfma_f32_16x16x32_bf16 v[42:45], v[142:145], v[174:177], v[42:45]
	v_mfma_f32_16x16x32_bf16 v[30:33], v[134:137], v[198:201], v[30:33]
	v_mfma_f32_16x16x32_bf16 v[26:29], v[142:145], v[198:201], v[26:29]
	v_mfma_f32_16x16x32_bf16 v[14:17], v[134:137], v[214:217], v[14:17]
	v_mfma_f32_16x16x32_bf16 v[10:13], v[142:145], v[214:217], v[10:13]
	v_mfma_f32_16x16x32_bf16 v[54:57], v[146:149], v[162:165], v[54:57]
	v_mfma_f32_16x16x32_bf16 v[50:53], v[154:157], v[162:165], v[50:53]
	v_mfma_f32_16x16x32_bf16 v[38:41], v[146:149], v[170:173], v[38:41]
	v_mfma_f32_16x16x32_bf16 v[34:37], v[154:157], v[170:173], v[34:37]
	v_mfma_f32_16x16x32_bf16 v[22:25], v[146:149], v[194:197], v[22:25]
	v_mfma_f32_16x16x32_bf16 v[18:21], v[154:157], v[194:197], v[18:21]
	v_mfma_f32_16x16x32_bf16 v[6:9], v[146:149], v[202:205], v[6:9]
	v_mfma_f32_16x16x32_bf16 v[2:5], v[154:157], v[202:205], v[2:5]
	v_mfma_f32_16x16x32_bf16 v[54:57], v[150:153], v[166:169], v[54:57]
	v_mfma_f32_16x16x32_bf16 v[50:53], v[158:161], v[166:169], v[50:53]
	v_mfma_f32_16x16x32_bf16 v[38:41], v[150:153], v[174:177], v[38:41]
	v_mfma_f32_16x16x32_bf16 v[34:37], v[158:161], v[174:177], v[34:37]
	v_mfma_f32_16x16x32_bf16 v[22:25], v[150:153], v[198:201], v[22:25]
	v_mfma_f32_16x16x32_bf16 v[18:21], v[158:161], v[198:201], v[18:21]
	v_mfma_f32_16x16x32_bf16 v[6:9], v[150:153], v[214:217], v[6:9]
	v_mfma_f32_16x16x32_bf16 v[2:5], v[158:161], v[214:217], v[2:5]
	s_add_i32 s61, s61, 2
	s_add_u32 s35, s35, 0x100
	s_addc_u32 s60, s60, 0
	s_add_u32 s36, s36, 0x100
	s_addc_u32 s37, s37, 0
	s_cmp_gt_u32 s61, 61
	s_cbranch_scc0 .Lber_689
	s_barrier
	s_setprio 0
	v_mov_b32_e32 v214, v206
	s_cmp_gt_i32 s16, 63
	s_mov_b64 s[38:39], -1
	s_cbranch_scc0 .LBB0_692
	s_sub_i32 s20, s16, 64
	s_lshl_b64 s[36:37], s[20:21], 22
	s_add_u32 s36, s14, s36
	s_addc_u32 s37, s15, s37
	s_mov_b32 s17, s21
	s_mov_b64 s[38:39], 0

; template <class Epi, class Sched, bool ALIGN_EPI = false, bool SP2 = false, bool F8 = false>
; __device__ __forceinline__ void gemm_phase(PG8_LAS unsigned char* lds, const Gemm g, const Sched& S, const Epi& E) {
;     ...
;         const bool has_next = S.next(ui + 1, nxt);
;         const char* nA = has_next ? (const char*)g.A + (size_t)nxt.pm * tA + (size_t)(nxt.pn >> g.gshift) * g.goff : cA; const char* nB = has_next ? (const char*)g.Bt + (size_t)nxt.pn * tB : cB;
;     ...
; #pragma unroll
;         for (int a = 0; a < 2; ++a)
; #pragma unroll
;             for (int b = 0; b < 2; ++b)
; #pragma unroll
;                 for (int m = 0; m < 4; ++m)
; #pragma unroll
;                     for (int n = 0; n < 2; ++n) acc[a][b][m][n] = (f32x4){0.f, 0.f, 0.f, 0.f};
.LBB0_769:
	s_ashr_i32 s63, s62, 31
	s_lshl_b64 s[16:17], s[62:63], 21
	s_add_u32 s64, s85, s16
	s_addc_u32 s65, s87, s17
	s_and_b64 s[16:17], s[8:9], exec
	s_cselect_b32 s11, s65, s15
	s_cselect_b32 s63, s64, s14
	s_ashr_i32 s61, s60, 31
	s_lshl_b64 s[16:17], s[60:61], 21
	s_add_u32 s66, s88, s16
	s_addc_u32 s67, s89, s17
	s_and_b64 s[16:17], s[8:9], exec
	s_cselect_b32 s61, s67, s13
	s_cselect_b32 s77, s66, s12
	s_add_u32 s78, s12, 0x100
	s_addc_u32 s79, s13, 0
	s_add_u32 s12, s14, 0x100080
	v_mov_b32_e32 v66, 0
	s_addc_u32 s13, s15, 0
	s_mov_b32 s80, -2
	v_mov_b32_e32 v67, v66
	v_mov_b32_e32 v68, v66
	v_mov_b32_e32 v69, v66
	v_mov_b32_e32 v58, v66
	v_mov_b32_e32 v59, v66
	v_mov_b32_e32 v60, v66
	v_mov_b32_e32 v61, v66
	v_mov_b32_e32 v22, v66
	v_mov_b32_e32 v23, v66
	v_mov_b32_e32 v24, v66
	v_mov_b32_e32 v25, v66
	v_mov_b32_e32 v18, v66
	v_mov_b32_e32 v19, v66
	v_mov_b32_e32 v20, v66
	v_mov_b32_e32 v21, v66
	v_mov_b32_e32 v54, v66
	v_mov_b32_e32 v55, v66
	v_mov_b32_e32 v56, v66
	v_mov_b32_e32 v57, v66
	v_mov_b32_e32 v2, v66
	v_mov_b32_e32 v3, v66
	v_mov_b32_e32 v4, v66
	v_mov_b32_e32 v5, v66
	v_mov_b32_e32 v26, v66
	v_mov_b32_e32 v27, v66
	v_mov_b32_e32 v28, v66
	v_mov_b32_e32 v29, v66
	v_mov_b32_e32 v6, v66
	v_mov_b32_e32 v7, v66
	v_mov_b32_e32 v8, v66
	v_mov_b32_e32 v9, v66
	v_mov_b32_e32 v30, v66
	v_mov_b32_e32 v31, v66
	v_mov_b32_e32 v32, v66
	v_mov_b32_e32 v33, v66
	v_mov_b32_e32 v46, v66
	v_mov_b32_e32 v47, v66
	v_mov_b32_e32 v48, v66
	v_mov_b32_e32 v49, v66
	v_mov_b32_e32 v114, v66
	v_mov_b32_e32 v115, v66
	v_mov_b32_e32 v116, v66
	v_mov_b32_e32 v117, v66
	v_mov_b32_e32 v50, v66
	v_mov_b32_e32 v51, v66
	v_mov_b32_e32 v52, v66
	v_mov_b32_e32 v53, v66
	v_mov_b32_e32 v10, v66
	v_mov_b32_e32 v11, v66
	v_mov_b32_e32 v12, v66
	v_mov_b32_e32 v13, v66
	v_mov_b32_e32 v34, v66
	v_mov_b32_e32 v35, v66
	v_mov_b32_e32 v36, v66
	v_mov_b32_e32 v37, v66
	v_mov_b32_e32 v14, v66
	v_mov_b32_e32 v15, v66
	v_mov_b32_e32 v16, v66
	v_mov_b32_e32 v17, v66
	v_mov_b32_e32 v42, v66
	v_mov_b32_e32 v43, v66
	v_mov_b32_e32 v44, v66
	v_mov_b32_e32 v45, v66
	v_mov_b32_e32 v38, v66
	v_mov_b32_e32 v39, v66
	v_mov_b32_e32 v40, v66
	v_mov_b32_e32 v41, v66
	v_mov_b32_e32 v62, v66
	v_mov_b32_e32 v63, v66
	v_mov_b32_e32 v64, v66
	v_mov_b32_e32 v65, v66
	v_mov_b32_e32 v70, v66
	v_mov_b32_e32 v71, v66
	v_mov_b32_e32 v72, v66
	v_mov_b32_e32 v73, v66
	v_mov_b32_e32 v74, v66
	v_mov_b32_e32 v75, v66
	v_mov_b32_e32 v76, v66
	v_mov_b32_e32 v77, v66
	v_mov_b32_e32 v98, v66
	v_mov_b32_e32 v99, v66
	v_mov_b32_e32 v100, v66
	v_mov_b32_e32 v101, v66
	v_mov_b32_e32 v78, v66
	v_mov_b32_e32 v79, v66
	v_mov_b32_e32 v80, v66
	v_mov_b32_e32 v81, v66
	v_mov_b32_e32 v102, v66
	v_mov_b32_e32 v103, v66
	v_mov_b32_e32 v104, v66
	v_mov_b32_e32 v105, v66
	v_mov_b32_e32 v94, v66
	v_mov_b32_e32 v95, v66
	v_mov_b32_e32 v96, v66
	v_mov_b32_e32 v97, v66
	v_mov_b32_e32 v122, v66
	v_mov_b32_e32 v123, v66
	v_mov_b32_e32 v124, v66
	v_mov_b32_e32 v125, v66
	v_mov_b32_e32 v118, v66
	v_mov_b32_e32 v119, v66
	v_mov_b32_e32 v120, v66
	v_mov_b32_e32 v121, v66
	v_mov_b32_e32 v82, v66
	v_mov_b32_e32 v83, v66
	v_mov_b32_e32 v84, v66
	v_mov_b32_e32 v85, v66
	v_mov_b32_e32 v106, v66
	v_mov_b32_e32 v107, v66
	v_mov_b32_e32 v108, v66
	v_mov_b32_e32 v109, v66
	v_mov_b32_e32 v86, v66
	v_mov_b32_e32 v87, v66
	v_mov_b32_e32 v88, v66
	v_mov_b32_e32 v89, v66
	v_mov_b32_e32 v110, v66
	v_mov_b32_e32 v111, v66
	v_mov_b32_e32 v112, v66
	v_mov_b32_e32 v113, v66
	v_mov_b32_e32 v90, v66
	v_mov_b32_e32 v91, v66
	v_mov_b32_e32 v92, v66
	v_mov_b32_e32 v93, v66
	v_mov_b32_e32 v126, v66
	v_mov_b32_e32 v127, v66
	v_mov_b32_e32 v128, v66
	v_mov_b32_e32 v129, v66
	s_branch .LBB0_770

; #define PG8_STAGE(bufoff, gbase, voff) do { _Pragma("unroll") for (int _i = 0; _i < 2; ++_i) \
;         __builtin_amdgcn_global_load_lds((const unsigned*)((const char*)(gbase) + (voff)[_i]), (PG8_LAS unsigned*)(lds + (bufoff) + ldsw + _i * 8192), 16, 0, 0); } while (0)
; #define PG8_LDA(dst, b, h) do { _Pragma("unroll") for (int m = 0; m < 4; ++m) _Pragma("unroll") for (int k = 0; k < 2; ++k) dst[m][k] = *(const PG8_LAS bf16x8*)(lds + PG8_SA(b, h) + aoff + m * 2048 + k * 1024); } while (0)
; #define PG8_LDB(dst, b, h) do { _Pragma("unroll") for (int n = 0; n < 2; ++n) _Pragma("unroll") for (int k = 0; k < 2; ++k) dst[n][k] = *(const PG8_LAS bf16x8*)(lds + PG8_SB(b, h) + boff + n * 2048 + k * 1024); } while (0)
; #define PG8_WAIT_V(n) asm volatile("s_waitcnt vmcnt(" #n ")" ::: "memory")
; #define PG8_WAIT_L(n) asm volatile("s_waitcnt lgkmcnt(" #n ")" ::: "memory")
; #define PG8_BAR __builtin_amdgcn_s_barrier()
; #define PG8_SCHED __builtin_amdgcn_sched_barrier(0)
; template <class Epi, class Sched, bool ALIGN_EPI = false, bool SP2 = false, bool F8 = false>
; __device__ __forceinline__ void gemm_phase(PG8_LAS unsigned char* lds, const Gemm g, const Sched& S, const Epi& E) {
;     ...
;             PG8_LDB(B0, 0, 0); PG8_LDB(B1, 0, 1); PG8_SCHED; PG8_LDA(At, 0, 0); PG8_STAGE(PG8_SA(1, 1), a1 + hA, voffA);
;             PG8_WAIT_V(8); PG8_WAIT_L(0); PG8_BAR; PG8_MMA(0, 0, At, B0); PG8_MMA(0, 1, At, B1); PG8_BAR; PG8_SCHED;
;             PG8_LDA(At, 0, 1); PG8_STAGE(PG8_SB(0, 0), b2, voffB); PG8_STAGE(PG8_SB(0, 1), b2 + hB, voffB); PG8_STAGE(PG8_SA(0, 0), a2, voffA);
.LBB0_770:
	ds_read_b128 v[130:133], v241
	ds_read_b128 v[134:137], v241 offset:1024
	ds_read_b128 v[138:141], v241 offset:2048
	ds_read_b128 v[142:145], v241 offset:3072
	ds_read_b128 v[146:149], v242
	ds_read_b128 v[150:153], v242 offset:1024
	ds_read_b128 v[154:157], v242 offset:2048
	ds_read_b128 v[158:161], v242 offset:3072
	s_add_u32 s14, s12, 0xfff00080
	s_addc_u32 s15, s13, -1
	s_cmp_eq_u32 s80, 60
	s_cselect_b32 s17, s11, s15
	s_cselect_b32 s16, s63, s14
	s_cselect_b32 s15, s61, s79
	s_cselect_b32 s14, s77, s78
	v_lshl_add_u64 v[208:209], s[12:13], 0, v[188:189]
	s_add_i32 m0, s7, 0xc000
	ds_read_b128 v[162:165], v243
	ds_read_b128 v[166:169], v243 offset:1024
	ds_read_b128 v[170:173], v243 offset:2048
	ds_read_b128 v[174:177], v243 offset:3072
	ds_read_b128 v[192:195], v243 offset:4096
	ds_read_b128 v[196:199], v243 offset:5120
	ds_read_b128 v[200:203], v243 offset:6144
	ds_read_b128 v[204:207], v243 offset:7168
	global_load_lds_dwordx4 v[208:209], off
	v_lshl_add_u64 v[208:209], s[12:13], 0, v[186:187]
	s_add_i32 m0, s7, 0xe000
	s_nop 0
	global_load_lds_dwordx4 v[208:209], off
	s_waitcnt vmcnt(8)
	s_waitcnt lgkmcnt(0)
	s_setprio 1
	s_barrier
	v_mfma_f32_16x16x32_bf16 v[126:129], v[130:133], v[162:165], v[126:129]
	v_mfma_f32_16x16x32_bf16 v[90:93], v[138:141], v[162:165], v[90:93]
	v_mfma_f32_16x16x32_bf16 v[110:113], v[130:133], v[170:173], v[110:113]
	v_mfma_f32_16x16x32_bf16 v[86:89], v[138:141], v[170:173], v[86:89]
	v_mfma_f32_16x16x32_bf16 v[106:109], v[130:133], v[192:195], v[106:109]
	v_mfma_f32_16x16x32_bf16 v[82:85], v[138:141], v[192:195], v[82:85]
	v_mfma_f32_16x16x32_bf16 v[118:121], v[130:133], v[200:203], v[118:121]
	v_mfma_f32_16x16x32_bf16 v[122:125], v[138:141], v[200:203], v[122:125]
	v_mfma_f32_16x16x32_bf16 v[126:129], v[134:137], v[166:169], v[126:129]
	v_mfma_f32_16x16x32_bf16 v[90:93], v[142:145], v[166:169], v[90:93]
	v_mfma_f32_16x16x32_bf16 v[110:113], v[134:137], v[174:177], v[110:113]
	v_mfma_f32_16x16x32_bf16 v[86:89], v[142:145], v[174:177], v[86:89]
	v_mfma_f32_16x16x32_bf16 v[106:109], v[134:137], v[196:199], v[106:109]
	v_mfma_f32_16x16x32_bf16 v[82:85], v[142:145], v[196:199], v[82:85]
	v_mfma_f32_16x16x32_bf16 v[118:121], v[134:137], v[204:207], v[118:121]
	v_mfma_f32_16x16x32_bf16 v[122:125], v[142:145], v[204:207], v[122:125]
	v_mfma_f32_16x16x32_bf16 v[94:97], v[146:149], v[162:165], v[94:97]
	v_mfma_f32_16x16x32_bf16 v[66:69], v[154:157], v[162:165], v[66:69]
	v_mfma_f32_16x16x32_bf16 v[102:105], v[146:149], v[170:173], v[102:105]
	v_mfma_f32_16x16x32_bf16 v[78:81], v[154:157], v[170:173], v[78:81]
	v_mfma_f32_16x16x32_bf16 v[98:101], v[146:149], v[192:195], v[98:101]
	v_mfma_f32_16x16x32_bf16 v[74:77], v[154:157], v[192:195], v[74:77]
	v_mfma_f32_16x16x32_bf16 v[70:73], v[146:149], v[200:203], v[70:73]
	v_mfma_f32_16x16x32_bf16 v[58:61], v[154:157], v[200:203], v[58:61]
	v_mfma_f32_16x16x32_bf16 v[94:97], v[150:153], v[166:169], v[94:97]
	v_mfma_f32_16x16x32_bf16 v[66:69], v[158:161], v[166:169], v[66:69]
	v_mfma_f32_16x16x32_bf16 v[102:105], v[150:153], v[174:177], v[102:105]
	v_mfma_f32_16x16x32_bf16 v[78:81], v[158:161], v[174:177], v[78:81]
	v_mfma_f32_16x16x32_bf16 v[98:101], v[150:153], v[196:199], v[98:101]
	v_mfma_f32_16x16x32_bf16 v[74:77], v[158:161], v[196:199], v[74:77]
	v_mfma_f32_16x16x32_bf16 v[70:73], v[150:153], v[204:207], v[70:73]
	v_mfma_f32_16x16x32_bf16 v[58:61], v[158:161], v[204:207], v[58:61]
	s_barrier
	s_setprio 0
	s_add_i32 s81, s97, s6
	v_lshl_add_u64 v[208:209], s[14:15], 0, v[180:181]
	s_mov_b32 m0, s81
	ds_read_b128 v[162:165], v243 offset:16384
	ds_read_b128 v[166:169], v243 offset:17408
	ds_read_b128 v[170:173], v243 offset:18432
	ds_read_b128 v[174:177], v243 offset:19456
	ds_read_b128 v[192:195], v243 offset:20480
	ds_read_b128 v[196:199], v243 offset:21504
	ds_read_b128 v[200:203], v243 offset:22528
	ds_read_b128 v[204:207], v243 offset:23552
	global_load_lds_dwordx4 v[208:209], off
	s_add_i32 m0, s81, 0x2000
	s_add_u32 vcc_lo, s14, 0x100000
	v_lshl_add_u64 v[210:211], s[14:15], 0, v[184:185]
	s_addc_u32 vcc_hi, s15, 0
	s_add_i32 s81, s86, s6
	global_load_lds_dwordx4 v[210:211], off
	v_lshl_add_u64 v[212:213], vcc, 0, v[180:181]
	s_mov_b32 m0, s81
	v_lshl_add_u64 v[214:215], s[16:17], 0, v[182:183]
	global_load_lds_dwordx4 v[212:213], off
	v_lshl_add_u64 v[212:213], vcc, 0, v[184:185]
	s_add_i32 m0, s81, 0x2000
	s_nop 0
	global_load_lds_dwordx4 v[212:213], off
	v_lshl_add_u64 v[212:213], s[16:17], 0, v[178:179]
	s_mov_b32 m0, s7
	s_nop 0
	global_load_lds_dwordx4 v[212:213], off
	s_mov_b32 m0, s18
	s_nop 0
	global_load_lds_dwordx4 v[214:215], off
	s_waitcnt vmcnt(8)
	s_waitcnt lgkmcnt(0)
	s_setprio 1
	s_barrier
; #define PG8_STAGE(bufoff, gbase, voff) do { _Pragma("unroll") for (int _i = 0; _i < 2; ++_i) \
;         __builtin_amdgcn_global_load_lds((const unsigned*)((const char*)(gbase) + (voff)[_i]), (PG8_LAS unsigned*)(lds + (bufoff) + ldsw + _i * 8192), 16, 0, 0); } while (0)
; #define PG8_LDA(dst, b, h) do { _Pragma("unroll") for (int m = 0; m < 4; ++m) _Pragma("unroll") for (int k = 0; k < 2; ++k) dst[m][k] = *(const PG8_LAS bf16x8*)(lds + PG8_SA(b, h) + aoff + m * 2048 + k * 1024); } while (0)
; #define PG8_LDB(dst, b, h) do { _Pragma("unroll") for (int n = 0; n < 2; ++n) _Pragma("unroll") for (int k = 0; k < 2; ++k) dst[n][k] = *(const PG8_LAS bf16x8*)(lds + PG8_SB(b, h) + boff + n * 2048 + k * 1024); } while (0)
; #define PG8_WAIT_V(n) asm volatile("s_waitcnt vmcnt(" #n ")" ::: "memory")
; #define PG8_WAIT_L(n) asm volatile("s_waitcnt lgkmcnt(" #n ")" ::: "memory")
; #define PG8_BAR __builtin_amdgcn_s_barrier()
; #define PG8_SCHED __builtin_amdgcn_sched_barrier(0)
; template <class Epi, class Sched, bool ALIGN_EPI = false, bool SP2 = false, bool F8 = false>
; __device__ __forceinline__ void gemm_phase(PG8_LAS unsigned char* lds, const Gemm g, const Sched& S, const Epi& E) {
;     ...
;             PG8_WAIT_V(8); PG8_WAIT_L(0); PG8_BAR; PG8_MMA(1, 0, At, B0); PG8_MMA(1, 1, At, B1); PG8_BAR; PG8_SCHED;
;             PG8_LDB(B0, 1, 0); PG8_LDB(B1, 1, 1); PG8_SCHED; PG8_LDA(At, 1, 0); PG8_STAGE(PG8_SA(0, 1), a2 + hA, voffA);
;             PG8_WAIT_V(8); PG8_WAIT_L(0); PG8_BAR; PG8_MMA(0, 0, At, B0); PG8_MMA(0, 1, At, B1); PG8_BAR; PG8_SCHED;
	v_mfma_f32_16x16x32_bf16 v[62:65], v[130:133], v[162:165], v[62:65]
	v_mfma_f32_16x16x32_bf16 v[38:41], v[138:141], v[162:165], v[38:41]
	v_mfma_f32_16x16x32_bf16 v[42:45], v[130:133], v[170:173], v[42:45]
	v_mfma_f32_16x16x32_bf16 v[14:17], v[138:141], v[170:173], v[14:17]
	v_mfma_f32_16x16x32_bf16 v[34:37], v[130:133], v[192:195], v[34:37]
	v_mfma_f32_16x16x32_bf16 v[10:13], v[138:141], v[192:195], v[10:13]
	v_mfma_f32_16x16x32_bf16 v[50:53], v[130:133], v[200:203], v[50:53]
	v_mfma_f32_16x16x32_bf16 v[114:117], v[138:141], v[200:203], v[114:117]
	v_mfma_f32_16x16x32_bf16 v[62:65], v[134:137], v[166:169], v[62:65]
	v_mfma_f32_16x16x32_bf16 v[38:41], v[142:145], v[166:169], v[38:41]
	v_mfma_f32_16x16x32_bf16 v[42:45], v[134:137], v[174:177], v[42:45]
	v_mfma_f32_16x16x32_bf16 v[14:17], v[142:145], v[174:177], v[14:17]
	v_mfma_f32_16x16x32_bf16 v[34:37], v[134:137], v[196:199], v[34:37]
	v_mfma_f32_16x16x32_bf16 v[10:13], v[142:145], v[196:199], v[10:13]
	v_mfma_f32_16x16x32_bf16 v[50:53], v[134:137], v[204:207], v[50:53]
	v_mfma_f32_16x16x32_bf16 v[114:117], v[142:145], v[204:207], v[114:117]
	v_mfma_f32_16x16x32_bf16 v[46:49], v[146:149], v[162:165], v[46:49]
	v_mfma_f32_16x16x32_bf16 v[22:25], v[154:157], v[162:165], v[22:25]
	v_mfma_f32_16x16x32_bf16 v[30:33], v[146:149], v[170:173], v[30:33]
	v_mfma_f32_16x16x32_bf16 v[6:9], v[154:157], v[170:173], v[6:9]
	v_mfma_f32_16x16x32_bf16 v[26:29], v[146:149], v[192:195], v[26:29]
	v_mfma_f32_16x16x32_bf16 v[2:5], v[154:157], v[192:195], v[2:5]
	v_mfma_f32_16x16x32_bf16 v[54:57], v[146:149], v[200:203], v[54:57]
	v_mfma_f32_16x16x32_bf16 v[18:21], v[154:157], v[200:203], v[18:21]
	v_mfma_f32_16x16x32_bf16 v[46:49], v[150:153], v[166:169], v[46:49]
	v_mfma_f32_16x16x32_bf16 v[22:25], v[158:161], v[166:169], v[22:25]
	v_mfma_f32_16x16x32_bf16 v[30:33], v[150:153], v[174:177], v[30:33]
	v_mfma_f32_16x16x32_bf16 v[6:9], v[158:161], v[174:177], v[6:9]
	v_mfma_f32_16x16x32_bf16 v[26:29], v[150:153], v[196:199], v[26:29]
	v_mfma_f32_16x16x32_bf16 v[2:5], v[158:161], v[196:199], v[2:5]
	v_mfma_f32_16x16x32_bf16 v[54:57], v[150:153], v[204:207], v[54:57]
	v_mfma_f32_16x16x32_bf16 v[18:21], v[158:161], v[204:207], v[18:21]
	s_barrier
	s_setprio 0
	s_add_i32 s81, 0, 0x18000
	s_add_i32 vcc_lo, 0, 0x1c000
	v_add_u32_e32 v142, s81, v240
	v_add_u32_e32 v158, vcc_lo, v240
	ds_read_b128 v[130:133], v142
	ds_read_b128 v[134:137], v142 offset:1024
	ds_read_b128 v[138:141], v142 offset:2048
	ds_read_b128 v[142:145], v142 offset:3072
	ds_read_b128 v[146:149], v158
	ds_read_b128 v[150:153], v158 offset:1024
	ds_read_b128 v[154:157], v158 offset:2048
	ds_read_b128 v[158:161], v158 offset:3072
	s_add_u32 s16, s16, 0x100000
	s_addc_u32 s17, s17, 0
	s_mov_b32 m0, s19
	v_lshl_add_u64 v[216:217], s[16:17], 0, v[178:179]
	ds_read_b128 v[162:165], v243 offset:32768
	ds_read_b128 v[166:169], v243 offset:33792
	ds_read_b128 v[170:173], v243 offset:34816
	ds_read_b128 v[174:177], v243 offset:35840
	ds_read_b128 v[192:195], v243 offset:36864
	ds_read_b128 v[196:199], v243 offset:37888
	ds_read_b128 v[200:203], v243 offset:38912
	ds_read_b128 v[204:207], v243 offset:39936
	global_load_lds_dwordx4 v[216:217], off
	v_lshl_add_u64 v[216:217], s[16:17], 0, v[182:183]
	s_mov_b32 m0, s33
	s_nop 0
	global_load_lds_dwordx4 v[216:217], off
	s_waitcnt vmcnt(8)
	s_waitcnt lgkmcnt(0)
	s_setprio 1
	s_barrier
	v_mfma_f32_16x16x32_bf16 v[126:129], v[130:133], v[162:165], v[126:129]
	v_mfma_f32_16x16x32_bf16 v[90:93], v[138:141], v[162:165], v[90:93]
	v_mfma_f32_16x16x32_bf16 v[110:113], v[130:133], v[170:173], v[110:113]
	v_mfma_f32_16x16x32_bf16 v[86:89], v[138:141], v[170:173], v[86:89]
	v_mfma_f32_16x16x32_bf16 v[106:109], v[130:133], v[192:195], v[106:109]
	v_mfma_f32_16x16x32_bf16 v[82:85], v[138:141], v[192:195], v[82:85]
	v_mfma_f32_16x16x32_bf16 v[118:121], v[130:133], v[200:203], v[118:121]
	v_mfma_f32_16x16x32_bf16 v[122:125], v[138:141], v[200:203], v[122:125]
	v_mfma_f32_16x16x32_bf16 v[126:129], v[134:137], v[166:169], v[126:129]
	v_mfma_f32_16x16x32_bf16 v[90:93], v[142:145], v[166:169], v[90:93]
	v_mfma_f32_16x16x32_bf16 v[110:113], v[134:137], v[174:177], v[110:113]
	v_mfma_f32_16x16x32_bf16 v[86:89], v[142:145], v[174:177], v[86:89]
	v_mfma_f32_16x16x32_bf16 v[106:109], v[134:137], v[196:199], v[106:109]
	v_mfma_f32_16x16x32_bf16 v[82:85], v[142:145], v[196:199], v[82:85]
	v_mfma_f32_16x16x32_bf16 v[118:121], v[134:137], v[204:207], v[118:121]
	v_mfma_f32_16x16x32_bf16 v[122:125], v[142:145], v[204:207], v[122:125]
	v_mfma_f32_16x16x32_bf16 v[94:97], v[146:149], v[162:165], v[94:97]
	v_mfma_f32_16x16x32_bf16 v[66:69], v[154:157], v[162:165], v[66:69]
	v_mfma_f32_16x16x32_bf16 v[102:105], v[146:149], v[170:173], v[102:105]
	v_mfma_f32_16x16x32_bf16 v[78:81], v[154:157], v[170:173], v[78:81]
	v_mfma_f32_16x16x32_bf16 v[98:101], v[146:149], v[192:195], v[98:101]
	v_mfma_f32_16x16x32_bf16 v[74:77], v[154:157], v[192:195], v[74:77]
	v_mfma_f32_16x16x32_bf16 v[70:73], v[146:149], v[200:203], v[70:73]
	v_mfma_f32_16x16x32_bf16 v[58:61], v[154:157], v[200:203], v[58:61]
	v_mfma_f32_16x16x32_bf16 v[94:97], v[150:153], v[166:169], v[94:97]
	v_mfma_f32_16x16x32_bf16 v[66:69], v[158:161], v[166:169], v[66:69]
	v_mfma_f32_16x16x32_bf16 v[102:105], v[150:153], v[174:177], v[102:105]
	v_mfma_f32_16x16x32_bf16 v[78:81], v[158:161], v[174:177], v[78:81]
	v_mfma_f32_16x16x32_bf16 v[98:101], v[150:153], v[196:199], v[98:101]
	v_mfma_f32_16x16x32_bf16 v[74:77], v[158:161], v[196:199], v[74:77]
	v_mfma_f32_16x16x32_bf16 v[70:73], v[150:153], v[204:207], v[70:73]
	v_mfma_f32_16x16x32_bf16 v[58:61], v[158:161], v[204:207], v[58:61]
	s_barrier
; #define PG8_STAGE(bufoff, gbase, voff) do { _Pragma("unroll") for (int _i = 0; _i < 2; ++_i) \
;         __builtin_amdgcn_global_load_lds((const unsigned*)((const char*)(gbase) + (voff)[_i]), (PG8_LAS unsigned*)(lds + (bufoff) + ldsw + _i * 8192), 16, 0, 0); } while (0)
; #define PG8_LDA(dst, b, h) do { _Pragma("unroll") for (int m = 0; m < 4; ++m) _Pragma("unroll") for (int k = 0; k < 2; ++k) dst[m][k] = *(const PG8_LAS bf16x8*)(lds + PG8_SA(b, h) + aoff + m * 2048 + k * 1024); } while (0)
; #define PG8_WAIT_V(n) asm volatile("s_waitcnt vmcnt(" #n ")" ::: "memory")
; #define PG8_WAIT_L(n) asm volatile("s_waitcnt lgkmcnt(" #n ")" ::: "memory")
; #define PG8_BAR __builtin_amdgcn_s_barrier()
; #define PG8_SCHED __builtin_amdgcn_sched_barrier(0)
; template <class Epi, class Sched, bool ALIGN_EPI = false, bool SP2 = false, bool F8 = false>
; __device__ __forceinline__ void gemm_phase(PG8_LAS unsigned char* lds, const Gemm g, const Sched& S, const Epi& E) {
;     ...
;         for (int t = 0; t < nt; t += 2) {
;             const bool last = (t == nt - 2);
;             const char* a1 = cA + (size_t)(t + 1) * kstep;
;             const char* a2 = last ? nA : cA + (size_t)(t + 2) * kstep; const char* b2 = last ? nB : cB + (size_t)(t + 2) * kstep;
;     ...
;             PG8_LDA(At, 1, 1); PG8_STAGE(PG8_SB(1, 0), b3, voffB); PG8_STAGE(PG8_SB(1, 1), b3 + hB, voffB); PG8_STAGE(PG8_SA(1, 0), a3, voffA);
;             PG8_WAIT_V(8); PG8_WAIT_L(0); PG8_BAR; PG8_MMA(1, 0, At, B0); PG8_MMA(1, 1, At, B1); PG8_BAR; PG8_SCHED;
;     ...
;         if constexpr (ALIGN_EPI) { if (wr == 0) PG8_BAR; }
	s_setprio 0
	s_add_i32 s16, s81, s6
	v_lshl_add_u64 v[208:209], v[208:209], 0, s[36:37]
	s_mov_b32 m0, s16
	ds_read_b128 v[162:165], v243 offset:49152
	ds_read_b128 v[166:169], v243 offset:50176
	ds_read_b128 v[170:173], v243 offset:51200
	ds_read_b128 v[174:177], v243 offset:52224
	ds_read_b128 v[192:195], v243 offset:53248
	ds_read_b128 v[196:199], v243 offset:54272
	ds_read_b128 v[200:203], v243 offset:55296
	ds_read_b128 v[204:207], v243 offset:56320
	global_load_lds_dwordx4 v[208:209], off
	s_add_i32 m0, s16, 0x2000
	s_add_u32 s14, s14, 0x100080
	v_lshl_add_u64 v[208:209], v[210:211], 0, s[36:37]
	s_addc_u32 s15, s15, 0
	s_add_i32 s16, vcc_lo, s6
	global_load_lds_dwordx4 v[208:209], off
	v_lshl_add_u64 v[208:209], s[14:15], 0, v[180:181]
	s_mov_b32 m0, s16
	s_nop 0
	global_load_lds_dwordx4 v[208:209], off
	v_lshl_add_u64 v[208:209], s[14:15], 0, v[184:185]
	s_add_i32 m0, s16, 0x2000
	s_nop 0
	global_load_lds_dwordx4 v[208:209], off
	v_lshl_add_u64 v[208:209], v[212:213], 0, s[36:37]
	s_mov_b32 m0, s71
	s_nop 0
	global_load_lds_dwordx4 v[208:209], off
	v_lshl_add_u64 v[208:209], v[214:215], 0, s[36:37]
	s_mov_b32 m0, s74
	s_nop 0
	global_load_lds_dwordx4 v[208:209], off
	s_waitcnt vmcnt(8)
	s_waitcnt lgkmcnt(0)
	s_setprio 1
	s_barrier
	v_mfma_f32_16x16x32_bf16 v[62:65], v[130:133], v[162:165], v[62:65]
	v_mfma_f32_16x16x32_bf16 v[38:41], v[138:141], v[162:165], v[38:41]
	v_mfma_f32_16x16x32_bf16 v[42:45], v[130:133], v[170:173], v[42:45]
	v_mfma_f32_16x16x32_bf16 v[14:17], v[138:141], v[170:173], v[14:17]
	v_mfma_f32_16x16x32_bf16 v[34:37], v[130:133], v[192:195], v[34:37]
	v_mfma_f32_16x16x32_bf16 v[10:13], v[138:141], v[192:195], v[10:13]
	v_mfma_f32_16x16x32_bf16 v[50:53], v[130:133], v[200:203], v[50:53]
	v_mfma_f32_16x16x32_bf16 v[114:117], v[138:141], v[200:203], v[114:117]
	v_mfma_f32_16x16x32_bf16 v[62:65], v[134:137], v[166:169], v[62:65]
	v_mfma_f32_16x16x32_bf16 v[38:41], v[142:145], v[166:169], v[38:41]
	v_mfma_f32_16x16x32_bf16 v[42:45], v[134:137], v[174:177], v[42:45]
	v_mfma_f32_16x16x32_bf16 v[14:17], v[142:145], v[174:177], v[14:17]
	v_mfma_f32_16x16x32_bf16 v[34:37], v[134:137], v[196:199], v[34:37]
	v_mfma_f32_16x16x32_bf16 v[10:13], v[142:145], v[196:199], v[10:13]
	v_mfma_f32_16x16x32_bf16 v[50:53], v[134:137], v[204:207], v[50:53]
	v_mfma_f32_16x16x32_bf16 v[114:117], v[142:145], v[204:207], v[114:117]
	v_mfma_f32_16x16x32_bf16 v[46:49], v[146:149], v[162:165], v[46:49]
	v_mfma_f32_16x16x32_bf16 v[22:25], v[154:157], v[162:165], v[22:25]
	v_mfma_f32_16x16x32_bf16 v[30:33], v[146:149], v[170:173], v[30:33]
	v_mfma_f32_16x16x32_bf16 v[6:9], v[154:157], v[170:173], v[6:9]
	v_mfma_f32_16x16x32_bf16 v[26:29], v[146:149], v[192:195], v[26:29]
	v_mfma_f32_16x16x32_bf16 v[2:5], v[154:157], v[192:195], v[2:5]
	v_mfma_f32_16x16x32_bf16 v[54:57], v[146:149], v[200:203], v[54:57]
	v_mfma_f32_16x16x32_bf16 v[18:21], v[154:157], v[200:203], v[18:21]
	v_mfma_f32_16x16x32_bf16 v[46:49], v[150:153], v[166:169], v[46:49]
	v_mfma_f32_16x16x32_bf16 v[22:25], v[158:161], v[166:169], v[22:25]
	v_mfma_f32_16x16x32_bf16 v[30:33], v[150:153], v[174:177], v[30:33]
	v_mfma_f32_16x16x32_bf16 v[6:9], v[158:161], v[174:177], v[6:9]
	v_mfma_f32_16x16x32_bf16 v[26:29], v[150:153], v[196:199], v[26:29]
	v_mfma_f32_16x16x32_bf16 v[2:5], v[158:161], v[196:199], v[2:5]
	v_mfma_f32_16x16x32_bf16 v[54:57], v[150:153], v[204:207], v[54:57]
	v_mfma_f32_16x16x32_bf16 v[18:21], v[158:161], v[204:207], v[18:21]
	s_add_i32 s80, s80, 2
	s_add_u32 s78, s78, 0x100
	s_addc_u32 s79, s79, 0
	s_add_u32 s12, s12, 0x100
	s_addc_u32 s13, s13, 0
	s_cmp_gt_u32 s80, 61
	s_cbranch_scc0 .Lber_770
	s_barrier
	s_setprio 0
	s_and_b64 vcc, exec, s[38:39]
	s_cbranch_vccz .LBB0_773
	s_barrier

; template <class Epi, class Sched, bool ALIGN_EPI = false, bool SP2 = false, bool F8 = false>
; __device__ __forceinline__ void gemm_phase(PG8_LAS unsigned char* lds, const Gemm g, const Sched& S, const Epi& E) {
;     ...
;         const bool has_next = S.next(ui + 1, nxt);
;         const char* nA = has_next ? (const char*)g.A + (size_t)nxt.pm * tA + (size_t)(nxt.pn >> g.gshift) * g.goff : cA; const char* nB = has_next ? (const char*)g.Bt + (size_t)nxt.pn * tB : cB;
;     ...
; #pragma unroll
;         for (int a = 0; a < 2; ++a)
; #pragma unroll
;             for (int b = 0; b < 2; ++b)
; #pragma unroll
;                 for (int m = 0; m < 4; ++m)
; #pragma unroll
;                     for (int n = 0; n < 2; ++n) acc[a][b][m][n] = (f32x4){0.f, 0.f, 0.f, 0.f};
.LBB0_824:
	s_ashr_i32 s63, s62, 31
	s_lshl_b64 s[16:17], s[62:63], 21
	s_add_u32 s66, s85, s16
	s_addc_u32 s67, s87, s17
	s_and_b64 s[16:17], s[8:9], exec
	s_cselect_b32 s11, s67, s15
	s_cselect_b32 s63, s66, s14
	s_ashr_i32 s65, s64, 31
	s_lshl_b64 s[16:17], s[64:65], 21
	s_add_u32 s76, s88, s16
	s_addc_u32 s77, s89, s17
	s_and_b64 s[16:17], s[8:9], exec
	s_cselect_b32 s65, s77, s13
	s_cselect_b32 s79, s76, s12
	s_add_u32 s80, s12, 0x100
	s_addc_u32 s81, s13, 0
	s_add_u32 s12, s14, 0x100080
	v_mov_b32_e32 v66, 0
	s_addc_u32 s13, s15, 0
	s_mov_b32 s82, -2
	v_mov_b32_e32 v67, v66
	v_mov_b32_e32 v68, v66
	v_mov_b32_e32 v69, v66
	v_mov_b32_e32 v58, v66
	v_mov_b32_e32 v59, v66
	v_mov_b32_e32 v60, v66
	v_mov_b32_e32 v61, v66
	v_mov_b32_e32 v22, v66
	v_mov_b32_e32 v23, v66
	v_mov_b32_e32 v24, v66
	v_mov_b32_e32 v25, v66
	v_mov_b32_e32 v18, v66
	v_mov_b32_e32 v19, v66
	v_mov_b32_e32 v20, v66
	v_mov_b32_e32 v21, v66
	v_mov_b32_e32 v54, v66
	v_mov_b32_e32 v55, v66
	v_mov_b32_e32 v56, v66
	v_mov_b32_e32 v57, v66
	v_mov_b32_e32 v2, v66
	v_mov_b32_e32 v3, v66
	v_mov_b32_e32 v4, v66
	v_mov_b32_e32 v5, v66
	v_mov_b32_e32 v26, v66
	v_mov_b32_e32 v27, v66
	v_mov_b32_e32 v28, v66
	v_mov_b32_e32 v29, v66
	v_mov_b32_e32 v6, v66
	v_mov_b32_e32 v7, v66
	v_mov_b32_e32 v8, v66
	v_mov_b32_e32 v9, v66
	v_mov_b32_e32 v30, v66
	v_mov_b32_e32 v31, v66
	v_mov_b32_e32 v32, v66
	v_mov_b32_e32 v33, v66
	v_mov_b32_e32 v46, v66
	v_mov_b32_e32 v47, v66
	v_mov_b32_e32 v48, v66
	v_mov_b32_e32 v49, v66
	v_mov_b32_e32 v114, v66
	v_mov_b32_e32 v115, v66
	v_mov_b32_e32 v116, v66
	v_mov_b32_e32 v117, v66
	v_mov_b32_e32 v50, v66
	v_mov_b32_e32 v51, v66
	v_mov_b32_e32 v52, v66
	v_mov_b32_e32 v53, v66
	v_mov_b32_e32 v10, v66
	v_mov_b32_e32 v11, v66
	v_mov_b32_e32 v12, v66
	v_mov_b32_e32 v13, v66
	v_mov_b32_e32 v34, v66
	v_mov_b32_e32 v35, v66
	v_mov_b32_e32 v36, v66
	v_mov_b32_e32 v37, v66
	v_mov_b32_e32 v14, v66
	v_mov_b32_e32 v15, v66
	v_mov_b32_e32 v16, v66
	v_mov_b32_e32 v17, v66
	v_mov_b32_e32 v42, v66
	v_mov_b32_e32 v43, v66
	v_mov_b32_e32 v44, v66
	v_mov_b32_e32 v45, v66
	v_mov_b32_e32 v38, v66
	v_mov_b32_e32 v39, v66
	v_mov_b32_e32 v40, v66
	v_mov_b32_e32 v41, v66
	v_mov_b32_e32 v62, v66
	v_mov_b32_e32 v63, v66
	v_mov_b32_e32 v64, v66
	v_mov_b32_e32 v65, v66
	v_mov_b32_e32 v70, v66
	v_mov_b32_e32 v71, v66
	v_mov_b32_e32 v72, v66
	v_mov_b32_e32 v73, v66
	v_mov_b32_e32 v74, v66
	v_mov_b32_e32 v75, v66
	v_mov_b32_e32 v76, v66
	v_mov_b32_e32 v77, v66
	v_mov_b32_e32 v98, v66
	v_mov_b32_e32 v99, v66
	v_mov_b32_e32 v100, v66
	v_mov_b32_e32 v101, v66
	v_mov_b32_e32 v78, v66
	v_mov_b32_e32 v79, v66
	v_mov_b32_e32 v80, v66
	v_mov_b32_e32 v81, v66
	v_mov_b32_e32 v102, v66
	v_mov_b32_e32 v103, v66
	v_mov_b32_e32 v104, v66
	v_mov_b32_e32 v105, v66
	v_mov_b32_e32 v94, v66
	v_mov_b32_e32 v95, v66
	v_mov_b32_e32 v96, v66
	v_mov_b32_e32 v97, v66
	v_mov_b32_e32 v122, v66
	v_mov_b32_e32 v123, v66
	v_mov_b32_e32 v124, v66
	v_mov_b32_e32 v125, v66
	v_mov_b32_e32 v118, v66
	v_mov_b32_e32 v119, v66
	v_mov_b32_e32 v120, v66
	v_mov_b32_e32 v121, v66
	v_mov_b32_e32 v82, v66
	v_mov_b32_e32 v83, v66
	v_mov_b32_e32 v84, v66
	v_mov_b32_e32 v85, v66
	v_mov_b32_e32 v106, v66
	v_mov_b32_e32 v107, v66
	v_mov_b32_e32 v108, v66
	v_mov_b32_e32 v109, v66
	v_mov_b32_e32 v86, v66
	v_mov_b32_e32 v87, v66
	v_mov_b32_e32 v88, v66
	v_mov_b32_e32 v89, v66
	v_mov_b32_e32 v110, v66
	v_mov_b32_e32 v111, v66
	v_mov_b32_e32 v112, v66
	v_mov_b32_e32 v113, v66
	v_mov_b32_e32 v90, v66
	v_mov_b32_e32 v91, v66
	v_mov_b32_e32 v92, v66
	v_mov_b32_e32 v93, v66
	v_mov_b32_e32 v126, v66
	v_mov_b32_e32 v127, v66
	v_mov_b32_e32 v128, v66
	v_mov_b32_e32 v129, v66
	s_branch .LBB0_825

; #define PG8_STAGE(bufoff, gbase, voff) do { _Pragma("unroll") for (int _i = 0; _i < 2; ++_i) \
;         __builtin_amdgcn_global_load_lds((const unsigned*)((const char*)(gbase) + (voff)[_i]), (PG8_LAS unsigned*)(lds + (bufoff) + ldsw + _i * 8192), 16, 0, 0); } while (0)
; #define PG8_LDA(dst, b, h) do { _Pragma("unroll") for (int m = 0; m < 4; ++m) _Pragma("unroll") for (int k = 0; k < 2; ++k) dst[m][k] = *(const PG8_LAS bf16x8*)(lds + PG8_SA(b, h) + aoff + m * 2048 + k * 1024); } while (0)
; #define PG8_LDB(dst, b, h) do { _Pragma("unroll") for (int n = 0; n < 2; ++n) _Pragma("unroll") for (int k = 0; k < 2; ++k) dst[n][k] = *(const PG8_LAS bf16x8*)(lds + PG8_SB(b, h) + boff + n * 2048 + k * 1024); } while (0)
; #define PG8_WAIT_V(n) asm volatile("s_waitcnt vmcnt(" #n ")" ::: "memory")
; #define PG8_WAIT_L(n) asm volatile("s_waitcnt lgkmcnt(" #n ")" ::: "memory")
; #define PG8_BAR __builtin_amdgcn_s_barrier()
; #define PG8_SCHED __builtin_amdgcn_sched_barrier(0)
; template <class Epi, class Sched, bool ALIGN_EPI = false, bool SP2 = false, bool F8 = false>
; __device__ __forceinline__ void gemm_phase(PG8_LAS unsigned char* lds, const Gemm g, const Sched& S, const Epi& E) {
;     ...
;             PG8_LDB(B0, 0, 0); PG8_LDB(B1, 0, 1); PG8_SCHED; PG8_LDA(At, 0, 0); PG8_STAGE(PG8_SA(1, 1), a1 + hA, voffA);
;             PG8_WAIT_V(8); PG8_WAIT_L(0); PG8_BAR; PG8_MMA(0, 0, At, B0); PG8_MMA(0, 1, At, B1); PG8_BAR; PG8_SCHED;
;             PG8_LDA(At, 0, 1); PG8_STAGE(PG8_SB(0, 0), b2, voffB); PG8_STAGE(PG8_SB(0, 1), b2 + hB, voffB); PG8_STAGE(PG8_SA(0, 0), a2, voffA);
.LBB0_825:
	ds_read_b128 v[130:133], v241
	ds_read_b128 v[134:137], v241 offset:1024
	ds_read_b128 v[138:141], v241 offset:2048
	ds_read_b128 v[142:145], v241 offset:3072
	ds_read_b128 v[146:149], v242
	ds_read_b128 v[150:153], v242 offset:1024
	ds_read_b128 v[154:157], v242 offset:2048
	ds_read_b128 v[158:161], v242 offset:3072
	s_add_u32 s14, s12, 0xfff00080
	s_addc_u32 s15, s13, -1
	s_cmp_eq_u32 s82, 60
	s_cselect_b32 s17, s11, s15
	s_cselect_b32 s16, s63, s14
	s_cselect_b32 s15, s65, s81
	s_cselect_b32 s14, s79, s80
	v_lshl_add_u64 v[208:209], s[12:13], 0, v[188:189]
	s_add_i32 m0, s7, 0xc000
	ds_read_b128 v[162:165], v243
	ds_read_b128 v[166:169], v243 offset:1024
	ds_read_b128 v[170:173], v243 offset:2048
	ds_read_b128 v[174:177], v243 offset:3072
	ds_read_b128 v[192:195], v243 offset:4096
	ds_read_b128 v[196:199], v243 offset:5120
	ds_read_b128 v[200:203], v243 offset:6144
	ds_read_b128 v[204:207], v243 offset:7168
	global_load_lds_dwordx4 v[208:209], off
	v_lshl_add_u64 v[208:209], s[12:13], 0, v[186:187]
	s_add_i32 m0, s7, 0xe000
	s_nop 0
	global_load_lds_dwordx4 v[208:209], off
	s_waitcnt vmcnt(8)
	s_waitcnt lgkmcnt(0)
	s_setprio 1
	s_barrier
	v_mfma_f32_16x16x32_bf16 v[126:129], v[130:133], v[162:165], v[126:129]
	v_mfma_f32_16x16x32_bf16 v[90:93], v[138:141], v[162:165], v[90:93]
	v_mfma_f32_16x16x32_bf16 v[110:113], v[130:133], v[170:173], v[110:113]
	v_mfma_f32_16x16x32_bf16 v[86:89], v[138:141], v[170:173], v[86:89]
	v_mfma_f32_16x16x32_bf16 v[106:109], v[130:133], v[192:195], v[106:109]
	v_mfma_f32_16x16x32_bf16 v[82:85], v[138:141], v[192:195], v[82:85]
	v_mfma_f32_16x16x32_bf16 v[118:121], v[130:133], v[200:203], v[118:121]
	v_mfma_f32_16x16x32_bf16 v[122:125], v[138:141], v[200:203], v[122:125]
	v_mfma_f32_16x16x32_bf16 v[126:129], v[134:137], v[166:169], v[126:129]
	v_mfma_f32_16x16x32_bf16 v[90:93], v[142:145], v[166:169], v[90:93]
	v_mfma_f32_16x16x32_bf16 v[110:113], v[134:137], v[174:177], v[110:113]
	v_mfma_f32_16x16x32_bf16 v[86:89], v[142:145], v[174:177], v[86:89]
	v_mfma_f32_16x16x32_bf16 v[106:109], v[134:137], v[196:199], v[106:109]
	v_mfma_f32_16x16x32_bf16 v[82:85], v[142:145], v[196:199], v[82:85]
	v_mfma_f32_16x16x32_bf16 v[118:121], v[134:137], v[204:207], v[118:121]
	v_mfma_f32_16x16x32_bf16 v[122:125], v[142:145], v[204:207], v[122:125]
	v_mfma_f32_16x16x32_bf16 v[94:97], v[146:149], v[162:165], v[94:97]
	v_mfma_f32_16x16x32_bf16 v[66:69], v[154:157], v[162:165], v[66:69]
	v_mfma_f32_16x16x32_bf16 v[102:105], v[146:149], v[170:173], v[102:105]
	v_mfma_f32_16x16x32_bf16 v[78:81], v[154:157], v[170:173], v[78:81]
	v_mfma_f32_16x16x32_bf16 v[98:101], v[146:149], v[192:195], v[98:101]
	v_mfma_f32_16x16x32_bf16 v[74:77], v[154:157], v[192:195], v[74:77]
	v_mfma_f32_16x16x32_bf16 v[70:73], v[146:149], v[200:203], v[70:73]
	v_mfma_f32_16x16x32_bf16 v[58:61], v[154:157], v[200:203], v[58:61]
	v_mfma_f32_16x16x32_bf16 v[94:97], v[150:153], v[166:169], v[94:97]
	v_mfma_f32_16x16x32_bf16 v[66:69], v[158:161], v[166:169], v[66:69]
	v_mfma_f32_16x16x32_bf16 v[102:105], v[150:153], v[174:177], v[102:105]
	v_mfma_f32_16x16x32_bf16 v[78:81], v[158:161], v[174:177], v[78:81]
	v_mfma_f32_16x16x32_bf16 v[98:101], v[150:153], v[196:199], v[98:101]
	v_mfma_f32_16x16x32_bf16 v[74:77], v[158:161], v[196:199], v[74:77]
	v_mfma_f32_16x16x32_bf16 v[70:73], v[150:153], v[204:207], v[70:73]
	v_mfma_f32_16x16x32_bf16 v[58:61], v[158:161], v[204:207], v[58:61]
	s_barrier
	s_setprio 0
	s_add_i32 s83, s30, s5
	v_lshl_add_u64 v[208:209], s[14:15], 0, v[180:181]
	s_mov_b32 m0, s83
	ds_read_b128 v[162:165], v243 offset:16384
	ds_read_b128 v[166:169], v243 offset:17408
	ds_read_b128 v[170:173], v243 offset:18432
	ds_read_b128 v[174:177], v243 offset:19456
	ds_read_b128 v[192:195], v243 offset:20480
	ds_read_b128 v[196:199], v243 offset:21504
	ds_read_b128 v[200:203], v243 offset:22528
	ds_read_b128 v[204:207], v243 offset:23552
	global_load_lds_dwordx4 v[208:209], off
	s_add_i32 m0, s83, 0x2000
	s_add_u32 vcc_lo, s14, 0x100000
	v_lshl_add_u64 v[210:211], s[14:15], 0, v[184:185]
	s_addc_u32 vcc_hi, s15, 0
	s_add_i32 s83, s86, s5
	global_load_lds_dwordx4 v[210:211], off
	v_lshl_add_u64 v[212:213], vcc, 0, v[180:181]
	s_mov_b32 m0, s83
	v_lshl_add_u64 v[214:215], s[16:17], 0, v[182:183]
	global_load_lds_dwordx4 v[212:213], off
	v_lshl_add_u64 v[212:213], vcc, 0, v[184:185]
	s_add_i32 m0, s83, 0x2000
	s_nop 0
	global_load_lds_dwordx4 v[212:213], off
	v_lshl_add_u64 v[212:213], s[16:17], 0, v[178:179]
	s_mov_b32 m0, s7
	s_nop 0
	global_load_lds_dwordx4 v[212:213], off
	s_mov_b32 m0, s18
	s_nop 0
	global_load_lds_dwordx4 v[214:215], off
	s_waitcnt vmcnt(8)
	s_waitcnt lgkmcnt(0)
	s_setprio 1
	s_barrier
; #define PG8_STAGE(bufoff, gbase, voff) do { _Pragma("unroll") for (int _i = 0; _i < 2; ++_i) \
;         __builtin_amdgcn_global_load_lds((const unsigned*)((const char*)(gbase) + (voff)[_i]), (PG8_LAS unsigned*)(lds + (bufoff) + ldsw + _i * 8192), 16, 0, 0); } while (0)
; #define PG8_LDA(dst, b, h) do { _Pragma("unroll") for (int m = 0; m < 4; ++m) _Pragma("unroll") for (int k = 0; k < 2; ++k) dst[m][k] = *(const PG8_LAS bf16x8*)(lds + PG8_SA(b, h) + aoff + m * 2048 + k * 1024); } while (0)
; #define PG8_LDB(dst, b, h) do { _Pragma("unroll") for (int n = 0; n < 2; ++n) _Pragma("unroll") for (int k = 0; k < 2; ++k) dst[n][k] = *(const PG8_LAS bf16x8*)(lds + PG8_SB(b, h) + boff + n * 2048 + k * 1024); } while (0)
; #define PG8_WAIT_V(n) asm volatile("s_waitcnt vmcnt(" #n ")" ::: "memory")
; #define PG8_WAIT_L(n) asm volatile("s_waitcnt lgkmcnt(" #n ")" ::: "memory")
; #define PG8_BAR __builtin_amdgcn_s_barrier()
; #define PG8_SCHED __builtin_amdgcn_sched_barrier(0)
; template <class Epi, class Sched, bool ALIGN_EPI = false, bool SP2 = false, bool F8 = false>
; __device__ __forceinline__ void gemm_phase(PG8_LAS unsigned char* lds, const Gemm g, const Sched& S, const Epi& E) {
;     ...
;             PG8_WAIT_V(8); PG8_WAIT_L(0); PG8_BAR; PG8_MMA(1, 0, At, B0); PG8_MMA(1, 1, At, B1); PG8_BAR; PG8_SCHED;
;             PG8_LDB(B0, 1, 0); PG8_LDB(B1, 1, 1); PG8_SCHED; PG8_LDA(At, 1, 0); PG8_STAGE(PG8_SA(0, 1), a2 + hA, voffA);
;             PG8_WAIT_V(8); PG8_WAIT_L(0); PG8_BAR; PG8_MMA(0, 0, At, B0); PG8_MMA(0, 1, At, B1); PG8_BAR; PG8_SCHED;
	v_mfma_f32_16x16x32_bf16 v[62:65], v[130:133], v[162:165], v[62:65]
	v_mfma_f32_16x16x32_bf16 v[38:41], v[138:141], v[162:165], v[38:41]
	v_mfma_f32_16x16x32_bf16 v[42:45], v[130:133], v[170:173], v[42:45]
	v_mfma_f32_16x16x32_bf16 v[14:17], v[138:141], v[170:173], v[14:17]
	v_mfma_f32_16x16x32_bf16 v[34:37], v[130:133], v[192:195], v[34:37]
	v_mfma_f32_16x16x32_bf16 v[10:13], v[138:141], v[192:195], v[10:13]
	v_mfma_f32_16x16x32_bf16 v[50:53], v[130:133], v[200:203], v[50:53]
	v_mfma_f32_16x16x32_bf16 v[114:117], v[138:141], v[200:203], v[114:117]
	v_mfma_f32_16x16x32_bf16 v[62:65], v[134:137], v[166:169], v[62:65]
	v_mfma_f32_16x16x32_bf16 v[38:41], v[142:145], v[166:169], v[38:41]
	v_mfma_f32_16x16x32_bf16 v[42:45], v[134:137], v[174:177], v[42:45]
	v_mfma_f32_16x16x32_bf16 v[14:17], v[142:145], v[174:177], v[14:17]
	v_mfma_f32_16x16x32_bf16 v[34:37], v[134:137], v[196:199], v[34:37]
	v_mfma_f32_16x16x32_bf16 v[10:13], v[142:145], v[196:199], v[10:13]
	v_mfma_f32_16x16x32_bf16 v[50:53], v[134:137], v[204:207], v[50:53]
	v_mfma_f32_16x16x32_bf16 v[114:117], v[142:145], v[204:207], v[114:117]
	v_mfma_f32_16x16x32_bf16 v[46:49], v[146:149], v[162:165], v[46:49]
	v_mfma_f32_16x16x32_bf16 v[22:25], v[154:157], v[162:165], v[22:25]
	v_mfma_f32_16x16x32_bf16 v[30:33], v[146:149], v[170:173], v[30:33]
	v_mfma_f32_16x16x32_bf16 v[6:9], v[154:157], v[170:173], v[6:9]
	v_mfma_f32_16x16x32_bf16 v[26:29], v[146:149], v[192:195], v[26:29]
	v_mfma_f32_16x16x32_bf16 v[2:5], v[154:157], v[192:195], v[2:5]
	v_mfma_f32_16x16x32_bf16 v[54:57], v[146:149], v[200:203], v[54:57]
	v_mfma_f32_16x16x32_bf16 v[18:21], v[154:157], v[200:203], v[18:21]
	v_mfma_f32_16x16x32_bf16 v[46:49], v[150:153], v[166:169], v[46:49]
	v_mfma_f32_16x16x32_bf16 v[22:25], v[158:161], v[166:169], v[22:25]
	v_mfma_f32_16x16x32_bf16 v[30:33], v[150:153], v[174:177], v[30:33]
	v_mfma_f32_16x16x32_bf16 v[6:9], v[158:161], v[174:177], v[6:9]
	v_mfma_f32_16x16x32_bf16 v[26:29], v[150:153], v[196:199], v[26:29]
	v_mfma_f32_16x16x32_bf16 v[2:5], v[158:161], v[196:199], v[2:5]
	v_mfma_f32_16x16x32_bf16 v[54:57], v[150:153], v[204:207], v[54:57]
	v_mfma_f32_16x16x32_bf16 v[18:21], v[158:161], v[204:207], v[18:21]
	s_barrier
	s_setprio 0
	s_add_i32 s83, 0, 0x18000
	s_add_i32 vcc_lo, 0, 0x1c000
	v_add_u32_e32 v142, s83, v240
	v_add_u32_e32 v158, vcc_lo, v240
	ds_read_b128 v[130:133], v142
	ds_read_b128 v[134:137], v142 offset:1024
	ds_read_b128 v[138:141], v142 offset:2048
	ds_read_b128 v[142:145], v142 offset:3072
	ds_read_b128 v[146:149], v158
	ds_read_b128 v[150:153], v158 offset:1024
	ds_read_b128 v[154:157], v158 offset:2048
	ds_read_b128 v[158:161], v158 offset:3072
	s_add_u32 s16, s16, 0x100000
	s_addc_u32 s17, s17, 0
	s_mov_b32 m0, s19
	v_lshl_add_u64 v[216:217], s[16:17], 0, v[178:179]
	ds_read_b128 v[162:165], v243 offset:32768
	ds_read_b128 v[166:169], v243 offset:33792
	ds_read_b128 v[170:173], v243 offset:34816
	ds_read_b128 v[174:177], v243 offset:35840
	ds_read_b128 v[192:195], v243 offset:36864
	ds_read_b128 v[196:199], v243 offset:37888
	ds_read_b128 v[200:203], v243 offset:38912
	ds_read_b128 v[204:207], v243 offset:39936
	global_load_lds_dwordx4 v[216:217], off
	v_lshl_add_u64 v[216:217], s[16:17], 0, v[182:183]
	s_mov_b32 m0, s29
	s_nop 0
	global_load_lds_dwordx4 v[216:217], off
	s_waitcnt vmcnt(8)
	s_waitcnt lgkmcnt(0)
	s_setprio 1
	s_barrier
	v_mfma_f32_16x16x32_bf16 v[126:129], v[130:133], v[162:165], v[126:129]
	v_mfma_f32_16x16x32_bf16 v[90:93], v[138:141], v[162:165], v[90:93]
	v_mfma_f32_16x16x32_bf16 v[110:113], v[130:133], v[170:173], v[110:113]
	v_mfma_f32_16x16x32_bf16 v[86:89], v[138:141], v[170:173], v[86:89]
	v_mfma_f32_16x16x32_bf16 v[106:109], v[130:133], v[192:195], v[106:109]
	v_mfma_f32_16x16x32_bf16 v[82:85], v[138:141], v[192:195], v[82:85]
	v_mfma_f32_16x16x32_bf16 v[118:121], v[130:133], v[200:203], v[118:121]
	v_mfma_f32_16x16x32_bf16 v[122:125], v[138:141], v[200:203], v[122:125]
	v_mfma_f32_16x16x32_bf16 v[126:129], v[134:137], v[166:169], v[126:129]
	v_mfma_f32_16x16x32_bf16 v[90:93], v[142:145], v[166:169], v[90:93]
	v_mfma_f32_16x16x32_bf16 v[110:113], v[134:137], v[174:177], v[110:113]
	v_mfma_f32_16x16x32_bf16 v[86:89], v[142:145], v[174:177], v[86:89]
	v_mfma_f32_16x16x32_bf16 v[106:109], v[134:137], v[196:199], v[106:109]
	v_mfma_f32_16x16x32_bf16 v[82:85], v[142:145], v[196:199], v[82:85]
	v_mfma_f32_16x16x32_bf16 v[118:121], v[134:137], v[204:207], v[118:121]
	v_mfma_f32_16x16x32_bf16 v[122:125], v[142:145], v[204:207], v[122:125]
	v_mfma_f32_16x16x32_bf16 v[94:97], v[146:149], v[162:165], v[94:97]
	v_mfma_f32_16x16x32_bf16 v[66:69], v[154:157], v[162:165], v[66:69]
	v_mfma_f32_16x16x32_bf16 v[102:105], v[146:149], v[170:173], v[102:105]
	v_mfma_f32_16x16x32_bf16 v[78:81], v[154:157], v[170:173], v[78:81]
	v_mfma_f32_16x16x32_bf16 v[98:101], v[146:149], v[192:195], v[98:101]
	v_mfma_f32_16x16x32_bf16 v[74:77], v[154:157], v[192:195], v[74:77]
	v_mfma_f32_16x16x32_bf16 v[70:73], v[146:149], v[200:203], v[70:73]
	v_mfma_f32_16x16x32_bf16 v[58:61], v[154:157], v[200:203], v[58:61]
	v_mfma_f32_16x16x32_bf16 v[94:97], v[150:153], v[166:169], v[94:97]
	v_mfma_f32_16x16x32_bf16 v[66:69], v[158:161], v[166:169], v[66:69]
	v_mfma_f32_16x16x32_bf16 v[102:105], v[150:153], v[174:177], v[102:105]
	v_mfma_f32_16x16x32_bf16 v[78:81], v[158:161], v[174:177], v[78:81]
	v_mfma_f32_16x16x32_bf16 v[98:101], v[150:153], v[196:199], v[98:101]
	v_mfma_f32_16x16x32_bf16 v[74:77], v[158:161], v[196:199], v[74:77]
	v_mfma_f32_16x16x32_bf16 v[70:73], v[150:153], v[204:207], v[70:73]
	v_mfma_f32_16x16x32_bf16 v[58:61], v[158:161], v[204:207], v[58:61]
	s_barrier
; #define PG8_STAGE(bufoff, gbase, voff) do { _Pragma("unroll") for (int _i = 0; _i < 2; ++_i) \
;         __builtin_amdgcn_global_load_lds((const unsigned*)((const char*)(gbase) + (voff)[_i]), (PG8_LAS unsigned*)(lds + (bufoff) + ldsw + _i * 8192), 16, 0, 0); } while (0)
; #define PG8_LDA(dst, b, h) do { _Pragma("unroll") for (int m = 0; m < 4; ++m) _Pragma("unroll") for (int k = 0; k < 2; ++k) dst[m][k] = *(const PG8_LAS bf16x8*)(lds + PG8_SA(b, h) + aoff + m * 2048 + k * 1024); } while (0)
; #define PG8_WAIT_V(n) asm volatile("s_waitcnt vmcnt(" #n ")" ::: "memory")
; #define PG8_WAIT_L(n) asm volatile("s_waitcnt lgkmcnt(" #n ")" ::: "memory")
; #define PG8_BAR __builtin_amdgcn_s_barrier()
; #define PG8_SCHED __builtin_amdgcn_sched_barrier(0)
; template <class Epi, class Sched, bool ALIGN_EPI = false, bool SP2 = false, bool F8 = false>
; __device__ __forceinline__ void gemm_phase(PG8_LAS unsigned char* lds, const Gemm g, const Sched& S, const Epi& E) {
;     ...
;         for (int t = 0; t < nt; t += 2) {
;             const bool last = (t == nt - 2);
;             const char* a1 = cA + (size_t)(t + 1) * kstep;
;             const char* a2 = last ? nA : cA + (size_t)(t + 2) * kstep; const char* b2 = last ? nB : cB + (size_t)(t + 2) * kstep;
;     ...
;             PG8_LDA(At, 1, 1); PG8_STAGE(PG8_SB(1, 0), b3, voffB); PG8_STAGE(PG8_SB(1, 1), b3 + hB, voffB); PG8_STAGE(PG8_SA(1, 0), a3, voffA);
;             PG8_WAIT_V(8); PG8_WAIT_L(0); PG8_BAR; PG8_MMA(1, 0, At, B0); PG8_MMA(1, 1, At, B1); PG8_BAR; PG8_SCHED;
;     ...
;         if constexpr (ALIGN_EPI) { if (wr == 0) PG8_BAR; }
	s_setprio 0
	s_add_i32 s16, s83, s5
	v_lshl_add_u64 v[208:209], v[208:209], 0, s[38:39]
	s_mov_b32 m0, s16
	ds_read_b128 v[162:165], v243 offset:49152
	ds_read_b128 v[166:169], v243 offset:50176
	ds_read_b128 v[170:173], v243 offset:51200
	ds_read_b128 v[174:177], v243 offset:52224
	ds_read_b128 v[192:195], v243 offset:53248
	ds_read_b128 v[196:199], v243 offset:54272
	ds_read_b128 v[200:203], v243 offset:55296
	ds_read_b128 v[204:207], v243 offset:56320
	global_load_lds_dwordx4 v[208:209], off
	s_add_i32 m0, s16, 0x2000
	s_add_u32 s14, s14, 0x100080
	v_lshl_add_u64 v[208:209], v[210:211], 0, s[38:39]
	s_addc_u32 s15, s15, 0
	s_add_i32 s16, vcc_lo, s5
	global_load_lds_dwordx4 v[208:209], off
	v_lshl_add_u64 v[208:209], s[14:15], 0, v[180:181]
	s_mov_b32 m0, s16
	s_nop 0
	global_load_lds_dwordx4 v[208:209], off
	v_lshl_add_u64 v[208:209], s[14:15], 0, v[184:185]
	s_add_i32 m0, s16, 0x2000
	s_nop 0
	global_load_lds_dwordx4 v[208:209], off
	v_lshl_add_u64 v[208:209], v[212:213], 0, s[38:39]
	s_mov_b32 m0, s70
	s_nop 0
	global_load_lds_dwordx4 v[208:209], off
	v_lshl_add_u64 v[208:209], v[214:215], 0, s[38:39]
	s_mov_b32 m0, s71
	s_nop 0
	global_load_lds_dwordx4 v[208:209], off
	s_waitcnt vmcnt(8)
	s_waitcnt lgkmcnt(0)
	s_setprio 1
	s_barrier
	v_mfma_f32_16x16x32_bf16 v[62:65], v[130:133], v[162:165], v[62:65]
	v_mfma_f32_16x16x32_bf16 v[38:41], v[138:141], v[162:165], v[38:41]
	v_mfma_f32_16x16x32_bf16 v[42:45], v[130:133], v[170:173], v[42:45]
	v_mfma_f32_16x16x32_bf16 v[14:17], v[138:141], v[170:173], v[14:17]
	v_mfma_f32_16x16x32_bf16 v[34:37], v[130:133], v[192:195], v[34:37]
	v_mfma_f32_16x16x32_bf16 v[10:13], v[138:141], v[192:195], v[10:13]
	v_mfma_f32_16x16x32_bf16 v[50:53], v[130:133], v[200:203], v[50:53]
	v_mfma_f32_16x16x32_bf16 v[114:117], v[138:141], v[200:203], v[114:117]
	v_mfma_f32_16x16x32_bf16 v[62:65], v[134:137], v[166:169], v[62:65]
	v_mfma_f32_16x16x32_bf16 v[38:41], v[142:145], v[166:169], v[38:41]
	v_mfma_f32_16x16x32_bf16 v[42:45], v[134:137], v[174:177], v[42:45]
	v_mfma_f32_16x16x32_bf16 v[14:17], v[142:145], v[174:177], v[14:17]
	v_mfma_f32_16x16x32_bf16 v[34:37], v[134:137], v[196:199], v[34:37]
	v_mfma_f32_16x16x32_bf16 v[10:13], v[142:145], v[196:199], v[10:13]
	v_mfma_f32_16x16x32_bf16 v[50:53], v[134:137], v[204:207], v[50:53]
	v_mfma_f32_16x16x32_bf16 v[114:117], v[142:145], v[204:207], v[114:117]
	v_mfma_f32_16x16x32_bf16 v[46:49], v[146:149], v[162:165], v[46:49]
	v_mfma_f32_16x16x32_bf16 v[22:25], v[154:157], v[162:165], v[22:25]
	v_mfma_f32_16x16x32_bf16 v[30:33], v[146:149], v[170:173], v[30:33]
	v_mfma_f32_16x16x32_bf16 v[6:9], v[154:157], v[170:173], v[6:9]
	v_mfma_f32_16x16x32_bf16 v[26:29], v[146:149], v[192:195], v[26:29]
	v_mfma_f32_16x16x32_bf16 v[2:5], v[154:157], v[192:195], v[2:5]
	v_mfma_f32_16x16x32_bf16 v[54:57], v[146:149], v[200:203], v[54:57]
	v_mfma_f32_16x16x32_bf16 v[18:21], v[154:157], v[200:203], v[18:21]
	v_mfma_f32_16x16x32_bf16 v[46:49], v[150:153], v[166:169], v[46:49]
	v_mfma_f32_16x16x32_bf16 v[22:25], v[158:161], v[166:169], v[22:25]
	v_mfma_f32_16x16x32_bf16 v[30:33], v[150:153], v[174:177], v[30:33]
	v_mfma_f32_16x16x32_bf16 v[6:9], v[158:161], v[174:177], v[6:9]
	v_mfma_f32_16x16x32_bf16 v[26:29], v[150:153], v[196:199], v[26:29]
	v_mfma_f32_16x16x32_bf16 v[2:5], v[158:161], v[196:199], v[2:5]
	v_mfma_f32_16x16x32_bf16 v[54:57], v[150:153], v[204:207], v[54:57]
	v_mfma_f32_16x16x32_bf16 v[18:21], v[158:161], v[204:207], v[18:21]
	s_add_i32 s82, s82, 2
	s_add_u32 s80, s80, 0x100
	s_addc_u32 s81, s81, 0
	s_add_u32 s12, s12, 0x100
	s_addc_u32 s13, s13, 0
	s_cmp_gt_u32 s82, 61
	s_cbranch_scc0 .Lber_825
	s_barrier
	s_setprio 0
	s_and_b64 vcc, exec, s[40:41]
	s_cbranch_vccz .LBB0_828
	s_barrier

; template <class Epi, class Sched, bool ALIGN_EPI = false, bool SP2 = false, bool F8 = false>
; __device__ __forceinline__ void gemm_phase(PG8_LAS unsigned char* lds, const Gemm g, const Sched& S, const Epi& E) {
;     ...
;         const bool has_next = S.next(ui + 1, nxt);
;         const char* nA = has_next ? (const char*)g.A + (size_t)nxt.pm * tA + (size_t)(nxt.pn >> g.gshift) * g.goff : cA; const char* nB = has_next ? (const char*)g.Bt + (size_t)nxt.pn * tB : cB;
;     ...
; #pragma unroll
;         for (int a = 0; a < 2; ++a)
; #pragma unroll
;             for (int b = 0; b < 2; ++b)
; #pragma unroll
;                 for (int m = 0; m < 4; ++m)
; #pragma unroll
;                     for (int n = 0; n < 2; ++n) acc[a][b][m][n] = (f32x4){0.f, 0.f, 0.f, 0.f};
.LBB0_882:
	s_ashr_i32 s77, s76, 31
	s_lshl_b64 s[16:17], s[76:77], 21
	v_readlane_b32 s13, v254, 15
	s_add_u32 s80, s13, s16
	v_readlane_b32 s13, v254, 16
	s_addc_u32 s81, s13, s17
	s_and_b64 s[16:17], s[8:9], exec
	s_cselect_b32 s13, s81, s15
	s_cselect_b32 s77, s80, s14
	s_ashr_i32 s79, s78, 31
	s_lshl_b64 s[16:17], s[78:79], 21
	v_readlane_b32 s79, v254, 19
	s_add_u32 s82, s79, s16
	v_readlane_b32 s16, v254, 20
	s_addc_u32 s83, s16, s17
	s_and_b64 s[16:17], s[8:9], exec
	s_cselect_b32 s79, s83, s11
	s_cselect_b32 s85, s82, s10
	s_add_u32 s86, s10, 0x100
	s_addc_u32 s87, s11, 0
	s_add_u32 s10, s14, 0x100080
	v_mov_b32_e32 v2, 0
	s_addc_u32 s11, s15, 0
	s_mov_b32 s88, -2
	v_mov_b32_e32 v3, v2
	v_mov_b32_e32 v4, v2
	v_mov_b32_e32 v5, v2
	v_mov_b32_e32 v18, v2
	v_mov_b32_e32 v19, v2
	v_mov_b32_e32 v20, v2
	v_mov_b32_e32 v21, v2
	v_mov_b32_e32 v62, v2
	v_mov_b32_e32 v63, v2
	v_mov_b32_e32 v64, v2
	v_mov_b32_e32 v65, v2
	v_mov_b32_e32 v74, v2
	v_mov_b32_e32 v75, v2
	v_mov_b32_e32 v76, v2
	v_mov_b32_e32 v77, v2
	v_mov_b32_e32 v82, v2
	v_mov_b32_e32 v83, v2
	v_mov_b32_e32 v84, v2
	v_mov_b32_e32 v85, v2
	v_mov_b32_e32 v70, v2
	v_mov_b32_e32 v71, v2
	v_mov_b32_e32 v72, v2
	v_mov_b32_e32 v73, v2
	v_mov_b32_e32 v30, v2
	v_mov_b32_e32 v31, v2
	v_mov_b32_e32 v32, v2
	v_mov_b32_e32 v33, v2
	v_mov_b32_e32 v6, v2
	v_mov_b32_e32 v7, v2
	v_mov_b32_e32 v8, v2
	v_mov_b32_e32 v9, v2
	v_mov_b32_e32 v10, v2
	v_mov_b32_e32 v11, v2
	v_mov_b32_e32 v12, v2
	v_mov_b32_e32 v13, v2
	v_mov_b32_e32 v14, v2
	v_mov_b32_e32 v15, v2
	v_mov_b32_e32 v16, v2
	v_mov_b32_e32 v17, v2
	v_mov_b32_e32 v22, v2
	v_mov_b32_e32 v23, v2
	v_mov_b32_e32 v24, v2
	v_mov_b32_e32 v25, v2
	v_mov_b32_e32 v26, v2
	v_mov_b32_e32 v27, v2
	v_mov_b32_e32 v28, v2
	v_mov_b32_e32 v29, v2
	v_mov_b32_e32 v34, v2
	v_mov_b32_e32 v35, v2
	v_mov_b32_e32 v36, v2
	v_mov_b32_e32 v37, v2
	v_mov_b32_e32 v38, v2
	v_mov_b32_e32 v39, v2
	v_mov_b32_e32 v40, v2
	v_mov_b32_e32 v41, v2
	v_mov_b32_e32 v42, v2
	v_mov_b32_e32 v43, v2
	v_mov_b32_e32 v44, v2
	v_mov_b32_e32 v45, v2
	v_mov_b32_e32 v46, v2
	v_mov_b32_e32 v47, v2
	v_mov_b32_e32 v48, v2
	v_mov_b32_e32 v49, v2
	v_mov_b32_e32 v50, v2
	v_mov_b32_e32 v51, v2
	v_mov_b32_e32 v52, v2
	v_mov_b32_e32 v53, v2
	v_mov_b32_e32 v54, v2
	v_mov_b32_e32 v55, v2
	v_mov_b32_e32 v56, v2
	v_mov_b32_e32 v57, v2
	v_mov_b32_e32 v58, v2
	v_mov_b32_e32 v59, v2
	v_mov_b32_e32 v60, v2
	v_mov_b32_e32 v61, v2
	v_mov_b32_e32 v66, v2
	v_mov_b32_e32 v67, v2
	v_mov_b32_e32 v68, v2
	v_mov_b32_e32 v69, v2
	v_mov_b32_e32 v78, v2
	v_mov_b32_e32 v79, v2
	v_mov_b32_e32 v80, v2
	v_mov_b32_e32 v81, v2
	v_mov_b32_e32 v86, v2
	v_mov_b32_e32 v87, v2
	v_mov_b32_e32 v88, v2
	v_mov_b32_e32 v89, v2
	v_mov_b32_e32 v90, v2
	v_mov_b32_e32 v91, v2
	v_mov_b32_e32 v92, v2
	v_mov_b32_e32 v93, v2
	v_mov_b32_e32 v94, v2
	v_mov_b32_e32 v95, v2
	v_mov_b32_e32 v96, v2
	v_mov_b32_e32 v97, v2
	v_mov_b32_e32 v98, v2
	v_mov_b32_e32 v99, v2
	v_mov_b32_e32 v100, v2
	v_mov_b32_e32 v101, v2
	v_mov_b32_e32 v102, v2
	v_mov_b32_e32 v103, v2
	v_mov_b32_e32 v104, v2
	v_mov_b32_e32 v105, v2
	v_mov_b32_e32 v106, v2
	v_mov_b32_e32 v107, v2
	v_mov_b32_e32 v108, v2
	v_mov_b32_e32 v109, v2
	v_mov_b32_e32 v110, v2
	v_mov_b32_e32 v111, v2
	v_mov_b32_e32 v112, v2
	v_mov_b32_e32 v113, v2
	v_mov_b32_e32 v114, v2
	v_mov_b32_e32 v115, v2
	v_mov_b32_e32 v116, v2
	v_mov_b32_e32 v117, v2
	v_mov_b32_e32 v118, v2
	v_mov_b32_e32 v119, v2
	v_mov_b32_e32 v120, v2
	v_mov_b32_e32 v121, v2
	v_mov_b32_e32 v122, v2
	v_mov_b32_e32 v123, v2
	v_mov_b32_e32 v124, v2
	v_mov_b32_e32 v125, v2
	v_mov_b32_e32 v126, v2
	v_mov_b32_e32 v127, v2
	v_mov_b32_e32 v128, v2
	v_mov_b32_e32 v129, v2
	s_branch .LBB0_883

; #define PG8_STAGE(bufoff, gbase, voff) do { _Pragma("unroll") for (int _i = 0; _i < 2; ++_i) \
;         __builtin_amdgcn_global_load_lds((const unsigned*)((const char*)(gbase) + (voff)[_i]), (PG8_LAS unsigned*)(lds + (bufoff) + ldsw + _i * 8192), 16, 0, 0); } while (0)
; #define PG8_LDA(dst, b, h) do { _Pragma("unroll") for (int m = 0; m < 4; ++m) _Pragma("unroll") for (int k = 0; k < 2; ++k) dst[m][k] = *(const PG8_LAS bf16x8*)(lds + PG8_SA(b, h) + aoff + m * 2048 + k * 1024); } while (0)
; #define PG8_LDB(dst, b, h) do { _Pragma("unroll") for (int n = 0; n < 2; ++n) _Pragma("unroll") for (int k = 0; k < 2; ++k) dst[n][k] = *(const PG8_LAS bf16x8*)(lds + PG8_SB(b, h) + boff + n * 2048 + k * 1024); } while (0)
; #define PG8_WAIT_V(n) asm volatile("s_waitcnt vmcnt(" #n ")" ::: "memory")
; #define PG8_WAIT_L(n) asm volatile("s_waitcnt lgkmcnt(" #n ")" ::: "memory")
; #define PG8_BAR __builtin_amdgcn_s_barrier()
; #define PG8_SCHED __builtin_amdgcn_sched_barrier(0)
; template <class Epi, class Sched, bool ALIGN_EPI = false, bool SP2 = false, bool F8 = false>
; __device__ __forceinline__ void gemm_phase(PG8_LAS unsigned char* lds, const Gemm g, const Sched& S, const Epi& E) {
;     ...
;             PG8_LDB(B0, 0, 0); PG8_LDB(B1, 0, 1); PG8_SCHED; PG8_LDA(At, 0, 0); PG8_STAGE(PG8_SA(1, 1), a1 + hA, voffA);
;             PG8_WAIT_V(8); PG8_WAIT_L(0); PG8_BAR; PG8_MMA(0, 0, At, B0); PG8_MMA(0, 1, At, B1); PG8_BAR; PG8_SCHED;
;             PG8_LDA(At, 0, 1); PG8_STAGE(PG8_SB(0, 0), b2, voffB); PG8_STAGE(PG8_SB(0, 1), b2 + hB, voffB); PG8_STAGE(PG8_SA(0, 0), a2, voffA);
.LBB0_883:
	ds_read_b128 v[130:133], v247
	ds_read_b128 v[134:137], v247 offset:1024
	ds_read_b128 v[138:141], v247 offset:2048
	ds_read_b128 v[142:145], v247 offset:3072
	ds_read_b128 v[146:149], v248
	ds_read_b128 v[150:153], v248 offset:1024
	ds_read_b128 v[154:157], v248 offset:2048
	ds_read_b128 v[158:161], v248 offset:3072
	s_add_u32 s14, s10, 0xfff00080
	s_addc_u32 s15, s11, -1
	s_cmp_eq_u32 s88, 12
	s_cselect_b32 s17, s13, s15
	s_cselect_b32 s16, s77, s14
	s_cselect_b32 s15, s79, s87
	s_cselect_b32 s14, s85, s86
	v_lshl_add_u64 v[212:213], s[10:11], 0, v[194:195]
	s_add_i32 m0, s6, 0xc000
	ds_read_b128 v[162:165], v249
	ds_read_b128 v[166:169], v249 offset:1024
	ds_read_b128 v[170:173], v249 offset:2048
	ds_read_b128 v[174:177], v249 offset:3072
	ds_read_b128 v[178:181], v249 offset:4096
	ds_read_b128 v[200:203], v249 offset:5120
	ds_read_b128 v[204:207], v249 offset:6144
	ds_read_b128 v[208:211], v249 offset:7168
	global_load_lds_dwordx4 v[212:213], off
	v_lshl_add_u64 v[212:213], s[10:11], 0, v[192:193]
	s_add_i32 m0, s6, 0xe000
	s_nop 0
	global_load_lds_dwordx4 v[212:213], off
	s_waitcnt vmcnt(8)
	s_waitcnt lgkmcnt(0)
	s_setprio 1
	s_barrier
	v_mfma_f32_16x16x32_bf16 v[126:129], v[130:133], v[162:165], v[126:129]
	v_mfma_f32_16x16x32_bf16 v[122:125], v[138:141], v[162:165], v[122:125]
	v_mfma_f32_16x16x32_bf16 v[118:121], v[130:133], v[170:173], v[118:121]
	v_mfma_f32_16x16x32_bf16 v[114:117], v[138:141], v[170:173], v[114:117]
	v_mfma_f32_16x16x32_bf16 v[110:113], v[130:133], v[178:181], v[110:113]
	v_mfma_f32_16x16x32_bf16 v[106:109], v[138:141], v[178:181], v[106:109]
	v_mfma_f32_16x16x32_bf16 v[102:105], v[130:133], v[204:207], v[102:105]
	v_mfma_f32_16x16x32_bf16 v[98:101], v[138:141], v[204:207], v[98:101]
	v_mfma_f32_16x16x32_bf16 v[126:129], v[134:137], v[166:169], v[126:129]
	v_mfma_f32_16x16x32_bf16 v[122:125], v[142:145], v[166:169], v[122:125]
	v_mfma_f32_16x16x32_bf16 v[118:121], v[134:137], v[174:177], v[118:121]
	v_mfma_f32_16x16x32_bf16 v[114:117], v[142:145], v[174:177], v[114:117]
	v_mfma_f32_16x16x32_bf16 v[110:113], v[134:137], v[200:203], v[110:113]
	v_mfma_f32_16x16x32_bf16 v[106:109], v[142:145], v[200:203], v[106:109]
	v_mfma_f32_16x16x32_bf16 v[102:105], v[134:137], v[208:211], v[102:105]
	v_mfma_f32_16x16x32_bf16 v[98:101], v[142:145], v[208:211], v[98:101]
	v_mfma_f32_16x16x32_bf16 v[82:85], v[146:149], v[162:165], v[82:85]
	v_mfma_f32_16x16x32_bf16 v[74:77], v[154:157], v[162:165], v[74:77]
	v_mfma_f32_16x16x32_bf16 v[94:97], v[146:149], v[170:173], v[94:97]
	v_mfma_f32_16x16x32_bf16 v[90:93], v[154:157], v[170:173], v[90:93]
	v_mfma_f32_16x16x32_bf16 v[86:89], v[146:149], v[178:181], v[86:89]
	v_mfma_f32_16x16x32_bf16 v[78:81], v[154:157], v[178:181], v[78:81]
	v_mfma_f32_16x16x32_bf16 v[70:73], v[146:149], v[204:207], v[70:73]
	v_mfma_f32_16x16x32_bf16 v[62:65], v[154:157], v[204:207], v[62:65]
	v_mfma_f32_16x16x32_bf16 v[82:85], v[150:153], v[166:169], v[82:85]
	v_mfma_f32_16x16x32_bf16 v[74:77], v[158:161], v[166:169], v[74:77]
	v_mfma_f32_16x16x32_bf16 v[94:97], v[150:153], v[174:177], v[94:97]
	v_mfma_f32_16x16x32_bf16 v[90:93], v[158:161], v[174:177], v[90:93]
	v_mfma_f32_16x16x32_bf16 v[86:89], v[150:153], v[200:203], v[86:89]
	v_mfma_f32_16x16x32_bf16 v[78:81], v[158:161], v[200:203], v[78:81]
	v_mfma_f32_16x16x32_bf16 v[70:73], v[150:153], v[208:211], v[70:73]
	v_mfma_f32_16x16x32_bf16 v[62:65], v[158:161], v[208:211], v[62:65]
	s_barrier
	s_setprio 0
	s_add_i32 s89, s54, s96
	v_lshl_add_u64 v[212:213], s[14:15], 0, v[184:185]
	s_mov_b32 m0, s89
	ds_read_b128 v[162:165], v249 offset:16384
	ds_read_b128 v[166:169], v249 offset:17408
	ds_read_b128 v[170:173], v249 offset:18432
	ds_read_b128 v[174:177], v249 offset:19456
	ds_read_b128 v[178:181], v249 offset:20480
	ds_read_b128 v[200:203], v249 offset:21504
	ds_read_b128 v[204:207], v249 offset:22528
	ds_read_b128 v[208:211], v249 offset:23552
	global_load_lds_dwordx4 v[212:213], off
	s_add_i32 m0, s89, 0x2000
	s_add_u32 s90, s14, 0x100000
	v_lshl_add_u64 v[214:215], s[14:15], 0, v[188:189]
	s_addc_u32 s91, s15, 0
	s_add_i32 s89, s55, s96
	global_load_lds_dwordx4 v[214:215], off
	v_lshl_add_u64 v[216:217], s[90:91], 0, v[184:185]
	s_mov_b32 m0, s89
	v_lshl_add_u64 v[218:219], s[16:17], 0, v[186:187]
	global_load_lds_dwordx4 v[216:217], off
	v_lshl_add_u64 v[216:217], s[90:91], 0, v[188:189]
	s_add_i32 m0, s89, 0x2000
	s_nop 0
	global_load_lds_dwordx4 v[216:217], off
	v_lshl_add_u64 v[216:217], s[16:17], 0, v[182:183]
	s_mov_b32 m0, s6
	s_nop 0
	global_load_lds_dwordx4 v[216:217], off
	s_mov_b32 m0, s7
	s_nop 0
	global_load_lds_dwordx4 v[218:219], off
	s_waitcnt vmcnt(8)
	s_waitcnt lgkmcnt(0)
	s_setprio 1
	s_barrier
; #define PG8_STAGE(bufoff, gbase, voff) do { _Pragma("unroll") for (int _i = 0; _i < 2; ++_i) \
;         __builtin_amdgcn_global_load_lds((const unsigned*)((const char*)(gbase) + (voff)[_i]), (PG8_LAS unsigned*)(lds + (bufoff) + ldsw + _i * 8192), 16, 0, 0); } while (0)
; #define PG8_LDA(dst, b, h) do { _Pragma("unroll") for (int m = 0; m < 4; ++m) _Pragma("unroll") for (int k = 0; k < 2; ++k) dst[m][k] = *(const PG8_LAS bf16x8*)(lds + PG8_SA(b, h) + aoff + m * 2048 + k * 1024); } while (0)
; #define PG8_LDB(dst, b, h) do { _Pragma("unroll") for (int n = 0; n < 2; ++n) _Pragma("unroll") for (int k = 0; k < 2; ++k) dst[n][k] = *(const PG8_LAS bf16x8*)(lds + PG8_SB(b, h) + boff + n * 2048 + k * 1024); } while (0)
; #define PG8_WAIT_V(n) asm volatile("s_waitcnt vmcnt(" #n ")" ::: "memory")
; #define PG8_WAIT_L(n) asm volatile("s_waitcnt lgkmcnt(" #n ")" ::: "memory")
; #define PG8_BAR __builtin_amdgcn_s_barrier()
; #define PG8_SCHED __builtin_amdgcn_sched_barrier(0)
; template <class Epi, class Sched, bool ALIGN_EPI = false, bool SP2 = false, bool F8 = false>
; __device__ __forceinline__ void gemm_phase(PG8_LAS unsigned char* lds, const Gemm g, const Sched& S, const Epi& E) {
;     ...
;             PG8_WAIT_V(8); PG8_WAIT_L(0); PG8_BAR; PG8_MMA(1, 0, At, B0); PG8_MMA(1, 1, At, B1); PG8_BAR; PG8_SCHED;
;             PG8_LDB(B0, 1, 0); PG8_LDB(B1, 1, 1); PG8_SCHED; PG8_LDA(At, 1, 0); PG8_STAGE(PG8_SA(0, 1), a2 + hA, voffA);
;             PG8_WAIT_V(8); PG8_WAIT_L(0); PG8_BAR; PG8_MMA(0, 0, At, B0); PG8_MMA(0, 1, At, B1); PG8_BAR; PG8_SCHED;
	v_mfma_f32_16x16x32_bf16 v[66:69], v[130:133], v[162:165], v[66:69]
	v_mfma_f32_16x16x32_bf16 v[58:61], v[138:141], v[162:165], v[58:61]
	v_mfma_f32_16x16x32_bf16 v[54:57], v[130:133], v[170:173], v[54:57]
	v_mfma_f32_16x16x32_bf16 v[50:53], v[138:141], v[170:173], v[50:53]
	v_mfma_f32_16x16x32_bf16 v[46:49], v[130:133], v[178:181], v[46:49]
	v_mfma_f32_16x16x32_bf16 v[42:45], v[138:141], v[178:181], v[42:45]
	v_mfma_f32_16x16x32_bf16 v[38:41], v[130:133], v[204:207], v[38:41]
	v_mfma_f32_16x16x32_bf16 v[34:37], v[138:141], v[204:207], v[34:37]
	v_mfma_f32_16x16x32_bf16 v[66:69], v[134:137], v[166:169], v[66:69]
	v_mfma_f32_16x16x32_bf16 v[58:61], v[142:145], v[166:169], v[58:61]
	v_mfma_f32_16x16x32_bf16 v[54:57], v[134:137], v[174:177], v[54:57]
	v_mfma_f32_16x16x32_bf16 v[50:53], v[142:145], v[174:177], v[50:53]
	v_mfma_f32_16x16x32_bf16 v[46:49], v[134:137], v[200:203], v[46:49]
	v_mfma_f32_16x16x32_bf16 v[42:45], v[142:145], v[200:203], v[42:45]
	v_mfma_f32_16x16x32_bf16 v[38:41], v[134:137], v[208:211], v[38:41]
	v_mfma_f32_16x16x32_bf16 v[34:37], v[142:145], v[208:211], v[34:37]
	v_mfma_f32_16x16x32_bf16 v[30:33], v[146:149], v[162:165], v[30:33]
	v_mfma_f32_16x16x32_bf16 v[18:21], v[154:157], v[162:165], v[18:21]
	v_mfma_f32_16x16x32_bf16 v[26:29], v[146:149], v[170:173], v[26:29]
	v_mfma_f32_16x16x32_bf16 v[22:25], v[154:157], v[170:173], v[22:25]
	v_mfma_f32_16x16x32_bf16 v[14:17], v[146:149], v[178:181], v[14:17]
	v_mfma_f32_16x16x32_bf16 v[10:13], v[154:157], v[178:181], v[10:13]
	v_mfma_f32_16x16x32_bf16 v[6:9], v[146:149], v[204:207], v[6:9]
	v_mfma_f32_16x16x32_bf16 v[2:5], v[154:157], v[204:207], v[2:5]
	v_mfma_f32_16x16x32_bf16 v[30:33], v[150:153], v[166:169], v[30:33]
	v_mfma_f32_16x16x32_bf16 v[18:21], v[158:161], v[166:169], v[18:21]
	v_mfma_f32_16x16x32_bf16 v[26:29], v[150:153], v[174:177], v[26:29]
	v_mfma_f32_16x16x32_bf16 v[22:25], v[158:161], v[174:177], v[22:25]
	v_mfma_f32_16x16x32_bf16 v[14:17], v[150:153], v[200:203], v[14:17]
	v_mfma_f32_16x16x32_bf16 v[10:13], v[158:161], v[200:203], v[10:13]
	v_mfma_f32_16x16x32_bf16 v[6:9], v[150:153], v[208:211], v[6:9]
	v_mfma_f32_16x16x32_bf16 v[2:5], v[158:161], v[208:211], v[2:5]
	s_barrier
	s_setprio 0
	s_add_i32 s89, 0, 0x18000
	s_add_i32 s90, 0, 0x1c000
	v_add_u32_e32 v142, s89, v245
	v_add_u32_e32 v158, s90, v245
	ds_read_b128 v[130:133], v142
	ds_read_b128 v[134:137], v142 offset:1024
	ds_read_b128 v[138:141], v142 offset:2048
	ds_read_b128 v[142:145], v142 offset:3072
	ds_read_b128 v[146:149], v158
	ds_read_b128 v[150:153], v158 offset:1024
	ds_read_b128 v[154:157], v158 offset:2048
	ds_read_b128 v[158:161], v158 offset:3072
	s_add_u32 s16, s16, 0x100000
	s_addc_u32 s17, s17, 0
	s_mov_b32 m0, s5
	v_lshl_add_u64 v[220:221], s[16:17], 0, v[182:183]
	ds_read_b128 v[162:165], v249 offset:32768
	ds_read_b128 v[166:169], v249 offset:33792
	ds_read_b128 v[170:173], v249 offset:34816
	ds_read_b128 v[174:177], v249 offset:35840
	ds_read_b128 v[178:181], v249 offset:36864
	ds_read_b128 v[200:203], v249 offset:37888
	ds_read_b128 v[204:207], v249 offset:38912
	ds_read_b128 v[208:211], v249 offset:39936
	global_load_lds_dwordx4 v[220:221], off
	v_lshl_add_u64 v[220:221], s[16:17], 0, v[186:187]
	s_mov_b32 m0, s18
	s_nop 0
	global_load_lds_dwordx4 v[220:221], off
	s_waitcnt vmcnt(8)
	s_waitcnt lgkmcnt(0)
	s_setprio 1
	s_barrier
	v_mfma_f32_16x16x32_bf16 v[126:129], v[130:133], v[162:165], v[126:129]
	v_mfma_f32_16x16x32_bf16 v[122:125], v[138:141], v[162:165], v[122:125]
	v_mfma_f32_16x16x32_bf16 v[118:121], v[130:133], v[170:173], v[118:121]
	v_mfma_f32_16x16x32_bf16 v[114:117], v[138:141], v[170:173], v[114:117]
	v_mfma_f32_16x16x32_bf16 v[110:113], v[130:133], v[178:181], v[110:113]
	v_mfma_f32_16x16x32_bf16 v[106:109], v[138:141], v[178:181], v[106:109]
	v_mfma_f32_16x16x32_bf16 v[102:105], v[130:133], v[204:207], v[102:105]
	v_mfma_f32_16x16x32_bf16 v[98:101], v[138:141], v[204:207], v[98:101]
	v_mfma_f32_16x16x32_bf16 v[126:129], v[134:137], v[166:169], v[126:129]
	v_mfma_f32_16x16x32_bf16 v[122:125], v[142:145], v[166:169], v[122:125]
	v_mfma_f32_16x16x32_bf16 v[118:121], v[134:137], v[174:177], v[118:121]
	v_mfma_f32_16x16x32_bf16 v[114:117], v[142:145], v[174:177], v[114:117]
	v_mfma_f32_16x16x32_bf16 v[110:113], v[134:137], v[200:203], v[110:113]
	v_mfma_f32_16x16x32_bf16 v[106:109], v[142:145], v[200:203], v[106:109]
	v_mfma_f32_16x16x32_bf16 v[102:105], v[134:137], v[208:211], v[102:105]
	v_mfma_f32_16x16x32_bf16 v[98:101], v[142:145], v[208:211], v[98:101]
	v_mfma_f32_16x16x32_bf16 v[82:85], v[146:149], v[162:165], v[82:85]
	v_mfma_f32_16x16x32_bf16 v[74:77], v[154:157], v[162:165], v[74:77]
	v_mfma_f32_16x16x32_bf16 v[94:97], v[146:149], v[170:173], v[94:97]
	v_mfma_f32_16x16x32_bf16 v[90:93], v[154:157], v[170:173], v[90:93]
	v_mfma_f32_16x16x32_bf16 v[86:89], v[146:149], v[178:181], v[86:89]
	v_mfma_f32_16x16x32_bf16 v[78:81], v[154:157], v[178:181], v[78:81]
	v_mfma_f32_16x16x32_bf16 v[70:73], v[146:149], v[204:207], v[70:73]
	v_mfma_f32_16x16x32_bf16 v[62:65], v[154:157], v[204:207], v[62:65]
	v_mfma_f32_16x16x32_bf16 v[82:85], v[150:153], v[166:169], v[82:85]
	v_mfma_f32_16x16x32_bf16 v[74:77], v[158:161], v[166:169], v[74:77]
	v_mfma_f32_16x16x32_bf16 v[94:97], v[150:153], v[174:177], v[94:97]
	v_mfma_f32_16x16x32_bf16 v[90:93], v[158:161], v[174:177], v[90:93]
	v_mfma_f32_16x16x32_bf16 v[86:89], v[150:153], v[200:203], v[86:89]
	v_mfma_f32_16x16x32_bf16 v[78:81], v[158:161], v[200:203], v[78:81]
	v_mfma_f32_16x16x32_bf16 v[70:73], v[150:153], v[208:211], v[70:73]
	v_mfma_f32_16x16x32_bf16 v[62:65], v[158:161], v[208:211], v[62:65]
	s_barrier
; #define PG8_STAGE(bufoff, gbase, voff) do { _Pragma("unroll") for (int _i = 0; _i < 2; ++_i) \
;         __builtin_amdgcn_global_load_lds((const unsigned*)((const char*)(gbase) + (voff)[_i]), (PG8_LAS unsigned*)(lds + (bufoff) + ldsw + _i * 8192), 16, 0, 0); } while (0)
; #define PG8_LDA(dst, b, h) do { _Pragma("unroll") for (int m = 0; m < 4; ++m) _Pragma("unroll") for (int k = 0; k < 2; ++k) dst[m][k] = *(const PG8_LAS bf16x8*)(lds + PG8_SA(b, h) + aoff + m * 2048 + k * 1024); } while (0)
; #define PG8_WAIT_V(n) asm volatile("s_waitcnt vmcnt(" #n ")" ::: "memory")
; #define PG8_WAIT_L(n) asm volatile("s_waitcnt lgkmcnt(" #n ")" ::: "memory")
; #define PG8_BAR __builtin_amdgcn_s_barrier()
; #define PG8_SCHED __builtin_amdgcn_sched_barrier(0)
; template <class Epi, class Sched, bool ALIGN_EPI = false, bool SP2 = false, bool F8 = false>
; __device__ __forceinline__ void gemm_phase(PG8_LAS unsigned char* lds, const Gemm g, const Sched& S, const Epi& E) {
;     ...
;         for (int t = 0; t < nt; t += 2) {
;             const bool last = (t == nt - 2);
;             const char* a1 = cA + (size_t)(t + 1) * kstep;
;             const char* a2 = last ? nA : cA + (size_t)(t + 2) * kstep; const char* b2 = last ? nB : cB + (size_t)(t + 2) * kstep;
;     ...
;             PG8_LDA(At, 1, 1); PG8_STAGE(PG8_SB(1, 0), b3, voffB); PG8_STAGE(PG8_SB(1, 1), b3 + hB, voffB); PG8_STAGE(PG8_SA(1, 0), a3, voffA);
;             PG8_WAIT_V(8); PG8_WAIT_L(0); PG8_BAR; PG8_MMA(1, 0, At, B0); PG8_MMA(1, 1, At, B1); PG8_BAR; PG8_SCHED;
;     ...
;         if constexpr (ALIGN_EPI) { if (wr == 0) PG8_BAR; }
	s_setprio 0
	s_add_i32 s16, s89, s96
	v_lshl_add_u64 v[212:213], v[212:213], 0, s[34:35]
	s_mov_b32 m0, s16
	ds_read_b128 v[162:165], v249 offset:49152
	ds_read_b128 v[166:169], v249 offset:50176
	ds_read_b128 v[170:173], v249 offset:51200
	ds_read_b128 v[174:177], v249 offset:52224
	ds_read_b128 v[178:181], v249 offset:53248
	ds_read_b128 v[200:203], v249 offset:54272
	ds_read_b128 v[204:207], v249 offset:55296
	ds_read_b128 v[208:211], v249 offset:56320
	global_load_lds_dwordx4 v[212:213], off
	s_add_i32 m0, s16, 0x2000
	s_add_u32 s14, s14, 0x100080
	v_lshl_add_u64 v[212:213], v[214:215], 0, s[34:35]
	s_addc_u32 s15, s15, 0
	s_add_i32 s16, s90, s96
	global_load_lds_dwordx4 v[212:213], off
	v_lshl_add_u64 v[212:213], s[14:15], 0, v[184:185]
	s_mov_b32 m0, s16
	s_nop 0
	global_load_lds_dwordx4 v[212:213], off
	v_lshl_add_u64 v[212:213], s[14:15], 0, v[188:189]
	s_add_i32 m0, s16, 0x2000
	s_nop 0
	global_load_lds_dwordx4 v[212:213], off
	v_lshl_add_u64 v[212:213], v[216:217], 0, s[34:35]
	s_mov_b32 m0, s31
	s_nop 0
	global_load_lds_dwordx4 v[212:213], off
	v_lshl_add_u64 v[212:213], v[218:219], 0, s[34:35]
	s_mov_b32 m0, s50
	s_nop 0
	global_load_lds_dwordx4 v[212:213], off
	s_waitcnt vmcnt(8)
	s_waitcnt lgkmcnt(0)
	s_setprio 1
	s_barrier
	v_mfma_f32_16x16x32_bf16 v[66:69], v[130:133], v[162:165], v[66:69]
	v_mfma_f32_16x16x32_bf16 v[58:61], v[138:141], v[162:165], v[58:61]
	v_mfma_f32_16x16x32_bf16 v[54:57], v[130:133], v[170:173], v[54:57]
	v_mfma_f32_16x16x32_bf16 v[50:53], v[138:141], v[170:173], v[50:53]
	v_mfma_f32_16x16x32_bf16 v[46:49], v[130:133], v[178:181], v[46:49]
	v_mfma_f32_16x16x32_bf16 v[42:45], v[138:141], v[178:181], v[42:45]
	v_mfma_f32_16x16x32_bf16 v[38:41], v[130:133], v[204:207], v[38:41]
	v_mfma_f32_16x16x32_bf16 v[34:37], v[138:141], v[204:207], v[34:37]
	v_mfma_f32_16x16x32_bf16 v[66:69], v[134:137], v[166:169], v[66:69]
	v_mfma_f32_16x16x32_bf16 v[58:61], v[142:145], v[166:169], v[58:61]
	v_mfma_f32_16x16x32_bf16 v[54:57], v[134:137], v[174:177], v[54:57]
	v_mfma_f32_16x16x32_bf16 v[50:53], v[142:145], v[174:177], v[50:53]
	v_mfma_f32_16x16x32_bf16 v[46:49], v[134:137], v[200:203], v[46:49]
	v_mfma_f32_16x16x32_bf16 v[42:45], v[142:145], v[200:203], v[42:45]
	v_mfma_f32_16x16x32_bf16 v[38:41], v[134:137], v[208:211], v[38:41]
	v_mfma_f32_16x16x32_bf16 v[34:37], v[142:145], v[208:211], v[34:37]
	v_mfma_f32_16x16x32_bf16 v[30:33], v[146:149], v[162:165], v[30:33]
	v_mfma_f32_16x16x32_bf16 v[18:21], v[154:157], v[162:165], v[18:21]
	v_mfma_f32_16x16x32_bf16 v[26:29], v[146:149], v[170:173], v[26:29]
	v_mfma_f32_16x16x32_bf16 v[22:25], v[154:157], v[170:173], v[22:25]
	v_mfma_f32_16x16x32_bf16 v[14:17], v[146:149], v[178:181], v[14:17]
	v_mfma_f32_16x16x32_bf16 v[10:13], v[154:157], v[178:181], v[10:13]
	v_mfma_f32_16x16x32_bf16 v[6:9], v[146:149], v[204:207], v[6:9]
	v_mfma_f32_16x16x32_bf16 v[2:5], v[154:157], v[204:207], v[2:5]
	v_mfma_f32_16x16x32_bf16 v[30:33], v[150:153], v[166:169], v[30:33]
	v_mfma_f32_16x16x32_bf16 v[18:21], v[158:161], v[166:169], v[18:21]
	v_mfma_f32_16x16x32_bf16 v[26:29], v[150:153], v[174:177], v[26:29]
	v_mfma_f32_16x16x32_bf16 v[22:25], v[158:161], v[174:177], v[22:25]
	v_mfma_f32_16x16x32_bf16 v[14:17], v[150:153], v[200:203], v[14:17]
	v_mfma_f32_16x16x32_bf16 v[10:13], v[158:161], v[200:203], v[10:13]
	v_mfma_f32_16x16x32_bf16 v[6:9], v[150:153], v[208:211], v[6:9]
	v_mfma_f32_16x16x32_bf16 v[2:5], v[158:161], v[208:211], v[2:5]
	s_add_i32 s88, s88, 2
	s_add_u32 s86, s86, 0x100
	s_addc_u32 s87, s87, 0
	s_add_u32 s10, s10, 0x100
	s_addc_u32 s11, s11, 0
	s_cmp_gt_u32 s88, 13
	s_cbranch_scc0 .Lber_883
	s_barrier
	s_setprio 0
	s_and_b64 vcc, exec, s[36:37]
	s_cbranch_vccz .LBB0_886
	s_barrier

; template <class Epi, class Sched, bool ALIGN_EPI = false, bool SP2 = false, bool F8 = false>
; __device__ __forceinline__ void gemm_phase(PG8_LAS unsigned char* lds, const Gemm g, const Sched& S, const Epi& E) {
;     ...
; #pragma unroll
;         for (int a = 0; a < 2; ++a)
; #pragma unroll
;             for (int b = 0; b < 2; ++b)
; #pragma unroll
;                 for (int m = 0; m < 4; ++m)
; #pragma unroll
;                     for (int n = 0; n < 2; ++n) acc[a][b][m][n] = (f32x4){0.f, 0.f, 0.f, 0.f};
.LBB0_1077:
	s_add_u32 s53, s28, 0x100
	v_mov_b32_e32 v2, 0
	s_addc_u32 s54, s29, 0
	s_mov_b32 s55, -2
	v_mov_b32_e32 v3, v2
	v_mov_b32_e32 v4, v2
	v_mov_b32_e32 v5, v2
	v_mov_b32_e32 v6, v2
	v_mov_b32_e32 v7, v2
	v_mov_b32_e32 v8, v2
	v_mov_b32_e32 v9, v2
	v_mov_b32_e32 v14, v2
	v_mov_b32_e32 v15, v2
	v_mov_b32_e32 v16, v2
	v_mov_b32_e32 v17, v2
	v_mov_b32_e32 v22, v2
	v_mov_b32_e32 v23, v2
	v_mov_b32_e32 v24, v2
	v_mov_b32_e32 v25, v2
	v_mov_b32_e32 v30, v2
	v_mov_b32_e32 v31, v2
	v_mov_b32_e32 v32, v2
	v_mov_b32_e32 v33, v2
	v_mov_b32_e32 v38, v2
	v_mov_b32_e32 v39, v2
	v_mov_b32_e32 v40, v2
	v_mov_b32_e32 v41, v2
	v_mov_b32_e32 v46, v2
	v_mov_b32_e32 v47, v2
	v_mov_b32_e32 v48, v2
	v_mov_b32_e32 v49, v2
	v_mov_b32_e32 v54, v2
	v_mov_b32_e32 v55, v2
	v_mov_b32_e32 v56, v2
	v_mov_b32_e32 v57, v2
	v_mov_b32_e32 v10, v2
	v_mov_b32_e32 v11, v2
	v_mov_b32_e32 v12, v2
	v_mov_b32_e32 v13, v2
	v_mov_b32_e32 v18, v2
	v_mov_b32_e32 v19, v2
	v_mov_b32_e32 v20, v2
	v_mov_b32_e32 v21, v2
	v_mov_b32_e32 v26, v2
	v_mov_b32_e32 v27, v2
	v_mov_b32_e32 v28, v2
	v_mov_b32_e32 v29, v2
	v_mov_b32_e32 v34, v2
	v_mov_b32_e32 v35, v2
	v_mov_b32_e32 v36, v2
	v_mov_b32_e32 v37, v2
	v_mov_b32_e32 v42, v2
	v_mov_b32_e32 v43, v2
	v_mov_b32_e32 v44, v2
	v_mov_b32_e32 v45, v2
	v_mov_b32_e32 v50, v2
	v_mov_b32_e32 v51, v2
	v_mov_b32_e32 v52, v2
	v_mov_b32_e32 v53, v2
	v_mov_b32_e32 v58, v2
	v_mov_b32_e32 v59, v2
	v_mov_b32_e32 v60, v2
	v_mov_b32_e32 v61, v2
	v_mov_b32_e32 v62, v2
	v_mov_b32_e32 v63, v2
	v_mov_b32_e32 v64, v2
	v_mov_b32_e32 v65, v2
	v_mov_b32_e32 v66, v2
	v_mov_b32_e32 v67, v2
	v_mov_b32_e32 v68, v2
	v_mov_b32_e32 v69, v2
	v_mov_b32_e32 v70, v2
	v_mov_b32_e32 v71, v2
	v_mov_b32_e32 v72, v2
	v_mov_b32_e32 v73, v2
	v_mov_b32_e32 v78, v2
	v_mov_b32_e32 v79, v2
	v_mov_b32_e32 v80, v2
	v_mov_b32_e32 v81, v2
	v_mov_b32_e32 v86, v2
	v_mov_b32_e32 v87, v2
	v_mov_b32_e32 v88, v2
	v_mov_b32_e32 v89, v2
	v_mov_b32_e32 v94, v2
	v_mov_b32_e32 v95, v2
	v_mov_b32_e32 v96, v2
	v_mov_b32_e32 v97, v2
	v_mov_b32_e32 v102, v2
	v_mov_b32_e32 v103, v2
	v_mov_b32_e32 v104, v2
	v_mov_b32_e32 v105, v2
	v_mov_b32_e32 v110, v2
	v_mov_b32_e32 v111, v2
	v_mov_b32_e32 v112, v2
	v_mov_b32_e32 v113, v2
	v_mov_b32_e32 v114, v2
	v_mov_b32_e32 v115, v2
	v_mov_b32_e32 v116, v2
	v_mov_b32_e32 v117, v2
	v_mov_b32_e32 v74, v2
	v_mov_b32_e32 v75, v2
	v_mov_b32_e32 v76, v2
	v_mov_b32_e32 v77, v2
	v_mov_b32_e32 v82, v2
	v_mov_b32_e32 v83, v2
	v_mov_b32_e32 v84, v2
	v_mov_b32_e32 v85, v2
	v_mov_b32_e32 v90, v2
	v_mov_b32_e32 v91, v2
	v_mov_b32_e32 v92, v2
	v_mov_b32_e32 v93, v2
	v_mov_b32_e32 v98, v2
	v_mov_b32_e32 v99, v2
	v_mov_b32_e32 v100, v2
	v_mov_b32_e32 v101, v2
	v_mov_b32_e32 v106, v2
	v_mov_b32_e32 v107, v2
	v_mov_b32_e32 v108, v2
	v_mov_b32_e32 v109, v2
	v_mov_b32_e32 v118, v2
	v_mov_b32_e32 v119, v2
	v_mov_b32_e32 v120, v2
	v_mov_b32_e32 v121, v2
	v_mov_b32_e32 v122, v2
	v_mov_b32_e32 v123, v2
	v_mov_b32_e32 v124, v2
	v_mov_b32_e32 v125, v2
	v_mov_b32_e32 v126, v2
	v_mov_b32_e32 v127, v2
	v_mov_b32_e32 v128, v2
	v_mov_b32_e32 v129, v2
	s_branch .LBB0_1078

; #define PG8_STAGE(bufoff, gbase, voff) do { _Pragma("unroll") for (int _i = 0; _i < 2; ++_i) \
;         __builtin_amdgcn_global_load_lds((const unsigned*)((const char*)(gbase) + (voff)[_i]), (PG8_LAS unsigned*)(lds + (bufoff) + ldsw + _i * 8192), 16, 0, 0); } while (0)
; #define PG8_LDA(dst, b, h) do { _Pragma("unroll") for (int m = 0; m < 4; ++m) _Pragma("unroll") for (int k = 0; k < 2; ++k) dst[m][k] = *(const PG8_LAS bf16x8*)(lds + PG8_SA(b, h) + aoff + m * 2048 + k * 1024); } while (0)
; #define PG8_LDB(dst, b, h) do { _Pragma("unroll") for (int n = 0; n < 2; ++n) _Pragma("unroll") for (int k = 0; k < 2; ++k) dst[n][k] = *(const PG8_LAS bf16x8*)(lds + PG8_SB(b, h) + boff + n * 2048 + k * 1024); } while (0)
; #define PG8_WAIT_V(n) asm volatile("s_waitcnt vmcnt(" #n ")" ::: "memory")
; #define PG8_WAIT_L(n) asm volatile("s_waitcnt lgkmcnt(" #n ")" ::: "memory")
; #define PG8_BAR __builtin_amdgcn_s_barrier()
; #define PG8_SCHED __builtin_amdgcn_sched_barrier(0)
; template <class Epi, class Sched, bool ALIGN_EPI = false, bool SP2 = false, bool F8 = false>
; __device__ __forceinline__ void gemm_phase(PG8_LAS unsigned char* lds, const Gemm g, const Sched& S, const Epi& E) {
;     ...
;             PG8_LDB(B0, 0, 0); PG8_LDB(B1, 0, 1); PG8_SCHED; PG8_LDA(At, 0, 0); PG8_STAGE(PG8_SA(1, 1), a1 + hA, voffA);
;             PG8_WAIT_V(8); PG8_WAIT_L(0); PG8_BAR; PG8_MMA(0, 0, At, B0); PG8_MMA(0, 1, At, B1); PG8_BAR; PG8_SCHED;
;             PG8_LDA(At, 0, 1); PG8_STAGE(PG8_SB(0, 0), b2, voffB); PG8_STAGE(PG8_SB(0, 1), b2 + hB, voffB); PG8_STAGE(PG8_SA(0, 0), a2, voffA);
.LBB0_1078:
	ds_read_b128 v[130:133], v197
	ds_read_b128 v[134:137], v197 offset:1024
	ds_read_b128 v[138:141], v197 offset:2048
	ds_read_b128 v[142:145], v197 offset:3072
	ds_read_b128 v[146:149], v198
	ds_read_b128 v[150:153], v198 offset:1024
	ds_read_b128 v[154:157], v198 offset:2048
	ds_read_b128 v[158:161], v198 offset:3072
	s_add_u32 s28, s26, 0x100
	s_addc_u32 s29, s27, 0
	s_cmpk_eq_i32 s55, 0xa8
	s_cselect_b32 s35, s7, s29
	s_cselect_b32 s34, s6, s28
	s_cselect_b32 s31, s9, s54
	s_cselect_b32 s30, s8, s53
	v_lshl_add_u64 v[216:217], s[26:27], 0, v[176:177]
	s_add_i32 m0, s39, 0xc000
	ds_read_b128 v[162:165], v199
	ds_read_b128 v[182:185], v199 offset:1024
	ds_read_b128 v[186:189], v199 offset:2048
	ds_read_b128 v[190:193], v199 offset:3072
	ds_read_b128 v[200:203], v199 offset:4096
	ds_read_b128 v[204:207], v199 offset:5120
	ds_read_b128 v[208:211], v199 offset:6144
	ds_read_b128 v[212:215], v199 offset:7168
	global_load_lds_dwordx4 v[216:217], off
	v_lshl_add_u64 v[216:217], s[26:27], 0, v[174:175]
	s_add_i32 m0, s39, 0xe000
	s_nop 0
	global_load_lds_dwordx4 v[216:217], off
	s_waitcnt vmcnt(8)
	s_waitcnt lgkmcnt(0)
	s_setprio 1
	s_barrier
	v_mfma_f32_16x16x32_bf16 v[126:129], v[130:133], v[162:165], v[126:129]
	v_mfma_f32_16x16x32_bf16 v[122:125], v[138:141], v[162:165], v[122:125]
	v_mfma_f32_16x16x32_bf16 v[118:121], v[130:133], v[186:189], v[118:121]
	v_mfma_f32_16x16x32_bf16 v[106:109], v[138:141], v[186:189], v[106:109]
	v_mfma_f32_16x16x32_bf16 v[98:101], v[130:133], v[200:203], v[98:101]
	v_mfma_f32_16x16x32_bf16 v[90:93], v[138:141], v[200:203], v[90:93]
	v_mfma_f32_16x16x32_bf16 v[82:85], v[130:133], v[208:211], v[82:85]
	v_mfma_f32_16x16x32_bf16 v[74:77], v[138:141], v[208:211], v[74:77]
	v_mfma_f32_16x16x32_bf16 v[126:129], v[134:137], v[182:185], v[126:129]
	v_mfma_f32_16x16x32_bf16 v[122:125], v[142:145], v[182:185], v[122:125]
	v_mfma_f32_16x16x32_bf16 v[118:121], v[134:137], v[190:193], v[118:121]
	v_mfma_f32_16x16x32_bf16 v[106:109], v[142:145], v[190:193], v[106:109]
	v_mfma_f32_16x16x32_bf16 v[98:101], v[134:137], v[204:207], v[98:101]
	v_mfma_f32_16x16x32_bf16 v[90:93], v[142:145], v[204:207], v[90:93]
	v_mfma_f32_16x16x32_bf16 v[82:85], v[134:137], v[212:215], v[82:85]
	v_mfma_f32_16x16x32_bf16 v[74:77], v[142:145], v[212:215], v[74:77]
	v_mfma_f32_16x16x32_bf16 v[114:117], v[146:149], v[162:165], v[114:117]
	v_mfma_f32_16x16x32_bf16 v[110:113], v[154:157], v[162:165], v[110:113]
	v_mfma_f32_16x16x32_bf16 v[102:105], v[146:149], v[186:189], v[102:105]
	v_mfma_f32_16x16x32_bf16 v[94:97], v[154:157], v[186:189], v[94:97]
	v_mfma_f32_16x16x32_bf16 v[86:89], v[146:149], v[200:203], v[86:89]
	v_mfma_f32_16x16x32_bf16 v[78:81], v[154:157], v[200:203], v[78:81]
	v_mfma_f32_16x16x32_bf16 v[70:73], v[146:149], v[208:211], v[70:73]
	v_mfma_f32_16x16x32_bf16 v[66:69], v[154:157], v[208:211], v[66:69]
	v_mfma_f32_16x16x32_bf16 v[114:117], v[150:153], v[182:185], v[114:117]
	v_mfma_f32_16x16x32_bf16 v[110:113], v[158:161], v[182:185], v[110:113]
	v_mfma_f32_16x16x32_bf16 v[102:105], v[150:153], v[190:193], v[102:105]
	v_mfma_f32_16x16x32_bf16 v[94:97], v[158:161], v[190:193], v[94:97]
	v_mfma_f32_16x16x32_bf16 v[86:89], v[150:153], v[204:207], v[86:89]
	v_mfma_f32_16x16x32_bf16 v[78:81], v[158:161], v[204:207], v[78:81]
	v_mfma_f32_16x16x32_bf16 v[70:73], v[150:153], v[212:215], v[70:73]
	v_mfma_f32_16x16x32_bf16 v[66:69], v[158:161], v[212:215], v[66:69]
	s_barrier
	s_setprio 0
	s_add_i32 s26, s47, s36
	v_lshl_add_u64 v[216:217], s[30:31], 0, v[170:171]
	s_mov_b32 m0, s26
	ds_read_b128 v[162:165], v199 offset:16384
	ds_read_b128 v[182:185], v199 offset:17408
	ds_read_b128 v[186:189], v199 offset:18432
	ds_read_b128 v[190:193], v199 offset:19456
	ds_read_b128 v[200:203], v199 offset:20480
	ds_read_b128 v[204:207], v199 offset:21504
	ds_read_b128 v[208:211], v199 offset:22528
	ds_read_b128 v[212:215], v199 offset:23552
	global_load_lds_dwordx4 v[216:217], off
	s_add_i32 m0, s26, 0x2000
	s_add_u32 s26, s30, 0x2b0000
	v_lshl_add_u64 v[218:219], s[30:31], 0, v[166:167]
	s_addc_u32 s27, s31, 0
	s_add_i32 s56, s48, s36
	global_load_lds_dwordx4 v[218:219], off
	v_lshl_add_u64 v[220:221], s[26:27], 0, v[170:171]
	s_mov_b32 m0, s56
	v_lshl_add_u64 v[222:223], s[34:35], 0, v[168:169]
	global_load_lds_dwordx4 v[220:221], off
	v_lshl_add_u64 v[220:221], s[26:27], 0, v[166:167]
	s_add_i32 m0, s56, 0x2000
	s_nop 0
	global_load_lds_dwordx4 v[220:221], off
	v_lshl_add_u64 v[220:221], s[34:35], 0, v[172:173]
	s_mov_b32 m0, s39
	s_nop 0
	global_load_lds_dwordx4 v[220:221], off
	s_mov_b32 m0, s40
	s_nop 0
	global_load_lds_dwordx4 v[222:223], off
	s_waitcnt vmcnt(8)
	s_waitcnt lgkmcnt(0)
	s_setprio 1
	s_barrier
; #define PG8_STAGE(bufoff, gbase, voff) do { _Pragma("unroll") for (int _i = 0; _i < 2; ++_i) \
;         __builtin_amdgcn_global_load_lds((const unsigned*)((const char*)(gbase) + (voff)[_i]), (PG8_LAS unsigned*)(lds + (bufoff) + ldsw + _i * 8192), 16, 0, 0); } while (0)
; #define PG8_LDA(dst, b, h) do { _Pragma("unroll") for (int m = 0; m < 4; ++m) _Pragma("unroll") for (int k = 0; k < 2; ++k) dst[m][k] = *(const PG8_LAS bf16x8*)(lds + PG8_SA(b, h) + aoff + m * 2048 + k * 1024); } while (0)
; #define PG8_LDB(dst, b, h) do { _Pragma("unroll") for (int n = 0; n < 2; ++n) _Pragma("unroll") for (int k = 0; k < 2; ++k) dst[n][k] = *(const PG8_LAS bf16x8*)(lds + PG8_SB(b, h) + boff + n * 2048 + k * 1024); } while (0)
; #define PG8_WAIT_V(n) asm volatile("s_waitcnt vmcnt(" #n ")" ::: "memory")
; #define PG8_WAIT_L(n) asm volatile("s_waitcnt lgkmcnt(" #n ")" ::: "memory")
; #define PG8_BAR __builtin_amdgcn_s_barrier()
; #define PG8_SCHED __builtin_amdgcn_sched_barrier(0)
; template <class Epi, class Sched, bool ALIGN_EPI = false, bool SP2 = false, bool F8 = false>
; __device__ __forceinline__ void gemm_phase(PG8_LAS unsigned char* lds, const Gemm g, const Sched& S, const Epi& E) {
;     ...
;             PG8_WAIT_V(8); PG8_WAIT_L(0); PG8_BAR; PG8_MMA(1, 0, At, B0); PG8_MMA(1, 1, At, B1); PG8_BAR; PG8_SCHED;
;             PG8_LDB(B0, 1, 0); PG8_LDB(B1, 1, 1); PG8_SCHED; PG8_LDA(At, 1, 0); PG8_STAGE(PG8_SA(0, 1), a2 + hA, voffA);
;             PG8_WAIT_V(8); PG8_WAIT_L(0); PG8_BAR; PG8_MMA(0, 0, At, B0); PG8_MMA(0, 1, At, B1); PG8_BAR; PG8_SCHED;
	v_mfma_f32_16x16x32_bf16 v[62:65], v[130:133], v[162:165], v[62:65]
	v_mfma_f32_16x16x32_bf16 v[58:61], v[138:141], v[162:165], v[58:61]
	v_mfma_f32_16x16x32_bf16 v[50:53], v[130:133], v[186:189], v[50:53]
	v_mfma_f32_16x16x32_bf16 v[42:45], v[138:141], v[186:189], v[42:45]
	v_mfma_f32_16x16x32_bf16 v[34:37], v[130:133], v[200:203], v[34:37]
	v_mfma_f32_16x16x32_bf16 v[26:29], v[138:141], v[200:203], v[26:29]
	v_mfma_f32_16x16x32_bf16 v[18:21], v[130:133], v[208:211], v[18:21]
	v_mfma_f32_16x16x32_bf16 v[10:13], v[138:141], v[208:211], v[10:13]
	v_mfma_f32_16x16x32_bf16 v[62:65], v[134:137], v[182:185], v[62:65]
	v_mfma_f32_16x16x32_bf16 v[58:61], v[142:145], v[182:185], v[58:61]
	v_mfma_f32_16x16x32_bf16 v[50:53], v[134:137], v[190:193], v[50:53]
	v_mfma_f32_16x16x32_bf16 v[42:45], v[142:145], v[190:193], v[42:45]
	v_mfma_f32_16x16x32_bf16 v[34:37], v[134:137], v[204:207], v[34:37]
	v_mfma_f32_16x16x32_bf16 v[26:29], v[142:145], v[204:207], v[26:29]
	v_mfma_f32_16x16x32_bf16 v[18:21], v[134:137], v[212:215], v[18:21]
	v_mfma_f32_16x16x32_bf16 v[10:13], v[142:145], v[212:215], v[10:13]
	v_mfma_f32_16x16x32_bf16 v[54:57], v[146:149], v[162:165], v[54:57]
	v_mfma_f32_16x16x32_bf16 v[46:49], v[154:157], v[162:165], v[46:49]
	v_mfma_f32_16x16x32_bf16 v[38:41], v[146:149], v[186:189], v[38:41]
	v_mfma_f32_16x16x32_bf16 v[30:33], v[154:157], v[186:189], v[30:33]
	v_mfma_f32_16x16x32_bf16 v[22:25], v[146:149], v[200:203], v[22:25]
	v_mfma_f32_16x16x32_bf16 v[14:17], v[154:157], v[200:203], v[14:17]
	v_mfma_f32_16x16x32_bf16 v[6:9], v[146:149], v[208:211], v[6:9]
	v_mfma_f32_16x16x32_bf16 v[2:5], v[154:157], v[208:211], v[2:5]
	v_mfma_f32_16x16x32_bf16 v[54:57], v[150:153], v[182:185], v[54:57]
	v_mfma_f32_16x16x32_bf16 v[46:49], v[158:161], v[182:185], v[46:49]
	v_mfma_f32_16x16x32_bf16 v[38:41], v[150:153], v[190:193], v[38:41]
	v_mfma_f32_16x16x32_bf16 v[30:33], v[158:161], v[190:193], v[30:33]
	v_mfma_f32_16x16x32_bf16 v[22:25], v[150:153], v[204:207], v[22:25]
	v_mfma_f32_16x16x32_bf16 v[14:17], v[158:161], v[204:207], v[14:17]
	v_mfma_f32_16x16x32_bf16 v[6:9], v[150:153], v[212:215], v[6:9]
	v_mfma_f32_16x16x32_bf16 v[2:5], v[158:161], v[212:215], v[2:5]
	s_barrier
	s_setprio 0
	s_add_i32 s56, 0, 0x18000
	s_add_i32 s57, 0, 0x1c000
	v_add_u32_e32 v142, s56, v195
	v_add_u32_e32 v158, s57, v195
	ds_read_b128 v[130:133], v142
	ds_read_b128 v[134:137], v142 offset:1024
	ds_read_b128 v[138:141], v142 offset:2048
	ds_read_b128 v[142:145], v142 offset:3072
	ds_read_b128 v[146:149], v158
	ds_read_b128 v[150:153], v158 offset:1024
	ds_read_b128 v[154:157], v158 offset:2048
	ds_read_b128 v[158:161], v158 offset:3072
	s_add_u32 s26, s34, 0x2b0000
	s_addc_u32 s27, s35, 0
	s_mov_b32 m0, s41
	v_lshl_add_u64 v[224:225], s[26:27], 0, v[172:173]
	ds_read_b128 v[162:165], v199 offset:32768
	ds_read_b128 v[182:185], v199 offset:33792
	ds_read_b128 v[186:189], v199 offset:34816
	ds_read_b128 v[190:193], v199 offset:35840
	ds_read_b128 v[200:203], v199 offset:36864
	ds_read_b128 v[204:207], v199 offset:37888
	ds_read_b128 v[208:211], v199 offset:38912
	ds_read_b128 v[212:215], v199 offset:39936
	global_load_lds_dwordx4 v[224:225], off
	v_lshl_add_u64 v[224:225], s[26:27], 0, v[168:169]
	s_mov_b32 m0, s42
	s_nop 0
	global_load_lds_dwordx4 v[224:225], off
	s_waitcnt vmcnt(8)
	s_waitcnt lgkmcnt(0)
	s_setprio 1
	s_barrier
	v_mfma_f32_16x16x32_bf16 v[126:129], v[130:133], v[162:165], v[126:129]
	v_mfma_f32_16x16x32_bf16 v[122:125], v[138:141], v[162:165], v[122:125]
	v_mfma_f32_16x16x32_bf16 v[118:121], v[130:133], v[186:189], v[118:121]
	v_mfma_f32_16x16x32_bf16 v[106:109], v[138:141], v[186:189], v[106:109]
	v_mfma_f32_16x16x32_bf16 v[98:101], v[130:133], v[200:203], v[98:101]
	v_mfma_f32_16x16x32_bf16 v[90:93], v[138:141], v[200:203], v[90:93]
	v_mfma_f32_16x16x32_bf16 v[82:85], v[130:133], v[208:211], v[82:85]
	v_mfma_f32_16x16x32_bf16 v[74:77], v[138:141], v[208:211], v[74:77]
	v_mfma_f32_16x16x32_bf16 v[126:129], v[134:137], v[182:185], v[126:129]
	v_mfma_f32_16x16x32_bf16 v[122:125], v[142:145], v[182:185], v[122:125]
	v_mfma_f32_16x16x32_bf16 v[118:121], v[134:137], v[190:193], v[118:121]
	v_mfma_f32_16x16x32_bf16 v[106:109], v[142:145], v[190:193], v[106:109]
	v_mfma_f32_16x16x32_bf16 v[98:101], v[134:137], v[204:207], v[98:101]
	v_mfma_f32_16x16x32_bf16 v[90:93], v[142:145], v[204:207], v[90:93]
	v_mfma_f32_16x16x32_bf16 v[82:85], v[134:137], v[212:215], v[82:85]
	v_mfma_f32_16x16x32_bf16 v[74:77], v[142:145], v[212:215], v[74:77]
	v_mfma_f32_16x16x32_bf16 v[114:117], v[146:149], v[162:165], v[114:117]
	v_mfma_f32_16x16x32_bf16 v[110:113], v[154:157], v[162:165], v[110:113]
	v_mfma_f32_16x16x32_bf16 v[102:105], v[146:149], v[186:189], v[102:105]
	v_mfma_f32_16x16x32_bf16 v[94:97], v[154:157], v[186:189], v[94:97]
	v_mfma_f32_16x16x32_bf16 v[86:89], v[146:149], v[200:203], v[86:89]
	v_mfma_f32_16x16x32_bf16 v[78:81], v[154:157], v[200:203], v[78:81]
	v_mfma_f32_16x16x32_bf16 v[70:73], v[146:149], v[208:211], v[70:73]
	v_mfma_f32_16x16x32_bf16 v[66:69], v[154:157], v[208:211], v[66:69]
	v_mfma_f32_16x16x32_bf16 v[114:117], v[150:153], v[182:185], v[114:117]
	v_mfma_f32_16x16x32_bf16 v[110:113], v[158:161], v[182:185], v[110:113]
	v_mfma_f32_16x16x32_bf16 v[102:105], v[150:153], v[190:193], v[102:105]
	v_mfma_f32_16x16x32_bf16 v[94:97], v[158:161], v[190:193], v[94:97]
	v_mfma_f32_16x16x32_bf16 v[86:89], v[150:153], v[204:207], v[86:89]
	v_mfma_f32_16x16x32_bf16 v[78:81], v[158:161], v[204:207], v[78:81]
	v_mfma_f32_16x16x32_bf16 v[70:73], v[150:153], v[212:215], v[70:73]
	v_mfma_f32_16x16x32_bf16 v[66:69], v[158:161], v[212:215], v[66:69]
	s_barrier
; #define PG8_GAS __attribute__((address_space(1)))
; #define PG8_STAGE(bufoff, gbase, voff) do { _Pragma("unroll") for (int _i = 0; _i < 2; ++_i) \
;         __builtin_amdgcn_global_load_lds((const unsigned*)((const char*)(gbase) + (voff)[_i]), (PG8_LAS unsigned*)(lds + (bufoff) + ldsw + _i * 8192), 16, 0, 0); } while (0)
; #define PG8_LDA(dst, b, h) do { _Pragma("unroll") for (int m = 0; m < 4; ++m) _Pragma("unroll") for (int k = 0; k < 2; ++k) dst[m][k] = *(const PG8_LAS bf16x8*)(lds + PG8_SA(b, h) + aoff + m * 2048 + k * 1024); } while (0)
; #define PG8_WAIT_V(n) asm volatile("s_waitcnt vmcnt(" #n ")" ::: "memory")
; #define PG8_WAIT_L(n) asm volatile("s_waitcnt lgkmcnt(" #n ")" ::: "memory")
; #define PG8_BAR __builtin_amdgcn_s_barrier()
; #define PG8_SCHED __builtin_amdgcn_sched_barrier(0)
;     __device__ __forceinline__ void operator()(const f32x4 (&acc)[2][2][4][2], const Unit& un, int wr, int wc, int fr, int fq) const {
;         const int row0 = un.pm * BM + wr * 64 + fr, col0 = un.pn * BM + wc * 32 + 8 * fq;
;         u32x4 rr[2][4][2];
; #pragma unroll
;         for (int ai = 0; ai < 2; ++ai)
; #pragma unroll
;             for (int m = 0; m < 4; ++m)
; #pragma unroll
;                 for (int bj = 0; bj < 2; ++bj) rr[ai][m][bj] = *(const PG8_GAS u32x4*)((PG8_GAS bf16_t*)h + (size_t)(row0 + ai * HALF + m * 16) * 4096 + col0 + bj * HALF);
;         asm volatile("" ::: "memory");
; template <class Epi, class Sched, bool ALIGN_EPI = false, bool SP2 = false, bool F8 = false>
; __device__ __forceinline__ void gemm_phase(PG8_LAS unsigned char* lds, const Gemm g, const Sched& S, const Epi& E) {
;     ...
;         for (int t = 0; t < nt; t += 2) {
;             const bool last = (t == nt - 2);
;             const char* a1 = cA + (size_t)(t + 1) * kstep;
;             const char* a2 = last ? nA : cA + (size_t)(t + 2) * kstep; const char* b2 = last ? nB : cB + (size_t)(t + 2) * kstep;
;     ...
;             PG8_LDA(At, 1, 1); PG8_STAGE(PG8_SB(1, 0), b3, voffB); PG8_STAGE(PG8_SB(1, 1), b3 + hB, voffB); PG8_STAGE(PG8_SA(1, 0), a3, voffA);
;             PG8_WAIT_V(8); PG8_WAIT_L(0); PG8_BAR; PG8_MMA(1, 0, At, B0); PG8_MMA(1, 1, At, B1); PG8_BAR; PG8_SCHED;
	s_setprio 0
	s_add_i32 s26, s56, s36
	v_lshl_add_u64 v[216:217], v[216:217], 0, s[14:15]
	s_mov_b32 m0, s26
	ds_read_b128 v[162:165], v199 offset:49152
	ds_read_b128 v[182:185], v199 offset:50176
	ds_read_b128 v[186:189], v199 offset:51200
	ds_read_b128 v[190:193], v199 offset:52224
	ds_read_b128 v[200:203], v199 offset:53248
	ds_read_b128 v[204:207], v199 offset:54272
	ds_read_b128 v[208:211], v199 offset:55296
	ds_read_b128 v[212:215], v199 offset:56320
	global_load_lds_dwordx4 v[216:217], off
	s_add_i32 m0, s26, 0x2000
	s_add_u32 s26, s30, 0x2b0080
	v_lshl_add_u64 v[216:217], v[218:219], 0, s[14:15]
	s_addc_u32 s27, s31, 0
	s_add_i32 s30, s57, s36
	global_load_lds_dwordx4 v[216:217], off
	v_lshl_add_u64 v[216:217], s[26:27], 0, v[170:171]
	s_mov_b32 m0, s30
	s_nop 0
	global_load_lds_dwordx4 v[216:217], off
	v_lshl_add_u64 v[216:217], s[26:27], 0, v[166:167]
	s_add_i32 m0, s30, 0x2000
	s_nop 0
	global_load_lds_dwordx4 v[216:217], off
	v_lshl_add_u64 v[216:217], v[220:221], 0, s[14:15]
	s_mov_b32 m0, s44
	s_nop 0
	global_load_lds_dwordx4 v[216:217], off
	v_lshl_add_u64 v[216:217], v[222:223], 0, s[14:15]
	s_mov_b32 m0, s45
	s_nop 0
	global_load_lds_dwordx4 v[216:217], off
	s_waitcnt vmcnt(8)
	s_waitcnt lgkmcnt(0)
	s_setprio 1
	s_barrier
	v_mfma_f32_16x16x32_bf16 v[62:65], v[130:133], v[162:165], v[62:65]
	v_mfma_f32_16x16x32_bf16 v[58:61], v[138:141], v[162:165], v[58:61]
	v_mfma_f32_16x16x32_bf16 v[50:53], v[130:133], v[186:189], v[50:53]
	v_mfma_f32_16x16x32_bf16 v[42:45], v[138:141], v[186:189], v[42:45]
	v_mfma_f32_16x16x32_bf16 v[34:37], v[130:133], v[200:203], v[34:37]
	v_mfma_f32_16x16x32_bf16 v[26:29], v[138:141], v[200:203], v[26:29]
	v_mfma_f32_16x16x32_bf16 v[18:21], v[130:133], v[208:211], v[18:21]
	v_mfma_f32_16x16x32_bf16 v[10:13], v[138:141], v[208:211], v[10:13]
	v_mfma_f32_16x16x32_bf16 v[62:65], v[134:137], v[182:185], v[62:65]
	v_mfma_f32_16x16x32_bf16 v[58:61], v[142:145], v[182:185], v[58:61]
	v_mfma_f32_16x16x32_bf16 v[50:53], v[134:137], v[190:193], v[50:53]
	v_mfma_f32_16x16x32_bf16 v[42:45], v[142:145], v[190:193], v[42:45]
	v_mfma_f32_16x16x32_bf16 v[34:37], v[134:137], v[204:207], v[34:37]
	v_mfma_f32_16x16x32_bf16 v[26:29], v[142:145], v[204:207], v[26:29]
	v_mfma_f32_16x16x32_bf16 v[18:21], v[134:137], v[212:215], v[18:21]
	v_mfma_f32_16x16x32_bf16 v[10:13], v[142:145], v[212:215], v[10:13]
	v_mfma_f32_16x16x32_bf16 v[54:57], v[146:149], v[162:165], v[54:57]
	v_mfma_f32_16x16x32_bf16 v[46:49], v[154:157], v[162:165], v[46:49]
	v_mfma_f32_16x16x32_bf16 v[38:41], v[146:149], v[186:189], v[38:41]
	v_mfma_f32_16x16x32_bf16 v[30:33], v[154:157], v[186:189], v[30:33]
	v_mfma_f32_16x16x32_bf16 v[22:25], v[146:149], v[200:203], v[22:25]
	v_mfma_f32_16x16x32_bf16 v[14:17], v[154:157], v[200:203], v[14:17]
	v_mfma_f32_16x16x32_bf16 v[6:9], v[146:149], v[208:211], v[6:9]
	v_mfma_f32_16x16x32_bf16 v[2:5], v[154:157], v[208:211], v[2:5]
	v_mfma_f32_16x16x32_bf16 v[54:57], v[150:153], v[182:185], v[54:57]
	v_mfma_f32_16x16x32_bf16 v[46:49], v[158:161], v[182:185], v[46:49]
	v_mfma_f32_16x16x32_bf16 v[38:41], v[150:153], v[190:193], v[38:41]
	v_mfma_f32_16x16x32_bf16 v[30:33], v[158:161], v[190:193], v[30:33]
	v_mfma_f32_16x16x32_bf16 v[22:25], v[150:153], v[204:207], v[22:25]
	v_mfma_f32_16x16x32_bf16 v[14:17], v[158:161], v[204:207], v[14:17]
	v_mfma_f32_16x16x32_bf16 v[6:9], v[150:153], v[212:215], v[6:9]
	v_mfma_f32_16x16x32_bf16 v[2:5], v[158:161], v[212:215], v[2:5]
	s_add_i32 s55, s55, 2
	s_add_u32 s53, s53, 0x100
	s_addc_u32 s54, s54, 0
	s_cmpk_gt_u32 s55, 0xa9
	s_mov_b64 s[26:27], s[28:29]
	s_cbranch_scc0 .Lber_1078
	s_barrier
	s_setprio 0
	v_lshl_or_b32 v132, s52, 8, v196
	v_lshl_add_u32 v130, s51, 8, v194
	v_ashrrev_i32_e32 v133, 31, v132
	v_lshlrev_b64 v[182:183], 1, v[132:133]
	v_ashrrev_i32_e32 v131, 31, v130
	v_lshl_add_u64 v[132:133], s[12:13], 0, v[182:183]
	v_lshlrev_b64 v[134:135], 13, v[130:131]
	v_lshl_add_u64 v[136:137], v[132:133], 0, v[134:135]
	global_load_dwordx4 v[200:203], v[136:137], off
	global_load_dwordx4 v[204:207], v[136:137], off offset:256
	v_or_b32_e32 v136, 16, v130
	v_ashrrev_i32_e32 v137, 31, v136
	v_lshlrev_b64 v[228:229], 13, v[136:137]
	v_lshl_add_u64 v[136:137], v[132:133], 0, v[228:229]
	global_load_dwordx4 v[208:211], v[136:137], off
	global_load_dwordx4 v[212:215], v[136:137], off offset:256
	v_or_b32_e32 v138, 32, v130
	v_or_b32_e32 v130, 48, v130
	v_ashrrev_i32_e32 v139, 31, v138
	v_ashrrev_i32_e32 v131, 31, v130
	v_lshlrev_b64 v[230:231], 13, v[138:139]
	v_lshlrev_b64 v[192:193], 13, v[130:131]
	v_lshl_add_u64 v[190:191], v[134:135], 0, s[16:17]
	v_lshl_add_u64 v[188:189], v[134:135], 0, s[20:21]
	v_lshl_add_u64 v[186:187], v[134:135], 0, s[22:23]
	v_lshl_add_u64 v[184:185], v[134:135], 0, s[24:25]
	v_lshl_add_u64 v[130:131], s[12:13], 0, v[134:135]
	v_lshl_add_u64 v[134:135], v[132:133], 0, v[230:231]
	v_lshl_add_u64 v[136:137], v[132:133], 0, v[192:193]
	v_lshl_add_u64 v[138:139], v[132:133], 0, v[190:191]
	v_lshl_add_u64 v[140:141], v[132:133], 0, v[188:189]
	v_lshl_add_u64 v[232:233], v[132:133], 0, v[186:187]
	v_lshl_add_u64 v[132:133], v[132:133], 0, v[184:185]
	v_lshl_add_u64 v[234:235], v[130:131], 0, v[182:183]
	global_load_dwordx4 v[216:219], v[134:135], off
	global_load_dwordx4 v[220:223], v[134:135], off offset:256
	global_load_dwordx4 v[224:227], v[136:137], off
	global_load_dwordx4 v[162:165], v[136:137], off offset:256
	global_load_dwordx4 v[158:161], v[138:139], off
	global_load_dwordx4 v[154:157], v[138:139], off offset:256
	global_load_dwordx4 v[150:153], v[140:141], off
	global_load_dwordx4 v[146:149], v[140:141], off offset:256
	global_load_dwordx4 v[142:145], v[232:233], off
	s_nop 0
	global_load_dwordx4 v[138:141], v[232:233], off offset:256
	global_load_dwordx4 v[134:137], v[132:133], off
	s_nop 0
	global_load_dwordx4 v[130:133], v[132:133], off offset:256
	s_and_b64 vcc, exec, s[4:5]
	s_mov_b32 s52, s49
	s_mov_b32 s51, s50
	s_mov_b64 s[28:29], s[8:9]
	s_mov_b64 s[26:27], s[6:7]
	s_waitcnt vmcnt(0)
; #define PG8_GAS __attribute__((address_space(1)))
; __device__ __forceinline__ unsigned cvt_pk_bf16(float lo, float hi) { const f32x2c v = {lo, hi}; return __builtin_bit_cast(unsigned, __builtin_convertvector(v, bf16x2c)); }
; __device__ __forceinline__ float bf_lo(unsigned w) { return __uint_as_float(w << 16); }
; __device__ __forceinline__ float bf_hi(unsigned w) { return __uint_as_float(w & 0xffff0000u); }
;     __device__ __forceinline__ void operator()(const f32x4 (&acc)[2][2][4][2], const Unit& un, int wr, int wc, int fr, int fq) const {
;     ...
; #pragma unroll
;         for (int ai = 0; ai < 2; ++ai)
; #pragma unroll
;             for (int m = 0; m < 4; ++m)
; #pragma unroll
;                 for (int bj = 0; bj < 2; ++bj) { const u32x4 r = rr[ai][m][bj]; const f32x4 v0 = acc[ai][bj][m][0], v1 = acc[ai][bj][m][1];
;                     u32x4 w; w.x = cvt_pk_bf16(v0[0] + bf_lo(r.x), v0[1] + bf_hi(r.x)); w.y = cvt_pk_bf16(v0[2] + bf_lo(r.y), v0[3] + bf_hi(r.y));
;                     w.z = cvt_pk_bf16(v1[0] + bf_lo(r.z), v1[1] + bf_hi(r.z)); w.w = cvt_pk_bf16(v1[2] + bf_lo(r.w), v1[3] + bf_hi(r.w));
;                     *(PG8_GAS u32x4*)((PG8_GAS bf16_t*)h + (size_t)(row0 + ai * HALF + m * 16) * 4096 + col0 + bj * HALF) = w; }
	v_lshlrev_b32_e32 v232, 16, v200
	v_and_b32_e32 v233, 0xffff0000, v200
	v_lshlrev_b32_e32 v200, 16, v201
	v_and_b32_e32 v201, 0xffff0000, v201
	v_lshlrev_b32_e32 v236, 16, v202
	v_and_b32_e32 v237, 0xffff0000, v202
	v_lshlrev_b32_e32 v202, 16, v203
	v_and_b32_e32 v203, 0xffff0000, v203
	v_lshlrev_b32_e32 v238, 16, v204
	v_and_b32_e32 v239, 0xffff0000, v204
	v_lshlrev_b32_e32 v204, 16, v205
	v_and_b32_e32 v205, 0xffff0000, v205
	v_lshlrev_b32_e32 v240, 16, v206
	v_and_b32_e32 v241, 0xffff0000, v206
	v_lshlrev_b32_e32 v206, 16, v207
	v_and_b32_e32 v207, 0xffff0000, v207
	v_pk_add_f32 v[126:127], v[126:127], v[232:233]
	v_pk_add_f32 v[128:129], v[128:129], v[200:201]
	v_pk_add_f32 v[122:123], v[122:123], v[236:237]
	v_pk_add_f32 v[124:125], v[124:125], v[202:203]
	v_pk_add_f32 v[114:115], v[114:115], v[238:239]
	v_pk_add_f32 v[116:117], v[116:117], v[204:205]
	v_pk_add_f32 v[200:201], v[110:111], v[240:241]
	v_pk_add_f32 v[202:203], v[112:113], v[206:207]
	v_cvt_pk_bf16_f32 v110, v126, v127
	v_cvt_pk_bf16_f32 v111, v128, v129
	v_cvt_pk_bf16_f32 v112, v122, v123
	v_cvt_pk_bf16_f32 v113, v124, v125
	v_lshlrev_b32_e32 v242, 16, v208
	v_and_b32_e32 v243, 0xffff0000, v208
	v_lshlrev_b32_e32 v208, 16, v209
	v_and_b32_e32 v209, 0xffff0000, v209
	v_cvt_pk_bf16_f32 v114, v114, v115
	v_cvt_pk_bf16_f32 v115, v116, v117
	v_cvt_pk_bf16_f32 v116, v200, v201
	v_cvt_pk_bf16_f32 v117, v202, v203
	global_store_dwordx4 v[234:235], v[110:113], off
	global_store_dwordx4 v[234:235], v[114:117], off offset:256
	v_pk_add_f32 v[118:119], v[118:119], v[242:243]
	v_lshlrev_b32_e32 v110, 16, v210
	v_and_b32_e32 v111, 0xffff0000, v210
	v_pk_add_f32 v[120:121], v[120:121], v[208:209]
	v_pk_add_f32 v[106:107], v[106:107], v[110:111]
	v_cvt_pk_bf16_f32 v118, v118, v119
	v_cvt_pk_bf16_f32 v119, v120, v121
	v_cvt_pk_bf16_f32 v120, v106, v107
	v_lshlrev_b32_e32 v106, 16, v211
	v_and_b32_e32 v107, 0xffff0000, v211
	v_pk_add_f32 v[106:107], v[108:109], v[106:107]
	v_lshlrev_b32_e32 v108, 16, v212
	v_and_b32_e32 v109, 0xffff0000, v212
	v_pk_add_f32 v[102:103], v[102:103], v[108:109]
	v_lshlrev_b32_e32 v108, 16, v213
	v_and_b32_e32 v109, 0xffff0000, v213
	v_pk_add_f32 v[104:105], v[104:105], v[108:109]
	v_cvt_pk_bf16_f32 v102, v102, v103
	v_cvt_pk_bf16_f32 v103, v104, v105
	v_lshlrev_b32_e32 v104, 16, v214
	v_and_b32_e32 v105, 0xffff0000, v214
	v_pk_add_f32 v[94:95], v[94:95], v[104:105]
	v_cvt_pk_bf16_f32 v121, v106, v107
	v_cvt_pk_bf16_f32 v104, v94, v95
	v_lshlrev_b32_e32 v94, 16, v215
	v_and_b32_e32 v95, 0xffff0000, v215
	v_pk_add_f32 v[94:95], v[96:97], v[94:95]
	v_lshlrev_b32_e32 v96, 16, v217
	v_cvt_pk_bf16_f32 v105, v94, v95
	v_lshlrev_b32_e32 v94, 16, v216
	v_and_b32_e32 v95, 0xffff0000, v216
	v_and_b32_e32 v97, 0xffff0000, v217
	v_pk_add_f32 v[94:95], v[98:99], v[94:95]
	v_pk_add_f32 v[96:97], v[100:101], v[96:97]
	v_cvt_pk_bf16_f32 v94, v94, v95
	v_cvt_pk_bf16_f32 v95, v96, v97
	v_lshlrev_b32_e32 v96, 16, v218
	v_and_b32_e32 v97, 0xffff0000, v218
	v_pk_add_f32 v[90:91], v[90:91], v[96:97]
	v_lshl_add_u64 v[106:107], s[12:13], 0, v[228:229]
	v_cvt_pk_bf16_f32 v96, v90, v91
	v_lshlrev_b32_e32 v90, 16, v219
	v_and_b32_e32 v91, 0xffff0000, v219
	v_pk_add_f32 v[90:91], v[92:93], v[90:91]
	v_lshlrev_b32_e32 v92, 16, v220
	v_and_b32_e32 v93, 0xffff0000, v220
	v_pk_add_f32 v[86:87], v[86:87], v[92:93]
	v_lshlrev_b32_e32 v92, 16, v221
	v_and_b32_e32 v93, 0xffff0000, v221
	v_pk_add_f32 v[88:89], v[88:89], v[92:93]
	v_cvt_pk_bf16_f32 v86, v86, v87
	v_cvt_pk_bf16_f32 v87, v88, v89
	v_lshlrev_b32_e32 v88, 16, v222
	v_and_b32_e32 v89, 0xffff0000, v222
	v_pk_add_f32 v[78:79], v[78:79], v[88:89]
	v_cvt_pk_bf16_f32 v97, v90, v91
	v_cvt_pk_bf16_f32 v88, v78, v79
	v_lshlrev_b32_e32 v78, 16, v223
	v_and_b32_e32 v79, 0xffff0000, v223
	v_pk_add_f32 v[78:79], v[80:81], v[78:79]
	v_lshlrev_b32_e32 v80, 16, v225
	v_cvt_pk_bf16_f32 v89, v78, v79
	v_lshlrev_b32_e32 v78, 16, v224
	v_and_b32_e32 v79, 0xffff0000, v224
	v_and_b32_e32 v81, 0xffff0000, v225
	v_pk_add_f32 v[78:79], v[82:83], v[78:79]
	v_pk_add_f32 v[80:81], v[84:85], v[80:81]
	v_cvt_pk_bf16_f32 v78, v78, v79
	v_cvt_pk_bf16_f32 v79, v80, v81
	v_lshlrev_b32_e32 v80, 16, v226
	v_and_b32_e32 v81, 0xffff0000, v226
	v_pk_add_f32 v[74:75], v[74:75], v[80:81]
	v_lshl_add_u64 v[90:91], s[12:13], 0, v[230:231]
	v_cvt_pk_bf16_f32 v80, v74, v75
	v_lshlrev_b32_e32 v74, 16, v227
	v_and_b32_e32 v75, 0xffff0000, v227
	v_pk_add_f32 v[74:75], v[76:77], v[74:75]
	v_lshlrev_b32_e32 v76, 16, v162
	v_and_b32_e32 v77, 0xffff0000, v162
	v_pk_add_f32 v[70:71], v[70:71], v[76:77]
	v_lshlrev_b32_e32 v76, 16, v163
	v_and_b32_e32 v77, 0xffff0000, v163
	v_pk_add_f32 v[72:73], v[72:73], v[76:77]
	v_cvt_pk_bf16_f32 v70, v70, v71
	v_cvt_pk_bf16_f32 v71, v72, v73
	v_lshlrev_b32_e32 v72, 16, v164
	v_and_b32_e32 v73, 0xffff0000, v164
	v_pk_add_f32 v[66:67], v[66:67], v[72:73]
	v_cvt_pk_bf16_f32 v81, v74, v75
	v_cvt_pk_bf16_f32 v72, v66, v67
	v_lshlrev_b32_e32 v66, 16, v165
	v_and_b32_e32 v67, 0xffff0000, v165
	v_pk_add_f32 v[66:67], v[68:69], v[66:67]
	v_lshl_add_u64 v[74:75], s[12:13], 0, v[192:193]
	v_cvt_pk_bf16_f32 v73, v66, v67
	v_lshlrev_b32_e32 v66, 16, v158
	v_and_b32_e32 v67, 0xffff0000, v158
	v_pk_add_f32 v[62:63], v[62:63], v[66:67]
	v_lshlrev_b32_e32 v66, 16, v159
	v_and_b32_e32 v67, 0xffff0000, v159
	v_pk_add_f32 v[64:65], v[64:65], v[66:67]
	v_cvt_pk_bf16_f32 v62, v62, v63
	v_cvt_pk_bf16_f32 v63, v64, v65
	v_lshlrev_b32_e32 v64, 16, v160
	v_and_b32_e32 v65, 0xffff0000, v160
	v_pk_add_f32 v[58:59], v[58:59], v[64:65]
	v_lshl_add_u64 v[106:107], v[106:107], 0, v[182:183]
; #define PG8_GAS __attribute__((address_space(1)))
; __device__ __forceinline__ unsigned cvt_pk_bf16(float lo, float hi) { const f32x2c v = {lo, hi}; return __builtin_bit_cast(unsigned, __builtin_convertvector(v, bf16x2c)); }
; __device__ __forceinline__ float bf_lo(unsigned w) { return __uint_as_float(w << 16); }
; __device__ __forceinline__ float bf_hi(unsigned w) { return __uint_as_float(w & 0xffff0000u); }
; #define PG8_WAIT_V(n) asm volatile("s_waitcnt vmcnt(" #n ")" ::: "memory")
; #define PG8_BAR __builtin_amdgcn_s_barrier()
;     __device__ __forceinline__ void operator()(const f32x4 (&acc)[2][2][4][2], const Unit& un, int wr, int wc, int fr, int fq) const {
;     ...
; #pragma unroll
;         for (int ai = 0; ai < 2; ++ai)
; #pragma unroll
;             for (int m = 0; m < 4; ++m)
; #pragma unroll
;                 for (int bj = 0; bj < 2; ++bj) { const u32x4 r = rr[ai][m][bj]; const f32x4 v0 = acc[ai][bj][m][0], v1 = acc[ai][bj][m][1];
;                     u32x4 w; w.x = cvt_pk_bf16(v0[0] + bf_lo(r.x), v0[1] + bf_hi(r.x)); w.y = cvt_pk_bf16(v0[2] + bf_lo(r.y), v0[3] + bf_hi(r.y));
;                     w.z = cvt_pk_bf16(v1[0] + bf_lo(r.z), v1[1] + bf_hi(r.z)); w.w = cvt_pk_bf16(v1[2] + bf_lo(r.w), v1[3] + bf_hi(r.w));
;                     *(PG8_GAS u32x4*)((PG8_GAS bf16_t*)h + (size_t)(row0 + ai * HALF + m * 16) * 4096 + col0 + bj * HALF) = w; }
; template <class Epi, class Sched, bool ALIGN_EPI = false, bool SP2 = false, bool F8 = false>
; __device__ __forceinline__ void gemm_phase(PG8_LAS unsigned char* lds, const Gemm g, const Sched& S, const Epi& E) {
;     ...
;         if (!has_next) break;
; #pragma unroll
;         for (int a = 0; a < 2; ++a)
; #pragma unroll
;             for (int b = 0; b < 2; ++b)
; #pragma unroll
;                 for (int m = 0; m < 4; ++m)
; #pragma unroll
;                     for (int n = 0; n < 2; ++n) acc[a][b][m][n] = (f32x4){0.f, 0.f, 0.f, 0.f};
;         cur = nxt; cA = nA; cB = nB; ++ui;
;         if constexpr (ALIGN_EPI) { if (wr == 1) PG8_BAR; }
;     }
;     PG8_WAIT_V(0);
;     if constexpr (!ALIGN_EPI) { if (wr == 0) PG8_BAR; }
;     PG8_BAR;
	v_cvt_pk_bf16_f32 v64, v58, v59
	v_lshlrev_b32_e32 v58, 16, v161
	v_and_b32_e32 v59, 0xffff0000, v161
	v_pk_add_f32 v[58:59], v[60:61], v[58:59]
	v_lshlrev_b32_e32 v60, 16, v154
	v_and_b32_e32 v61, 0xffff0000, v154
	v_pk_add_f32 v[54:55], v[54:55], v[60:61]
	v_lshlrev_b32_e32 v60, 16, v155
	v_and_b32_e32 v61, 0xffff0000, v155
	v_pk_add_f32 v[56:57], v[56:57], v[60:61]
	v_cvt_pk_bf16_f32 v54, v54, v55
	v_cvt_pk_bf16_f32 v55, v56, v57
	v_lshlrev_b32_e32 v56, 16, v156
	v_and_b32_e32 v57, 0xffff0000, v156
	v_pk_add_f32 v[46:47], v[46:47], v[56:57]
	v_cvt_pk_bf16_f32 v65, v58, v59
	v_cvt_pk_bf16_f32 v56, v46, v47
	v_lshlrev_b32_e32 v46, 16, v157
	v_and_b32_e32 v47, 0xffff0000, v157
	v_pk_add_f32 v[46:47], v[48:49], v[46:47]
	v_lshlrev_b32_e32 v48, 16, v151
	v_cvt_pk_bf16_f32 v57, v46, v47
	v_lshlrev_b32_e32 v46, 16, v150
	v_and_b32_e32 v47, 0xffff0000, v150
	v_and_b32_e32 v49, 0xffff0000, v151
	v_pk_add_f32 v[46:47], v[50:51], v[46:47]
	v_pk_add_f32 v[48:49], v[52:53], v[48:49]
	v_cvt_pk_bf16_f32 v46, v46, v47
	v_cvt_pk_bf16_f32 v47, v48, v49
	v_lshlrev_b32_e32 v48, 16, v152
	v_and_b32_e32 v49, 0xffff0000, v152
	v_pk_add_f32 v[42:43], v[42:43], v[48:49]
	v_lshl_add_u64 v[58:59], s[12:13], 0, v[190:191]
	v_cvt_pk_bf16_f32 v48, v42, v43
	v_lshlrev_b32_e32 v42, 16, v153
	v_and_b32_e32 v43, 0xffff0000, v153
	v_pk_add_f32 v[42:43], v[44:45], v[42:43]
	v_lshlrev_b32_e32 v44, 16, v146
	v_and_b32_e32 v45, 0xffff0000, v146
	v_pk_add_f32 v[38:39], v[38:39], v[44:45]
	v_lshlrev_b32_e32 v44, 16, v147
	v_and_b32_e32 v45, 0xffff0000, v147
	v_pk_add_f32 v[40:41], v[40:41], v[44:45]
	v_cvt_pk_bf16_f32 v38, v38, v39
	v_cvt_pk_bf16_f32 v39, v40, v41
	v_lshlrev_b32_e32 v40, 16, v148
	v_and_b32_e32 v41, 0xffff0000, v148
	v_pk_add_f32 v[30:31], v[30:31], v[40:41]
	v_cvt_pk_bf16_f32 v49, v42, v43
	v_cvt_pk_bf16_f32 v40, v30, v31
	v_lshlrev_b32_e32 v30, 16, v149
	v_and_b32_e32 v31, 0xffff0000, v149
	v_pk_add_f32 v[30:31], v[32:33], v[30:31]
	v_lshlrev_b32_e32 v32, 16, v143
	v_cvt_pk_bf16_f32 v41, v30, v31
	v_lshlrev_b32_e32 v30, 16, v142
	v_and_b32_e32 v31, 0xffff0000, v142
	v_and_b32_e32 v33, 0xffff0000, v143
	v_pk_add_f32 v[30:31], v[34:35], v[30:31]
	v_pk_add_f32 v[32:33], v[36:37], v[32:33]
	v_cvt_pk_bf16_f32 v30, v30, v31
	v_cvt_pk_bf16_f32 v31, v32, v33
	v_lshlrev_b32_e32 v32, 16, v144
	v_and_b32_e32 v33, 0xffff0000, v144
	v_pk_add_f32 v[26:27], v[26:27], v[32:33]
	v_lshl_add_u64 v[42:43], s[12:13], 0, v[188:189]
	v_cvt_pk_bf16_f32 v32, v26, v27
	v_lshlrev_b32_e32 v26, 16, v145
	v_and_b32_e32 v27, 0xffff0000, v145
	v_pk_add_f32 v[26:27], v[28:29], v[26:27]
	v_lshlrev_b32_e32 v28, 16, v138
	v_and_b32_e32 v29, 0xffff0000, v138
	v_pk_add_f32 v[22:23], v[22:23], v[28:29]
	v_lshlrev_b32_e32 v28, 16, v139
	v_and_b32_e32 v29, 0xffff0000, v139
	v_pk_add_f32 v[24:25], v[24:25], v[28:29]
	v_cvt_pk_bf16_f32 v22, v22, v23
	v_cvt_pk_bf16_f32 v23, v24, v25
	v_lshlrev_b32_e32 v24, 16, v140
	v_and_b32_e32 v25, 0xffff0000, v140
	v_pk_add_f32 v[14:15], v[14:15], v[24:25]
	v_cvt_pk_bf16_f32 v33, v26, v27
	v_cvt_pk_bf16_f32 v24, v14, v15
	v_lshlrev_b32_e32 v14, 16, v141
	v_and_b32_e32 v15, 0xffff0000, v141
	v_pk_add_f32 v[14:15], v[16:17], v[14:15]
	v_lshlrev_b32_e32 v16, 16, v135
	v_cvt_pk_bf16_f32 v25, v14, v15
	v_lshlrev_b32_e32 v14, 16, v134
	v_and_b32_e32 v15, 0xffff0000, v134
	v_and_b32_e32 v17, 0xffff0000, v135
	v_pk_add_f32 v[14:15], v[18:19], v[14:15]
	v_pk_add_f32 v[16:17], v[20:21], v[16:17]
	v_cvt_pk_bf16_f32 v14, v14, v15
	v_cvt_pk_bf16_f32 v15, v16, v17
	v_lshlrev_b32_e32 v16, 16, v136
	v_and_b32_e32 v17, 0xffff0000, v136
	v_pk_add_f32 v[10:11], v[10:11], v[16:17]
	v_lshl_add_u64 v[26:27], s[12:13], 0, v[186:187]
	v_cvt_pk_bf16_f32 v16, v10, v11
	v_lshlrev_b32_e32 v10, 16, v137
	v_and_b32_e32 v11, 0xffff0000, v137
	v_pk_add_f32 v[10:11], v[12:13], v[10:11]
	v_lshlrev_b32_e32 v12, 16, v130
	v_and_b32_e32 v13, 0xffff0000, v130
	v_pk_add_f32 v[6:7], v[6:7], v[12:13]
	v_lshlrev_b32_e32 v12, 16, v131
	v_and_b32_e32 v13, 0xffff0000, v131
	v_pk_add_f32 v[8:9], v[8:9], v[12:13]
	v_cvt_pk_bf16_f32 v6, v6, v7
	v_cvt_pk_bf16_f32 v7, v8, v9
	v_lshlrev_b32_e32 v8, 16, v132
	v_and_b32_e32 v9, 0xffff0000, v132
	v_pk_add_f32 v[2:3], v[2:3], v[8:9]
	v_cvt_pk_bf16_f32 v17, v10, v11
	v_cvt_pk_bf16_f32 v8, v2, v3
	v_lshlrev_b32_e32 v2, 16, v133
	v_and_b32_e32 v3, 0xffff0000, v133
	v_lshl_add_u64 v[10:11], s[12:13], 0, v[184:185]
	v_pk_add_f32 v[2:3], v[4:5], v[2:3]
	v_lshl_add_u64 v[90:91], v[90:91], 0, v[182:183]
	v_lshl_add_u64 v[74:75], v[74:75], 0, v[182:183]
	v_lshl_add_u64 v[58:59], v[58:59], 0, v[182:183]
	v_lshl_add_u64 v[42:43], v[42:43], 0, v[182:183]
	v_lshl_add_u64 v[26:27], v[26:27], 0, v[182:183]
	v_lshl_add_u64 v[10:11], v[10:11], 0, v[182:183]
	v_cvt_pk_bf16_f32 v9, v2, v3
	global_store_dwordx4 v[106:107], v[118:121], off
	global_store_dwordx4 v[106:107], v[102:105], off offset:256
	global_store_dwordx4 v[90:91], v[94:97], off
	global_store_dwordx4 v[90:91], v[86:89], off offset:256
	global_store_dwordx4 v[74:75], v[78:81], off
	global_store_dwordx4 v[74:75], v[70:73], off offset:256
	global_store_dwordx4 v[58:59], v[62:65], off
	global_store_dwordx4 v[58:59], v[54:57], off offset:256
	global_store_dwordx4 v[42:43], v[46:49], off
	global_store_dwordx4 v[42:43], v[38:41], off offset:256
	global_store_dwordx4 v[26:27], v[30:33], off
	global_store_dwordx4 v[26:27], v[22:25], off offset:256
	global_store_dwordx4 v[10:11], v[14:17], off
	global_store_dwordx4 v[10:11], v[6:9], off offset:256
	s_cbranch_vccz .LBB0_1071
	s_waitcnt vmcnt(0)
	s_cmpk_gt_u32 s18, 0xff
	s_cbranch_scc1 .LBB0_1082
	s_barrier
